# LDS-DMA tile loads in the GEMM loops use the SGPR-base (saddr) form; 91 64-bit VALU address adds removed from the load segments
# speedup vs baseline: 1.0043x; 1.0041x over previous
; #define PG8_STAGE(bufoff, gbase, voff) do { _Pragma("unroll") for (int _i = 0; _i < 2; ++_i) \
;         __builtin_amdgcn_global_load_lds((const unsigned*)((const char*)(gbase) + (voff)[_i]), (LAS unsigned*)(lds + (bufoff) + ldsw + _i * 8192), 16, 0, 0); } while (0)
; #define PG8_WAIT_V(n) asm volatile("s_waitcnt vmcnt(" #n ")" ::: "memory")
; #define PG8_BAR __builtin_amdgcn_s_barrier()
; template <class Epi>
; __device__ __forceinline__ void gemm_phase(LAS unsigned char* lds, const Gemm g, const StaticOrder& S, const Epi& E) {
;     ...
;     for (int i = 0; i < 2; ++i) { int R, C; stage_rc(tid * 16 + i * 8192, R, C); const int Rb = Epi::PERM ? ((R & ~31) + perm32(R & 31)) : R;
;         voffA[i] = (unsigned)(R * g.lda + C) * 2u; voffB[i] = (unsigned)(Rb * g.ldb + C) * 2u; }
;     const size_t kstep = (size_t)(BK * 2);
;     const size_t hstepA = (size_t)HALF * g.lda * 2, hstepB = (size_t)HALF * g.ldb * 2;
;     const size_t tstepA = 2 * hstepA, tstepB = 2 * hstepB;
;     const unsigned ldsw = (unsigned)wid * 1024u;
;     const int aoff = lds_byte(wr * 64 + fr, fq * 8), boff = lds_byte(wc * 32 + fr, fq * 8);
;     ...
;     Unit cur, nxt; int ui = 0;
;     if (!S.next(0, cur)) return;
;     f32x4 acc[2][2][4][2];
; #pragma unroll
;     for (int a = 0; a < 2; ++a)
; #pragma unroll
;         for (int b = 0; b < 2; ++b)
; #pragma unroll
;             for (int m = 0; m < 4; ++m)
; #pragma unroll
;                 for (int n = 0; n < 2; ++n) acc[a][b][m][n] = (f32x4){0.f, 0.f, 0.f, 0.f};
;     bf16x8 At[4][2], B0[2][2], B1[2][2];
;     const char* cA = (const char*)g.A + (size_t)cur.pm * tstepA; const char* cB = (const char*)g.Bt + (size_t)cur.pb * tstepB;
;     PG8_STAGE(PG8_SB(0, 0), cB, voffB); PG8_STAGE(PG8_SB(0, 1), cB + hstepB, voffB); PG8_STAGE(PG8_SA(0, 0), cA, voffA); PG8_STAGE(PG8_SA(0, 1), cA + hstepA, voffA);
;     if (wr == 1) PG8_BAR;
;     PG8_WAIT_V(2); PG8_BAR;
;     PG8_STAGE(PG8_SB(1, 0), cB + kstep, voffB); PG8_STAGE(PG8_SA(1, 0), cA + kstep, voffA); PG8_STAGE(PG8_SB(1, 1), cB + hstepB + kstep, voffB);
;     PG8_WAIT_V(6); PG8_BAR;
;     for (;;) {
;         const bool has_next = S.next(ui + 1, nxt);
;         const char* nA = has_next ? (const char*)g.A + (size_t)nxt.pm * tstepA : cA; const char* nB = has_next ? (const char*)g.Bt + (size_t)nxt.pb * tstepB : cB;
;         for (int t = 0; t < nt; t += 2) {
;             const bool last = (t == nt - 2);
.LBB0_238:
	s_ashr_i32 s9, s6, 31
	s_lshr_b32 s9, s9, 26
	s_add_i32 s9, s6, s9
	s_ashr_i32 s49, s9, 6
	s_lshl_b32 s14, s8, 6
	s_lshl_b32 s15, s8, 13
	s_lshl_b32 s7, s7, 5
	s_mov_b64 s[8:9], 0x80
	s_and_b32 s16, s7, 0x60
	s_add_i32 m0, s44, 0x18000
	v_lshl_add_u64 v[6:7], v[6:7], 0, s[8:9]
	s_lshl_b32 s7, s16, 7
	s_waitcnt vmcnt(2)
	s_barrier
	global_load_lds_dwordx4 v[6:7], off
	v_lshl_add_u64 v[4:5], v[4:5], 0, s[8:9]
	s_add_i32 m0, s44, 0x1a000
	s_add_i32 s52, s44, 0x8000
	s_add_i32 s53, s44, 0xa000
	global_load_lds_dwordx4 v[4:5], off
	v_lshl_add_u64 v[0:1], v[0:1], 0, s[8:9]
	s_mov_b32 m0, s52
	s_add_u32 s10, s26, 0x80080
	global_load_lds_dwordx4 v[0:1], off
	v_lshl_add_u64 v[0:1], v[2:3], 0, s[8:9]
	s_mov_b32 m0, s53
	s_addc_u32 s11, s27, 0
	global_load_lds_dwordx4 v[0:1], off
	s_add_i32 m0, s44, 0x1c000
	s_nop 0
	global_load_lds_dwordx4 v132, s[10:11]
	v_lshl_add_u64 v[0:1], s[10:11], 0, v[128:129]
	s_add_i32 m0, s44, 0x1e000
	v_lshlrev_b32_e32 v3, 2, v9
	global_load_lds_dwordx4 v[0:1], off
	v_lshrrev_b32_e32 v1, 1, v9
	v_and_b32_e32 v1, 24, v1
	v_and_b32_e32 v0, 15, v9
	v_lshlrev_b32_e32 v2, 1, v1
	v_lshl_or_b32 v2, v0, 6, v2
	v_or_b32_e32 v136, s14, v0
	v_lshlrev_b32_e32 v0, 15, v13
	v_and_b32_e32 v0, 0xffff0000, v0
	v_or_b32_e32 v147, s16, v1
	v_lshl_add_u32 v0, v12, 12, v0
	v_and_b32_e32 v1, 1, v13
	v_lshl_or_b32 v0, v1, 6, v0
	v_lshl_add_u32 v138, v14, 1, v0
	v_lshlrev_b32_e32 v0, 15, v8
	v_and_b32_e32 v3, 32, v3
	s_cmp_gt_i32 s6, 63
	v_and_b32_e32 v0, 0xffff0000, v0
	v_bitop3_b32 v146, v2, s7, v3 bitop3:0xde
	s_cselect_b64 s[6:7], -1, 0
	s_add_i32 s54, s49, -2
	v_lshl_add_u32 v0, v10, 12, v0
	v_and_b32_e32 v1, 1, v8
	s_waitcnt vmcnt(6)
	s_cmpk_lt_u32 s5, 0x100
	v_lshl_or_b32 v0, v1, 6, v0
	s_sext_i32_i16 s23, s4
	v_bitop3_b32 v4, v2, s15, v3 bitop3:0xde
	s_cselect_b64 s[10:11], -1, 0
	s_ashr_i32 s4, s14, 31
	v_lshl_add_u32 v140, v11, 1, v0
	v_cndmask_b32_e64 v0, 0, 1, s[6:7]
	s_add_i32 s57, 0, 0x10000
	s_add_i32 s58, 0, 0x14000
	v_mov_b32_e32 v137, s4
	s_ashr_i32 s55, s94, 31
	s_mov_b32 s56, s94
	v_mov_b32_e32 v139, v133
	v_mov_b32_e32 v141, v133
	v_mov_b64_e32 v[142:143], 0x1580
	v_mov_b64_e32 v[144:145], 0x157f
	v_cmp_ne_u32_e64 s[4:5], 1, v0
	v_add_u32_e32 v148, s57, v146
	v_add_u32_e32 v149, s58, v146
	v_add_u32_e32 v150, 0, v4
	s_movk_i32 s59, 0x2b00
	s_barrier
	s_branch .LBB0_241

; #define PG8_STAGE(bufoff, gbase, voff) do { _Pragma("unroll") for (int _i = 0; _i < 2; ++_i) \
;         __builtin_amdgcn_global_load_lds((const unsigned*)((const char*)(gbase) + (voff)[_i]), (LAS unsigned*)(lds + (bufoff) + ldsw + _i * 8192), 16, 0, 0); } while (0)
; #define PG8_LDA(dst, b, h) do { _Pragma("unroll") for (int m = 0; m < 4; ++m) _Pragma("unroll") for (int k = 0; k < 2; ++k) dst[m][k] = *(const LAS bf16x8*)(lds + PG8_SA(b, h) + aoff + m * 2048 + k * 1024); } while (0)
; #define PG8_LDB(dst, b, h) do { _Pragma("unroll") for (int n = 0; n < 2; ++n) _Pragma("unroll") for (int k = 0; k < 2; ++k) dst[n][k] = *(const LAS bf16x8*)(lds + PG8_SB(b, h) + boff + n * 2048 + k * 1024); } while (0)
; #define PG8_MMA(ai, bj, At, Bt) do { __builtin_amdgcn_s_setprio(1); _Pragma("unroll") for (int m = 0; m < 4; ++m) _Pragma("unroll") for (int n = 0; n < 2; ++n) _Pragma("unroll") for (int k = 0; k < 2; ++k) \
;         acc[ai][bj][m][n] = __builtin_amdgcn_mfma_f32_16x16x32_bf16(Bt[n][k], At[m][k], acc[ai][bj][m][n], 0, 0, 0); __builtin_amdgcn_s_setprio(0); } while (0)
; #define PG8_WAIT_V(n) asm volatile("s_waitcnt vmcnt(" #n ")" ::: "memory")
; #define PG8_WAIT_L(n) asm volatile("s_waitcnt lgkmcnt(" #n ")" ::: "memory")
; #define PG8_BAR __builtin_amdgcn_s_barrier()
; #define PG8_SCHED __builtin_amdgcn_sched_barrier(0)
; template <class Epi>
; __device__ __forceinline__ void gemm_phase(LAS unsigned char* lds, const Gemm g, const StaticOrder& S, const Epi& E) {
;     ...
;             PG8_LDB(B0, 0, 0); PG8_LDB(B1, 0, 1); PG8_SCHED; PG8_LDA(At, 0, 0); PG8_STAGE(PG8_SA(1, 1), a1 + hstepA, voffA);
;             PG8_WAIT_V(8); PG8_WAIT_L(0); PG8_BAR; PG8_MMA(0, 0, At, B0); PG8_MMA(0, 1, At, B1); PG8_BAR; PG8_SCHED;
;             PG8_LDA(At, 0, 1); PG8_STAGE(PG8_SB(0, 0), b2, voffB); PG8_STAGE(PG8_SB(0, 1), b2 + hstepB, voffB); PG8_STAGE(PG8_SA(0, 0), a2, voffA);
.LBB0_245:
	ds_read_b128 v[152:155], v148
	ds_read_b128 v[156:159], v148 offset:1024
	ds_read_b128 v[160:163], v148 offset:2048
	ds_read_b128 v[164:167], v148 offset:3072
	ds_read_b128 v[168:171], v149
	ds_read_b128 v[172:175], v149 offset:1024
	ds_read_b128 v[176:179], v149 offset:2048
	ds_read_b128 v[180:183], v149 offset:3072
	s_add_i32 s64, s26, 2
	s_add_u32 s27, s24, 0xfff80080
	s_addc_u32 s30, s25, -1
	s_cmp_eq_u32 s54, s26
	s_cselect_b32 s26, s61, s62
	s_cselect_b32 s31, s15, s30
	s_cselect_b32 s30, s17, s27
	s_cselect_b32 s27, s60, s63
	s_add_i32 m0, s44, 0xc000
	ds_read_b128 v[184:187], v150
	ds_read_b128 v[188:191], v150 offset:1024
	ds_read_b128 v[192:195], v150 offset:2048
	ds_read_b128 v[196:199], v150 offset:3072
	ds_read_b128 v[200:203], v150 offset:4096
	ds_read_b128 v[208:211], v150 offset:5120
	ds_read_b128 v[212:215], v150 offset:6144
	ds_read_b128 v[216:219], v150 offset:7168
	global_load_lds_dwordx4 v138, s[24:25]
	s_add_i32 m0, s44, 0xe000
	s_nop 0
	global_load_lds_dwordx4 v140, s[24:25]
	s_waitcnt vmcnt(8)
	s_waitcnt lgkmcnt(0)
	s_barrier
	s_setprio 1
	s_waitcnt lgkmcnt(0)
	v_mfma_f32_16x16x32_bf16 v[120:123], v[152:155], v[184:187], v[120:123]
	v_mfma_f32_16x16x32_bf16 v[120:123], v[156:159], v[188:191], v[120:123]
	v_mfma_f32_16x16x32_bf16 v[116:119], v[164:167], v[188:191], v[116:119]
	v_mfma_f32_16x16x32_bf16 v[116:119], v[160:163], v[184:187], v[116:119]
	v_mfma_f32_16x16x32_bf16 v[124:127], v[168:171], v[184:187], v[124:127]
	v_mfma_f32_16x16x32_bf16 v[124:127], v[172:175], v[188:191], v[124:127]
	v_mfma_f32_16x16x32_bf16 v[112:115], v[180:183], v[188:191], v[112:115]
	v_mfma_f32_16x16x32_bf16 v[112:115], v[176:179], v[184:187], v[112:115]
	v_mfma_f32_16x16x32_bf16 v[96:99], v[176:179], v[192:195], v[96:99]
	v_mfma_f32_16x16x32_bf16 v[96:99], v[180:183], v[196:199], v[96:99]
	v_mfma_f32_16x16x32_bf16 v[104:107], v[172:175], v[196:199], v[104:107]
	v_mfma_f32_16x16x32_bf16 v[104:107], v[168:171], v[192:195], v[104:107]
	v_mfma_f32_16x16x32_bf16 v[100:103], v[160:163], v[192:195], v[100:103]
	v_mfma_f32_16x16x32_bf16 v[100:103], v[164:167], v[196:199], v[100:103]
	v_mfma_f32_16x16x32_bf16 v[108:111], v[156:159], v[196:199], v[108:111]
	v_mfma_f32_16x16x32_bf16 v[108:111], v[152:155], v[192:195], v[108:111]
	s_setprio 0
	s_setprio 1
	v_mfma_f32_16x16x32_bf16 v[92:95], v[152:155], v[200:203], v[92:95]
	v_mfma_f32_16x16x32_bf16 v[92:95], v[156:159], v[208:211], v[92:95]
	v_mfma_f32_16x16x32_bf16 v[84:87], v[164:167], v[208:211], v[84:87]
	v_mfma_f32_16x16x32_bf16 v[84:87], v[160:163], v[200:203], v[84:87]
	v_mfma_f32_16x16x32_bf16 v[88:91], v[168:171], v[200:203], v[88:91]
	v_mfma_f32_16x16x32_bf16 v[88:91], v[172:175], v[208:211], v[88:91]
	v_mfma_f32_16x16x32_bf16 v[80:83], v[180:183], v[208:211], v[80:83]
	v_mfma_f32_16x16x32_bf16 v[80:83], v[176:179], v[200:203], v[80:83]
	v_mfma_f32_16x16x32_bf16 v[64:67], v[176:179], v[212:215], v[64:67]
	v_mfma_f32_16x16x32_bf16 v[64:67], v[180:183], v[216:219], v[64:67]
	v_mfma_f32_16x16x32_bf16 v[72:75], v[172:175], v[216:219], v[72:75]
	v_mfma_f32_16x16x32_bf16 v[72:75], v[168:171], v[212:215], v[72:75]
	v_mfma_f32_16x16x32_bf16 v[68:71], v[160:163], v[212:215], v[68:71]
	v_mfma_f32_16x16x32_bf16 v[68:71], v[164:167], v[216:219], v[68:71]
	v_mfma_f32_16x16x32_bf16 v[76:79], v[156:159], v[216:219], v[76:79]
	v_mfma_f32_16x16x32_bf16 v[76:79], v[152:155], v[212:215], v[76:79]
	s_setprio 0
	s_barrier
	s_add_i32 s65, s57, s33
	v_lshl_add_u64 v[220:221], s[26:27], 0, v[132:133]
	s_mov_b32 m0, s65
	ds_read_b128 v[184:187], v150 offset:16384
	ds_read_b128 v[188:191], v150 offset:17408
	ds_read_b128 v[192:195], v150 offset:18432
	ds_read_b128 v[196:199], v150 offset:19456
	ds_read_b128 v[200:203], v150 offset:20480
	ds_read_b128 v[208:211], v150 offset:21504
	ds_read_b128 v[212:215], v150 offset:22528
	ds_read_b128 v[216:219], v150 offset:23552
	global_load_lds_dwordx4 v[220:221], off
	s_add_i32 m0, s65, 0x2000
	s_add_u32 s66, s26, 0x80000
	v_lshl_add_u64 v[222:223], s[26:27], 0, v[128:129]
	s_addc_u32 s67, s27, 0
	s_add_i32 s65, s58, s33
	global_load_lds_dwordx4 v[222:223], off
	s_mov_b32 m0, s65
	v_lshl_add_u64 v[226:227], s[30:31], 0, v[130:131]
	global_load_lds_dwordx4 v132, s[66:67]
	s_add_i32 m0, s65, 0x2000
	s_nop 0
	global_load_lds_dwordx4 v128, s[66:67]
	v_lshl_add_u64 v[224:225], s[30:31], 0, v[134:135]
	s_mov_b32 m0, s44
	s_nop 0
	global_load_lds_dwordx4 v[224:225], off
	s_mov_b32 m0, s45
	s_nop 0
	global_load_lds_dwordx4 v[226:227], off
	s_waitcnt vmcnt(8)
	s_waitcnt lgkmcnt(0)
	s_barrier
; #define PG8_STAGE(bufoff, gbase, voff) do { _Pragma("unroll") for (int _i = 0; _i < 2; ++_i) \
;         __builtin_amdgcn_global_load_lds((const unsigned*)((const char*)(gbase) + (voff)[_i]), (LAS unsigned*)(lds + (bufoff) + ldsw + _i * 8192), 16, 0, 0); } while (0)
; #define PG8_LDA(dst, b, h) do { _Pragma("unroll") for (int m = 0; m < 4; ++m) _Pragma("unroll") for (int k = 0; k < 2; ++k) dst[m][k] = *(const LAS bf16x8*)(lds + PG8_SA(b, h) + aoff + m * 2048 + k * 1024); } while (0)
; #define PG8_LDB(dst, b, h) do { _Pragma("unroll") for (int n = 0; n < 2; ++n) _Pragma("unroll") for (int k = 0; k < 2; ++k) dst[n][k] = *(const LAS bf16x8*)(lds + PG8_SB(b, h) + boff + n * 2048 + k * 1024); } while (0)
; #define PG8_MMA(ai, bj, At, Bt) do { __builtin_amdgcn_s_setprio(1); _Pragma("unroll") for (int m = 0; m < 4; ++m) _Pragma("unroll") for (int n = 0; n < 2; ++n) _Pragma("unroll") for (int k = 0; k < 2; ++k) \
;         acc[ai][bj][m][n] = __builtin_amdgcn_mfma_f32_16x16x32_bf16(Bt[n][k], At[m][k], acc[ai][bj][m][n], 0, 0, 0); __builtin_amdgcn_s_setprio(0); } while (0)
; #define PG8_WAIT_V(n) asm volatile("s_waitcnt vmcnt(" #n ")" ::: "memory")
; #define PG8_WAIT_L(n) asm volatile("s_waitcnt lgkmcnt(" #n ")" ::: "memory")
; #define PG8_BAR __builtin_amdgcn_s_barrier()
; #define PG8_SCHED __builtin_amdgcn_sched_barrier(0)
; template <class Epi>
; __device__ __forceinline__ void gemm_phase(LAS unsigned char* lds, const Gemm g, const StaticOrder& S, const Epi& E) {
;     ...
;             PG8_WAIT_V(8); PG8_WAIT_L(0); PG8_BAR; PG8_MMA(1, 0, At, B0); PG8_MMA(1, 1, At, B1); PG8_BAR; PG8_SCHED;
;             PG8_LDB(B0, 1, 0); PG8_LDB(B1, 1, 1); PG8_SCHED; PG8_LDA(At, 1, 0); PG8_STAGE(PG8_SA(0, 1), a2 + hstepA, voffA);
;             PG8_WAIT_V(8); PG8_WAIT_L(0); PG8_BAR; PG8_MMA(0, 0, At, B0); PG8_MMA(0, 1, At, B1); PG8_BAR; PG8_SCHED;
	s_setprio 1
	s_waitcnt lgkmcnt(0)
	v_mfma_f32_16x16x32_bf16 v[60:63], v[152:155], v[184:187], v[60:63]
	v_mfma_f32_16x16x32_bf16 v[60:63], v[156:159], v[188:191], v[60:63]
	v_mfma_f32_16x16x32_bf16 v[52:55], v[164:167], v[188:191], v[52:55]
	v_mfma_f32_16x16x32_bf16 v[52:55], v[160:163], v[184:187], v[52:55]
	v_mfma_f32_16x16x32_bf16 v[56:59], v[168:171], v[184:187], v[56:59]
	v_mfma_f32_16x16x32_bf16 v[56:59], v[172:175], v[188:191], v[56:59]
	v_mfma_f32_16x16x32_bf16 v[48:51], v[180:183], v[188:191], v[48:51]
	v_mfma_f32_16x16x32_bf16 v[48:51], v[176:179], v[184:187], v[48:51]
	v_mfma_f32_16x16x32_bf16 v[32:35], v[176:179], v[192:195], v[32:35]
	v_mfma_f32_16x16x32_bf16 v[32:35], v[180:183], v[196:199], v[32:35]
	v_mfma_f32_16x16x32_bf16 v[40:43], v[172:175], v[196:199], v[40:43]
	v_mfma_f32_16x16x32_bf16 v[40:43], v[168:171], v[192:195], v[40:43]
	v_mfma_f32_16x16x32_bf16 v[36:39], v[160:163], v[192:195], v[36:39]
	v_mfma_f32_16x16x32_bf16 v[36:39], v[164:167], v[196:199], v[36:39]
	v_mfma_f32_16x16x32_bf16 v[44:47], v[156:159], v[196:199], v[44:47]
	v_mfma_f32_16x16x32_bf16 v[44:47], v[152:155], v[192:195], v[44:47]
	s_setprio 0
	s_setprio 1
	v_mfma_f32_16x16x32_bf16 v[28:31], v[152:155], v[200:203], v[28:31]
	v_mfma_f32_16x16x32_bf16 v[28:31], v[156:159], v[208:211], v[28:31]
	v_mfma_f32_16x16x32_bf16 v[20:23], v[164:167], v[208:211], v[20:23]
	v_mfma_f32_16x16x32_bf16 v[20:23], v[160:163], v[200:203], v[20:23]
	v_mfma_f32_16x16x32_bf16 v[24:27], v[168:171], v[200:203], v[24:27]
	v_mfma_f32_16x16x32_bf16 v[24:27], v[172:175], v[208:211], v[24:27]
	v_mfma_f32_16x16x32_bf16 v[16:19], v[180:183], v[208:211], v[16:19]
	v_mfma_f32_16x16x32_bf16 v[16:19], v[176:179], v[200:203], v[16:19]
	v_mfma_f32_16x16x32_bf16 v[0:3], v[176:179], v[212:215], v[0:3]
	v_mfma_f32_16x16x32_bf16 v[0:3], v[180:183], v[216:219], v[0:3]
	v_mfma_f32_16x16x32_bf16 v[8:11], v[172:175], v[216:219], v[8:11]
	v_mfma_f32_16x16x32_bf16 v[8:11], v[168:171], v[212:215], v[8:11]
	v_mfma_f32_16x16x32_bf16 v[4:7], v[160:163], v[212:215], v[4:7]
	v_mfma_f32_16x16x32_bf16 v[4:7], v[164:167], v[216:219], v[4:7]
	v_mfma_f32_16x16x32_bf16 v[12:15], v[156:159], v[216:219], v[12:15]
	v_mfma_f32_16x16x32_bf16 v[12:15], v[152:155], v[212:215], v[12:15]
	s_setprio 0
	s_barrier
	s_add_i32 s65, 0, 0x18000
	v_add_u32_e32 v151, s65, v146
	s_add_i32 s66, 0, 0x1c000
	ds_read_b128 v[152:155], v151
	ds_read_b128 v[156:159], v151 offset:1024
	ds_read_b128 v[160:163], v151 offset:2048
	ds_read_b128 v[164:167], v151 offset:3072
	v_add_u32_e32 v151, s66, v146
	ds_read_b128 v[168:171], v151
	ds_read_b128 v[172:175], v151 offset:1024
	ds_read_b128 v[176:179], v151 offset:2048
	ds_read_b128 v[180:183], v151 offset:3072
	s_add_u32 s30, s30, 0x80000
	s_addc_u32 s31, s31, 0
	s_mov_b32 m0, s46
	ds_read_b128 v[184:187], v150 offset:32768
	ds_read_b128 v[188:191], v150 offset:33792
	ds_read_b128 v[192:195], v150 offset:34816
	ds_read_b128 v[196:199], v150 offset:35840
	ds_read_b128 v[200:203], v150 offset:36864
	ds_read_b128 v[208:211], v150 offset:37888
	ds_read_b128 v[212:215], v150 offset:38912
	ds_read_b128 v[216:219], v150 offset:39936
	global_load_lds_dwordx4 v134, s[30:31]
	s_mov_b32 m0, s47
	s_nop 0
	global_load_lds_dwordx4 v130, s[30:31]
	s_waitcnt vmcnt(8)
	s_waitcnt lgkmcnt(0)
	s_barrier
	s_setprio 1
	s_waitcnt lgkmcnt(0)
	v_mfma_f32_16x16x32_bf16 v[120:123], v[152:155], v[184:187], v[120:123]
	v_mfma_f32_16x16x32_bf16 v[120:123], v[156:159], v[188:191], v[120:123]
	v_mfma_f32_16x16x32_bf16 v[116:119], v[164:167], v[188:191], v[116:119]
	v_mfma_f32_16x16x32_bf16 v[116:119], v[160:163], v[184:187], v[116:119]
	v_mfma_f32_16x16x32_bf16 v[124:127], v[168:171], v[184:187], v[124:127]
	v_mfma_f32_16x16x32_bf16 v[124:127], v[172:175], v[188:191], v[124:127]
	v_mfma_f32_16x16x32_bf16 v[112:115], v[180:183], v[188:191], v[112:115]
	v_mfma_f32_16x16x32_bf16 v[112:115], v[176:179], v[184:187], v[112:115]
	v_mfma_f32_16x16x32_bf16 v[96:99], v[176:179], v[192:195], v[96:99]
	v_mfma_f32_16x16x32_bf16 v[96:99], v[180:183], v[196:199], v[96:99]
	v_mfma_f32_16x16x32_bf16 v[104:107], v[172:175], v[196:199], v[104:107]
	v_mfma_f32_16x16x32_bf16 v[104:107], v[168:171], v[192:195], v[104:107]
	v_mfma_f32_16x16x32_bf16 v[100:103], v[160:163], v[192:195], v[100:103]
	v_mfma_f32_16x16x32_bf16 v[100:103], v[164:167], v[196:199], v[100:103]
	v_mfma_f32_16x16x32_bf16 v[108:111], v[156:159], v[196:199], v[108:111]
	v_mfma_f32_16x16x32_bf16 v[108:111], v[152:155], v[192:195], v[108:111]
	s_setprio 0
	s_setprio 1
	v_mfma_f32_16x16x32_bf16 v[92:95], v[152:155], v[200:203], v[92:95]
	v_mfma_f32_16x16x32_bf16 v[92:95], v[156:159], v[208:211], v[92:95]
	v_mfma_f32_16x16x32_bf16 v[84:87], v[164:167], v[208:211], v[84:87]
	v_mfma_f32_16x16x32_bf16 v[84:87], v[160:163], v[200:203], v[84:87]
	v_mfma_f32_16x16x32_bf16 v[88:91], v[168:171], v[200:203], v[88:91]
	v_mfma_f32_16x16x32_bf16 v[88:91], v[172:175], v[208:211], v[88:91]
	v_mfma_f32_16x16x32_bf16 v[80:83], v[180:183], v[208:211], v[80:83]
	v_mfma_f32_16x16x32_bf16 v[80:83], v[176:179], v[200:203], v[80:83]
	v_mfma_f32_16x16x32_bf16 v[64:67], v[176:179], v[212:215], v[64:67]
	v_mfma_f32_16x16x32_bf16 v[64:67], v[180:183], v[216:219], v[64:67]
	v_mfma_f32_16x16x32_bf16 v[72:75], v[172:175], v[216:219], v[72:75]
	v_mfma_f32_16x16x32_bf16 v[72:75], v[168:171], v[212:215], v[72:75]
	v_mfma_f32_16x16x32_bf16 v[68:71], v[160:163], v[212:215], v[68:71]
	v_mfma_f32_16x16x32_bf16 v[68:71], v[164:167], v[216:219], v[68:71]
	v_mfma_f32_16x16x32_bf16 v[76:79], v[156:159], v[216:219], v[76:79]
	v_mfma_f32_16x16x32_bf16 v[76:79], v[152:155], v[212:215], v[76:79]
	s_setprio 0
	s_barrier
; #define PG8_STAGE(bufoff, gbase, voff) do { _Pragma("unroll") for (int _i = 0; _i < 2; ++_i) \
;         __builtin_amdgcn_global_load_lds((const unsigned*)((const char*)(gbase) + (voff)[_i]), (LAS unsigned*)(lds + (bufoff) + ldsw + _i * 8192), 16, 0, 0); } while (0)
; #define PG8_LDA(dst, b, h) do { _Pragma("unroll") for (int m = 0; m < 4; ++m) _Pragma("unroll") for (int k = 0; k < 2; ++k) dst[m][k] = *(const LAS bf16x8*)(lds + PG8_SA(b, h) + aoff + m * 2048 + k * 1024); } while (0)
; #define PG8_MMA(ai, bj, At, Bt) do { __builtin_amdgcn_s_setprio(1); _Pragma("unroll") for (int m = 0; m < 4; ++m) _Pragma("unroll") for (int n = 0; n < 2; ++n) _Pragma("unroll") for (int k = 0; k < 2; ++k) \
;         acc[ai][bj][m][n] = __builtin_amdgcn_mfma_f32_16x16x32_bf16(Bt[n][k], At[m][k], acc[ai][bj][m][n], 0, 0, 0); __builtin_amdgcn_s_setprio(0); } while (0)
; #define PG8_WAIT_V(n) asm volatile("s_waitcnt vmcnt(" #n ")" ::: "memory")
; #define PG8_WAIT_L(n) asm volatile("s_waitcnt lgkmcnt(" #n ")" ::: "memory")
; #define PG8_BAR __builtin_amdgcn_s_barrier()
; #define PG8_SCHED __builtin_amdgcn_sched_barrier(0)
; template <class Epi>
; __device__ __forceinline__ void gemm_phase(LAS unsigned char* lds, const Gemm g, const StaticOrder& S, const Epi& E) {
;     ...
;             PG8_LDA(At, 1, 1); PG8_STAGE(PG8_SB(1, 0), b3, voffB); PG8_STAGE(PG8_SB(1, 1), b3 + hstepB, voffB); PG8_STAGE(PG8_SA(1, 0), a3, voffA);
;             PG8_WAIT_V(8); PG8_WAIT_L(0); PG8_BAR; PG8_MMA(1, 0, At, B0); PG8_MMA(1, 1, At, B1); PG8_BAR; PG8_SCHED;
;         }
	s_add_i32 s30, s65, s33
	v_lshl_add_u64 v[220:221], v[220:221], 0, s[8:9]
	s_mov_b32 m0, s30
	ds_read_b128 v[184:187], v150 offset:49152
	ds_read_b128 v[188:191], v150 offset:50176
	ds_read_b128 v[192:195], v150 offset:51200
	ds_read_b128 v[196:199], v150 offset:52224
	ds_read_b128 v[200:203], v150 offset:53248
	ds_read_b128 v[208:211], v150 offset:54272
	ds_read_b128 v[212:215], v150 offset:55296
	ds_read_b128 v[216:219], v150 offset:56320
	global_load_lds_dwordx4 v[220:221], off
	s_add_i32 m0, s30, 0x2000
	s_add_u32 s26, s26, 0x80080
	v_lshl_add_u64 v[220:221], v[222:223], 0, s[8:9]
	s_addc_u32 s27, s27, 0
	s_add_i32 s30, s66, s33
	global_load_lds_dwordx4 v[220:221], off
	s_mov_b32 m0, s30
	s_nop 0
	global_load_lds_dwordx4 v132, s[26:27]
	s_add_i32 m0, s30, 0x2000
	s_nop 0
	global_load_lds_dwordx4 v128, s[26:27]
	v_lshl_add_u64 v[220:221], v[224:225], 0, s[8:9]
	s_mov_b32 m0, s52
	s_nop 0
	global_load_lds_dwordx4 v[220:221], off
	v_lshl_add_u64 v[220:221], v[226:227], 0, s[8:9]
	s_mov_b32 m0, s53
	s_nop 0
	global_load_lds_dwordx4 v[220:221], off
	s_waitcnt vmcnt(8)
	s_waitcnt lgkmcnt(0)
	s_barrier
	s_setprio 1
	s_waitcnt lgkmcnt(0)
	v_mfma_f32_16x16x32_bf16 v[60:63], v[152:155], v[184:187], v[60:63]
	v_mfma_f32_16x16x32_bf16 v[60:63], v[156:159], v[188:191], v[60:63]
	v_mfma_f32_16x16x32_bf16 v[52:55], v[164:167], v[188:191], v[52:55]
	v_mfma_f32_16x16x32_bf16 v[52:55], v[160:163], v[184:187], v[52:55]
	v_mfma_f32_16x16x32_bf16 v[56:59], v[168:171], v[184:187], v[56:59]
	v_mfma_f32_16x16x32_bf16 v[56:59], v[172:175], v[188:191], v[56:59]
	v_mfma_f32_16x16x32_bf16 v[48:51], v[180:183], v[188:191], v[48:51]
	v_mfma_f32_16x16x32_bf16 v[48:51], v[176:179], v[184:187], v[48:51]
	v_mfma_f32_16x16x32_bf16 v[32:35], v[176:179], v[192:195], v[32:35]
	v_mfma_f32_16x16x32_bf16 v[32:35], v[180:183], v[196:199], v[32:35]
	v_mfma_f32_16x16x32_bf16 v[40:43], v[172:175], v[196:199], v[40:43]
	v_mfma_f32_16x16x32_bf16 v[40:43], v[168:171], v[192:195], v[40:43]
	v_mfma_f32_16x16x32_bf16 v[36:39], v[160:163], v[192:195], v[36:39]
	v_mfma_f32_16x16x32_bf16 v[36:39], v[164:167], v[196:199], v[36:39]
	v_mfma_f32_16x16x32_bf16 v[44:47], v[156:159], v[196:199], v[44:47]
	v_mfma_f32_16x16x32_bf16 v[44:47], v[152:155], v[192:195], v[44:47]
	s_setprio 0
	s_setprio 1
	v_mfma_f32_16x16x32_bf16 v[28:31], v[152:155], v[200:203], v[28:31]
	v_mfma_f32_16x16x32_bf16 v[28:31], v[156:159], v[208:211], v[28:31]
	v_mfma_f32_16x16x32_bf16 v[20:23], v[164:167], v[208:211], v[20:23]
	v_mfma_f32_16x16x32_bf16 v[20:23], v[160:163], v[200:203], v[20:23]
	v_mfma_f32_16x16x32_bf16 v[24:27], v[168:171], v[200:203], v[24:27]
	v_mfma_f32_16x16x32_bf16 v[24:27], v[172:175], v[208:211], v[24:27]
	v_mfma_f32_16x16x32_bf16 v[16:19], v[180:183], v[208:211], v[16:19]
	v_mfma_f32_16x16x32_bf16 v[16:19], v[176:179], v[200:203], v[16:19]
	v_mfma_f32_16x16x32_bf16 v[0:3], v[176:179], v[212:215], v[0:3]
	v_mfma_f32_16x16x32_bf16 v[0:3], v[180:183], v[216:219], v[0:3]
	v_mfma_f32_16x16x32_bf16 v[8:11], v[172:175], v[216:219], v[8:11]
	v_mfma_f32_16x16x32_bf16 v[8:11], v[168:171], v[212:215], v[8:11]
	v_mfma_f32_16x16x32_bf16 v[4:7], v[160:163], v[212:215], v[4:7]
	v_mfma_f32_16x16x32_bf16 v[4:7], v[164:167], v[216:219], v[4:7]
	v_mfma_f32_16x16x32_bf16 v[12:15], v[156:159], v[216:219], v[12:15]
	v_mfma_f32_16x16x32_bf16 v[12:15], v[152:155], v[212:215], v[12:15]
	s_setprio 0
	s_barrier
	s_add_u32 s24, s24, 0x100
	s_addc_u32 s25, s25, 0
	s_add_u32 s62, s62, 0x100
	s_addc_u32 s63, s63, 0
	s_cmp_ge_i32 s64, s49
	s_mov_b32 s26, s64
	s_cbranch_scc0 .LBB0_245

; #define PG8_STAGE(bufoff, gbase, voff) do { _Pragma("unroll") for (int _i = 0; _i < 2; ++_i) \
;         __builtin_amdgcn_global_load_lds((const unsigned*)((const char*)(gbase) + (voff)[_i]), (LAS unsigned*)(lds + (bufoff) + ldsw + _i * 8192), 16, 0, 0); } while (0)
; #define PG8_WAIT_V(n) asm volatile("s_waitcnt vmcnt(" #n ")" ::: "memory")
; #define PG8_BAR __builtin_amdgcn_s_barrier()
; template <class Epi>
; __device__ __forceinline__ void gemm_phase(LAS unsigned char* lds, const Gemm g, const StaticOrder& S, const Epi& E) {
;     ...
;     for (int i = 0; i < 2; ++i) { int R, C; stage_rc(tid * 16 + i * 8192, R, C); const int Rb = Epi::PERM ? ((R & ~31) + perm32(R & 31)) : R;
;         voffA[i] = (unsigned)(R * g.lda + C) * 2u; voffB[i] = (unsigned)(Rb * g.ldb + C) * 2u; }
;     const size_t kstep = (size_t)(BK * 2);
;     const size_t hstepA = (size_t)HALF * g.lda * 2, hstepB = (size_t)HALF * g.ldb * 2;
;     const size_t tstepA = 2 * hstepA, tstepB = 2 * hstepB;
;     const unsigned ldsw = (unsigned)wid * 1024u;
;     const int aoff = lds_byte(wr * 64 + fr, fq * 8), boff = lds_byte(wc * 32 + fr, fq * 8);
;     ...
;     Unit cur, nxt; int ui = 0;
;     if (!S.next(0, cur)) return;
;     f32x4 acc[2][2][4][2];
; #pragma unroll
;     for (int a = 0; a < 2; ++a)
; #pragma unroll
;         for (int b = 0; b < 2; ++b)
; #pragma unroll
;             for (int m = 0; m < 4; ++m)
; #pragma unroll
;                 for (int n = 0; n < 2; ++n) acc[a][b][m][n] = (f32x4){0.f, 0.f, 0.f, 0.f};
;     bf16x8 At[4][2], B0[2][2], B1[2][2];
;     const char* cA = (const char*)g.A + (size_t)cur.pm * tstepA; const char* cB = (const char*)g.Bt + (size_t)cur.pb * tstepB;
;     PG8_STAGE(PG8_SB(0, 0), cB, voffB); PG8_STAGE(PG8_SB(0, 1), cB + hstepB, voffB); PG8_STAGE(PG8_SA(0, 0), cA, voffA); PG8_STAGE(PG8_SA(0, 1), cA + hstepA, voffA);
;     if (wr == 1) PG8_BAR;
;     PG8_WAIT_V(2); PG8_BAR;
;     PG8_STAGE(PG8_SB(1, 0), cB + kstep, voffB); PG8_STAGE(PG8_SA(1, 0), cA + kstep, voffA); PG8_STAGE(PG8_SB(1, 1), cB + hstepB + kstep, voffB);
;     PG8_WAIT_V(6); PG8_BAR;
;     for (;;) {
;         const bool has_next = S.next(ui + 1, nxt);
;         const char* nA = has_next ? (const char*)g.A + (size_t)nxt.pm * tstepA : cA; const char* nB = has_next ? (const char*)g.Bt + (size_t)nxt.pb * tstepB : cB;
;         for (int t = 0; t < nt; t += 2) {
;             const bool last = (t == nt - 2);
.LBB0_430:
	s_ashr_i32 s10, s7, 31
	s_lshr_b32 s10, s10, 26
	s_add_i32 s10, s7, s10
	s_ashr_i32 s46, s10, 6
	s_lshl_b32 s10, s8, 6
	s_lshl_b32 s11, s8, 13
	s_lshl_b32 s8, s9, 5
	s_mov_b64 s[16:17], 0x80
	s_and_b32 s22, s8, 0x60
	s_add_i32 m0, s41, 0x18000
	v_lshl_add_u64 v[6:7], v[6:7], 0, s[16:17]
	s_lshl_b32 s18, s22, 7
	s_waitcnt vmcnt(2)
	s_barrier
	global_load_lds_dwordx4 v[6:7], off
	v_lshl_add_u64 v[4:5], v[4:5], 0, s[16:17]
	s_add_i32 m0, s41, 0x1a000
	s_add_i32 s47, s41, 0x8000
	s_add_i32 s48, s41, 0xa000
	global_load_lds_dwordx4 v[4:5], off
	v_lshl_add_u64 v[0:1], v[0:1], 0, s[16:17]
	s_mov_b32 m0, s47
	s_add_u32 s8, s30, 0x158080
	global_load_lds_dwordx4 v[0:1], off
	v_lshl_add_u64 v[0:1], v[2:3], 0, s[16:17]
	s_mov_b32 m0, s48
	s_addc_u32 s9, s31, 0
	global_load_lds_dwordx4 v[0:1], off
	s_add_i32 m0, s41, 0x1c000
	s_nop 0
	global_load_lds_dwordx4 v130, s[8:9]
	v_lshl_add_u64 v[0:1], s[8:9], 0, v[134:135]
	s_add_i32 m0, s41, 0x1e000
	v_bfe_u32 v4, v8, 4, 2
	global_load_lds_dwordx4 v[0:1], off
	v_and_b32_e32 v1, 15, v8
	v_lshlrev_b32_e32 v0, 4, v4
	v_lshl_or_b32 v2, v1, 6, v0
	v_lshlrev_b32_e32 v0, 2, v1
	v_and_b32_e32 v3, 32, v0
	s_cmp_gt_i32 s7, 63
	v_bitop3_b32 v207, v2, s18, v3 bitop3:0xde
	s_cselect_b64 s[18:19], -1, 0
	s_add_i32 s49, s46, -2
	s_cmpk_lt_u32 s6, 0x100
	v_bitop3_b32 v6, v2, s11, v3 bitop3:0xde
	s_cselect_b64 s[20:21], -1, 0
	s_ashr_i32 s11, s10, 31
	v_or_b32_e32 v2, s10, v1
	v_mov_b32_e32 v3, s11
	s_ashr_i32 s52, s94, 31
	s_lshl_b64 s[10:11], s[10:11], 2
	s_add_u32 s10, s28, s10
	v_lshlrev_b32_e32 v5, 3, v4
	v_lshlrev_b64 v[136:137], 11, v[2:3]
	s_addc_u32 s11, s29, s11
	v_mov_b32_e32 v1, v131
	v_lshl_add_u64 v[138:139], s[10:11], 0, v[0:1]
	v_or3_b32 v136, s22, v5, v136
	v_lshrrev_b32_e32 v1, 1, v9
	v_mul_lo_u32 v0, v11, s1
	s_mov_b32 s22, 0x15800
	v_mad_u64_u32 v[0:1], s[10:11], v1, s22, v[0:1]
	v_or_b32_e32 v0, v0, v10
	s_mov_b64 s[8:9], 0x158080
	v_add_lshl_u32 v0, v0, v12, 1
	v_mov_b32_e32 v1, v131
	v_lshl_add_u64 v[140:141], v[0:1], 0, s[8:9]
	v_lshrrev_b32_e32 v1, 1, v13
	v_mul_lo_u32 v0, v14, s1
	v_mad_u64_u32 v[0:1], s[10:11], v1, s22, v[0:1]
	s_waitcnt vmcnt(6)
	v_or_b32_e32 v0, v0, v15
	v_add_lshl_u32 v0, v0, v16, 1
	v_mov_b32_e32 v1, v131
	s_add_i32 s54, 0, 0x10000
	s_add_i32 s55, 0, 0x14000
	v_cmp_eq_u32_e64 s[6:7], 0, v4
	s_mov_b32 s53, s94
	v_lshl_add_u64 v[142:143], v[0:1], 0, s[8:9]
	v_mov_b64_e32 v[144:145], 0x400
	v_mov_b64_e32 v[146:147], 0x3ff
	v_add_u32_e32 v218, s54, v207
	v_add_u32_e32 v219, s55, v207
	v_add_u32_e32 v220, 0, v6
	s_mov_b32 s56, 0x20000
	v_mbcnt_hi_u32_b32 v221, -1, v205
	s_mov_b64 s[22:23], 0x160000
	s_mov_b32 s57, 0x160000
	s_mov_b64 s[24:25], 0x160200
	s_mov_b32 s58, 0x80000
	s_mov_b32 s59, 0x90000
	s_mov_b32 s60, 0xa0000
	s_mov_b32 s61, 0xb0000
	s_barrier
	s_branch .LBB0_433

; #define PG8_STAGE(bufoff, gbase, voff) do { _Pragma("unroll") for (int _i = 0; _i < 2; ++_i) \
;         __builtin_amdgcn_global_load_lds((const unsigned*)((const char*)(gbase) + (voff)[_i]), (LAS unsigned*)(lds + (bufoff) + ldsw + _i * 8192), 16, 0, 0); } while (0)
; #define PG8_LDA(dst, b, h) do { _Pragma("unroll") for (int m = 0; m < 4; ++m) _Pragma("unroll") for (int k = 0; k < 2; ++k) dst[m][k] = *(const LAS bf16x8*)(lds + PG8_SA(b, h) + aoff + m * 2048 + k * 1024); } while (0)
; #define PG8_LDB(dst, b, h) do { _Pragma("unroll") for (int n = 0; n < 2; ++n) _Pragma("unroll") for (int k = 0; k < 2; ++k) dst[n][k] = *(const LAS bf16x8*)(lds + PG8_SB(b, h) + boff + n * 2048 + k * 1024); } while (0)
; #define PG8_MMA(ai, bj, At, Bt) do { __builtin_amdgcn_s_setprio(1); _Pragma("unroll") for (int m = 0; m < 4; ++m) _Pragma("unroll") for (int n = 0; n < 2; ++n) _Pragma("unroll") for (int k = 0; k < 2; ++k) \
;         acc[ai][bj][m][n] = __builtin_amdgcn_mfma_f32_16x16x32_bf16(Bt[n][k], At[m][k], acc[ai][bj][m][n], 0, 0, 0); __builtin_amdgcn_s_setprio(0); } while (0)
; #define PG8_WAIT_V(n) asm volatile("s_waitcnt vmcnt(" #n ")" ::: "memory")
; #define PG8_WAIT_L(n) asm volatile("s_waitcnt lgkmcnt(" #n ")" ::: "memory")
; #define PG8_BAR __builtin_amdgcn_s_barrier()
; #define PG8_SCHED __builtin_amdgcn_sched_barrier(0)
; template <class Epi>
; __device__ __forceinline__ void gemm_phase(LAS unsigned char* lds, const Gemm g, const StaticOrder& S, const Epi& E) {
;     ...
;             PG8_LDB(B0, 0, 0); PG8_LDB(B1, 0, 1); PG8_SCHED; PG8_LDA(At, 0, 0); PG8_STAGE(PG8_SA(1, 1), a1 + hstepA, voffA);
;             PG8_WAIT_V(8); PG8_WAIT_L(0); PG8_BAR; PG8_MMA(0, 0, At, B0); PG8_MMA(0, 1, At, B1); PG8_BAR; PG8_SCHED;
;             PG8_LDA(At, 0, 1); PG8_STAGE(PG8_SB(0, 0), b2, voffB); PG8_STAGE(PG8_SB(0, 1), b2 + hstepB, voffB); PG8_STAGE(PG8_SA(0, 0), a2, voffA);
.LBB0_445:
	ds_read_b128 v[148:151], v218
	ds_read_b128 v[152:155], v218 offset:1024
	ds_read_b128 v[156:159], v218 offset:2048
	ds_read_b128 v[160:163], v218 offset:3072
	ds_read_b128 v[164:167], v219
	ds_read_b128 v[168:171], v219 offset:1024
	ds_read_b128 v[172:175], v219 offset:2048
	ds_read_b128 v[176:179], v219 offset:3072
	s_add_i32 s65, s34, 2
	s_add_u32 s30, s4, 0x100
	s_addc_u32 s31, s5, 0
	s_cmp_eq_u32 s49, s34
	s_cselect_b32 s34, s26, s1
	s_cselect_b32 s37, s11, s31
	s_cselect_b32 s36, s10, s30
	s_cselect_b32 s35, s27, s64
	v_lshl_add_u64 v[216:217], s[4:5], 0, v[140:141]
	s_add_i32 m0, s41, 0xc000
	ds_read_b128 v[180:183], v220
	ds_read_b128 v[184:187], v220 offset:1024
	ds_read_b128 v[188:191], v220 offset:2048
	ds_read_b128 v[192:195], v220 offset:3072
	ds_read_b128 v[196:199], v220 offset:4096
	ds_read_b128 v[200:203], v220 offset:5120
	ds_read_b128 v[208:211], v220 offset:6144
	ds_read_b128 v[212:215], v220 offset:7168
	global_load_lds_dwordx4 v[216:217], off
	v_lshl_add_u64 v[216:217], s[4:5], 0, v[142:143]
	s_add_i32 m0, s41, 0xe000
	s_nop 0
	global_load_lds_dwordx4 v[216:217], off
	s_waitcnt vmcnt(8)
	s_waitcnt lgkmcnt(0)
	s_barrier
	s_setprio 1
	s_waitcnt lgkmcnt(0)
	v_mfma_f32_16x16x32_bf16 v[124:127], v[148:151], v[180:183], v[124:127]
	v_mfma_f32_16x16x32_bf16 v[124:127], v[152:155], v[184:187], v[124:127]
	v_mfma_f32_16x16x32_bf16 v[120:123], v[160:163], v[184:187], v[120:123]
	v_mfma_f32_16x16x32_bf16 v[120:123], v[156:159], v[180:183], v[120:123]
	v_mfma_f32_16x16x32_bf16 v[108:111], v[164:167], v[180:183], v[108:111]
	v_mfma_f32_16x16x32_bf16 v[108:111], v[168:171], v[184:187], v[108:111]
	v_mfma_f32_16x16x32_bf16 v[100:103], v[176:179], v[184:187], v[100:103]
	v_mfma_f32_16x16x32_bf16 v[100:103], v[172:175], v[180:183], v[100:103]
	v_mfma_f32_16x16x32_bf16 v[84:87], v[172:175], v[188:191], v[84:87]
	v_mfma_f32_16x16x32_bf16 v[84:87], v[176:179], v[192:195], v[84:87]
	v_mfma_f32_16x16x32_bf16 v[92:95], v[168:171], v[192:195], v[92:95]
	v_mfma_f32_16x16x32_bf16 v[92:95], v[164:167], v[188:191], v[92:95]
	v_mfma_f32_16x16x32_bf16 v[112:115], v[156:159], v[188:191], v[112:115]
	v_mfma_f32_16x16x32_bf16 v[112:115], v[160:163], v[192:195], v[112:115]
	v_mfma_f32_16x16x32_bf16 v[116:119], v[152:155], v[192:195], v[116:119]
	v_mfma_f32_16x16x32_bf16 v[116:119], v[148:151], v[188:191], v[116:119]
	s_setprio 0
	s_setprio 1
	v_mfma_f32_16x16x32_bf16 v[104:107], v[148:151], v[196:199], v[104:107]
	v_mfma_f32_16x16x32_bf16 v[104:107], v[152:155], v[200:203], v[104:107]
	v_mfma_f32_16x16x32_bf16 v[96:99], v[160:163], v[200:203], v[96:99]
	v_mfma_f32_16x16x32_bf16 v[96:99], v[156:159], v[196:199], v[96:99]
	v_mfma_f32_16x16x32_bf16 v[76:79], v[164:167], v[196:199], v[76:79]
	v_mfma_f32_16x16x32_bf16 v[76:79], v[168:171], v[200:203], v[76:79]
	v_mfma_f32_16x16x32_bf16 v[72:75], v[176:179], v[200:203], v[72:75]
	v_mfma_f32_16x16x32_bf16 v[72:75], v[172:175], v[196:199], v[72:75]
	v_mfma_f32_16x16x32_bf16 v[64:67], v[172:175], v[208:211], v[64:67]
	v_mfma_f32_16x16x32_bf16 v[64:67], v[176:179], v[212:215], v[64:67]
	v_mfma_f32_16x16x32_bf16 v[68:71], v[168:171], v[212:215], v[68:71]
	v_mfma_f32_16x16x32_bf16 v[68:71], v[164:167], v[208:211], v[68:71]
	v_mfma_f32_16x16x32_bf16 v[80:83], v[156:159], v[208:211], v[80:83]
	v_mfma_f32_16x16x32_bf16 v[80:83], v[160:163], v[212:215], v[80:83]
	v_mfma_f32_16x16x32_bf16 v[88:91], v[152:155], v[212:215], v[88:91]
	v_mfma_f32_16x16x32_bf16 v[88:91], v[148:151], v[208:211], v[88:91]
	s_setprio 0
	s_barrier
	s_add_i32 s4, s54, s40
	v_lshl_add_u64 v[216:217], s[34:35], 0, v[130:131]
	s_mov_b32 m0, s4
	ds_read_b128 v[180:183], v220 offset:16384
	ds_read_b128 v[184:187], v220 offset:17408
	ds_read_b128 v[188:191], v220 offset:18432
	ds_read_b128 v[192:195], v220 offset:19456
	ds_read_b128 v[196:199], v220 offset:20480
	ds_read_b128 v[200:203], v220 offset:21504
	ds_read_b128 v[208:211], v220 offset:22528
	ds_read_b128 v[212:215], v220 offset:23552
	global_load_lds_dwordx4 v[216:217], off
	s_add_i32 m0, s4, 0x2000
	s_add_u32 s4, s34, 0x158000
	v_lshl_add_u64 v[222:223], s[34:35], 0, v[134:135]
	s_addc_u32 s5, s35, 0
	s_add_i32 s66, s55, s40
	global_load_lds_dwordx4 v[222:223], off
	s_mov_b32 m0, s66
	v_lshl_add_u64 v[226:227], s[36:37], 0, v[132:133]
	global_load_lds_dwordx4 v130, s[4:5]
	s_add_i32 m0, s66, 0x2000
	s_nop 0
	global_load_lds_dwordx4 v134, s[4:5]
	v_lshl_add_u64 v[224:225], s[36:37], 0, v[128:129]
	s_mov_b32 m0, s41
	s_nop 0
	global_load_lds_dwordx4 v[224:225], off
	s_mov_b32 m0, s42
	s_nop 0
	global_load_lds_dwordx4 v[226:227], off
	s_waitcnt vmcnt(8)
	s_waitcnt lgkmcnt(0)
	s_barrier
; #define PG8_STAGE(bufoff, gbase, voff) do { _Pragma("unroll") for (int _i = 0; _i < 2; ++_i) \
;         __builtin_amdgcn_global_load_lds((const unsigned*)((const char*)(gbase) + (voff)[_i]), (LAS unsigned*)(lds + (bufoff) + ldsw + _i * 8192), 16, 0, 0); } while (0)
; #define PG8_LDA(dst, b, h) do { _Pragma("unroll") for (int m = 0; m < 4; ++m) _Pragma("unroll") for (int k = 0; k < 2; ++k) dst[m][k] = *(const LAS bf16x8*)(lds + PG8_SA(b, h) + aoff + m * 2048 + k * 1024); } while (0)
; #define PG8_LDB(dst, b, h) do { _Pragma("unroll") for (int n = 0; n < 2; ++n) _Pragma("unroll") for (int k = 0; k < 2; ++k) dst[n][k] = *(const LAS bf16x8*)(lds + PG8_SB(b, h) + boff + n * 2048 + k * 1024); } while (0)
; #define PG8_MMA(ai, bj, At, Bt) do { __builtin_amdgcn_s_setprio(1); _Pragma("unroll") for (int m = 0; m < 4; ++m) _Pragma("unroll") for (int n = 0; n < 2; ++n) _Pragma("unroll") for (int k = 0; k < 2; ++k) \
;         acc[ai][bj][m][n] = __builtin_amdgcn_mfma_f32_16x16x32_bf16(Bt[n][k], At[m][k], acc[ai][bj][m][n], 0, 0, 0); __builtin_amdgcn_s_setprio(0); } while (0)
; #define PG8_WAIT_V(n) asm volatile("s_waitcnt vmcnt(" #n ")" ::: "memory")
; #define PG8_WAIT_L(n) asm volatile("s_waitcnt lgkmcnt(" #n ")" ::: "memory")
; #define PG8_BAR __builtin_amdgcn_s_barrier()
; #define PG8_SCHED __builtin_amdgcn_sched_barrier(0)
; template <class Epi>
; __device__ __forceinline__ void gemm_phase(LAS unsigned char* lds, const Gemm g, const StaticOrder& S, const Epi& E) {
;     ...
;             PG8_WAIT_V(8); PG8_WAIT_L(0); PG8_BAR; PG8_MMA(1, 0, At, B0); PG8_MMA(1, 1, At, B1); PG8_BAR; PG8_SCHED;
;             PG8_LDB(B0, 1, 0); PG8_LDB(B1, 1, 1); PG8_SCHED; PG8_LDA(At, 1, 0); PG8_STAGE(PG8_SA(0, 1), a2 + hstepA, voffA);
;             PG8_WAIT_V(8); PG8_WAIT_L(0); PG8_BAR; PG8_MMA(0, 0, At, B0); PG8_MMA(0, 1, At, B1); PG8_BAR; PG8_SCHED;
	s_setprio 1
	s_waitcnt lgkmcnt(0)
	v_mfma_f32_16x16x32_bf16 v[60:63], v[148:151], v[180:183], v[60:63]
	v_mfma_f32_16x16x32_bf16 v[60:63], v[152:155], v[184:187], v[60:63]
	v_mfma_f32_16x16x32_bf16 v[56:59], v[160:163], v[184:187], v[56:59]
	v_mfma_f32_16x16x32_bf16 v[56:59], v[156:159], v[180:183], v[56:59]
	v_mfma_f32_16x16x32_bf16 v[44:47], v[164:167], v[180:183], v[44:47]
	v_mfma_f32_16x16x32_bf16 v[44:47], v[168:171], v[184:187], v[44:47]
	v_mfma_f32_16x16x32_bf16 v[36:39], v[176:179], v[184:187], v[36:39]
	v_mfma_f32_16x16x32_bf16 v[36:39], v[172:175], v[180:183], v[36:39]
	v_mfma_f32_16x16x32_bf16 v[20:23], v[172:175], v[188:191], v[20:23]
	v_mfma_f32_16x16x32_bf16 v[20:23], v[176:179], v[192:195], v[20:23]
	v_mfma_f32_16x16x32_bf16 v[28:31], v[168:171], v[192:195], v[28:31]
	v_mfma_f32_16x16x32_bf16 v[28:31], v[164:167], v[188:191], v[28:31]
	v_mfma_f32_16x16x32_bf16 v[48:51], v[156:159], v[188:191], v[48:51]
	v_mfma_f32_16x16x32_bf16 v[48:51], v[160:163], v[192:195], v[48:51]
	v_mfma_f32_16x16x32_bf16 v[52:55], v[152:155], v[192:195], v[52:55]
	v_mfma_f32_16x16x32_bf16 v[52:55], v[148:151], v[188:191], v[52:55]
	s_setprio 0
	s_setprio 1
	v_mfma_f32_16x16x32_bf16 v[40:43], v[148:151], v[196:199], v[40:43]
	v_mfma_f32_16x16x32_bf16 v[40:43], v[152:155], v[200:203], v[40:43]
	v_mfma_f32_16x16x32_bf16 v[32:35], v[160:163], v[200:203], v[32:35]
	v_mfma_f32_16x16x32_bf16 v[32:35], v[156:159], v[196:199], v[32:35]
	v_mfma_f32_16x16x32_bf16 v[12:15], v[164:167], v[196:199], v[12:15]
	v_mfma_f32_16x16x32_bf16 v[12:15], v[168:171], v[200:203], v[12:15]
	v_mfma_f32_16x16x32_bf16 v[8:11], v[176:179], v[200:203], v[8:11]
	v_mfma_f32_16x16x32_bf16 v[8:11], v[172:175], v[196:199], v[8:11]
	v_mfma_f32_16x16x32_bf16 v[0:3], v[172:175], v[208:211], v[0:3]
	v_mfma_f32_16x16x32_bf16 v[0:3], v[176:179], v[212:215], v[0:3]
	v_mfma_f32_16x16x32_bf16 v[4:7], v[168:171], v[212:215], v[4:7]
	v_mfma_f32_16x16x32_bf16 v[4:7], v[164:167], v[208:211], v[4:7]
	v_mfma_f32_16x16x32_bf16 v[16:19], v[156:159], v[208:211], v[16:19]
	v_mfma_f32_16x16x32_bf16 v[16:19], v[160:163], v[212:215], v[16:19]
	v_mfma_f32_16x16x32_bf16 v[24:27], v[152:155], v[212:215], v[24:27]
	v_mfma_f32_16x16x32_bf16 v[24:27], v[148:151], v[208:211], v[24:27]
	s_setprio 0
	s_barrier
	s_add_i32 s66, 0, 0x18000
	s_add_i32 s67, 0, 0x1c000
	v_add_u32_e32 v160, s66, v207
	v_add_u32_e32 v176, s67, v207
	ds_read_b128 v[148:151], v160
	ds_read_b128 v[152:155], v160 offset:1024
	ds_read_b128 v[156:159], v160 offset:2048
	ds_read_b128 v[160:163], v160 offset:3072
	ds_read_b128 v[164:167], v176
	ds_read_b128 v[168:171], v176 offset:1024
	ds_read_b128 v[172:175], v176 offset:2048
	ds_read_b128 v[176:179], v176 offset:3072
	s_add_u32 s4, s36, 0x158000
	s_addc_u32 s5, s37, 0
	s_mov_b32 m0, s43
	ds_read_b128 v[180:183], v220 offset:32768
	ds_read_b128 v[184:187], v220 offset:33792
	ds_read_b128 v[188:191], v220 offset:34816
	ds_read_b128 v[192:195], v220 offset:35840
	ds_read_b128 v[196:199], v220 offset:36864
	ds_read_b128 v[200:203], v220 offset:37888
	ds_read_b128 v[208:211], v220 offset:38912
	ds_read_b128 v[212:215], v220 offset:39936
	global_load_lds_dwordx4 v128, s[4:5]
	s_mov_b32 m0, s44
	s_nop 0
	global_load_lds_dwordx4 v132, s[4:5]
	s_waitcnt vmcnt(8)
	s_waitcnt lgkmcnt(0)
	s_barrier
	s_setprio 1
	s_waitcnt lgkmcnt(0)
	v_mfma_f32_16x16x32_bf16 v[124:127], v[148:151], v[180:183], v[124:127]
	v_mfma_f32_16x16x32_bf16 v[124:127], v[152:155], v[184:187], v[124:127]
	v_mfma_f32_16x16x32_bf16 v[120:123], v[160:163], v[184:187], v[120:123]
	v_mfma_f32_16x16x32_bf16 v[120:123], v[156:159], v[180:183], v[120:123]
	v_mfma_f32_16x16x32_bf16 v[108:111], v[164:167], v[180:183], v[108:111]
	v_mfma_f32_16x16x32_bf16 v[108:111], v[168:171], v[184:187], v[108:111]
	v_mfma_f32_16x16x32_bf16 v[100:103], v[176:179], v[184:187], v[100:103]
	v_mfma_f32_16x16x32_bf16 v[100:103], v[172:175], v[180:183], v[100:103]
	v_mfma_f32_16x16x32_bf16 v[84:87], v[172:175], v[188:191], v[84:87]
	v_mfma_f32_16x16x32_bf16 v[84:87], v[176:179], v[192:195], v[84:87]
	v_mfma_f32_16x16x32_bf16 v[92:95], v[168:171], v[192:195], v[92:95]
	v_mfma_f32_16x16x32_bf16 v[92:95], v[164:167], v[188:191], v[92:95]
	v_mfma_f32_16x16x32_bf16 v[112:115], v[156:159], v[188:191], v[112:115]
	v_mfma_f32_16x16x32_bf16 v[112:115], v[160:163], v[192:195], v[112:115]
	v_mfma_f32_16x16x32_bf16 v[116:119], v[152:155], v[192:195], v[116:119]
	v_mfma_f32_16x16x32_bf16 v[116:119], v[148:151], v[188:191], v[116:119]
	s_setprio 0
	s_setprio 1
	v_mfma_f32_16x16x32_bf16 v[104:107], v[148:151], v[196:199], v[104:107]
	v_mfma_f32_16x16x32_bf16 v[104:107], v[152:155], v[200:203], v[104:107]
	v_mfma_f32_16x16x32_bf16 v[96:99], v[160:163], v[200:203], v[96:99]
	v_mfma_f32_16x16x32_bf16 v[96:99], v[156:159], v[196:199], v[96:99]
	v_mfma_f32_16x16x32_bf16 v[76:79], v[164:167], v[196:199], v[76:79]
	v_mfma_f32_16x16x32_bf16 v[76:79], v[168:171], v[200:203], v[76:79]
	v_mfma_f32_16x16x32_bf16 v[72:75], v[176:179], v[200:203], v[72:75]
	v_mfma_f32_16x16x32_bf16 v[72:75], v[172:175], v[196:199], v[72:75]
	v_mfma_f32_16x16x32_bf16 v[64:67], v[172:175], v[208:211], v[64:67]
	v_mfma_f32_16x16x32_bf16 v[64:67], v[176:179], v[212:215], v[64:67]
	v_mfma_f32_16x16x32_bf16 v[68:71], v[168:171], v[212:215], v[68:71]
	v_mfma_f32_16x16x32_bf16 v[68:71], v[164:167], v[208:211], v[68:71]
	v_mfma_f32_16x16x32_bf16 v[80:83], v[156:159], v[208:211], v[80:83]
	v_mfma_f32_16x16x32_bf16 v[80:83], v[160:163], v[212:215], v[80:83]
	v_mfma_f32_16x16x32_bf16 v[88:91], v[152:155], v[212:215], v[88:91]
	v_mfma_f32_16x16x32_bf16 v[88:91], v[148:151], v[208:211], v[88:91]
	s_setprio 0
	s_barrier
; #define PG8_STAGE(bufoff, gbase, voff) do { _Pragma("unroll") for (int _i = 0; _i < 2; ++_i) \
;         __builtin_amdgcn_global_load_lds((const unsigned*)((const char*)(gbase) + (voff)[_i]), (LAS unsigned*)(lds + (bufoff) + ldsw + _i * 8192), 16, 0, 0); } while (0)
; #define PG8_LDA(dst, b, h) do { _Pragma("unroll") for (int m = 0; m < 4; ++m) _Pragma("unroll") for (int k = 0; k < 2; ++k) dst[m][k] = *(const LAS bf16x8*)(lds + PG8_SA(b, h) + aoff + m * 2048 + k * 1024); } while (0)
; #define PG8_MMA(ai, bj, At, Bt) do { __builtin_amdgcn_s_setprio(1); _Pragma("unroll") for (int m = 0; m < 4; ++m) _Pragma("unroll") for (int n = 0; n < 2; ++n) _Pragma("unroll") for (int k = 0; k < 2; ++k) \
;         acc[ai][bj][m][n] = __builtin_amdgcn_mfma_f32_16x16x32_bf16(Bt[n][k], At[m][k], acc[ai][bj][m][n], 0, 0, 0); __builtin_amdgcn_s_setprio(0); } while (0)
; #define PG8_WAIT_V(n) asm volatile("s_waitcnt vmcnt(" #n ")" ::: "memory")
; #define PG8_WAIT_L(n) asm volatile("s_waitcnt lgkmcnt(" #n ")" ::: "memory")
; #define PG8_BAR __builtin_amdgcn_s_barrier()
; #define PG8_SCHED __builtin_amdgcn_sched_barrier(0)
; template <class Epi>
; __device__ __forceinline__ void gemm_phase(LAS unsigned char* lds, const Gemm g, const StaticOrder& S, const Epi& E) {
;     ...
;             PG8_LDA(At, 1, 1); PG8_STAGE(PG8_SB(1, 0), b3, voffB); PG8_STAGE(PG8_SB(1, 1), b3 + hstepB, voffB); PG8_STAGE(PG8_SA(1, 0), a3, voffA);
;             PG8_WAIT_V(8); PG8_WAIT_L(0); PG8_BAR; PG8_MMA(1, 0, At, B0); PG8_MMA(1, 1, At, B1); PG8_BAR; PG8_SCHED;
;         }
	s_add_i32 s4, s66, s40
	v_lshl_add_u64 v[216:217], v[216:217], 0, s[16:17]
	s_mov_b32 m0, s4
	ds_read_b128 v[180:183], v220 offset:49152
	ds_read_b128 v[184:187], v220 offset:50176
	ds_read_b128 v[188:191], v220 offset:51200
	ds_read_b128 v[192:195], v220 offset:52224
	ds_read_b128 v[196:199], v220 offset:53248
	ds_read_b128 v[200:203], v220 offset:54272
	ds_read_b128 v[208:211], v220 offset:55296
	ds_read_b128 v[212:215], v220 offset:56320
	global_load_lds_dwordx4 v[216:217], off
	s_add_i32 m0, s4, 0x2000
	s_add_u32 s4, s34, 0x158080
	v_lshl_add_u64 v[216:217], v[222:223], 0, s[16:17]
	s_addc_u32 s5, s35, 0
	s_add_i32 s34, s67, s40
	global_load_lds_dwordx4 v[216:217], off
	s_mov_b32 m0, s34
	s_nop 0
	global_load_lds_dwordx4 v130, s[4:5]
	s_add_i32 m0, s34, 0x2000
	s_nop 0
	global_load_lds_dwordx4 v134, s[4:5]
	v_lshl_add_u64 v[216:217], v[224:225], 0, s[16:17]
	s_mov_b32 m0, s47
	s_nop 0
	global_load_lds_dwordx4 v[216:217], off
	v_lshl_add_u64 v[216:217], v[226:227], 0, s[16:17]
	s_mov_b32 m0, s48
	s_nop 0
	global_load_lds_dwordx4 v[216:217], off
	s_waitcnt vmcnt(8)
	s_waitcnt lgkmcnt(0)
	s_barrier
	s_setprio 1
	s_waitcnt lgkmcnt(0)
	v_mfma_f32_16x16x32_bf16 v[60:63], v[148:151], v[180:183], v[60:63]
	v_mfma_f32_16x16x32_bf16 v[60:63], v[152:155], v[184:187], v[60:63]
	v_mfma_f32_16x16x32_bf16 v[56:59], v[160:163], v[184:187], v[56:59]
	v_mfma_f32_16x16x32_bf16 v[56:59], v[156:159], v[180:183], v[56:59]
	v_mfma_f32_16x16x32_bf16 v[44:47], v[164:167], v[180:183], v[44:47]
	v_mfma_f32_16x16x32_bf16 v[44:47], v[168:171], v[184:187], v[44:47]
	v_mfma_f32_16x16x32_bf16 v[36:39], v[176:179], v[184:187], v[36:39]
	v_mfma_f32_16x16x32_bf16 v[36:39], v[172:175], v[180:183], v[36:39]
	v_mfma_f32_16x16x32_bf16 v[20:23], v[172:175], v[188:191], v[20:23]
	v_mfma_f32_16x16x32_bf16 v[20:23], v[176:179], v[192:195], v[20:23]
	v_mfma_f32_16x16x32_bf16 v[28:31], v[168:171], v[192:195], v[28:31]
	v_mfma_f32_16x16x32_bf16 v[28:31], v[164:167], v[188:191], v[28:31]
	v_mfma_f32_16x16x32_bf16 v[48:51], v[156:159], v[188:191], v[48:51]
	v_mfma_f32_16x16x32_bf16 v[48:51], v[160:163], v[192:195], v[48:51]
	v_mfma_f32_16x16x32_bf16 v[52:55], v[152:155], v[192:195], v[52:55]
	v_mfma_f32_16x16x32_bf16 v[52:55], v[148:151], v[188:191], v[52:55]
	s_setprio 0
	s_setprio 1
	v_mfma_f32_16x16x32_bf16 v[40:43], v[148:151], v[196:199], v[40:43]
	v_mfma_f32_16x16x32_bf16 v[40:43], v[152:155], v[200:203], v[40:43]
	v_mfma_f32_16x16x32_bf16 v[32:35], v[160:163], v[200:203], v[32:35]
	v_mfma_f32_16x16x32_bf16 v[32:35], v[156:159], v[196:199], v[32:35]
	v_mfma_f32_16x16x32_bf16 v[12:15], v[164:167], v[196:199], v[12:15]
	v_mfma_f32_16x16x32_bf16 v[12:15], v[168:171], v[200:203], v[12:15]
	v_mfma_f32_16x16x32_bf16 v[8:11], v[176:179], v[200:203], v[8:11]
	v_mfma_f32_16x16x32_bf16 v[8:11], v[172:175], v[196:199], v[8:11]
	v_mfma_f32_16x16x32_bf16 v[0:3], v[172:175], v[208:211], v[0:3]
	v_mfma_f32_16x16x32_bf16 v[0:3], v[176:179], v[212:215], v[0:3]
	v_mfma_f32_16x16x32_bf16 v[4:7], v[168:171], v[212:215], v[4:7]
	v_mfma_f32_16x16x32_bf16 v[4:7], v[164:167], v[208:211], v[4:7]
	v_mfma_f32_16x16x32_bf16 v[16:19], v[156:159], v[208:211], v[16:19]
	v_mfma_f32_16x16x32_bf16 v[16:19], v[160:163], v[212:215], v[16:19]
	v_mfma_f32_16x16x32_bf16 v[24:27], v[152:155], v[212:215], v[24:27]
	v_mfma_f32_16x16x32_bf16 v[24:27], v[148:151], v[208:211], v[24:27]
	s_setprio 0
	s_barrier
	s_add_u32 s1, s1, 0x100
	s_addc_u32 s64, s64, 0
	s_cmp_ge_i32 s65, s46
	s_mov_b64 s[4:5], s[30:31]
	s_mov_b32 s34, s65
	s_cbranch_scc0 .LBB0_445
;     __device__ __forceinline__ void operator()(Acc& acc, const Unit& u, int wr, int wc, int fr, int fq) const {
;         const size_t off0 = ((size_t)u.pm * BM + wr * 64 + fr) * DM + u.pn * BM + wc * 32 + 8 * fq;
;         u32x4 pa[2][2], pb[2][2];
	v_pk_mul_f32 v[164:165], v[126:127], 0.5 op_sel_hi:[1,0]
	v_pk_mul_f32 v[200:201], v[124:125], 0.5 op_sel_hi:[1,0]
	v_pk_mul_f32 v[202:203], v[122:123], 0.5 op_sel_hi:[1,0]
	v_pk_mul_f32 v[208:209], v[120:121], 0.5 op_sel_hi:[1,0]
	v_pk_mul_f32 v[210:211], v[110:111], 0.5 op_sel_hi:[1,0]
	v_pk_mul_f32 v[212:213], v[108:109], 0.5 op_sel_hi:[1,0]
	v_pk_mul_f32 v[214:215], v[102:103], 0.5 op_sel_hi:[1,0]
	v_pk_mul_f32 v[216:217], v[100:101], 0.5 op_sel_hi:[1,0]
	v_pk_mul_f32 v[188:189], v[118:119], 0.5 op_sel_hi:[1,0]
	v_pk_mul_f32 v[186:187], v[116:117], 0.5 op_sel_hi:[1,0]
	v_pk_mul_f32 v[184:185], v[114:115], 0.5 op_sel_hi:[1,0]
	v_pk_mul_f32 v[182:183], v[112:113], 0.5 op_sel_hi:[1,0]
	v_pk_mul_f32 v[196:197], v[94:95], 0.5 op_sel_hi:[1,0]
	v_pk_mul_f32 v[194:195], v[92:93], 0.5 op_sel_hi:[1,0]
	v_pk_mul_f32 v[192:193], v[86:87], 0.5 op_sel_hi:[1,0]
	v_pk_mul_f32 v[190:191], v[84:85], 0.5 op_sel_hi:[1,0]
	v_pk_mul_f32 v[166:167], v[106:107], 0.5 op_sel_hi:[1,0]
	v_pk_mul_f32 v[168:169], v[104:105], 0.5 op_sel_hi:[1,0]
	v_pk_mul_f32 v[170:171], v[98:99], 0.5 op_sel_hi:[1,0]
	v_pk_mul_f32 v[172:173], v[96:97], 0.5 op_sel_hi:[1,0]
	v_pk_mul_f32 v[174:175], v[78:79], 0.5 op_sel_hi:[1,0]
	v_pk_mul_f32 v[176:177], v[76:77], 0.5 op_sel_hi:[1,0]
	v_pk_mul_f32 v[178:179], v[74:75], 0.5 op_sel_hi:[1,0]
	v_pk_mul_f32 v[180:181], v[72:73], 0.5 op_sel_hi:[1,0]
	v_pk_mul_f32 v[154:155], v[90:91], 0.5 op_sel_hi:[1,0]
	v_pk_mul_f32 v[152:153], v[88:89], 0.5 op_sel_hi:[1,0]
	v_pk_mul_f32 v[150:151], v[82:83], 0.5 op_sel_hi:[1,0]
	v_pk_mul_f32 v[148:149], v[80:81], 0.5 op_sel_hi:[1,0]
	v_pk_mul_f32 v[162:163], v[70:71], 0.5 op_sel_hi:[1,0]
	v_pk_mul_f32 v[160:161], v[68:69], 0.5 op_sel_hi:[1,0]
	v_pk_mul_f32 v[158:159], v[66:67], 0.5 op_sel_hi:[1,0]
	v_pk_mul_f32 v[156:157], v[64:65], 0.5 op_sel_hi:[1,0]
	v_pk_mul_f32 v[112:113], v[62:63], 0.5 op_sel_hi:[1,0]
	v_pk_mul_f32 v[114:115], v[60:61], 0.5 op_sel_hi:[1,0]
	v_pk_mul_f32 v[116:117], v[58:59], 0.5 op_sel_hi:[1,0]
	v_pk_mul_f32 v[118:119], v[56:57], 0.5 op_sel_hi:[1,0]
	v_pk_mul_f32 v[120:121], v[46:47], 0.5 op_sel_hi:[1,0]
	v_pk_mul_f32 v[122:123], v[44:45], 0.5 op_sel_hi:[1,0]
	v_pk_mul_f32 v[124:125], v[38:39], 0.5 op_sel_hi:[1,0]
	v_pk_mul_f32 v[126:127], v[36:37], 0.5 op_sel_hi:[1,0]
	v_pk_mul_f32 v[102:103], v[54:55], 0.5 op_sel_hi:[1,0]
	v_pk_mul_f32 v[100:101], v[52:53], 0.5 op_sel_hi:[1,0]
	v_pk_mul_f32 v[98:99], v[50:51], 0.5 op_sel_hi:[1,0]
	v_pk_mul_f32 v[96:97], v[48:49], 0.5 op_sel_hi:[1,0]
	v_pk_mul_f32 v[110:111], v[30:31], 0.5 op_sel_hi:[1,0]
	v_pk_mul_f32 v[108:109], v[28:29], 0.5 op_sel_hi:[1,0]
	v_pk_mul_f32 v[106:107], v[22:23], 0.5 op_sel_hi:[1,0]
	v_pk_mul_f32 v[104:105], v[20:21], 0.5 op_sel_hi:[1,0]
	v_pk_mul_f32 v[86:87], v[42:43], 0.5 op_sel_hi:[1,0]
	v_pk_mul_f32 v[84:85], v[40:41], 0.5 op_sel_hi:[1,0]
	v_pk_mul_f32 v[82:83], v[34:35], 0.5 op_sel_hi:[1,0]
	v_pk_mul_f32 v[80:81], v[32:33], 0.5 op_sel_hi:[1,0]
	v_pk_mul_f32 v[94:95], v[14:15], 0.5 op_sel_hi:[1,0]
	v_pk_mul_f32 v[92:93], v[12:13], 0.5 op_sel_hi:[1,0]
	v_pk_mul_f32 v[90:91], v[10:11], 0.5 op_sel_hi:[1,0]
	v_pk_mul_f32 v[88:89], v[8:9], 0.5 op_sel_hi:[1,0]
	v_pk_mul_f32 v[70:71], v[26:27], 0.5 op_sel_hi:[1,0]
	v_pk_mul_f32 v[68:69], v[24:25], 0.5 op_sel_hi:[1,0]
	v_pk_mul_f32 v[66:67], v[18:19], 0.5 op_sel_hi:[1,0]
	v_pk_mul_f32 v[64:65], v[16:17], 0.5 op_sel_hi:[1,0]
	v_pk_mul_f32 v[78:79], v[6:7], 0.5 op_sel_hi:[1,0]
	v_pk_mul_f32 v[76:77], v[4:5], 0.5 op_sel_hi:[1,0]
	v_pk_mul_f32 v[74:75], v[2:3], 0.5 op_sel_hi:[1,0]
	v_pk_mul_f32 v[72:73], v[0:1], 0.5 op_sel_hi:[1,0]

; #define PG8_STAGE(bufoff, gbase, voff) do { _Pragma("unroll") for (int _i = 0; _i < 2; ++_i) \
;         __builtin_amdgcn_global_load_lds((const unsigned*)((const char*)(gbase) + (voff)[_i]), (LAS unsigned*)(lds + (bufoff) + ldsw + _i * 8192), 16, 0, 0); } while (0)
; #define PG8_WAIT_V(n) asm volatile("s_waitcnt vmcnt(" #n ")" ::: "memory")
; #define PG8_BAR __builtin_amdgcn_s_barrier()
; template <class Epi>
; __device__ __forceinline__ void gemm_phase(LAS unsigned char* lds, const Gemm g, const StaticOrder& S, const Epi& E) {
;     ...
;     for (int i = 0; i < 2; ++i) { int R, C; stage_rc(tid * 16 + i * 8192, R, C); const int Rb = Epi::PERM ? ((R & ~31) + perm32(R & 31)) : R;
;         voffA[i] = (unsigned)(R * g.lda + C) * 2u; voffB[i] = (unsigned)(Rb * g.ldb + C) * 2u; }
;     const size_t kstep = (size_t)(BK * 2);
;     const size_t hstepA = (size_t)HALF * g.lda * 2, hstepB = (size_t)HALF * g.ldb * 2;
;     const size_t tstepA = 2 * hstepA, tstepB = 2 * hstepB;
;     const unsigned ldsw = (unsigned)wid * 1024u;
;     const int aoff = lds_byte(wr * 64 + fr, fq * 8), boff = lds_byte(wc * 32 + fr, fq * 8);
;     ...
;     Unit cur, nxt; int ui = 0;
;     if (!S.next(0, cur)) return;
;     f32x4 acc[2][2][4][2];
; #pragma unroll
;     for (int a = 0; a < 2; ++a)
; #pragma unroll
;         for (int b = 0; b < 2; ++b)
; #pragma unroll
;             for (int m = 0; m < 4; ++m)
; #pragma unroll
;                 for (int n = 0; n < 2; ++n) acc[a][b][m][n] = (f32x4){0.f, 0.f, 0.f, 0.f};
;     bf16x8 At[4][2], B0[2][2], B1[2][2];
;     const char* cA = (const char*)g.A + (size_t)cur.pm * tstepA; const char* cB = (const char*)g.Bt + (size_t)cur.pb * tstepB;
;     PG8_STAGE(PG8_SB(0, 0), cB, voffB); PG8_STAGE(PG8_SB(0, 1), cB + hstepB, voffB); PG8_STAGE(PG8_SA(0, 0), cA, voffA); PG8_STAGE(PG8_SA(0, 1), cA + hstepA, voffA);
;     if (wr == 1) PG8_BAR;
;     PG8_WAIT_V(2); PG8_BAR;
;     PG8_STAGE(PG8_SB(1, 0), cB + kstep, voffB); PG8_STAGE(PG8_SA(1, 0), cA + kstep, voffA); PG8_STAGE(PG8_SB(1, 1), cB + hstepB + kstep, voffB);
;     PG8_WAIT_V(6); PG8_BAR;
;     for (;;) {
;         const bool has_next = S.next(ui + 1, nxt);
;         const char* nA = has_next ? (const char*)g.A + (size_t)nxt.pm * tstepA : cA; const char* nB = has_next ? (const char*)g.Bt + (size_t)nxt.pb * tstepB : cB;
;         for (int t = 0; t < nt; t += 2) {
;             const bool last = (t == nt - 2);
.LBB0_530:
	s_ashr_i32 s1, s14, 31
	s_lshr_b32 s1, s1, 26
	s_lshl_b32 s5, s7, 5
	s_mov_b64 s[12:13], 0x80
	s_add_i32 s1, s14, s1
	s_and_b32 s46, s5, 0x60
	s_add_i32 m0, s39, 0x18000
	v_lshl_add_u64 v[6:7], v[6:7], 0, s[12:13]
	s_ashr_i32 s44, s1, 6
	s_lshl_b32 s45, s6, 6
	s_lshl_b32 s1, s6, 13
	s_lshl_b32 s5, s46, 7
	s_waitcnt vmcnt(2)
	s_barrier
	global_load_lds_dwordx4 v[6:7], off
	v_lshl_add_u64 v[4:5], v[4:5], 0, s[12:13]
	s_add_i32 m0, s39, 0x1a000
	s_add_i32 s47, s39, 0x8000
	s_add_i32 s48, s39, 0xa000
	global_load_lds_dwordx4 v[4:5], off
	v_lshl_add_u64 v[0:1], v[0:1], 0, s[12:13]
	s_mov_b32 m0, s47
	s_add_u32 s6, s26, 0x80080
	global_load_lds_dwordx4 v[0:1], off
	v_lshl_add_u64 v[0:1], v[2:3], 0, s[12:13]
	s_mov_b32 m0, s48
	s_addc_u32 s7, s27, 0
	global_load_lds_dwordx4 v[0:1], off
	s_add_i32 m0, s39, 0x1c000
	s_nop 0
	global_load_lds_dwordx4 v130, s[6:7]
	v_lshl_add_u64 v[0:1], s[6:7], 0, v[134:135]
	s_add_i32 m0, s39, 0x1e000
	v_and_b32_e32 v152, 15, v8
	global_load_lds_dwordx4 v[0:1], off
	v_lshrrev_b32_e32 v0, 1, v8
	v_and_b32_e32 v153, 24, v0
	v_lshlrev_b32_e32 v0, 1, v153
	v_lshlrev_b32_e32 v1, 2, v8
	v_readlane_b32 s6, v251, 48
	v_lshl_or_b32 v0, v152, 6, v0
	v_and_b32_e32 v1, 32, v1
	v_lshlrev_b32_e32 v136, 5, v152
	v_readlane_b32 s7, v251, 49
	v_bitop3_b32 v2, v0, s1, v1 bitop3:0xde
	v_bitop3_b32 v154, v0, s5, v1 bitop3:0xde
	v_lshl_add_u64 v[0:1], s[6:7], 0, v[136:137]
	v_and_b32_e32 v136, 16, v8
	v_lshl_add_u64 v[138:139], v[0:1], 0, v[136:137]
	v_lshlrev_b32_e32 v0, 15, v9
	v_and_b32_e32 v0, 0xffff0000, v0
	v_lshl_add_u32 v0, v10, 12, v0
	v_and_b32_e32 v1, 1, v9
	v_lshl_or_b32 v0, v1, 6, v0
	s_cmp_gt_i32 s14, 63
	v_lshl_add_u32 v140, v11, 1, v0
	v_lshlrev_b32_e32 v0, 15, v12
	s_cselect_b64 s[14:15], -1, 0
	s_add_i32 s49, s44, -2
	v_and_b32_e32 v0, 0xffff0000, v0
	s_waitcnt vmcnt(6)
	s_cmpk_lt_u32 s16, 0x100
	v_lshl_add_u32 v0, v13, 12, v0
	v_and_b32_e32 v1, 1, v12
	s_cselect_b64 s[16:17], -1, 0
	v_lshl_or_b32 v0, v1, 6, v0
	s_add_i32 s54, 0, 0x10000
	s_add_i32 s55, 0, 0x14000
	s_ashr_i32 s52, s94, 31
	s_mov_b32 s53, s94
	v_mov_b32_e32 v141, v137
	v_lshl_add_u32 v142, v14, 1, v0
	v_mov_b32_e32 v143, v137
	v_mov_b64_e32 v[144:145], 0x800
	v_mov_b64_e32 v[146:147], 0x7ff
	v_add_u32_e32 v155, s54, v154
	v_add_u32_e32 v156, s55, v154
	v_add_u32_e32 v157, 0, v2
	v_mov_b32_e32 v158, 0x358637bd
	s_mov_b32 s56, 0x800000
	s_movk_i32 s57, 0x300
	s_barrier
	s_branch .LBB0_533

; #define PG8_STAGE(bufoff, gbase, voff) do { _Pragma("unroll") for (int _i = 0; _i < 2; ++_i) \
;         __builtin_amdgcn_global_load_lds((const unsigned*)((const char*)(gbase) + (voff)[_i]), (LAS unsigned*)(lds + (bufoff) + ldsw + _i * 8192), 16, 0, 0); } while (0)
; #define PG8_LDA(dst, b, h) do { _Pragma("unroll") for (int m = 0; m < 4; ++m) _Pragma("unroll") for (int k = 0; k < 2; ++k) dst[m][k] = *(const LAS bf16x8*)(lds + PG8_SA(b, h) + aoff + m * 2048 + k * 1024); } while (0)
; #define PG8_LDB(dst, b, h) do { _Pragma("unroll") for (int n = 0; n < 2; ++n) _Pragma("unroll") for (int k = 0; k < 2; ++k) dst[n][k] = *(const LAS bf16x8*)(lds + PG8_SB(b, h) + boff + n * 2048 + k * 1024); } while (0)
; #define PG8_MMA(ai, bj, At, Bt) do { __builtin_amdgcn_s_setprio(1); _Pragma("unroll") for (int m = 0; m < 4; ++m) _Pragma("unroll") for (int n = 0; n < 2; ++n) _Pragma("unroll") for (int k = 0; k < 2; ++k) \
;         acc[ai][bj][m][n] = __builtin_amdgcn_mfma_f32_16x16x32_bf16(Bt[n][k], At[m][k], acc[ai][bj][m][n], 0, 0, 0); __builtin_amdgcn_s_setprio(0); } while (0)
; #define PG8_WAIT_V(n) asm volatile("s_waitcnt vmcnt(" #n ")" ::: "memory")
; #define PG8_WAIT_L(n) asm volatile("s_waitcnt lgkmcnt(" #n ")" ::: "memory")
; #define PG8_BAR __builtin_amdgcn_s_barrier()
; #define PG8_SCHED __builtin_amdgcn_sched_barrier(0)
; template <class Epi>
; __device__ __forceinline__ void gemm_phase(LAS unsigned char* lds, const Gemm g, const StaticOrder& S, const Epi& E) {
;     ...
;             PG8_LDB(B0, 0, 0); PG8_LDB(B1, 0, 1); PG8_SCHED; PG8_LDA(At, 0, 0); PG8_STAGE(PG8_SA(1, 1), a1 + hstepA, voffA);
;             PG8_WAIT_V(8); PG8_WAIT_L(0); PG8_BAR; PG8_MMA(0, 0, At, B0); PG8_MMA(0, 1, At, B1); PG8_BAR; PG8_SCHED;
;             PG8_LDA(At, 0, 1); PG8_STAGE(PG8_SB(0, 0), b2, voffB); PG8_STAGE(PG8_SB(0, 1), b2 + hstepB, voffB); PG8_STAGE(PG8_SA(0, 0), a2, voffA);
.LBB0_541:
	ds_read_b128 v[148:151], v155
	ds_read_b128 v[160:163], v155 offset:1024
	ds_read_b128 v[164:167], v155 offset:2048
	ds_read_b128 v[168:171], v155 offset:3072
	ds_read_b128 v[172:175], v156
	ds_read_b128 v[176:179], v156 offset:1024
	ds_read_b128 v[180:183], v156 offset:2048
	ds_read_b128 v[184:187], v156 offset:3072
	s_add_i32 s35, s26, 2
	s_add_u32 s27, s8, 0xfff80080
	s_addc_u32 s30, s9, -1
	s_cmp_eq_u32 s49, s26
	s_cselect_b32 s26, s21, s33
	s_cselect_b32 s31, s1, s30
	s_cselect_b32 s30, s5, s27
	s_cselect_b32 s27, s19, s34
	s_add_i32 m0, s39, 0xc000
	ds_read_b128 v[188:191], v157
	ds_read_b128 v[192:195], v157 offset:1024
	ds_read_b128 v[196:199], v157 offset:2048
	ds_read_b128 v[200:203], v157 offset:3072
	ds_read_b128 v[208:211], v157 offset:4096
	ds_read_b128 v[212:215], v157 offset:5120
	ds_read_b128 v[216:219], v157 offset:6144
	ds_read_b128 v[220:223], v157 offset:7168
	global_load_lds_dwordx4 v140, s[8:9]
	s_add_i32 m0, s39, 0xe000
	s_nop 0
	global_load_lds_dwordx4 v142, s[8:9]
	s_waitcnt vmcnt(8)
	s_waitcnt lgkmcnt(0)
	s_barrier
	s_setprio 1
	s_waitcnt lgkmcnt(0)
	v_mfma_f32_16x16x32_bf16 v[120:123], v[148:151], v[188:191], v[120:123]
	v_mfma_f32_16x16x32_bf16 v[120:123], v[160:163], v[192:195], v[120:123]
	v_mfma_f32_16x16x32_bf16 v[124:127], v[168:171], v[192:195], v[124:127]
	v_mfma_f32_16x16x32_bf16 v[124:127], v[164:167], v[188:191], v[124:127]
	v_mfma_f32_16x16x32_bf16 v[116:119], v[172:175], v[188:191], v[116:119]
	v_mfma_f32_16x16x32_bf16 v[116:119], v[176:179], v[192:195], v[116:119]
	v_mfma_f32_16x16x32_bf16 v[112:115], v[184:187], v[192:195], v[112:115]
	v_mfma_f32_16x16x32_bf16 v[112:115], v[180:183], v[188:191], v[112:115]
	v_mfma_f32_16x16x32_bf16 v[96:99], v[180:183], v[196:199], v[96:99]
	v_mfma_f32_16x16x32_bf16 v[96:99], v[184:187], v[200:203], v[96:99]
	v_mfma_f32_16x16x32_bf16 v[100:103], v[176:179], v[200:203], v[100:103]
	v_mfma_f32_16x16x32_bf16 v[100:103], v[172:175], v[196:199], v[100:103]
	v_mfma_f32_16x16x32_bf16 v[104:107], v[164:167], v[196:199], v[104:107]
	v_mfma_f32_16x16x32_bf16 v[104:107], v[168:171], v[200:203], v[104:107]
	v_mfma_f32_16x16x32_bf16 v[108:111], v[160:163], v[200:203], v[108:111]
	v_mfma_f32_16x16x32_bf16 v[108:111], v[148:151], v[196:199], v[108:111]
	s_setprio 0
	s_setprio 1
	v_mfma_f32_16x16x32_bf16 v[92:95], v[148:151], v[208:211], v[92:95]
	v_mfma_f32_16x16x32_bf16 v[92:95], v[160:163], v[212:215], v[92:95]
	v_mfma_f32_16x16x32_bf16 v[88:91], v[168:171], v[212:215], v[88:91]
	v_mfma_f32_16x16x32_bf16 v[88:91], v[164:167], v[208:211], v[88:91]
	v_mfma_f32_16x16x32_bf16 v[84:87], v[172:175], v[208:211], v[84:87]
	v_mfma_f32_16x16x32_bf16 v[84:87], v[176:179], v[212:215], v[84:87]
	v_mfma_f32_16x16x32_bf16 v[80:83], v[184:187], v[212:215], v[80:83]
	v_mfma_f32_16x16x32_bf16 v[80:83], v[180:183], v[208:211], v[80:83]
	v_mfma_f32_16x16x32_bf16 v[64:67], v[180:183], v[216:219], v[64:67]
	v_mfma_f32_16x16x32_bf16 v[64:67], v[184:187], v[220:223], v[64:67]
	v_mfma_f32_16x16x32_bf16 v[68:71], v[176:179], v[220:223], v[68:71]
	v_mfma_f32_16x16x32_bf16 v[68:71], v[172:175], v[216:219], v[68:71]
	v_mfma_f32_16x16x32_bf16 v[72:75], v[164:167], v[216:219], v[72:75]
	v_mfma_f32_16x16x32_bf16 v[72:75], v[168:171], v[220:223], v[72:75]
	v_mfma_f32_16x16x32_bf16 v[76:79], v[160:163], v[220:223], v[76:79]
	v_mfma_f32_16x16x32_bf16 v[76:79], v[148:151], v[216:219], v[76:79]
	s_setprio 0
	s_barrier
	s_add_i32 s58, s54, s38
	v_lshl_add_u64 v[224:225], s[26:27], 0, v[130:131]
	s_mov_b32 m0, s58
	ds_read_b128 v[188:191], v157 offset:16384
	ds_read_b128 v[192:195], v157 offset:17408
	ds_read_b128 v[196:199], v157 offset:18432
	ds_read_b128 v[200:203], v157 offset:19456
	ds_read_b128 v[208:211], v157 offset:20480
	ds_read_b128 v[212:215], v157 offset:21504
	ds_read_b128 v[216:219], v157 offset:22528
	ds_read_b128 v[220:223], v157 offset:23552
	global_load_lds_dwordx4 v[224:225], off
	s_add_i32 m0, s58, 0x2000
	s_add_u32 s58, s26, 0x80000
	v_lshl_add_u64 v[226:227], s[26:27], 0, v[134:135]
	s_addc_u32 s59, s27, 0
	s_add_i32 s60, s55, s38
	global_load_lds_dwordx4 v[226:227], off
	s_mov_b32 m0, s60
	v_lshl_add_u64 v[232:233], s[30:31], 0, v[132:133]
	global_load_lds_dwordx4 v130, s[58:59]
	s_add_i32 m0, s60, 0x2000
	s_nop 0
	global_load_lds_dwordx4 v134, s[58:59]
	v_lshl_add_u64 v[230:231], s[30:31], 0, v[128:129]
	s_mov_b32 m0, s39
	s_nop 0
	global_load_lds_dwordx4 v[230:231], off
	s_mov_b32 m0, s40
	s_nop 0
	global_load_lds_dwordx4 v[232:233], off
	s_waitcnt vmcnt(8)
	s_waitcnt lgkmcnt(0)
	s_barrier
; #define PG8_STAGE(bufoff, gbase, voff) do { _Pragma("unroll") for (int _i = 0; _i < 2; ++_i) \
;         __builtin_amdgcn_global_load_lds((const unsigned*)((const char*)(gbase) + (voff)[_i]), (LAS unsigned*)(lds + (bufoff) + ldsw + _i * 8192), 16, 0, 0); } while (0)
; #define PG8_LDA(dst, b, h) do { _Pragma("unroll") for (int m = 0; m < 4; ++m) _Pragma("unroll") for (int k = 0; k < 2; ++k) dst[m][k] = *(const LAS bf16x8*)(lds + PG8_SA(b, h) + aoff + m * 2048 + k * 1024); } while (0)
; #define PG8_LDB(dst, b, h) do { _Pragma("unroll") for (int n = 0; n < 2; ++n) _Pragma("unroll") for (int k = 0; k < 2; ++k) dst[n][k] = *(const LAS bf16x8*)(lds + PG8_SB(b, h) + boff + n * 2048 + k * 1024); } while (0)
; #define PG8_MMA(ai, bj, At, Bt) do { __builtin_amdgcn_s_setprio(1); _Pragma("unroll") for (int m = 0; m < 4; ++m) _Pragma("unroll") for (int n = 0; n < 2; ++n) _Pragma("unroll") for (int k = 0; k < 2; ++k) \
;         acc[ai][bj][m][n] = __builtin_amdgcn_mfma_f32_16x16x32_bf16(Bt[n][k], At[m][k], acc[ai][bj][m][n], 0, 0, 0); __builtin_amdgcn_s_setprio(0); } while (0)
; #define PG8_WAIT_V(n) asm volatile("s_waitcnt vmcnt(" #n ")" ::: "memory")
; #define PG8_WAIT_L(n) asm volatile("s_waitcnt lgkmcnt(" #n ")" ::: "memory")
; #define PG8_BAR __builtin_amdgcn_s_barrier()
; #define PG8_SCHED __builtin_amdgcn_sched_barrier(0)
; template <class Epi>
; __device__ __forceinline__ void gemm_phase(LAS unsigned char* lds, const Gemm g, const StaticOrder& S, const Epi& E) {
;     ...
;             PG8_WAIT_V(8); PG8_WAIT_L(0); PG8_BAR; PG8_MMA(1, 0, At, B0); PG8_MMA(1, 1, At, B1); PG8_BAR; PG8_SCHED;
;             PG8_LDB(B0, 1, 0); PG8_LDB(B1, 1, 1); PG8_SCHED; PG8_LDA(At, 1, 0); PG8_STAGE(PG8_SA(0, 1), a2 + hstepA, voffA);
;             PG8_WAIT_V(8); PG8_WAIT_L(0); PG8_BAR; PG8_MMA(0, 0, At, B0); PG8_MMA(0, 1, At, B1); PG8_BAR; PG8_SCHED;
	s_setprio 1
	s_waitcnt lgkmcnt(0)
	v_mfma_f32_16x16x32_bf16 v[60:63], v[148:151], v[188:191], v[60:63]
	v_mfma_f32_16x16x32_bf16 v[60:63], v[160:163], v[192:195], v[60:63]
	v_mfma_f32_16x16x32_bf16 v[56:59], v[168:171], v[192:195], v[56:59]
	v_mfma_f32_16x16x32_bf16 v[56:59], v[164:167], v[188:191], v[56:59]
	v_mfma_f32_16x16x32_bf16 v[52:55], v[172:175], v[188:191], v[52:55]
	v_mfma_f32_16x16x32_bf16 v[52:55], v[176:179], v[192:195], v[52:55]
	v_mfma_f32_16x16x32_bf16 v[48:51], v[184:187], v[192:195], v[48:51]
	v_mfma_f32_16x16x32_bf16 v[48:51], v[180:183], v[188:191], v[48:51]
	v_mfma_f32_16x16x32_bf16 v[32:35], v[180:183], v[196:199], v[32:35]
	v_mfma_f32_16x16x32_bf16 v[32:35], v[184:187], v[200:203], v[32:35]
	v_mfma_f32_16x16x32_bf16 v[36:39], v[176:179], v[200:203], v[36:39]
	v_mfma_f32_16x16x32_bf16 v[36:39], v[172:175], v[196:199], v[36:39]
	v_mfma_f32_16x16x32_bf16 v[40:43], v[164:167], v[196:199], v[40:43]
	v_mfma_f32_16x16x32_bf16 v[40:43], v[168:171], v[200:203], v[40:43]
	v_mfma_f32_16x16x32_bf16 v[44:47], v[160:163], v[200:203], v[44:47]
	v_mfma_f32_16x16x32_bf16 v[44:47], v[148:151], v[196:199], v[44:47]
	s_setprio 0
	s_setprio 1
	v_mfma_f32_16x16x32_bf16 v[28:31], v[148:151], v[208:211], v[28:31]
	v_mfma_f32_16x16x32_bf16 v[28:31], v[160:163], v[212:215], v[28:31]
	v_mfma_f32_16x16x32_bf16 v[24:27], v[168:171], v[212:215], v[24:27]
	v_mfma_f32_16x16x32_bf16 v[24:27], v[164:167], v[208:211], v[24:27]
	v_mfma_f32_16x16x32_bf16 v[20:23], v[172:175], v[208:211], v[20:23]
	v_mfma_f32_16x16x32_bf16 v[20:23], v[176:179], v[212:215], v[20:23]
	v_mfma_f32_16x16x32_bf16 v[16:19], v[184:187], v[212:215], v[16:19]
	v_mfma_f32_16x16x32_bf16 v[16:19], v[180:183], v[208:211], v[16:19]
	v_mfma_f32_16x16x32_bf16 v[0:3], v[180:183], v[216:219], v[0:3]
	v_mfma_f32_16x16x32_bf16 v[0:3], v[184:187], v[220:223], v[0:3]
	v_mfma_f32_16x16x32_bf16 v[4:7], v[176:179], v[220:223], v[4:7]
	v_mfma_f32_16x16x32_bf16 v[4:7], v[172:175], v[216:219], v[4:7]
	v_mfma_f32_16x16x32_bf16 v[8:11], v[164:167], v[216:219], v[8:11]
	v_mfma_f32_16x16x32_bf16 v[8:11], v[168:171], v[220:223], v[8:11]
	v_mfma_f32_16x16x32_bf16 v[12:15], v[160:163], v[220:223], v[12:15]
	v_mfma_f32_16x16x32_bf16 v[12:15], v[148:151], v[216:219], v[12:15]
	s_setprio 0
	s_barrier
	s_add_i32 s58, 0, 0x18000
	v_add_u32_e32 v136, s58, v154
	s_add_i32 s59, 0, 0x1c000
	ds_read_b128 v[148:151], v136
	ds_read_b128 v[160:163], v136 offset:1024
	ds_read_b128 v[164:167], v136 offset:2048
	ds_read_b128 v[168:171], v136 offset:3072
	v_add_u32_e32 v136, s59, v154
	ds_read_b128 v[172:175], v136
	ds_read_b128 v[176:179], v136 offset:1024
	ds_read_b128 v[180:183], v136 offset:2048
	ds_read_b128 v[184:187], v136 offset:3072
	s_add_u32 s30, s30, 0x80000
	s_addc_u32 s31, s31, 0
	s_mov_b32 m0, s41
	ds_read_b128 v[188:191], v157 offset:32768
	ds_read_b128 v[192:195], v157 offset:33792
	ds_read_b128 v[196:199], v157 offset:34816
	ds_read_b128 v[200:203], v157 offset:35840
	ds_read_b128 v[208:211], v157 offset:36864
	ds_read_b128 v[212:215], v157 offset:37888
	ds_read_b128 v[216:219], v157 offset:38912
	ds_read_b128 v[220:223], v157 offset:39936
	global_load_lds_dwordx4 v128, s[30:31]
	s_mov_b32 m0, s42
	s_nop 0
	global_load_lds_dwordx4 v132, s[30:31]
	s_waitcnt vmcnt(8)
	s_waitcnt lgkmcnt(0)
	s_barrier
	s_setprio 1
	s_waitcnt lgkmcnt(0)
	v_mfma_f32_16x16x32_bf16 v[120:123], v[148:151], v[188:191], v[120:123]
	v_mfma_f32_16x16x32_bf16 v[120:123], v[160:163], v[192:195], v[120:123]
	v_mfma_f32_16x16x32_bf16 v[124:127], v[168:171], v[192:195], v[124:127]
	v_mfma_f32_16x16x32_bf16 v[124:127], v[164:167], v[188:191], v[124:127]
	v_mfma_f32_16x16x32_bf16 v[116:119], v[172:175], v[188:191], v[116:119]
	v_mfma_f32_16x16x32_bf16 v[116:119], v[176:179], v[192:195], v[116:119]
	v_mfma_f32_16x16x32_bf16 v[112:115], v[184:187], v[192:195], v[112:115]
	v_mfma_f32_16x16x32_bf16 v[112:115], v[180:183], v[188:191], v[112:115]
	v_mfma_f32_16x16x32_bf16 v[96:99], v[180:183], v[196:199], v[96:99]
	v_mfma_f32_16x16x32_bf16 v[96:99], v[184:187], v[200:203], v[96:99]
	v_mfma_f32_16x16x32_bf16 v[100:103], v[176:179], v[200:203], v[100:103]
	v_mfma_f32_16x16x32_bf16 v[100:103], v[172:175], v[196:199], v[100:103]
	v_mfma_f32_16x16x32_bf16 v[104:107], v[164:167], v[196:199], v[104:107]
	v_mfma_f32_16x16x32_bf16 v[104:107], v[168:171], v[200:203], v[104:107]
	v_mfma_f32_16x16x32_bf16 v[108:111], v[160:163], v[200:203], v[108:111]
	v_mfma_f32_16x16x32_bf16 v[108:111], v[148:151], v[196:199], v[108:111]
	s_setprio 0
	s_setprio 1
	v_mfma_f32_16x16x32_bf16 v[92:95], v[148:151], v[208:211], v[92:95]
	v_mfma_f32_16x16x32_bf16 v[92:95], v[160:163], v[212:215], v[92:95]
	v_mfma_f32_16x16x32_bf16 v[88:91], v[168:171], v[212:215], v[88:91]
	v_mfma_f32_16x16x32_bf16 v[88:91], v[164:167], v[208:211], v[88:91]
	v_mfma_f32_16x16x32_bf16 v[84:87], v[172:175], v[208:211], v[84:87]
	v_mfma_f32_16x16x32_bf16 v[84:87], v[176:179], v[212:215], v[84:87]
	v_mfma_f32_16x16x32_bf16 v[80:83], v[184:187], v[212:215], v[80:83]
	v_mfma_f32_16x16x32_bf16 v[80:83], v[180:183], v[208:211], v[80:83]
	v_mfma_f32_16x16x32_bf16 v[64:67], v[180:183], v[216:219], v[64:67]
	v_mfma_f32_16x16x32_bf16 v[64:67], v[184:187], v[220:223], v[64:67]
	v_mfma_f32_16x16x32_bf16 v[68:71], v[176:179], v[220:223], v[68:71]
	v_mfma_f32_16x16x32_bf16 v[68:71], v[172:175], v[216:219], v[68:71]
	v_mfma_f32_16x16x32_bf16 v[72:75], v[164:167], v[216:219], v[72:75]
	v_mfma_f32_16x16x32_bf16 v[72:75], v[168:171], v[220:223], v[72:75]
	v_mfma_f32_16x16x32_bf16 v[76:79], v[160:163], v[220:223], v[76:79]
	v_mfma_f32_16x16x32_bf16 v[76:79], v[148:151], v[216:219], v[76:79]
	s_setprio 0
	s_barrier
; #define PG8_STAGE(bufoff, gbase, voff) do { _Pragma("unroll") for (int _i = 0; _i < 2; ++_i) \
;         __builtin_amdgcn_global_load_lds((const unsigned*)((const char*)(gbase) + (voff)[_i]), (LAS unsigned*)(lds + (bufoff) + ldsw + _i * 8192), 16, 0, 0); } while (0)
; #define PG8_LDA(dst, b, h) do { _Pragma("unroll") for (int m = 0; m < 4; ++m) _Pragma("unroll") for (int k = 0; k < 2; ++k) dst[m][k] = *(const LAS bf16x8*)(lds + PG8_SA(b, h) + aoff + m * 2048 + k * 1024); } while (0)
; #define PG8_MMA(ai, bj, At, Bt) do { __builtin_amdgcn_s_setprio(1); _Pragma("unroll") for (int m = 0; m < 4; ++m) _Pragma("unroll") for (int n = 0; n < 2; ++n) _Pragma("unroll") for (int k = 0; k < 2; ++k) \
;         acc[ai][bj][m][n] = __builtin_amdgcn_mfma_f32_16x16x32_bf16(Bt[n][k], At[m][k], acc[ai][bj][m][n], 0, 0, 0); __builtin_amdgcn_s_setprio(0); } while (0)
; #define PG8_WAIT_V(n) asm volatile("s_waitcnt vmcnt(" #n ")" ::: "memory")
; #define PG8_WAIT_L(n) asm volatile("s_waitcnt lgkmcnt(" #n ")" ::: "memory")
; #define PG8_BAR __builtin_amdgcn_s_barrier()
; #define PG8_SCHED __builtin_amdgcn_sched_barrier(0)
; template <class Epi>
; __device__ __forceinline__ void gemm_phase(LAS unsigned char* lds, const Gemm g, const StaticOrder& S, const Epi& E) {
;     ...
;             PG8_LDA(At, 1, 1); PG8_STAGE(PG8_SB(1, 0), b3, voffB); PG8_STAGE(PG8_SB(1, 1), b3 + hstepB, voffB); PG8_STAGE(PG8_SA(1, 0), a3, voffA);
;             PG8_WAIT_V(8); PG8_WAIT_L(0); PG8_BAR; PG8_MMA(1, 0, At, B0); PG8_MMA(1, 1, At, B1); PG8_BAR; PG8_SCHED;
;         }
	s_add_i32 s30, s58, s38
	v_lshl_add_u64 v[224:225], v[224:225], 0, s[12:13]
	s_mov_b32 m0, s30
	ds_read_b128 v[188:191], v157 offset:49152
	ds_read_b128 v[192:195], v157 offset:50176
	ds_read_b128 v[196:199], v157 offset:51200
	ds_read_b128 v[200:203], v157 offset:52224
	ds_read_b128 v[208:211], v157 offset:53248
	ds_read_b128 v[212:215], v157 offset:54272
	ds_read_b128 v[216:219], v157 offset:55296
	ds_read_b128 v[220:223], v157 offset:56320
	global_load_lds_dwordx4 v[224:225], off
	s_add_i32 m0, s30, 0x2000
	s_add_u32 s26, s26, 0x80080
	v_lshl_add_u64 v[224:225], v[226:227], 0, s[12:13]
	s_addc_u32 s27, s27, 0
	s_add_i32 s30, s59, s38
	global_load_lds_dwordx4 v[224:225], off
	s_mov_b32 m0, s30
	s_nop 0
	global_load_lds_dwordx4 v130, s[26:27]
	s_add_i32 m0, s30, 0x2000
	s_nop 0
	global_load_lds_dwordx4 v134, s[26:27]
	v_lshl_add_u64 v[224:225], v[230:231], 0, s[12:13]
	s_mov_b32 m0, s47
	s_nop 0
	global_load_lds_dwordx4 v[224:225], off
	v_lshl_add_u64 v[224:225], v[232:233], 0, s[12:13]
	s_mov_b32 m0, s48
	s_nop 0
	global_load_lds_dwordx4 v[224:225], off
	s_waitcnt vmcnt(8)
	s_waitcnt lgkmcnt(0)
	s_barrier
	s_setprio 1
	s_waitcnt lgkmcnt(0)
	v_mfma_f32_16x16x32_bf16 v[60:63], v[148:151], v[188:191], v[60:63]
	v_mfma_f32_16x16x32_bf16 v[60:63], v[160:163], v[192:195], v[60:63]
	v_mfma_f32_16x16x32_bf16 v[56:59], v[168:171], v[192:195], v[56:59]
	v_mfma_f32_16x16x32_bf16 v[56:59], v[164:167], v[188:191], v[56:59]
	v_mfma_f32_16x16x32_bf16 v[52:55], v[172:175], v[188:191], v[52:55]
	v_mfma_f32_16x16x32_bf16 v[52:55], v[176:179], v[192:195], v[52:55]
	v_mfma_f32_16x16x32_bf16 v[48:51], v[184:187], v[192:195], v[48:51]
	v_mfma_f32_16x16x32_bf16 v[48:51], v[180:183], v[188:191], v[48:51]
	v_mfma_f32_16x16x32_bf16 v[32:35], v[180:183], v[196:199], v[32:35]
	v_mfma_f32_16x16x32_bf16 v[32:35], v[184:187], v[200:203], v[32:35]
	v_mfma_f32_16x16x32_bf16 v[36:39], v[176:179], v[200:203], v[36:39]
	v_mfma_f32_16x16x32_bf16 v[36:39], v[172:175], v[196:199], v[36:39]
	v_mfma_f32_16x16x32_bf16 v[40:43], v[164:167], v[196:199], v[40:43]
	v_mfma_f32_16x16x32_bf16 v[40:43], v[168:171], v[200:203], v[40:43]
	v_mfma_f32_16x16x32_bf16 v[44:47], v[160:163], v[200:203], v[44:47]
	v_mfma_f32_16x16x32_bf16 v[44:47], v[148:151], v[196:199], v[44:47]
	s_setprio 0
	s_setprio 1
	v_mfma_f32_16x16x32_bf16 v[28:31], v[148:151], v[208:211], v[28:31]
	v_mfma_f32_16x16x32_bf16 v[28:31], v[160:163], v[212:215], v[28:31]
	v_mfma_f32_16x16x32_bf16 v[24:27], v[168:171], v[212:215], v[24:27]
	v_mfma_f32_16x16x32_bf16 v[24:27], v[164:167], v[208:211], v[24:27]
	v_mfma_f32_16x16x32_bf16 v[20:23], v[172:175], v[208:211], v[20:23]
	v_mfma_f32_16x16x32_bf16 v[20:23], v[176:179], v[212:215], v[20:23]
	v_mfma_f32_16x16x32_bf16 v[16:19], v[184:187], v[212:215], v[16:19]
	v_mfma_f32_16x16x32_bf16 v[16:19], v[180:183], v[208:211], v[16:19]
	v_mfma_f32_16x16x32_bf16 v[0:3], v[180:183], v[216:219], v[0:3]
	v_mfma_f32_16x16x32_bf16 v[0:3], v[184:187], v[220:223], v[0:3]
	v_mfma_f32_16x16x32_bf16 v[4:7], v[176:179], v[220:223], v[4:7]
	v_mfma_f32_16x16x32_bf16 v[4:7], v[172:175], v[216:219], v[4:7]
	v_mfma_f32_16x16x32_bf16 v[8:11], v[164:167], v[216:219], v[8:11]
	v_mfma_f32_16x16x32_bf16 v[8:11], v[168:171], v[220:223], v[8:11]
	v_mfma_f32_16x16x32_bf16 v[12:15], v[160:163], v[220:223], v[12:15]
	v_mfma_f32_16x16x32_bf16 v[12:15], v[148:151], v[216:219], v[12:15]
	s_setprio 0
	s_barrier
	s_add_u32 s8, s8, 0x100
	s_addc_u32 s9, s9, 0
	s_add_u32 s33, s33, 0x100
	s_addc_u32 s34, s34, 0
	s_cmp_ge_i32 s35, s44
	s_mov_b32 s26, s35
	s_cbranch_scc0 .LBB0_541

; #define PG8_STAGE(bufoff, gbase, voff) do { _Pragma("unroll") for (int _i = 0; _i < 2; ++_i) \
;         __builtin_amdgcn_global_load_lds((const unsigned*)((const char*)(gbase) + (voff)[_i]), (LAS unsigned*)(lds + (bufoff) + ldsw + _i * 8192), 16, 0, 0); } while (0)
; #define PG8_WAIT_V(n) asm volatile("s_waitcnt vmcnt(" #n ")" ::: "memory")
; #define PG8_BAR __builtin_amdgcn_s_barrier()
; template <class Epi>
; __device__ __forceinline__ void gemm_phase(LAS unsigned char* lds, const Gemm g, const StaticOrder& S, const Epi& E) {
;     ...
;     for (int i = 0; i < 2; ++i) { int R, C; stage_rc(tid * 16 + i * 8192, R, C); const int Rb = Epi::PERM ? ((R & ~31) + perm32(R & 31)) : R;
;         voffA[i] = (unsigned)(R * g.lda + C) * 2u; voffB[i] = (unsigned)(Rb * g.ldb + C) * 2u; }
;     const size_t kstep = (size_t)(BK * 2);
;     const size_t hstepA = (size_t)HALF * g.lda * 2, hstepB = (size_t)HALF * g.ldb * 2;
;     const size_t tstepA = 2 * hstepA, tstepB = 2 * hstepB;
;     const unsigned ldsw = (unsigned)wid * 1024u;
;     const int aoff = lds_byte(wr * 64 + fr, fq * 8), boff = lds_byte(wc * 32 + fr, fq * 8);
;     ...
;     Unit cur, nxt; int ui = 0;
;     if (!S.next(0, cur)) return;
;     f32x4 acc[2][2][4][2];
; #pragma unroll
;     for (int a = 0; a < 2; ++a)
; #pragma unroll
;         for (int b = 0; b < 2; ++b)
; #pragma unroll
;             for (int m = 0; m < 4; ++m)
; #pragma unroll
;                 for (int n = 0; n < 2; ++n) acc[a][b][m][n] = (f32x4){0.f, 0.f, 0.f, 0.f};
;     bf16x8 At[4][2], B0[2][2], B1[2][2];
;     const char* cA = (const char*)g.A + (size_t)cur.pm * tstepA; const char* cB = (const char*)g.Bt + (size_t)cur.pb * tstepB;
;     PG8_STAGE(PG8_SB(0, 0), cB, voffB); PG8_STAGE(PG8_SB(0, 1), cB + hstepB, voffB); PG8_STAGE(PG8_SA(0, 0), cA, voffA); PG8_STAGE(PG8_SA(0, 1), cA + hstepA, voffA);
;     if (wr == 1) PG8_BAR;
;     PG8_WAIT_V(2); PG8_BAR;
;     PG8_STAGE(PG8_SB(1, 0), cB + kstep, voffB); PG8_STAGE(PG8_SA(1, 0), cA + kstep, voffA); PG8_STAGE(PG8_SB(1, 1), cB + hstepB + kstep, voffB);
;     PG8_WAIT_V(6); PG8_BAR;
;     for (;;) {
;         const bool has_next = S.next(ui + 1, nxt);
;         const char* nA = has_next ? (const char*)g.A + (size_t)nxt.pm * tstepA : cA; const char* nB = has_next ? (const char*)g.Bt + (size_t)nxt.pb * tstepB : cB;
;         for (int t = 0; t < nt; t += 2) {
;             const bool last = (t == nt - 2);
.LBB0_672:
	s_ashr_i32 s10, s7, 31
	s_lshr_b32 s10, s10, 26
	s_add_i32 s10, s7, s10
	s_ashr_i32 s46, s10, 6
	s_lshl_b32 s17, s8, 6
	s_lshl_b32 s12, s8, 13
	s_lshl_b32 s8, s9, 5
	s_mov_b64 s[10:11], 0x80
	s_and_b32 s18, s8, 0x60
	s_add_i32 m0, s40, 0x18000
	v_lshl_add_u64 v[2:3], v[2:3], 0, s[10:11]
	s_lshl_b32 s13, s18, 7
	s_waitcnt vmcnt(2)
	s_barrier
	global_load_lds_dwordx4 v[2:3], off
	v_lshl_add_u64 v[0:1], v[0:1], 0, s[10:11]
	s_add_i32 m0, s40, 0x1a000
	s_add_i32 s47, s40, 0x8000
	s_add_i32 s48, s40, 0xa000
	global_load_lds_dwordx4 v[0:1], off
	v_lshl_add_u64 v[0:1], v[4:5], 0, s[10:11]
	s_mov_b32 m0, s47
	s_add_u32 s8, s34, 0x10080
	global_load_lds_dwordx4 v[0:1], off
	v_lshl_add_u64 v[0:1], v[6:7], 0, s[10:11]
	s_mov_b32 m0, s48
	s_addc_u32 s9, s35, 0
	s_add_i32 s49, s40, 0x1c000
	global_load_lds_dwordx4 v[0:1], off
	s_mov_b32 m0, s49
	s_add_i32 s52, s40, 0x1e000
	global_load_lds_dwordx4 v66, s[8:9]
	v_lshl_add_u64 v[0:1], s[8:9], 0, v[70:71]
	s_mov_b32 m0, s52
	v_bfe_u32 v2, v8, 4, 2
	global_load_lds_dwordx4 v[0:1], off
	v_and_b32_e32 v0, 15, v8
	v_lshlrev_b32_e32 v1, 4, v2
	v_lshlrev_b32_e32 v3, 2, v8
	v_lshl_or_b32 v1, v0, 6, v1
	v_and_b32_e32 v3, 32, v3
	s_cmp_gt_i32 s7, 63
	v_bitop3_b32 v4, v1, s12, v3 bitop3:0xde
	v_bitop3_b32 v84, v1, s13, v3 bitop3:0xde
	s_cselect_b64 s[12:13], -1, 0
	s_add_i32 s53, s46, -2
	s_cmpk_lt_u32 s6, 0x100
	s_cselect_b64 s[14:15], -1, 0
	s_ashr_i32 s6, s17, 31
	v_or_b32_e32 v0, s17, v0
	v_mov_b32_e32 v1, s6
	v_lshlrev_b64 v[0:1], 9, v[0:1]
	v_lshl_add_u64 v[74:75], s[84:85], 0, v[0:1]
	v_lshrrev_b32_e32 v1, 1, v9
	v_mul_lo_u32 v0, v11, s0
	s_movk_i32 s8, 0x1800
	v_mad_u64_u32 v[0:1], s[6:7], v1, s8, v[0:1]
	v_or_b32_e32 v0, v0, v10
	v_add_lshl_u32 v72, v0, v12, 1
	v_lshrrev_b32_e32 v1, 1, v13
	v_mul_lo_u32 v0, v14, s0
	v_mad_u64_u32 v[0:1], s[8:9], v1, s8, v[0:1]
	s_waitcnt vmcnt(6)
	s_mov_b64 s[6:7], 0x18080
	v_or_b32_e32 v0, v0, v15
	v_lshlrev_b32_e32 v2, 2, v2
	v_lshl_add_u64 v[76:77], v[72:73], 0, s[6:7]
	v_add_lshl_u32 v72, v0, v16, 1
	s_add_i32 s56, 0, 0x10000
	s_ashr_i32 s54, s94, 31
	s_mov_b32 s55, s94
	v_lshl_add_u64 v[78:79], v[72:73], 0, s[6:7]
	v_mov_b64_e32 v[80:81], 0x200
	v_mov_b64_e32 v[82:83], 0x1ff
	v_add_u32_e32 v85, s56, v84
	v_add_u32_e32 v86, 0, v4
	s_lshl_b32 s0, s18, 2
	v_lshlrev_b32_e32 v72, 2, v2
	s_mov_b64 s[18:19], 0x12000
	s_mov_b64 s[20:21], 0x14000
	s_mov_b64 s[22:23], 0x16000
	s_mov_b32 s57, s1
	s_barrier
	s_branch .LBB0_675

; #define PG8_STAGE(bufoff, gbase, voff) do { _Pragma("unroll") for (int _i = 0; _i < 2; ++_i) \
;         __builtin_amdgcn_global_load_lds((const unsigned*)((const char*)(gbase) + (voff)[_i]), (LAS unsigned*)(lds + (bufoff) + ldsw + _i * 8192), 16, 0, 0); } while (0)
; #define PG8_LDA(dst, b, h) do { _Pragma("unroll") for (int m = 0; m < 4; ++m) _Pragma("unroll") for (int k = 0; k < 2; ++k) dst[m][k] = *(const LAS bf16x8*)(lds + PG8_SA(b, h) + aoff + m * 2048 + k * 1024); } while (0)
; #define PG8_LDB(dst, b, h) do { _Pragma("unroll") for (int n = 0; n < 2; ++n) _Pragma("unroll") for (int k = 0; k < 2; ++k) dst[n][k] = *(const LAS bf16x8*)(lds + PG8_SB(b, h) + boff + n * 2048 + k * 1024); } while (0)
; #define PG8_MMA(ai, bj, At, Bt) do { __builtin_amdgcn_s_setprio(1); _Pragma("unroll") for (int m = 0; m < 4; ++m) _Pragma("unroll") for (int n = 0; n < 2; ++n) _Pragma("unroll") for (int k = 0; k < 2; ++k) \
;         acc[ai][bj][m][n] = __builtin_amdgcn_mfma_f32_16x16x32_bf16(Bt[n][k], At[m][k], acc[ai][bj][m][n], 0, 0, 0); __builtin_amdgcn_s_setprio(0); } while (0)
; #define PG8_WAIT_V(n) asm volatile("s_waitcnt vmcnt(" #n ")" ::: "memory")
; #define PG8_WAIT_L(n) asm volatile("s_waitcnt lgkmcnt(" #n ")" ::: "memory")
; #define PG8_BAR __builtin_amdgcn_s_barrier()
; #define PG8_SCHED __builtin_amdgcn_sched_barrier(0)
; template <class Epi>
; __device__ __forceinline__ void gemm_phase(LAS unsigned char* lds, const Gemm g, const StaticOrder& S, const Epi& E) {
;     ...
;             PG8_LDB(B0, 0, 0); PG8_LDB(B1, 0, 1); PG8_SCHED; PG8_LDA(At, 0, 0); PG8_STAGE(PG8_SA(1, 1), a1 + hstepA, voffA);
;             PG8_WAIT_V(8); PG8_WAIT_L(0); PG8_BAR; PG8_MMA(0, 0, At, B0); PG8_MMA(0, 1, At, B1); PG8_BAR; PG8_SCHED;
;             PG8_LDA(At, 0, 1); PG8_STAGE(PG8_SB(0, 0), b2, voffB); PG8_STAGE(PG8_SB(0, 1), b2 + hstepB, voffB); PG8_STAGE(PG8_SA(0, 0), a2, voffA);
;             PG8_WAIT_V(8); PG8_WAIT_L(0); PG8_BAR; PG8_MMA(1, 0, At, B0); PG8_MMA(1, 1, At, B1); PG8_BAR; PG8_SCHED;
.LBB0_685:
	ds_read_b128 v[88:91], v85
	ds_read_b128 v[92:95], v85 offset:1024
	ds_read_b128 v[96:99], v85 offset:2048
	ds_read_b128 v[100:103], v85 offset:3072
	s_add_i32 s61, s34, 2
	s_add_u32 s8, s30, 0x100
	s_addc_u32 s9, s31, 0
	s_cmp_eq_u32 s53, s34
	s_cselect_b32 s34, s25, s59
	s_cselect_b32 s37, s27, s9
	s_cselect_b32 s36, s26, s8
	s_cselect_b32 s35, s17, s60
	v_lshl_add_u64 v[136:137], s[30:31], 0, v[76:77]
	s_add_i32 m0, s40, 0xc000
	ds_read_b128 v[104:107], v86
	ds_read_b128 v[108:111], v86 offset:1024
	ds_read_b128 v[112:115], v86 offset:2048
	ds_read_b128 v[116:119], v86 offset:3072
	ds_read_b128 v[120:123], v86 offset:4096
	ds_read_b128 v[124:127], v86 offset:5120
	ds_read_b128 v[128:131], v86 offset:6144
	ds_read_b128 v[132:135], v86 offset:7168
	global_load_lds_dwordx4 v[136:137], off
	v_lshl_add_u64 v[136:137], s[30:31], 0, v[78:79]
	s_add_i32 m0, s40, 0xe000
	s_nop 0
	global_load_lds_dwordx4 v[136:137], off
	s_waitcnt vmcnt(8)
	s_waitcnt lgkmcnt(0)
	s_barrier
	s_setprio 1
	s_waitcnt lgkmcnt(0)
	v_mfma_f32_16x16x32_bf16 v[60:63], v[88:91], v[104:107], v[60:63]
	v_mfma_f32_16x16x32_bf16 v[60:63], v[92:95], v[108:111], v[60:63]
	v_mfma_f32_16x16x32_bf16 v[56:59], v[100:103], v[108:111], v[56:59]
	v_mfma_f32_16x16x32_bf16 v[56:59], v[96:99], v[104:107], v[56:59]
	v_mfma_f32_16x16x32_bf16 v[48:51], v[96:99], v[112:115], v[48:51]
	v_mfma_f32_16x16x32_bf16 v[48:51], v[100:103], v[116:119], v[48:51]
	v_mfma_f32_16x16x32_bf16 v[52:55], v[92:95], v[116:119], v[52:55]
	v_mfma_f32_16x16x32_bf16 v[52:55], v[88:91], v[112:115], v[52:55]
	v_mfma_f32_16x16x32_bf16 v[44:47], v[88:91], v[120:123], v[44:47]
	v_mfma_f32_16x16x32_bf16 v[44:47], v[92:95], v[124:127], v[44:47]
	v_mfma_f32_16x16x32_bf16 v[40:43], v[100:103], v[124:127], v[40:43]
	v_mfma_f32_16x16x32_bf16 v[40:43], v[96:99], v[120:123], v[40:43]
	v_mfma_f32_16x16x32_bf16 v[32:35], v[96:99], v[128:131], v[32:35]
	v_mfma_f32_16x16x32_bf16 v[32:35], v[100:103], v[132:135], v[32:35]
	v_mfma_f32_16x16x32_bf16 v[36:39], v[92:95], v[132:135], v[36:39]
	v_mfma_f32_16x16x32_bf16 v[36:39], v[88:91], v[128:131], v[36:39]
	s_setprio 0
	s_setprio 1
	s_setprio 0
	s_barrier
	s_add_i32 s30, s56, s39
	v_lshl_add_u64 v[136:137], s[34:35], 0, v[66:67]
	s_mov_b32 m0, s30
	ds_read_b128 v[104:107], v86 offset:16384
	ds_read_b128 v[108:111], v86 offset:17408
	ds_read_b128 v[112:115], v86 offset:18432
	ds_read_b128 v[116:119], v86 offset:19456
	ds_read_b128 v[120:123], v86 offset:20480
	ds_read_b128 v[124:127], v86 offset:21504
	ds_read_b128 v[128:131], v86 offset:22528
	ds_read_b128 v[132:135], v86 offset:23552
	global_load_lds_dwordx4 v[136:137], off
	s_add_i32 m0, s30, 0x2000
	s_add_u32 s30, s34, 0x10000
	v_lshl_add_u64 v[138:139], s[34:35], 0, v[70:71]
	s_addc_u32 s31, s35, 0
	global_load_lds_dwordx4 v[138:139], off
	s_mov_b32 m0, s41
	v_lshl_add_u64 v[142:143], s[36:37], 0, v[68:69]
	global_load_lds_dwordx4 v66, s[30:31]
	s_mov_b32 m0, s42
	s_nop 0
	global_load_lds_dwordx4 v70, s[30:31]
	v_lshl_add_u64 v[140:141], s[36:37], 0, v[64:65]
	s_mov_b32 m0, s40
	s_nop 0
	global_load_lds_dwordx4 v[140:141], off
	s_mov_b32 m0, s43
	s_nop 0
	global_load_lds_dwordx4 v[142:143], off
	s_waitcnt vmcnt(8)
	s_waitcnt lgkmcnt(0)
	s_barrier
	s_setprio 1
	s_waitcnt lgkmcnt(0)
	v_mfma_f32_16x16x32_bf16 v[28:31], v[88:91], v[104:107], v[28:31]
	v_mfma_f32_16x16x32_bf16 v[28:31], v[92:95], v[108:111], v[28:31]
	v_mfma_f32_16x16x32_bf16 v[24:27], v[100:103], v[108:111], v[24:27]
	v_mfma_f32_16x16x32_bf16 v[24:27], v[96:99], v[104:107], v[24:27]
	v_mfma_f32_16x16x32_bf16 v[16:19], v[96:99], v[112:115], v[16:19]
	v_mfma_f32_16x16x32_bf16 v[16:19], v[100:103], v[116:119], v[16:19]
	v_mfma_f32_16x16x32_bf16 v[20:23], v[92:95], v[116:119], v[20:23]
	v_mfma_f32_16x16x32_bf16 v[20:23], v[88:91], v[112:115], v[20:23]
	v_mfma_f32_16x16x32_bf16 v[12:15], v[88:91], v[120:123], v[12:15]
	v_mfma_f32_16x16x32_bf16 v[12:15], v[92:95], v[124:127], v[12:15]
	v_mfma_f32_16x16x32_bf16 v[8:11], v[100:103], v[124:127], v[8:11]
	v_mfma_f32_16x16x32_bf16 v[8:11], v[96:99], v[120:123], v[8:11]
	v_mfma_f32_16x16x32_bf16 v[0:3], v[96:99], v[128:131], v[0:3]
	v_mfma_f32_16x16x32_bf16 v[0:3], v[100:103], v[132:135], v[0:3]
	v_mfma_f32_16x16x32_bf16 v[4:7], v[92:95], v[132:135], v[4:7]
	v_mfma_f32_16x16x32_bf16 v[4:7], v[88:91], v[128:131], v[4:7]
	s_setprio 0
	s_setprio 1
	s_setprio 0
	s_barrier
; #define PG8_STAGE(bufoff, gbase, voff) do { _Pragma("unroll") for (int _i = 0; _i < 2; ++_i) \
;         __builtin_amdgcn_global_load_lds((const unsigned*)((const char*)(gbase) + (voff)[_i]), (LAS unsigned*)(lds + (bufoff) + ldsw + _i * 8192), 16, 0, 0); } while (0)
; #define PG8_LDA(dst, b, h) do { _Pragma("unroll") for (int m = 0; m < 4; ++m) _Pragma("unroll") for (int k = 0; k < 2; ++k) dst[m][k] = *(const LAS bf16x8*)(lds + PG8_SA(b, h) + aoff + m * 2048 + k * 1024); } while (0)
; #define PG8_LDB(dst, b, h) do { _Pragma("unroll") for (int n = 0; n < 2; ++n) _Pragma("unroll") for (int k = 0; k < 2; ++k) dst[n][k] = *(const LAS bf16x8*)(lds + PG8_SB(b, h) + boff + n * 2048 + k * 1024); } while (0)
; #define PG8_MMA(ai, bj, At, Bt) do { __builtin_amdgcn_s_setprio(1); _Pragma("unroll") for (int m = 0; m < 4; ++m) _Pragma("unroll") for (int n = 0; n < 2; ++n) _Pragma("unroll") for (int k = 0; k < 2; ++k) \
;         acc[ai][bj][m][n] = __builtin_amdgcn_mfma_f32_16x16x32_bf16(Bt[n][k], At[m][k], acc[ai][bj][m][n], 0, 0, 0); __builtin_amdgcn_s_setprio(0); } while (0)
; #define PG8_WAIT_V(n) asm volatile("s_waitcnt vmcnt(" #n ")" ::: "memory")
; #define PG8_WAIT_L(n) asm volatile("s_waitcnt lgkmcnt(" #n ")" ::: "memory")
; #define PG8_BAR __builtin_amdgcn_s_barrier()
; #define PG8_SCHED __builtin_amdgcn_sched_barrier(0)
; template <class Epi>
; __device__ __forceinline__ void gemm_phase(LAS unsigned char* lds, const Gemm g, const StaticOrder& S, const Epi& E) {
;     ...
;             PG8_LDB(B0, 1, 0); PG8_LDB(B1, 1, 1); PG8_SCHED; PG8_LDA(At, 1, 0); PG8_STAGE(PG8_SA(0, 1), a2 + hstepA, voffA);
;             PG8_WAIT_V(8); PG8_WAIT_L(0); PG8_BAR; PG8_MMA(0, 0, At, B0); PG8_MMA(0, 1, At, B1); PG8_BAR; PG8_SCHED;
;             PG8_LDA(At, 1, 1); PG8_STAGE(PG8_SB(1, 0), b3, voffB); PG8_STAGE(PG8_SB(1, 1), b3 + hstepB, voffB); PG8_STAGE(PG8_SA(1, 0), a3, voffA);
;             PG8_WAIT_V(8); PG8_WAIT_L(0); PG8_BAR; PG8_MMA(1, 0, At, B0); PG8_MMA(1, 1, At, B1); PG8_BAR; PG8_SCHED;
;         }
	s_add_i32 s62, 0, 0x18000
	v_add_u32_e32 v87, s62, v84
	ds_read_b128 v[88:91], v87
	ds_read_b128 v[92:95], v87 offset:1024
	ds_read_b128 v[96:99], v87 offset:2048
	ds_read_b128 v[100:103], v87 offset:3072
	s_add_u32 s30, s36, 0x18000
	s_addc_u32 s31, s37, 0
	s_mov_b32 m0, s44
	ds_read_b128 v[104:107], v86 offset:32768
	ds_read_b128 v[108:111], v86 offset:33792
	ds_read_b128 v[112:115], v86 offset:34816
	ds_read_b128 v[116:119], v86 offset:35840
	ds_read_b128 v[120:123], v86 offset:36864
	ds_read_b128 v[124:127], v86 offset:37888
	ds_read_b128 v[128:131], v86 offset:38912
	ds_read_b128 v[132:135], v86 offset:39936
	global_load_lds_dwordx4 v64, s[30:31]
	s_mov_b32 m0, s45
	s_nop 0
	global_load_lds_dwordx4 v68, s[30:31]
	s_waitcnt vmcnt(8)
	s_waitcnt lgkmcnt(0)
	s_barrier
	s_setprio 1
	s_waitcnt lgkmcnt(0)
	v_mfma_f32_16x16x32_bf16 v[60:63], v[88:91], v[104:107], v[60:63]
	v_mfma_f32_16x16x32_bf16 v[60:63], v[92:95], v[108:111], v[60:63]
	v_mfma_f32_16x16x32_bf16 v[56:59], v[100:103], v[108:111], v[56:59]
	v_mfma_f32_16x16x32_bf16 v[56:59], v[96:99], v[104:107], v[56:59]
	v_mfma_f32_16x16x32_bf16 v[48:51], v[96:99], v[112:115], v[48:51]
	v_mfma_f32_16x16x32_bf16 v[48:51], v[100:103], v[116:119], v[48:51]
	v_mfma_f32_16x16x32_bf16 v[52:55], v[92:95], v[116:119], v[52:55]
	v_mfma_f32_16x16x32_bf16 v[52:55], v[88:91], v[112:115], v[52:55]
	v_mfma_f32_16x16x32_bf16 v[44:47], v[88:91], v[120:123], v[44:47]
	v_mfma_f32_16x16x32_bf16 v[44:47], v[92:95], v[124:127], v[44:47]
	v_mfma_f32_16x16x32_bf16 v[40:43], v[100:103], v[124:127], v[40:43]
	v_mfma_f32_16x16x32_bf16 v[40:43], v[96:99], v[120:123], v[40:43]
	v_mfma_f32_16x16x32_bf16 v[32:35], v[96:99], v[128:131], v[32:35]
	v_mfma_f32_16x16x32_bf16 v[32:35], v[100:103], v[132:135], v[32:35]
	v_mfma_f32_16x16x32_bf16 v[36:39], v[92:95], v[132:135], v[36:39]
	v_mfma_f32_16x16x32_bf16 v[36:39], v[88:91], v[128:131], v[36:39]
	s_setprio 0
	s_setprio 1
	s_setprio 0
	s_barrier
	s_add_i32 s30, s62, s39
	v_lshl_add_u64 v[136:137], v[136:137], 0, s[10:11]
	s_mov_b32 m0, s30
	ds_read_b128 v[104:107], v86 offset:49152
	ds_read_b128 v[108:111], v86 offset:50176
	ds_read_b128 v[112:115], v86 offset:51200
	ds_read_b128 v[116:119], v86 offset:52224
	ds_read_b128 v[120:123], v86 offset:53248
	ds_read_b128 v[124:127], v86 offset:54272
	ds_read_b128 v[128:131], v86 offset:55296
	ds_read_b128 v[132:135], v86 offset:56320
	global_load_lds_dwordx4 v[136:137], off
	s_add_i32 m0, s30, 0x2000
	s_add_u32 s30, s34, 0x10080
	v_lshl_add_u64 v[136:137], v[138:139], 0, s[10:11]
	s_addc_u32 s31, s35, 0
	global_load_lds_dwordx4 v[136:137], off
	s_mov_b32 m0, s49
	s_nop 0
	global_load_lds_dwordx4 v66, s[30:31]
	s_mov_b32 m0, s52
	s_nop 0
	global_load_lds_dwordx4 v70, s[30:31]
	v_lshl_add_u64 v[136:137], v[140:141], 0, s[10:11]
	s_mov_b32 m0, s47
	s_nop 0
	global_load_lds_dwordx4 v[136:137], off
	v_lshl_add_u64 v[136:137], v[142:143], 0, s[10:11]
	s_mov_b32 m0, s48
	s_nop 0
	global_load_lds_dwordx4 v[136:137], off
	s_waitcnt vmcnt(8)
	s_waitcnt lgkmcnt(0)
	s_barrier
	s_setprio 1
	s_waitcnt lgkmcnt(0)
	v_mfma_f32_16x16x32_bf16 v[28:31], v[88:91], v[104:107], v[28:31]
	v_mfma_f32_16x16x32_bf16 v[28:31], v[92:95], v[108:111], v[28:31]
	v_mfma_f32_16x16x32_bf16 v[24:27], v[100:103], v[108:111], v[24:27]
	v_mfma_f32_16x16x32_bf16 v[24:27], v[96:99], v[104:107], v[24:27]
	v_mfma_f32_16x16x32_bf16 v[16:19], v[96:99], v[112:115], v[16:19]
	v_mfma_f32_16x16x32_bf16 v[16:19], v[100:103], v[116:119], v[16:19]
	v_mfma_f32_16x16x32_bf16 v[20:23], v[92:95], v[116:119], v[20:23]
	v_mfma_f32_16x16x32_bf16 v[20:23], v[88:91], v[112:115], v[20:23]
	v_mfma_f32_16x16x32_bf16 v[12:15], v[88:91], v[120:123], v[12:15]
	v_mfma_f32_16x16x32_bf16 v[12:15], v[92:95], v[124:127], v[12:15]
	v_mfma_f32_16x16x32_bf16 v[8:11], v[100:103], v[124:127], v[8:11]
	v_mfma_f32_16x16x32_bf16 v[8:11], v[96:99], v[120:123], v[8:11]
	v_mfma_f32_16x16x32_bf16 v[0:3], v[96:99], v[128:131], v[0:3]
	v_mfma_f32_16x16x32_bf16 v[0:3], v[100:103], v[132:135], v[0:3]
	v_mfma_f32_16x16x32_bf16 v[4:7], v[92:95], v[132:135], v[4:7]
	v_mfma_f32_16x16x32_bf16 v[4:7], v[88:91], v[128:131], v[4:7]
	s_setprio 0
	s_setprio 1
	s_setprio 0
	s_barrier
	s_add_u32 s59, s59, 0x100
	s_addc_u32 s60, s60, 0
	s_cmp_ge_i32 s61, s46
	s_mov_b64 s[30:31], s[8:9]
	s_mov_b32 s34, s61
	s_cbranch_scc0 .LBB0_685

; #define PG8_STAGE(bufoff, gbase, voff) do { _Pragma("unroll") for (int _i = 0; _i < 2; ++_i) \
;         __builtin_amdgcn_global_load_lds((const unsigned*)((const char*)(gbase) + (voff)[_i]), (LAS unsigned*)(lds + (bufoff) + ldsw + _i * 8192), 16, 0, 0); } while (0)
; #define PG8_WAIT_V(n) asm volatile("s_waitcnt vmcnt(" #n ")" ::: "memory")
; #define PG8_BAR __builtin_amdgcn_s_barrier()
; template <class Epi>
; __device__ __forceinline__ void gemm_phase(LAS unsigned char* lds, const Gemm g, const StaticOrder& S, const Epi& E) {
;     ...
;     for (int i = 0; i < 2; ++i) { int R, C; stage_rc(tid * 16 + i * 8192, R, C); const int Rb = Epi::PERM ? ((R & ~31) + perm32(R & 31)) : R;
;         voffA[i] = (unsigned)(R * g.lda + C) * 2u; voffB[i] = (unsigned)(Rb * g.ldb + C) * 2u; }
;     const size_t kstep = (size_t)(BK * 2);
;     const size_t hstepA = (size_t)HALF * g.lda * 2, hstepB = (size_t)HALF * g.ldb * 2;
;     const size_t tstepA = 2 * hstepA, tstepB = 2 * hstepB;
;     const unsigned ldsw = (unsigned)wid * 1024u;
;     const int aoff = lds_byte(wr * 64 + fr, fq * 8), boff = lds_byte(wc * 32 + fr, fq * 8);
;     ...
;     Unit cur, nxt; int ui = 0;
;     if (!S.next(0, cur)) return;
;     f32x4 acc[2][2][4][2];
; #pragma unroll
;     for (int a = 0; a < 2; ++a)
; #pragma unroll
;         for (int b = 0; b < 2; ++b)
; #pragma unroll
;             for (int m = 0; m < 4; ++m)
; #pragma unroll
;                 for (int n = 0; n < 2; ++n) acc[a][b][m][n] = (f32x4){0.f, 0.f, 0.f, 0.f};
;     bf16x8 At[4][2], B0[2][2], B1[2][2];
;     const char* cA = (const char*)g.A + (size_t)cur.pm * tstepA; const char* cB = (const char*)g.Bt + (size_t)cur.pb * tstepB;
;     PG8_STAGE(PG8_SB(0, 0), cB, voffB); PG8_STAGE(PG8_SB(0, 1), cB + hstepB, voffB); PG8_STAGE(PG8_SA(0, 0), cA, voffA); PG8_STAGE(PG8_SA(0, 1), cA + hstepA, voffA);
;     if (wr == 1) PG8_BAR;
;     PG8_WAIT_V(2); PG8_BAR;
;     PG8_STAGE(PG8_SB(1, 0), cB + kstep, voffB); PG8_STAGE(PG8_SA(1, 0), cA + kstep, voffA); PG8_STAGE(PG8_SB(1, 1), cB + hstepB + kstep, voffB);
;     PG8_WAIT_V(6); PG8_BAR;
;     for (;;) {
;         const bool has_next = S.next(ui + 1, nxt);
;         const char* nA = has_next ? (const char*)g.A + (size_t)nxt.pm * tstepA : cA; const char* nB = has_next ? (const char*)g.Bt + (size_t)nxt.pb * tstepB : cB;
;         for (int t = 0; t < nt; t += 2) {
;             const bool last = (t == nt - 2);
.LBB0_819:
	s_ashr_i32 s14, s9, 31
	s_lshr_b32 s14, s14, 26
	s_add_i32 s14, s9, s14
	s_ashr_i32 s36, s14, 6
	s_lshl_b32 s14, s20, 12
	s_and_b32 s18, s14, 0x3000
	s_mov_b64 s[14:15], 0x80
	s_add_i32 m0, s29, 0x18000
	v_lshl_add_u64 v[6:7], v[6:7], 0, s[14:15]
	s_lshl_b32 s37, s11, 6
	s_lshl_b32 s11, s11, 13
	s_waitcnt vmcnt(2)
	s_barrier
	global_load_lds_dwordx4 v[6:7], off
	v_lshl_add_u64 v[4:5], v[4:5], 0, s[14:15]
	s_add_i32 m0, s29, 0x1a000
	s_add_i32 s38, s29, 0x8000
	s_add_i32 s39, s29, 0xa000
	global_load_lds_dwordx4 v[4:5], off
	v_lshl_add_u64 v[0:1], v[0:1], 0, s[14:15]
	s_mov_b32 m0, s38
	s_add_u32 s16, s4, 0x18080
	global_load_lds_dwordx4 v[0:1], off
	v_lshl_add_u64 v[0:1], v[2:3], 0, s[14:15]
	s_mov_b32 m0, s39
	s_addc_u32 s17, s5, 0
	global_load_lds_dwordx4 v[0:1], off
	s_add_i32 m0, s29, 0x1c000
	s_nop 0
	global_load_lds_dwordx4 v130, s[16:17]
	v_lshl_add_u64 v[0:1], s[16:17], 0, v[134:135]
	s_add_i32 m0, s29, 0x1e000
	v_and_b32_e32 v148, 15, v8
	global_load_lds_dwordx4 v[0:1], off
	v_lshrrev_b32_e32 v0, 1, v8
	v_and_b32_e32 v1, 24, v0
	v_lshlrev_b32_e32 v5, 2, v8
	s_cmp_gt_i32 s9, 63
	v_lshlrev_b32_e32 v2, 1, v1
	v_lshlrev_b32_e32 v3, 6, v148
	v_and_b32_e32 v5, 32, v5
	s_cselect_b64 s[16:17], -1, 0
	s_add_i32 s40, s36, -2
	v_or_b32_e32 v4, v3, v2
	v_bitop3_b32 v2, v3, v5, v2 bitop3:0x36
	s_cmpk_lt_u32 s8, 0x100
	v_or_b32_e32 v149, s18, v2
	s_cselect_b64 s[18:19], -1, 0
	s_lshl_b32 s8, s20, 11
	v_lshlrev_b32_e32 v1, 6, v1
	v_mov_b32_e32 v2, 0x1c00
	v_bitop3_b32 v4, v4, s11, v5 bitop3:0xde
	v_bitop3_b32 v150, s8, v2, v1 bitop3:0xc8
	v_lshrrev_b32_e32 v1, 1, v9
	v_mul_lo_u32 v2, v11, s10
	s_movk_i32 s11, 0x1800
	v_mad_u64_u32 v[2:3], s[8:9], v1, s11, v[2:3]
	v_or_b32_e32 v1, v2, v10
	v_add_lshl_u32 v136, v1, v12, 1
	v_lshrrev_b32_e32 v1, 1, v13
	v_mul_lo_u32 v2, v14, s10
	v_mad_u64_u32 v[2:3], s[8:9], v1, s11, v[2:3]
	s_mov_b64 s[22:23], 0x18080
	s_waitcnt vmcnt(6)
	v_or_b32_e32 v1, v2, v15
	v_and_b32_e32 v0, 8, v0
	v_lshl_add_u64 v[138:139], v[136:137], 0, s[22:23]
	v_add_lshl_u32 v136, v1, v16, 1
	s_add_i32 s43, 0, 0x10000
	s_add_i32 s44, 0, 0x14000
	v_or_b32_e32 v151, 0x2000, v150
	s_ashr_i32 s41, s94, 31
	s_mov_b32 s42, s94
	v_lshl_add_u64 v[140:141], v[136:137], 0, s[22:23]
	v_mov_b64_e32 v[142:143], 0x200
	v_mov_b64_e32 v[144:145], 0x1ff
	v_add_u32_e32 v152, s43, v149
	v_add_u32_e32 v153, s44, v149
	v_add_u32_e32 v154, 0, v4
	v_lshlrev_b32_e32 v146, 1, v0
	s_barrier
	s_branch .LBB0_822

; #define PG8_STAGE(bufoff, gbase, voff) do { _Pragma("unroll") for (int _i = 0; _i < 2; ++_i) \
;         __builtin_amdgcn_global_load_lds((const unsigned*)((const char*)(gbase) + (voff)[_i]), (LAS unsigned*)(lds + (bufoff) + ldsw + _i * 8192), 16, 0, 0); } while (0)
; #define PG8_LDA(dst, b, h) do { _Pragma("unroll") for (int m = 0; m < 4; ++m) _Pragma("unroll") for (int k = 0; k < 2; ++k) dst[m][k] = *(const LAS bf16x8*)(lds + PG8_SA(b, h) + aoff + m * 2048 + k * 1024); } while (0)
; #define PG8_LDB(dst, b, h) do { _Pragma("unroll") for (int n = 0; n < 2; ++n) _Pragma("unroll") for (int k = 0; k < 2; ++k) dst[n][k] = *(const LAS bf16x8*)(lds + PG8_SB(b, h) + boff + n * 2048 + k * 1024); } while (0)
; #define PG8_MMA(ai, bj, At, Bt) do { __builtin_amdgcn_s_setprio(1); _Pragma("unroll") for (int m = 0; m < 4; ++m) _Pragma("unroll") for (int n = 0; n < 2; ++n) _Pragma("unroll") for (int k = 0; k < 2; ++k) \
;         acc[ai][bj][m][n] = __builtin_amdgcn_mfma_f32_16x16x32_bf16(Bt[n][k], At[m][k], acc[ai][bj][m][n], 0, 0, 0); __builtin_amdgcn_s_setprio(0); } while (0)
; #define PG8_WAIT_V(n) asm volatile("s_waitcnt vmcnt(" #n ")" ::: "memory")
; #define PG8_WAIT_L(n) asm volatile("s_waitcnt lgkmcnt(" #n ")" ::: "memory")
; #define PG8_BAR __builtin_amdgcn_s_barrier()
; #define PG8_SCHED __builtin_amdgcn_sched_barrier(0)
; template <class Epi>
; __device__ __forceinline__ void gemm_phase(LAS unsigned char* lds, const Gemm g, const StaticOrder& S, const Epi& E) {
;     ...
;             PG8_LDB(B0, 0, 0); PG8_LDB(B1, 0, 1); PG8_SCHED; PG8_LDA(At, 0, 0); PG8_STAGE(PG8_SA(1, 1), a1 + hstepA, voffA);
;             PG8_WAIT_V(8); PG8_WAIT_L(0); PG8_BAR; PG8_MMA(0, 0, At, B0); PG8_MMA(0, 1, At, B1); PG8_BAR; PG8_SCHED;
;             PG8_LDA(At, 0, 1); PG8_STAGE(PG8_SB(0, 0), b2, voffB); PG8_STAGE(PG8_SB(0, 1), b2 + hstepB, voffB); PG8_STAGE(PG8_SA(0, 0), a2, voffA);
.LBB0_834:
	ds_read_b128 v[156:159], v152
	ds_read_b128 v[160:163], v152 offset:1024
	ds_read_b128 v[164:167], v152 offset:2048
	ds_read_b128 v[168:171], v152 offset:3072
	ds_read_b128 v[172:175], v153
	ds_read_b128 v[176:179], v153 offset:1024
	ds_read_b128 v[180:183], v153 offset:2048
	ds_read_b128 v[184:187], v153 offset:3072
	s_add_i32 s49, s22, 2
	s_add_u32 s4, s0, 0x100
	s_addc_u32 s5, s1, 0
	s_cmp_eq_u32 s40, s22
	s_cselect_b32 s22, s20, s47
	s_cselect_b32 s25, s11, s5
	s_cselect_b32 s24, s10, s4
	s_cselect_b32 s23, s21, s48
	v_lshl_add_u64 v[224:225], s[0:1], 0, v[138:139]
	s_add_i32 m0, s29, 0xc000
	ds_read_b128 v[188:191], v154
	ds_read_b128 v[192:195], v154 offset:1024
	ds_read_b128 v[196:199], v154 offset:2048
	ds_read_b128 v[200:203], v154 offset:3072
	ds_read_b128 v[208:211], v154 offset:4096
	ds_read_b128 v[212:215], v154 offset:5120
	ds_read_b128 v[216:219], v154 offset:6144
	ds_read_b128 v[220:223], v154 offset:7168
	global_load_lds_dwordx4 v[224:225], off
	v_lshl_add_u64 v[224:225], s[0:1], 0, v[140:141]
	s_add_i32 m0, s29, 0xe000
	s_nop 0
	global_load_lds_dwordx4 v[224:225], off
	s_waitcnt vmcnt(8)
	s_waitcnt lgkmcnt(0)
	s_barrier
	s_setprio 1
	s_waitcnt lgkmcnt(0)
	v_mfma_f32_16x16x32_bf16 v[124:127], v[156:159], v[188:191], v[124:127]
	v_mfma_f32_16x16x32_bf16 v[124:127], v[160:163], v[192:195], v[124:127]
	v_mfma_f32_16x16x32_bf16 v[120:123], v[168:171], v[192:195], v[120:123]
	v_mfma_f32_16x16x32_bf16 v[120:123], v[164:167], v[188:191], v[120:123]
	v_mfma_f32_16x16x32_bf16 v[116:119], v[172:175], v[188:191], v[116:119]
	v_mfma_f32_16x16x32_bf16 v[116:119], v[176:179], v[192:195], v[116:119]
	v_mfma_f32_16x16x32_bf16 v[112:115], v[184:187], v[192:195], v[112:115]
	v_mfma_f32_16x16x32_bf16 v[112:115], v[180:183], v[188:191], v[112:115]
	v_mfma_f32_16x16x32_bf16 v[96:99], v[180:183], v[196:199], v[96:99]
	v_mfma_f32_16x16x32_bf16 v[96:99], v[184:187], v[200:203], v[96:99]
	v_mfma_f32_16x16x32_bf16 v[100:103], v[176:179], v[200:203], v[100:103]
	v_mfma_f32_16x16x32_bf16 v[100:103], v[172:175], v[196:199], v[100:103]
	v_mfma_f32_16x16x32_bf16 v[104:107], v[164:167], v[196:199], v[104:107]
	v_mfma_f32_16x16x32_bf16 v[104:107], v[168:171], v[200:203], v[104:107]
	v_mfma_f32_16x16x32_bf16 v[108:111], v[160:163], v[200:203], v[108:111]
	v_mfma_f32_16x16x32_bf16 v[108:111], v[156:159], v[196:199], v[108:111]
	s_setprio 0
	s_setprio 1
	v_mfma_f32_16x16x32_bf16 v[92:95], v[156:159], v[208:211], v[92:95]
	v_mfma_f32_16x16x32_bf16 v[92:95], v[160:163], v[212:215], v[92:95]
	v_mfma_f32_16x16x32_bf16 v[88:91], v[168:171], v[212:215], v[88:91]
	v_mfma_f32_16x16x32_bf16 v[88:91], v[164:167], v[208:211], v[88:91]
	v_mfma_f32_16x16x32_bf16 v[84:87], v[172:175], v[208:211], v[84:87]
	v_mfma_f32_16x16x32_bf16 v[84:87], v[176:179], v[212:215], v[84:87]
	v_mfma_f32_16x16x32_bf16 v[80:83], v[184:187], v[212:215], v[80:83]
	v_mfma_f32_16x16x32_bf16 v[80:83], v[180:183], v[208:211], v[80:83]
	v_mfma_f32_16x16x32_bf16 v[64:67], v[180:183], v[216:219], v[64:67]
	v_mfma_f32_16x16x32_bf16 v[64:67], v[184:187], v[220:223], v[64:67]
	v_mfma_f32_16x16x32_bf16 v[68:71], v[176:179], v[220:223], v[68:71]
	v_mfma_f32_16x16x32_bf16 v[68:71], v[172:175], v[216:219], v[68:71]
	v_mfma_f32_16x16x32_bf16 v[72:75], v[164:167], v[216:219], v[72:75]
	v_mfma_f32_16x16x32_bf16 v[72:75], v[168:171], v[220:223], v[72:75]
	v_mfma_f32_16x16x32_bf16 v[76:79], v[160:163], v[220:223], v[76:79]
	v_mfma_f32_16x16x32_bf16 v[76:79], v[156:159], v[216:219], v[76:79]
	s_setprio 0
	s_barrier
	s_add_i32 s0, s43, s28
	v_lshl_add_u64 v[224:225], s[22:23], 0, v[130:131]
	s_mov_b32 m0, s0
	ds_read_b128 v[188:191], v154 offset:16384
	ds_read_b128 v[192:195], v154 offset:17408
	ds_read_b128 v[196:199], v154 offset:18432
	ds_read_b128 v[200:203], v154 offset:19456
	ds_read_b128 v[208:211], v154 offset:20480
	ds_read_b128 v[212:215], v154 offset:21504
	ds_read_b128 v[216:219], v154 offset:22528
	ds_read_b128 v[220:223], v154 offset:23552
	global_load_lds_dwordx4 v[224:225], off
	s_add_i32 m0, s0, 0x2000
	s_add_u32 s0, s22, 0x18000
	v_lshl_add_u64 v[226:227], s[22:23], 0, v[134:135]
	s_addc_u32 s1, s23, 0
	s_add_i32 s50, s44, s28
	global_load_lds_dwordx4 v[226:227], off
	s_mov_b32 m0, s50
	v_lshl_add_u64 v[232:233], s[24:25], 0, v[132:133]
	global_load_lds_dwordx4 v130, s[0:1]
	s_add_i32 m0, s50, 0x2000
	s_nop 0
	global_load_lds_dwordx4 v134, s[0:1]
	v_lshl_add_u64 v[230:231], s[24:25], 0, v[128:129]
	s_mov_b32 m0, s29
	s_nop 0
	global_load_lds_dwordx4 v[230:231], off
	s_mov_b32 m0, s30
	s_nop 0
	global_load_lds_dwordx4 v[232:233], off
	s_waitcnt vmcnt(8)
	s_waitcnt lgkmcnt(0)
	s_barrier
; #define PG8_STAGE(bufoff, gbase, voff) do { _Pragma("unroll") for (int _i = 0; _i < 2; ++_i) \
;         __builtin_amdgcn_global_load_lds((const unsigned*)((const char*)(gbase) + (voff)[_i]), (LAS unsigned*)(lds + (bufoff) + ldsw + _i * 8192), 16, 0, 0); } while (0)
; #define PG8_LDA(dst, b, h) do { _Pragma("unroll") for (int m = 0; m < 4; ++m) _Pragma("unroll") for (int k = 0; k < 2; ++k) dst[m][k] = *(const LAS bf16x8*)(lds + PG8_SA(b, h) + aoff + m * 2048 + k * 1024); } while (0)
; #define PG8_LDB(dst, b, h) do { _Pragma("unroll") for (int n = 0; n < 2; ++n) _Pragma("unroll") for (int k = 0; k < 2; ++k) dst[n][k] = *(const LAS bf16x8*)(lds + PG8_SB(b, h) + boff + n * 2048 + k * 1024); } while (0)
; #define PG8_MMA(ai, bj, At, Bt) do { __builtin_amdgcn_s_setprio(1); _Pragma("unroll") for (int m = 0; m < 4; ++m) _Pragma("unroll") for (int n = 0; n < 2; ++n) _Pragma("unroll") for (int k = 0; k < 2; ++k) \
;         acc[ai][bj][m][n] = __builtin_amdgcn_mfma_f32_16x16x32_bf16(Bt[n][k], At[m][k], acc[ai][bj][m][n], 0, 0, 0); __builtin_amdgcn_s_setprio(0); } while (0)
; #define PG8_WAIT_V(n) asm volatile("s_waitcnt vmcnt(" #n ")" ::: "memory")
; #define PG8_WAIT_L(n) asm volatile("s_waitcnt lgkmcnt(" #n ")" ::: "memory")
; #define PG8_BAR __builtin_amdgcn_s_barrier()
; #define PG8_SCHED __builtin_amdgcn_sched_barrier(0)
; template <class Epi>
; __device__ __forceinline__ void gemm_phase(LAS unsigned char* lds, const Gemm g, const StaticOrder& S, const Epi& E) {
;     ...
;             PG8_WAIT_V(8); PG8_WAIT_L(0); PG8_BAR; PG8_MMA(1, 0, At, B0); PG8_MMA(1, 1, At, B1); PG8_BAR; PG8_SCHED;
;             PG8_LDB(B0, 1, 0); PG8_LDB(B1, 1, 1); PG8_SCHED; PG8_LDA(At, 1, 0); PG8_STAGE(PG8_SA(0, 1), a2 + hstepA, voffA);
;             PG8_WAIT_V(8); PG8_WAIT_L(0); PG8_BAR; PG8_MMA(0, 0, At, B0); PG8_MMA(0, 1, At, B1); PG8_BAR; PG8_SCHED;
	s_setprio 1
	s_waitcnt lgkmcnt(0)
	v_mfma_f32_16x16x32_bf16 v[60:63], v[156:159], v[188:191], v[60:63]
	v_mfma_f32_16x16x32_bf16 v[60:63], v[160:163], v[192:195], v[60:63]
	v_mfma_f32_16x16x32_bf16 v[56:59], v[168:171], v[192:195], v[56:59]
	v_mfma_f32_16x16x32_bf16 v[56:59], v[164:167], v[188:191], v[56:59]
	v_mfma_f32_16x16x32_bf16 v[52:55], v[172:175], v[188:191], v[52:55]
	v_mfma_f32_16x16x32_bf16 v[52:55], v[176:179], v[192:195], v[52:55]
	v_mfma_f32_16x16x32_bf16 v[48:51], v[184:187], v[192:195], v[48:51]
	v_mfma_f32_16x16x32_bf16 v[48:51], v[180:183], v[188:191], v[48:51]
	v_mfma_f32_16x16x32_bf16 v[32:35], v[180:183], v[196:199], v[32:35]
	v_mfma_f32_16x16x32_bf16 v[32:35], v[184:187], v[200:203], v[32:35]
	v_mfma_f32_16x16x32_bf16 v[36:39], v[176:179], v[200:203], v[36:39]
	v_mfma_f32_16x16x32_bf16 v[36:39], v[172:175], v[196:199], v[36:39]
	v_mfma_f32_16x16x32_bf16 v[40:43], v[164:167], v[196:199], v[40:43]
	v_mfma_f32_16x16x32_bf16 v[40:43], v[168:171], v[200:203], v[40:43]
	v_mfma_f32_16x16x32_bf16 v[44:47], v[160:163], v[200:203], v[44:47]
	v_mfma_f32_16x16x32_bf16 v[44:47], v[156:159], v[196:199], v[44:47]
	s_setprio 0
	s_setprio 1
	v_mfma_f32_16x16x32_bf16 v[28:31], v[156:159], v[208:211], v[28:31]
	v_mfma_f32_16x16x32_bf16 v[28:31], v[160:163], v[212:215], v[28:31]
	v_mfma_f32_16x16x32_bf16 v[24:27], v[168:171], v[212:215], v[24:27]
	v_mfma_f32_16x16x32_bf16 v[24:27], v[164:167], v[208:211], v[24:27]
	v_mfma_f32_16x16x32_bf16 v[20:23], v[172:175], v[208:211], v[20:23]
	v_mfma_f32_16x16x32_bf16 v[20:23], v[176:179], v[212:215], v[20:23]
	v_mfma_f32_16x16x32_bf16 v[16:19], v[184:187], v[212:215], v[16:19]
	v_mfma_f32_16x16x32_bf16 v[16:19], v[180:183], v[208:211], v[16:19]
	v_mfma_f32_16x16x32_bf16 v[0:3], v[180:183], v[216:219], v[0:3]
	v_mfma_f32_16x16x32_bf16 v[0:3], v[184:187], v[220:223], v[0:3]
	v_mfma_f32_16x16x32_bf16 v[4:7], v[176:179], v[220:223], v[4:7]
	v_mfma_f32_16x16x32_bf16 v[4:7], v[172:175], v[216:219], v[4:7]
	v_mfma_f32_16x16x32_bf16 v[8:11], v[164:167], v[216:219], v[8:11]
	v_mfma_f32_16x16x32_bf16 v[8:11], v[168:171], v[220:223], v[8:11]
	v_mfma_f32_16x16x32_bf16 v[12:15], v[160:163], v[220:223], v[12:15]
	v_mfma_f32_16x16x32_bf16 v[12:15], v[156:159], v[216:219], v[12:15]
	s_setprio 0
	s_barrier
	s_add_i32 s50, 0, 0x18000
	v_add_u32_e32 v136, s50, v149
	s_add_i32 s51, 0, 0x1c000
	ds_read_b128 v[156:159], v136
	ds_read_b128 v[160:163], v136 offset:1024
	ds_read_b128 v[164:167], v136 offset:2048
	ds_read_b128 v[168:171], v136 offset:3072
	v_add_u32_e32 v136, s51, v149
	ds_read_b128 v[172:175], v136
	ds_read_b128 v[176:179], v136 offset:1024
	ds_read_b128 v[180:183], v136 offset:2048
	ds_read_b128 v[184:187], v136 offset:3072
	s_add_u32 s0, s24, 0x18000
	s_addc_u32 s1, s25, 0
	s_mov_b32 m0, s31
	ds_read_b128 v[188:191], v154 offset:32768
	ds_read_b128 v[192:195], v154 offset:33792
	ds_read_b128 v[196:199], v154 offset:34816
	ds_read_b128 v[200:203], v154 offset:35840
	ds_read_b128 v[208:211], v154 offset:36864
	ds_read_b128 v[212:215], v154 offset:37888
	ds_read_b128 v[216:219], v154 offset:38912
	ds_read_b128 v[220:223], v154 offset:39936
	global_load_lds_dwordx4 v128, s[0:1]
	s_mov_b32 m0, s34
	s_nop 0
	global_load_lds_dwordx4 v132, s[0:1]
	s_waitcnt vmcnt(8)
	s_waitcnt lgkmcnt(0)
	s_barrier
	s_setprio 1
	s_waitcnt lgkmcnt(0)
	v_mfma_f32_16x16x32_bf16 v[124:127], v[156:159], v[188:191], v[124:127]
	v_mfma_f32_16x16x32_bf16 v[124:127], v[160:163], v[192:195], v[124:127]
	v_mfma_f32_16x16x32_bf16 v[120:123], v[168:171], v[192:195], v[120:123]
	v_mfma_f32_16x16x32_bf16 v[120:123], v[164:167], v[188:191], v[120:123]
	v_mfma_f32_16x16x32_bf16 v[116:119], v[172:175], v[188:191], v[116:119]
	v_mfma_f32_16x16x32_bf16 v[116:119], v[176:179], v[192:195], v[116:119]
	v_mfma_f32_16x16x32_bf16 v[112:115], v[184:187], v[192:195], v[112:115]
	v_mfma_f32_16x16x32_bf16 v[112:115], v[180:183], v[188:191], v[112:115]
	v_mfma_f32_16x16x32_bf16 v[96:99], v[180:183], v[196:199], v[96:99]
	v_mfma_f32_16x16x32_bf16 v[96:99], v[184:187], v[200:203], v[96:99]
	v_mfma_f32_16x16x32_bf16 v[100:103], v[176:179], v[200:203], v[100:103]
	v_mfma_f32_16x16x32_bf16 v[100:103], v[172:175], v[196:199], v[100:103]
	v_mfma_f32_16x16x32_bf16 v[104:107], v[164:167], v[196:199], v[104:107]
	v_mfma_f32_16x16x32_bf16 v[104:107], v[168:171], v[200:203], v[104:107]
	v_mfma_f32_16x16x32_bf16 v[108:111], v[160:163], v[200:203], v[108:111]
	v_mfma_f32_16x16x32_bf16 v[108:111], v[156:159], v[196:199], v[108:111]
	s_setprio 0
	s_setprio 1
	v_mfma_f32_16x16x32_bf16 v[92:95], v[156:159], v[208:211], v[92:95]
	v_mfma_f32_16x16x32_bf16 v[92:95], v[160:163], v[212:215], v[92:95]
	v_mfma_f32_16x16x32_bf16 v[88:91], v[168:171], v[212:215], v[88:91]
	v_mfma_f32_16x16x32_bf16 v[88:91], v[164:167], v[208:211], v[88:91]
	v_mfma_f32_16x16x32_bf16 v[84:87], v[172:175], v[208:211], v[84:87]
	v_mfma_f32_16x16x32_bf16 v[84:87], v[176:179], v[212:215], v[84:87]
	v_mfma_f32_16x16x32_bf16 v[80:83], v[184:187], v[212:215], v[80:83]
	v_mfma_f32_16x16x32_bf16 v[80:83], v[180:183], v[208:211], v[80:83]
	v_mfma_f32_16x16x32_bf16 v[64:67], v[180:183], v[216:219], v[64:67]
	v_mfma_f32_16x16x32_bf16 v[64:67], v[184:187], v[220:223], v[64:67]
	v_mfma_f32_16x16x32_bf16 v[68:71], v[176:179], v[220:223], v[68:71]
	v_mfma_f32_16x16x32_bf16 v[68:71], v[172:175], v[216:219], v[68:71]
	v_mfma_f32_16x16x32_bf16 v[72:75], v[164:167], v[216:219], v[72:75]
	v_mfma_f32_16x16x32_bf16 v[72:75], v[168:171], v[220:223], v[72:75]
	v_mfma_f32_16x16x32_bf16 v[76:79], v[160:163], v[220:223], v[76:79]
	v_mfma_f32_16x16x32_bf16 v[76:79], v[156:159], v[216:219], v[76:79]
	s_setprio 0
	s_barrier
; #define PG8_STAGE(bufoff, gbase, voff) do { _Pragma("unroll") for (int _i = 0; _i < 2; ++_i) \
;         __builtin_amdgcn_global_load_lds((const unsigned*)((const char*)(gbase) + (voff)[_i]), (LAS unsigned*)(lds + (bufoff) + ldsw + _i * 8192), 16, 0, 0); } while (0)
; #define PG8_LDA(dst, b, h) do { _Pragma("unroll") for (int m = 0; m < 4; ++m) _Pragma("unroll") for (int k = 0; k < 2; ++k) dst[m][k] = *(const LAS bf16x8*)(lds + PG8_SA(b, h) + aoff + m * 2048 + k * 1024); } while (0)
; #define PG8_MMA(ai, bj, At, Bt) do { __builtin_amdgcn_s_setprio(1); _Pragma("unroll") for (int m = 0; m < 4; ++m) _Pragma("unroll") for (int n = 0; n < 2; ++n) _Pragma("unroll") for (int k = 0; k < 2; ++k) \
;         acc[ai][bj][m][n] = __builtin_amdgcn_mfma_f32_16x16x32_bf16(Bt[n][k], At[m][k], acc[ai][bj][m][n], 0, 0, 0); __builtin_amdgcn_s_setprio(0); } while (0)
; #define PG8_WAIT_V(n) asm volatile("s_waitcnt vmcnt(" #n ")" ::: "memory")
; #define PG8_WAIT_L(n) asm volatile("s_waitcnt lgkmcnt(" #n ")" ::: "memory")
; #define PG8_BAR __builtin_amdgcn_s_barrier()
; #define PG8_SCHED __builtin_amdgcn_sched_barrier(0)
; template <class Epi>
; __device__ __forceinline__ void gemm_phase(LAS unsigned char* lds, const Gemm g, const StaticOrder& S, const Epi& E) {
;     ...
;             PG8_LDA(At, 1, 1); PG8_STAGE(PG8_SB(1, 0), b3, voffB); PG8_STAGE(PG8_SB(1, 1), b3 + hstepB, voffB); PG8_STAGE(PG8_SA(1, 0), a3, voffA);
;             PG8_WAIT_V(8); PG8_WAIT_L(0); PG8_BAR; PG8_MMA(1, 0, At, B0); PG8_MMA(1, 1, At, B1); PG8_BAR; PG8_SCHED;
;         }
	s_add_i32 s0, s50, s28
	v_lshl_add_u64 v[224:225], v[224:225], 0, s[14:15]
	s_mov_b32 m0, s0
	ds_read_b128 v[188:191], v154 offset:49152
	ds_read_b128 v[192:195], v154 offset:50176
	ds_read_b128 v[196:199], v154 offset:51200
	ds_read_b128 v[200:203], v154 offset:52224
	ds_read_b128 v[208:211], v154 offset:53248
	ds_read_b128 v[212:215], v154 offset:54272
	ds_read_b128 v[216:219], v154 offset:55296
	ds_read_b128 v[220:223], v154 offset:56320
	global_load_lds_dwordx4 v[224:225], off
	s_add_i32 m0, s0, 0x2000
	s_add_u32 s0, s22, 0x18080
	v_lshl_add_u64 v[224:225], v[226:227], 0, s[14:15]
	s_addc_u32 s1, s23, 0
	s_add_i32 s22, s51, s28
	global_load_lds_dwordx4 v[224:225], off
	s_mov_b32 m0, s22
	s_nop 0
	global_load_lds_dwordx4 v130, s[0:1]
	s_add_i32 m0, s22, 0x2000
	s_nop 0
	global_load_lds_dwordx4 v134, s[0:1]
	v_lshl_add_u64 v[224:225], v[230:231], 0, s[14:15]
	s_mov_b32 m0, s38
	s_nop 0
	global_load_lds_dwordx4 v[224:225], off
	v_lshl_add_u64 v[224:225], v[232:233], 0, s[14:15]
	s_mov_b32 m0, s39
	s_nop 0
	global_load_lds_dwordx4 v[224:225], off
	s_waitcnt vmcnt(8)
	s_waitcnt lgkmcnt(0)
	s_barrier
	s_setprio 1
	s_waitcnt lgkmcnt(0)
	v_mfma_f32_16x16x32_bf16 v[60:63], v[156:159], v[188:191], v[60:63]
	v_mfma_f32_16x16x32_bf16 v[60:63], v[160:163], v[192:195], v[60:63]
	v_mfma_f32_16x16x32_bf16 v[56:59], v[168:171], v[192:195], v[56:59]
	v_mfma_f32_16x16x32_bf16 v[56:59], v[164:167], v[188:191], v[56:59]
	v_mfma_f32_16x16x32_bf16 v[52:55], v[172:175], v[188:191], v[52:55]
	v_mfma_f32_16x16x32_bf16 v[52:55], v[176:179], v[192:195], v[52:55]
	v_mfma_f32_16x16x32_bf16 v[48:51], v[184:187], v[192:195], v[48:51]
	v_mfma_f32_16x16x32_bf16 v[48:51], v[180:183], v[188:191], v[48:51]
	v_mfma_f32_16x16x32_bf16 v[32:35], v[180:183], v[196:199], v[32:35]
	v_mfma_f32_16x16x32_bf16 v[32:35], v[184:187], v[200:203], v[32:35]
	v_mfma_f32_16x16x32_bf16 v[36:39], v[176:179], v[200:203], v[36:39]
	v_mfma_f32_16x16x32_bf16 v[36:39], v[172:175], v[196:199], v[36:39]
	v_mfma_f32_16x16x32_bf16 v[40:43], v[164:167], v[196:199], v[40:43]
	v_mfma_f32_16x16x32_bf16 v[40:43], v[168:171], v[200:203], v[40:43]
	v_mfma_f32_16x16x32_bf16 v[44:47], v[160:163], v[200:203], v[44:47]
	v_mfma_f32_16x16x32_bf16 v[44:47], v[156:159], v[196:199], v[44:47]
	s_setprio 0
	s_setprio 1
	v_mfma_f32_16x16x32_bf16 v[28:31], v[156:159], v[208:211], v[28:31]
	v_mfma_f32_16x16x32_bf16 v[28:31], v[160:163], v[212:215], v[28:31]
	v_mfma_f32_16x16x32_bf16 v[24:27], v[168:171], v[212:215], v[24:27]
	v_mfma_f32_16x16x32_bf16 v[24:27], v[164:167], v[208:211], v[24:27]
	v_mfma_f32_16x16x32_bf16 v[20:23], v[172:175], v[208:211], v[20:23]
	v_mfma_f32_16x16x32_bf16 v[20:23], v[176:179], v[212:215], v[20:23]
	v_mfma_f32_16x16x32_bf16 v[16:19], v[184:187], v[212:215], v[16:19]
	v_mfma_f32_16x16x32_bf16 v[16:19], v[180:183], v[208:211], v[16:19]
	v_mfma_f32_16x16x32_bf16 v[0:3], v[180:183], v[216:219], v[0:3]
	v_mfma_f32_16x16x32_bf16 v[0:3], v[184:187], v[220:223], v[0:3]
	v_mfma_f32_16x16x32_bf16 v[4:7], v[176:179], v[220:223], v[4:7]
	v_mfma_f32_16x16x32_bf16 v[4:7], v[172:175], v[216:219], v[4:7]
	v_mfma_f32_16x16x32_bf16 v[8:11], v[164:167], v[216:219], v[8:11]
	v_mfma_f32_16x16x32_bf16 v[8:11], v[168:171], v[220:223], v[8:11]
	v_mfma_f32_16x16x32_bf16 v[12:15], v[160:163], v[220:223], v[12:15]
	v_mfma_f32_16x16x32_bf16 v[12:15], v[156:159], v[216:219], v[12:15]
	s_setprio 0
	s_barrier
	s_add_u32 s47, s47, 0x100
	s_addc_u32 s48, s48, 0
	s_cmp_ge_i32 s49, s36
	s_mov_b64 s[0:1], s[4:5]
	s_mov_b32 s22, s49
	s_cbranch_scc0 .LBB0_834

; #define PG8_STAGE(bufoff, gbase, voff) do { _Pragma("unroll") for (int _i = 0; _i < 2; ++_i) \
;         __builtin_amdgcn_global_load_lds((const unsigned*)((const char*)(gbase) + (voff)[_i]), (LAS unsigned*)(lds + (bufoff) + ldsw + _i * 8192), 16, 0, 0); } while (0)
; #define PG8_WAIT_V(n) asm volatile("s_waitcnt vmcnt(" #n ")" ::: "memory")
; #define PG8_BAR __builtin_amdgcn_s_barrier()
; template <class Epi>
; __device__ __forceinline__ void gemm_phase(LAS unsigned char* lds, const Gemm g, const StaticOrder& S, const Epi& E) {
;     ...
;     for (int i = 0; i < 2; ++i) { int R, C; stage_rc(tid * 16 + i * 8192, R, C); const int Rb = Epi::PERM ? ((R & ~31) + perm32(R & 31)) : R;
;         voffA[i] = (unsigned)(R * g.lda + C) * 2u; voffB[i] = (unsigned)(Rb * g.ldb + C) * 2u; }
;     const size_t kstep = (size_t)(BK * 2);
;     const size_t hstepA = (size_t)HALF * g.lda * 2, hstepB = (size_t)HALF * g.ldb * 2;
;     const size_t tstepA = 2 * hstepA, tstepB = 2 * hstepB;
;     const unsigned ldsw = (unsigned)wid * 1024u;
;     const int aoff = lds_byte(wr * 64 + fr, fq * 8), boff = lds_byte(wc * 32 + fr, fq * 8);
;     ...
;     Unit cur, nxt; int ui = 0;
;     if (!S.next(0, cur)) return;
;     f32x4 acc[2][2][4][2];
; #pragma unroll
;     for (int a = 0; a < 2; ++a)
; #pragma unroll
;         for (int b = 0; b < 2; ++b)
; #pragma unroll
;             for (int m = 0; m < 4; ++m)
; #pragma unroll
;                 for (int n = 0; n < 2; ++n) acc[a][b][m][n] = (f32x4){0.f, 0.f, 0.f, 0.f};
;     bf16x8 At[4][2], B0[2][2], B1[2][2];
;     const char* cA = (const char*)g.A + (size_t)cur.pm * tstepA; const char* cB = (const char*)g.Bt + (size_t)cur.pb * tstepB;
;     PG8_STAGE(PG8_SB(0, 0), cB, voffB); PG8_STAGE(PG8_SB(0, 1), cB + hstepB, voffB); PG8_STAGE(PG8_SA(0, 0), cA, voffA); PG8_STAGE(PG8_SA(0, 1), cA + hstepA, voffA);
;     if (wr == 1) PG8_BAR;
;     PG8_WAIT_V(2); PG8_BAR;
;     PG8_STAGE(PG8_SB(1, 0), cB + kstep, voffB); PG8_STAGE(PG8_SA(1, 0), cA + kstep, voffA); PG8_STAGE(PG8_SB(1, 1), cB + hstepB + kstep, voffB);
;     PG8_WAIT_V(6); PG8_BAR;
;     for (;;) {
;         const bool has_next = S.next(ui + 1, nxt);
;         const char* nA = has_next ? (const char*)g.A + (size_t)nxt.pm * tstepA : cA; const char* nB = has_next ? (const char*)g.Bt + (size_t)nxt.pb * tstepB : cB;
;         for (int t = 0; t < nt; t += 2) {
;             const bool last = (t == nt - 2);
.LBB0_901:
	s_ashr_i32 s1, s12, 31
	s_lshr_b32 s1, s1, 26
	s_add_i32 s1, s12, s1
	s_ashr_i32 s39, s1, 6
	s_lshl_b32 s1, s10, 5
	s_mov_b64 s[10:11], 0x80
	s_and_b32 s19, s1, 0x60
	s_add_i32 m0, s31, 0x18000
	v_lshl_add_u64 v[6:7], v[6:7], 0, s[10:11]
	s_lshl_b32 s18, s7, 6
	s_lshl_b32 s7, s7, 13
	s_lshl_b32 s13, s19, 7
	s_waitcnt vmcnt(2)
	s_barrier
	global_load_lds_dwordx4 v[6:7], off
	v_lshl_add_u64 v[4:5], v[4:5], 0, s[10:11]
	s_add_i32 m0, s31, 0x1a000
	s_add_i32 s40, s31, 0x8000
	s_add_i32 s41, s31, 0xa000
	global_load_lds_dwordx4 v[4:5], off
	v_lshl_add_u64 v[0:1], v[0:1], 0, s[10:11]
	s_mov_b32 m0, s40
	s_add_u32 s16, s24, 0x40080
	global_load_lds_dwordx4 v[0:1], off
	v_lshl_add_u64 v[0:1], v[2:3], 0, s[10:11]
	s_mov_b32 m0, s41
	s_addc_u32 s17, s25, 0
	global_load_lds_dwordx4 v[0:1], off
	s_add_i32 m0, s31, 0x1c000
	s_nop 0
	global_load_lds_dwordx4 v210, s[16:17]
	v_lshl_add_u64 v[0:1], s[16:17], 0, v[214:215]
	s_add_i32 m0, s31, 0x1e000
	v_lshlrev_b32_e32 v3, 2, v9
	global_load_lds_dwordx4 v[0:1], off
	v_lshrrev_b32_e32 v1, 1, v9
	v_and_b32_e32 v2, 24, v1
	v_and_b32_e32 v0, 15, v9
	v_lshlrev_b32_e32 v1, 1, v2
	v_lshl_or_b32 v1, v0, 6, v1
	v_and_b32_e32 v3, 32, v3
	s_cmp_gt_i32 s12, 63
	v_bitop3_b32 v229, v1, s13, v3 bitop3:0xde
	s_cselect_b64 s[12:13], -1, 0
	s_add_i32 s44, s39, -2
	s_cmpk_lt_u32 s14, 0x100
	v_readlane_b32 s48, v251, 1
	s_sext_i32_i8 s1, s6
	s_cselect_b64 s[14:15], -1, 0
	s_ashr_i32 s6, s18, 31
	v_readlane_b32 s52, v251, 5
	v_readlane_b32 s53, v251, 6
	v_bitop3_b32 v4, v1, s7, v3 bitop3:0xde
	v_mov_b32_e32 v1, s6
	s_ashr_i32 s45, s94, 31
	s_lshl_b32 s6, s19, 2
	v_readlane_b32 s54, v251, 7
	v_readlane_b32 s55, v251, 8
	s_mov_b64 s[20:21], s[52:53]
	v_or_b32_e32 v0, s18, v0
	s_add_u32 s6, s20, s6
	v_lshlrev_b64 v[216:217], 10, v[0:1]
	s_addc_u32 s7, s21, 0
	v_lshlrev_b32_e32 v0, 2, v2
	v_mov_b32_e32 v1, v211
	v_lshl_add_u64 v[218:219], s[6:7], 0, v[0:1]
	v_lshlrev_b32_e32 v0, 14, v8
	v_and_b32_e32 v0, 0xffff8000, v0
	v_lshl_add_u32 v0, v10, 11, v0
	v_and_b32_e32 v1, 1, v8
	v_lshl_or_b32 v0, v1, 6, v0
	v_lshl_add_u32 v220, v11, 1, v0
	v_lshlrev_b32_e32 v0, 14, v12
	v_and_b32_e32 v0, 0xffff8000, v0
	s_waitcnt vmcnt(6)
	v_lshl_add_u32 v0, v13, 11, v0
	v_and_b32_e32 v1, 1, v12
	v_readlane_b32 s49, v251, 2
	v_readlane_b32 s50, v251, 3
	v_readlane_b32 s51, v251, 4
	v_lshl_or_b32 v0, v1, 6, v0
	s_add_i32 s47, 0, 0x10000
	s_add_i32 s48, 0, 0x14000
	s_mov_b32 s42, 0x18000
	s_mov_b32 s43, 0x8000
	s_mov_b32 s46, s94
	s_mov_b64 s[22:23], s[54:55]
	v_or3_b32 v216, v216, v2, s19
	v_mov_b32_e32 v221, v211
	v_lshl_add_u32 v222, v14, 1, v0
	v_mov_b32_e32 v223, v211
	v_mov_b64_e32 v[224:225], 0x200
	v_mov_b64_e32 v[226:227], 0x1ff
	v_add_u32_e32 v230, s47, v229
	v_add_u32_e32 v231, s48, v229
	v_add_u32_e32 v232, 0, v4
	s_mov_b32 s49, 0x40000
	s_mov_b32 s50, 0x48000
	s_mov_b32 s51, 0x50000
	s_mov_b32 s52, 0x58000
	s_barrier
	v_readlane_b32 s56, v251, 9
	v_readlane_b32 s57, v251, 10
	v_readlane_b32 s58, v251, 11
	v_readlane_b32 s59, v251, 12
	v_readlane_b32 s60, v251, 13
	v_readlane_b32 s61, v251, 14
	v_readlane_b32 s62, v251, 15
	v_readlane_b32 s63, v251, 16
	s_branch .LBB0_904

; #define PG8_STAGE(bufoff, gbase, voff) do { _Pragma("unroll") for (int _i = 0; _i < 2; ++_i) \
;         __builtin_amdgcn_global_load_lds((const unsigned*)((const char*)(gbase) + (voff)[_i]), (LAS unsigned*)(lds + (bufoff) + ldsw + _i * 8192), 16, 0, 0); } while (0)
; #define PG8_LDA(dst, b, h) do { _Pragma("unroll") for (int m = 0; m < 4; ++m) _Pragma("unroll") for (int k = 0; k < 2; ++k) dst[m][k] = *(const LAS bf16x8*)(lds + PG8_SA(b, h) + aoff + m * 2048 + k * 1024); } while (0)
; #define PG8_LDB(dst, b, h) do { _Pragma("unroll") for (int n = 0; n < 2; ++n) _Pragma("unroll") for (int k = 0; k < 2; ++k) dst[n][k] = *(const LAS bf16x8*)(lds + PG8_SB(b, h) + boff + n * 2048 + k * 1024); } while (0)
; #define PG8_MMA(ai, bj, At, Bt) do { __builtin_amdgcn_s_setprio(1); _Pragma("unroll") for (int m = 0; m < 4; ++m) _Pragma("unroll") for (int n = 0; n < 2; ++n) _Pragma("unroll") for (int k = 0; k < 2; ++k) \
;         acc[ai][bj][m][n] = __builtin_amdgcn_mfma_f32_16x16x32_bf16(Bt[n][k], At[m][k], acc[ai][bj][m][n], 0, 0, 0); __builtin_amdgcn_s_setprio(0); } while (0)
; #define PG8_WAIT_V(n) asm volatile("s_waitcnt vmcnt(" #n ")" ::: "memory")
; #define PG8_WAIT_L(n) asm volatile("s_waitcnt lgkmcnt(" #n ")" ::: "memory")
; #define PG8_BAR __builtin_amdgcn_s_barrier()
; #define PG8_SCHED __builtin_amdgcn_sched_barrier(0)
; template <class Epi>
; __device__ __forceinline__ void gemm_phase(LAS unsigned char* lds, const Gemm g, const StaticOrder& S, const Epi& E) {
;     ...
;             PG8_LDB(B0, 0, 0); PG8_LDB(B1, 0, 1); PG8_SCHED; PG8_LDA(At, 0, 0); PG8_STAGE(PG8_SA(1, 1), a1 + hstepA, voffA);
;             PG8_WAIT_V(8); PG8_WAIT_L(0); PG8_BAR; PG8_MMA(0, 0, At, B0); PG8_MMA(0, 1, At, B1); PG8_BAR; PG8_SCHED;
;             PG8_LDA(At, 0, 1); PG8_STAGE(PG8_SB(0, 0), b2, voffB); PG8_STAGE(PG8_SB(0, 1), b2 + hstepB, voffB); PG8_STAGE(PG8_SA(0, 0), a2, voffA);
.LBB0_912:
	ds_read_b128 v[96:99], v230
	ds_read_b128 v[100:103], v230 offset:1024
	ds_read_b128 v[104:107], v230 offset:2048
	ds_read_b128 v[116:119], v230 offset:3072
	ds_read_b128 v[120:123], v231
	ds_read_b128 v[124:127], v231 offset:1024
	ds_read_b128 v[136:139], v231 offset:2048
	ds_read_b128 v[148:151], v231 offset:3072
	s_add_i32 s56, s24, 2
	s_add_u32 s25, s4, 0xfffc0080
	s_addc_u32 s26, s5, -1
	s_cmp_eq_u32 s44, s24
	s_cselect_b32 s24, s53, s54
	s_cselect_b32 s27, s17, s26
	s_cselect_b32 s26, s19, s25
	s_cselect_b32 s25, s33, s55
	s_add_i32 m0, s31, 0xc000
	ds_read_b128 v[160:163], v232
	ds_read_b128 v[164:167], v232 offset:1024
	ds_read_b128 v[168:171], v232 offset:2048
	ds_read_b128 v[172:175], v232 offset:3072
	ds_read_b128 v[176:179], v232 offset:4096
	ds_read_b128 v[180:183], v232 offset:5120
	ds_read_b128 v[184:187], v232 offset:6144
	ds_read_b128 v[188:191], v232 offset:7168
	global_load_lds_dwordx4 v220, s[4:5]
	s_add_i32 m0, s31, 0xe000
	s_nop 0
	global_load_lds_dwordx4 v222, s[4:5]
	s_waitcnt vmcnt(8)
	s_waitcnt lgkmcnt(0)
	s_barrier
	s_setprio 1
	s_waitcnt lgkmcnt(0)
	v_mfma_f32_16x16x32_bf16 v[156:159], v[96:99], v[160:163], v[156:159]
	v_mfma_f32_16x16x32_bf16 v[156:159], v[100:103], v[164:167], v[156:159]
	v_mfma_f32_16x16x32_bf16 v[152:155], v[116:119], v[164:167], v[152:155]
	v_mfma_f32_16x16x32_bf16 v[152:155], v[104:107], v[160:163], v[152:155]
	v_mfma_f32_16x16x32_bf16 v[144:147], v[120:123], v[160:163], v[144:147]
	v_mfma_f32_16x16x32_bf16 v[144:147], v[124:127], v[164:167], v[144:147]
	v_mfma_f32_16x16x32_bf16 v[140:143], v[148:151], v[164:167], v[140:143]
	v_mfma_f32_16x16x32_bf16 v[140:143], v[136:139], v[160:163], v[140:143]
	v_mfma_f32_16x16x32_bf16 v[108:111], v[136:139], v[168:171], v[108:111]
	v_mfma_f32_16x16x32_bf16 v[108:111], v[148:151], v[172:175], v[108:111]
	v_mfma_f32_16x16x32_bf16 v[112:115], v[124:127], v[172:175], v[112:115]
	v_mfma_f32_16x16x32_bf16 v[112:115], v[120:123], v[168:171], v[112:115]
	v_mfma_f32_16x16x32_bf16 v[128:131], v[104:107], v[168:171], v[128:131]
	v_mfma_f32_16x16x32_bf16 v[128:131], v[116:119], v[172:175], v[128:131]
	v_mfma_f32_16x16x32_bf16 v[132:135], v[100:103], v[172:175], v[132:135]
	v_mfma_f32_16x16x32_bf16 v[132:135], v[96:99], v[168:171], v[132:135]
	s_setprio 0
	s_setprio 1
	v_mfma_f32_16x16x32_bf16 v[92:95], v[96:99], v[176:179], v[92:95]
	v_mfma_f32_16x16x32_bf16 v[92:95], v[100:103], v[180:183], v[92:95]
	v_mfma_f32_16x16x32_bf16 v[88:91], v[116:119], v[180:183], v[88:91]
	v_mfma_f32_16x16x32_bf16 v[88:91], v[104:107], v[176:179], v[88:91]
	v_mfma_f32_16x16x32_bf16 v[84:87], v[120:123], v[176:179], v[84:87]
	v_mfma_f32_16x16x32_bf16 v[84:87], v[124:127], v[180:183], v[84:87]
	v_mfma_f32_16x16x32_bf16 v[80:83], v[148:151], v[180:183], v[80:83]
	v_mfma_f32_16x16x32_bf16 v[80:83], v[136:139], v[176:179], v[80:83]
	v_mfma_f32_16x16x32_bf16 v[64:67], v[136:139], v[184:187], v[64:67]
	v_mfma_f32_16x16x32_bf16 v[64:67], v[148:151], v[188:191], v[64:67]
	v_mfma_f32_16x16x32_bf16 v[68:71], v[124:127], v[188:191], v[68:71]
	v_mfma_f32_16x16x32_bf16 v[68:71], v[120:123], v[184:187], v[68:71]
	v_mfma_f32_16x16x32_bf16 v[72:75], v[104:107], v[184:187], v[72:75]
	v_mfma_f32_16x16x32_bf16 v[72:75], v[116:119], v[188:191], v[72:75]
	v_mfma_f32_16x16x32_bf16 v[76:79], v[100:103], v[188:191], v[76:79]
	v_mfma_f32_16x16x32_bf16 v[76:79], v[96:99], v[184:187], v[76:79]
	s_setprio 0
	s_barrier
	s_add_i32 s57, s47, s30
	v_lshl_add_u64 v[192:193], s[24:25], 0, v[210:211]
	s_mov_b32 m0, s57
	ds_read_b128 v[160:163], v232 offset:16384
	ds_read_b128 v[164:167], v232 offset:17408
	ds_read_b128 v[168:171], v232 offset:18432
	ds_read_b128 v[172:175], v232 offset:19456
	ds_read_b128 v[176:179], v232 offset:20480
	ds_read_b128 v[180:183], v232 offset:21504
	ds_read_b128 v[184:187], v232 offset:22528
	ds_read_b128 v[188:191], v232 offset:23552
	global_load_lds_dwordx4 v[192:193], off
	s_add_i32 m0, s57, 0x2000
	s_add_u32 s58, s24, 0x40000
	v_lshl_add_u64 v[194:195], s[24:25], 0, v[214:215]
	s_addc_u32 s59, s25, 0
	s_add_i32 s57, s48, s30
	global_load_lds_dwordx4 v[194:195], off
	s_mov_b32 m0, s57
	v_lshl_add_u64 v[198:199], s[26:27], 0, v[212:213]
	global_load_lds_dwordx4 v210, s[58:59]
	s_add_i32 m0, s57, 0x2000
	s_nop 0
	global_load_lds_dwordx4 v214, s[58:59]
	v_lshl_add_u64 v[196:197], s[26:27], 0, v[208:209]
	s_mov_b32 m0, s31
	s_nop 0
	global_load_lds_dwordx4 v[196:197], off
	s_mov_b32 m0, s34
	s_nop 0
	global_load_lds_dwordx4 v[198:199], off
	s_waitcnt vmcnt(8)
	s_waitcnt lgkmcnt(0)
	s_barrier
; #define PG8_STAGE(bufoff, gbase, voff) do { _Pragma("unroll") for (int _i = 0; _i < 2; ++_i) \
;         __builtin_amdgcn_global_load_lds((const unsigned*)((const char*)(gbase) + (voff)[_i]), (LAS unsigned*)(lds + (bufoff) + ldsw + _i * 8192), 16, 0, 0); } while (0)
; #define PG8_LDA(dst, b, h) do { _Pragma("unroll") for (int m = 0; m < 4; ++m) _Pragma("unroll") for (int k = 0; k < 2; ++k) dst[m][k] = *(const LAS bf16x8*)(lds + PG8_SA(b, h) + aoff + m * 2048 + k * 1024); } while (0)
; #define PG8_LDB(dst, b, h) do { _Pragma("unroll") for (int n = 0; n < 2; ++n) _Pragma("unroll") for (int k = 0; k < 2; ++k) dst[n][k] = *(const LAS bf16x8*)(lds + PG8_SB(b, h) + boff + n * 2048 + k * 1024); } while (0)
; #define PG8_MMA(ai, bj, At, Bt) do { __builtin_amdgcn_s_setprio(1); _Pragma("unroll") for (int m = 0; m < 4; ++m) _Pragma("unroll") for (int n = 0; n < 2; ++n) _Pragma("unroll") for (int k = 0; k < 2; ++k) \
;         acc[ai][bj][m][n] = __builtin_amdgcn_mfma_f32_16x16x32_bf16(Bt[n][k], At[m][k], acc[ai][bj][m][n], 0, 0, 0); __builtin_amdgcn_s_setprio(0); } while (0)
; #define PG8_WAIT_V(n) asm volatile("s_waitcnt vmcnt(" #n ")" ::: "memory")
; #define PG8_WAIT_L(n) asm volatile("s_waitcnt lgkmcnt(" #n ")" ::: "memory")
; #define PG8_BAR __builtin_amdgcn_s_barrier()
; #define PG8_SCHED __builtin_amdgcn_sched_barrier(0)
; template <class Epi>
; __device__ __forceinline__ void gemm_phase(LAS unsigned char* lds, const Gemm g, const StaticOrder& S, const Epi& E) {
;     ...
;             PG8_WAIT_V(8); PG8_WAIT_L(0); PG8_BAR; PG8_MMA(1, 0, At, B0); PG8_MMA(1, 1, At, B1); PG8_BAR; PG8_SCHED;
;             PG8_LDB(B0, 1, 0); PG8_LDB(B1, 1, 1); PG8_SCHED; PG8_LDA(At, 1, 0); PG8_STAGE(PG8_SA(0, 1), a2 + hstepA, voffA);
;             PG8_WAIT_V(8); PG8_WAIT_L(0); PG8_BAR; PG8_MMA(0, 0, At, B0); PG8_MMA(0, 1, At, B1); PG8_BAR; PG8_SCHED;
	s_setprio 1
	s_waitcnt lgkmcnt(0)
	v_mfma_f32_16x16x32_bf16 v[60:63], v[96:99], v[160:163], v[60:63]
	v_mfma_f32_16x16x32_bf16 v[60:63], v[100:103], v[164:167], v[60:63]
	v_mfma_f32_16x16x32_bf16 v[56:59], v[116:119], v[164:167], v[56:59]
	v_mfma_f32_16x16x32_bf16 v[56:59], v[104:107], v[160:163], v[56:59]
	v_mfma_f32_16x16x32_bf16 v[52:55], v[120:123], v[160:163], v[52:55]
	v_mfma_f32_16x16x32_bf16 v[52:55], v[124:127], v[164:167], v[52:55]
	v_mfma_f32_16x16x32_bf16 v[48:51], v[148:151], v[164:167], v[48:51]
	v_mfma_f32_16x16x32_bf16 v[48:51], v[136:139], v[160:163], v[48:51]
	v_mfma_f32_16x16x32_bf16 v[32:35], v[136:139], v[168:171], v[32:35]
	v_mfma_f32_16x16x32_bf16 v[32:35], v[148:151], v[172:175], v[32:35]
	v_mfma_f32_16x16x32_bf16 v[36:39], v[124:127], v[172:175], v[36:39]
	v_mfma_f32_16x16x32_bf16 v[36:39], v[120:123], v[168:171], v[36:39]
	v_mfma_f32_16x16x32_bf16 v[40:43], v[104:107], v[168:171], v[40:43]
	v_mfma_f32_16x16x32_bf16 v[40:43], v[116:119], v[172:175], v[40:43]
	v_mfma_f32_16x16x32_bf16 v[44:47], v[100:103], v[172:175], v[44:47]
	v_mfma_f32_16x16x32_bf16 v[44:47], v[96:99], v[168:171], v[44:47]
	s_setprio 0
	s_setprio 1
	v_mfma_f32_16x16x32_bf16 v[28:31], v[96:99], v[176:179], v[28:31]
	v_mfma_f32_16x16x32_bf16 v[28:31], v[100:103], v[180:183], v[28:31]
	v_mfma_f32_16x16x32_bf16 v[24:27], v[116:119], v[180:183], v[24:27]
	v_mfma_f32_16x16x32_bf16 v[24:27], v[104:107], v[176:179], v[24:27]
	v_mfma_f32_16x16x32_bf16 v[20:23], v[120:123], v[176:179], v[20:23]
	v_mfma_f32_16x16x32_bf16 v[20:23], v[124:127], v[180:183], v[20:23]
	v_mfma_f32_16x16x32_bf16 v[16:19], v[148:151], v[180:183], v[16:19]
	v_mfma_f32_16x16x32_bf16 v[16:19], v[136:139], v[176:179], v[16:19]
	v_mfma_f32_16x16x32_bf16 v[0:3], v[136:139], v[184:187], v[0:3]
	v_mfma_f32_16x16x32_bf16 v[0:3], v[148:151], v[188:191], v[0:3]
	v_mfma_f32_16x16x32_bf16 v[4:7], v[124:127], v[188:191], v[4:7]
	v_mfma_f32_16x16x32_bf16 v[4:7], v[120:123], v[184:187], v[4:7]
	v_mfma_f32_16x16x32_bf16 v[8:11], v[104:107], v[184:187], v[8:11]
	v_mfma_f32_16x16x32_bf16 v[8:11], v[116:119], v[188:191], v[8:11]
	v_mfma_f32_16x16x32_bf16 v[12:15], v[100:103], v[188:191], v[12:15]
	v_mfma_f32_16x16x32_bf16 v[12:15], v[96:99], v[184:187], v[12:15]
	s_setprio 0
	s_barrier
	s_add_i32 s57, 0, 0x18000
	s_add_i32 s58, 0, 0x1c000
	v_add_u32_e32 v116, s57, v229
	v_add_u32_e32 v148, s58, v229
	ds_read_b128 v[96:99], v116
	ds_read_b128 v[100:103], v116 offset:1024
	ds_read_b128 v[104:107], v116 offset:2048
	ds_read_b128 v[116:119], v116 offset:3072
	ds_read_b128 v[120:123], v148
	ds_read_b128 v[124:127], v148 offset:1024
	ds_read_b128 v[136:139], v148 offset:2048
	ds_read_b128 v[148:151], v148 offset:3072
	s_add_u32 s26, s26, 0x40000
	s_addc_u32 s27, s27, 0
	s_mov_b32 m0, s35
	ds_read_b128 v[160:163], v232 offset:32768
	ds_read_b128 v[164:167], v232 offset:33792
	ds_read_b128 v[168:171], v232 offset:34816
	ds_read_b128 v[172:175], v232 offset:35840
	ds_read_b128 v[176:179], v232 offset:36864
	ds_read_b128 v[180:183], v232 offset:37888
	ds_read_b128 v[184:187], v232 offset:38912
	ds_read_b128 v[188:191], v232 offset:39936
	global_load_lds_dwordx4 v208, s[26:27]
	s_mov_b32 m0, s36
	s_nop 0
	global_load_lds_dwordx4 v212, s[26:27]
	s_waitcnt vmcnt(8)
	s_waitcnt lgkmcnt(0)
	s_barrier
	s_setprio 1
	s_waitcnt lgkmcnt(0)
	v_mfma_f32_16x16x32_bf16 v[156:159], v[96:99], v[160:163], v[156:159]
	v_mfma_f32_16x16x32_bf16 v[156:159], v[100:103], v[164:167], v[156:159]
	v_mfma_f32_16x16x32_bf16 v[152:155], v[116:119], v[164:167], v[152:155]
	v_mfma_f32_16x16x32_bf16 v[152:155], v[104:107], v[160:163], v[152:155]
	v_mfma_f32_16x16x32_bf16 v[144:147], v[120:123], v[160:163], v[144:147]
	v_mfma_f32_16x16x32_bf16 v[144:147], v[124:127], v[164:167], v[144:147]
	v_mfma_f32_16x16x32_bf16 v[140:143], v[148:151], v[164:167], v[140:143]
	v_mfma_f32_16x16x32_bf16 v[140:143], v[136:139], v[160:163], v[140:143]
	v_mfma_f32_16x16x32_bf16 v[108:111], v[136:139], v[168:171], v[108:111]
	v_mfma_f32_16x16x32_bf16 v[108:111], v[148:151], v[172:175], v[108:111]
	v_mfma_f32_16x16x32_bf16 v[112:115], v[124:127], v[172:175], v[112:115]
	v_mfma_f32_16x16x32_bf16 v[112:115], v[120:123], v[168:171], v[112:115]
	v_mfma_f32_16x16x32_bf16 v[128:131], v[104:107], v[168:171], v[128:131]
	v_mfma_f32_16x16x32_bf16 v[128:131], v[116:119], v[172:175], v[128:131]
	v_mfma_f32_16x16x32_bf16 v[132:135], v[100:103], v[172:175], v[132:135]
	v_mfma_f32_16x16x32_bf16 v[132:135], v[96:99], v[168:171], v[132:135]
	s_setprio 0
	s_setprio 1
	v_mfma_f32_16x16x32_bf16 v[92:95], v[96:99], v[176:179], v[92:95]
	v_mfma_f32_16x16x32_bf16 v[92:95], v[100:103], v[180:183], v[92:95]
	v_mfma_f32_16x16x32_bf16 v[88:91], v[116:119], v[180:183], v[88:91]
	v_mfma_f32_16x16x32_bf16 v[88:91], v[104:107], v[176:179], v[88:91]
	v_mfma_f32_16x16x32_bf16 v[84:87], v[120:123], v[176:179], v[84:87]
	v_mfma_f32_16x16x32_bf16 v[84:87], v[124:127], v[180:183], v[84:87]
	v_mfma_f32_16x16x32_bf16 v[80:83], v[148:151], v[180:183], v[80:83]
	v_mfma_f32_16x16x32_bf16 v[80:83], v[136:139], v[176:179], v[80:83]
	v_mfma_f32_16x16x32_bf16 v[64:67], v[136:139], v[184:187], v[64:67]
	v_mfma_f32_16x16x32_bf16 v[64:67], v[148:151], v[188:191], v[64:67]
	v_mfma_f32_16x16x32_bf16 v[68:71], v[124:127], v[188:191], v[68:71]
	v_mfma_f32_16x16x32_bf16 v[68:71], v[120:123], v[184:187], v[68:71]
	v_mfma_f32_16x16x32_bf16 v[72:75], v[104:107], v[184:187], v[72:75]
	v_mfma_f32_16x16x32_bf16 v[72:75], v[116:119], v[188:191], v[72:75]
	v_mfma_f32_16x16x32_bf16 v[76:79], v[100:103], v[188:191], v[76:79]
	v_mfma_f32_16x16x32_bf16 v[76:79], v[96:99], v[184:187], v[76:79]
	s_setprio 0
	s_barrier
; #define PG8_STAGE(bufoff, gbase, voff) do { _Pragma("unroll") for (int _i = 0; _i < 2; ++_i) \
;         __builtin_amdgcn_global_load_lds((const unsigned*)((const char*)(gbase) + (voff)[_i]), (LAS unsigned*)(lds + (bufoff) + ldsw + _i * 8192), 16, 0, 0); } while (0)
; #define PG8_LDA(dst, b, h) do { _Pragma("unroll") for (int m = 0; m < 4; ++m) _Pragma("unroll") for (int k = 0; k < 2; ++k) dst[m][k] = *(const LAS bf16x8*)(lds + PG8_SA(b, h) + aoff + m * 2048 + k * 1024); } while (0)
; #define PG8_MMA(ai, bj, At, Bt) do { __builtin_amdgcn_s_setprio(1); _Pragma("unroll") for (int m = 0; m < 4; ++m) _Pragma("unroll") for (int n = 0; n < 2; ++n) _Pragma("unroll") for (int k = 0; k < 2; ++k) \
;         acc[ai][bj][m][n] = __builtin_amdgcn_mfma_f32_16x16x32_bf16(Bt[n][k], At[m][k], acc[ai][bj][m][n], 0, 0, 0); __builtin_amdgcn_s_setprio(0); } while (0)
; #define PG8_WAIT_V(n) asm volatile("s_waitcnt vmcnt(" #n ")" ::: "memory")
; #define PG8_WAIT_L(n) asm volatile("s_waitcnt lgkmcnt(" #n ")" ::: "memory")
; #define PG8_BAR __builtin_amdgcn_s_barrier()
; #define PG8_SCHED __builtin_amdgcn_sched_barrier(0)
; template <class Epi>
; __device__ __forceinline__ void gemm_phase(LAS unsigned char* lds, const Gemm g, const StaticOrder& S, const Epi& E) {
;     ...
;             PG8_LDA(At, 1, 1); PG8_STAGE(PG8_SB(1, 0), b3, voffB); PG8_STAGE(PG8_SB(1, 1), b3 + hstepB, voffB); PG8_STAGE(PG8_SA(1, 0), a3, voffA);
;             PG8_WAIT_V(8); PG8_WAIT_L(0); PG8_BAR; PG8_MMA(1, 0, At, B0); PG8_MMA(1, 1, At, B1); PG8_BAR; PG8_SCHED;
;         }
	s_add_i32 s26, s57, s30
	v_lshl_add_u64 v[192:193], v[192:193], 0, s[10:11]
	s_mov_b32 m0, s26
	ds_read_b128 v[160:163], v232 offset:49152
	ds_read_b128 v[164:167], v232 offset:50176
	ds_read_b128 v[168:171], v232 offset:51200
	ds_read_b128 v[172:175], v232 offset:52224
	ds_read_b128 v[176:179], v232 offset:53248
	ds_read_b128 v[180:183], v232 offset:54272
	ds_read_b128 v[184:187], v232 offset:55296
	ds_read_b128 v[188:191], v232 offset:56320
	global_load_lds_dwordx4 v[192:193], off
	s_add_i32 m0, s26, 0x2000
	s_add_u32 s24, s24, 0x40080
	v_lshl_add_u64 v[192:193], v[194:195], 0, s[10:11]
	s_addc_u32 s25, s25, 0
	s_add_i32 s26, s58, s30
	global_load_lds_dwordx4 v[192:193], off
	s_mov_b32 m0, s26
	s_nop 0
	global_load_lds_dwordx4 v210, s[24:25]
	s_add_i32 m0, s26, 0x2000
	s_nop 0
	global_load_lds_dwordx4 v214, s[24:25]
	v_lshl_add_u64 v[192:193], v[196:197], 0, s[10:11]
	s_mov_b32 m0, s40
	s_nop 0
	global_load_lds_dwordx4 v[192:193], off
	v_lshl_add_u64 v[192:193], v[198:199], 0, s[10:11]
	s_mov_b32 m0, s41
	s_nop 0
	global_load_lds_dwordx4 v[192:193], off
	s_waitcnt vmcnt(8)
	s_waitcnt lgkmcnt(0)
	s_barrier
	s_setprio 1
	s_waitcnt lgkmcnt(0)
	v_mfma_f32_16x16x32_bf16 v[60:63], v[96:99], v[160:163], v[60:63]
	v_mfma_f32_16x16x32_bf16 v[60:63], v[100:103], v[164:167], v[60:63]
	v_mfma_f32_16x16x32_bf16 v[56:59], v[116:119], v[164:167], v[56:59]
	v_mfma_f32_16x16x32_bf16 v[56:59], v[104:107], v[160:163], v[56:59]
	v_mfma_f32_16x16x32_bf16 v[52:55], v[120:123], v[160:163], v[52:55]
	v_mfma_f32_16x16x32_bf16 v[52:55], v[124:127], v[164:167], v[52:55]
	v_mfma_f32_16x16x32_bf16 v[48:51], v[148:151], v[164:167], v[48:51]
	v_mfma_f32_16x16x32_bf16 v[48:51], v[136:139], v[160:163], v[48:51]
	v_mfma_f32_16x16x32_bf16 v[32:35], v[136:139], v[168:171], v[32:35]
	v_mfma_f32_16x16x32_bf16 v[32:35], v[148:151], v[172:175], v[32:35]
	v_mfma_f32_16x16x32_bf16 v[36:39], v[124:127], v[172:175], v[36:39]
	v_mfma_f32_16x16x32_bf16 v[36:39], v[120:123], v[168:171], v[36:39]
	v_mfma_f32_16x16x32_bf16 v[40:43], v[104:107], v[168:171], v[40:43]
	v_mfma_f32_16x16x32_bf16 v[40:43], v[116:119], v[172:175], v[40:43]
	v_mfma_f32_16x16x32_bf16 v[44:47], v[100:103], v[172:175], v[44:47]
	v_mfma_f32_16x16x32_bf16 v[44:47], v[96:99], v[168:171], v[44:47]
	s_setprio 0
	s_setprio 1
	v_mfma_f32_16x16x32_bf16 v[28:31], v[96:99], v[176:179], v[28:31]
	v_mfma_f32_16x16x32_bf16 v[28:31], v[100:103], v[180:183], v[28:31]
	v_mfma_f32_16x16x32_bf16 v[24:27], v[116:119], v[180:183], v[24:27]
	v_mfma_f32_16x16x32_bf16 v[24:27], v[104:107], v[176:179], v[24:27]
	v_mfma_f32_16x16x32_bf16 v[20:23], v[120:123], v[176:179], v[20:23]
	v_mfma_f32_16x16x32_bf16 v[20:23], v[124:127], v[180:183], v[20:23]
	v_mfma_f32_16x16x32_bf16 v[16:19], v[148:151], v[180:183], v[16:19]
	v_mfma_f32_16x16x32_bf16 v[16:19], v[136:139], v[176:179], v[16:19]
	v_mfma_f32_16x16x32_bf16 v[0:3], v[136:139], v[184:187], v[0:3]
	v_mfma_f32_16x16x32_bf16 v[0:3], v[148:151], v[188:191], v[0:3]
	v_mfma_f32_16x16x32_bf16 v[4:7], v[124:127], v[188:191], v[4:7]
	v_mfma_f32_16x16x32_bf16 v[4:7], v[120:123], v[184:187], v[4:7]
	v_mfma_f32_16x16x32_bf16 v[8:11], v[104:107], v[184:187], v[8:11]
	v_mfma_f32_16x16x32_bf16 v[8:11], v[116:119], v[188:191], v[8:11]
	v_mfma_f32_16x16x32_bf16 v[12:15], v[100:103], v[188:191], v[12:15]
	v_mfma_f32_16x16x32_bf16 v[12:15], v[96:99], v[184:187], v[12:15]
	s_setprio 0
	s_barrier
	s_add_u32 s4, s4, 0x100
	s_addc_u32 s5, s5, 0
	s_add_u32 s54, s54, 0x100
	s_addc_u32 s55, s55, 0
	s_cmp_ge_i32 s56, s39
	s_mov_b32 s24, s56
	s_cbranch_scc0 .LBB0_912

; #define PG8_STAGE(bufoff, gbase, voff) do { _Pragma("unroll") for (int _i = 0; _i < 2; ++_i) \
;         __builtin_amdgcn_global_load_lds((const unsigned*)((const char*)(gbase) + (voff)[_i]), (LAS unsigned*)(lds + (bufoff) + ldsw + _i * 8192), 16, 0, 0); } while (0)
; #define PG8_WAIT_V(n) asm volatile("s_waitcnt vmcnt(" #n ")" ::: "memory")
; #define PG8_BAR __builtin_amdgcn_s_barrier()
; template <class Epi>
; __device__ __forceinline__ void gemm_phase(LAS unsigned char* lds, const Gemm g, const StaticOrder& S, const Epi& E) {
;     ...
;     for (int i = 0; i < 2; ++i) { int R, C; stage_rc(tid * 16 + i * 8192, R, C); const int Rb = Epi::PERM ? ((R & ~31) + perm32(R & 31)) : R;
;         voffA[i] = (unsigned)(R * g.lda + C) * 2u; voffB[i] = (unsigned)(Rb * g.ldb + C) * 2u; }
;     const size_t kstep = (size_t)(BK * 2);
;     const size_t hstepA = (size_t)HALF * g.lda * 2, hstepB = (size_t)HALF * g.ldb * 2;
;     const size_t tstepA = 2 * hstepA, tstepB = 2 * hstepB;
;     const unsigned ldsw = (unsigned)wid * 1024u;
;     const int aoff = lds_byte(wr * 64 + fr, fq * 8), boff = lds_byte(wc * 32 + fr, fq * 8);
;     ...
;     Unit cur, nxt; int ui = 0;
;     if (!S.next(0, cur)) return;
;     f32x4 acc[2][2][4][2];
; #pragma unroll
;     for (int a = 0; a < 2; ++a)
; #pragma unroll
;         for (int b = 0; b < 2; ++b)
; #pragma unroll
;             for (int m = 0; m < 4; ++m)
; #pragma unroll
;                 for (int n = 0; n < 2; ++n) acc[a][b][m][n] = (f32x4){0.f, 0.f, 0.f, 0.f};
;     bf16x8 At[4][2], B0[2][2], B1[2][2];
;     const char* cA = (const char*)g.A + (size_t)cur.pm * tstepA; const char* cB = (const char*)g.Bt + (size_t)cur.pb * tstepB;
;     PG8_STAGE(PG8_SB(0, 0), cB, voffB); PG8_STAGE(PG8_SB(0, 1), cB + hstepB, voffB); PG8_STAGE(PG8_SA(0, 0), cA, voffA); PG8_STAGE(PG8_SA(0, 1), cA + hstepA, voffA);
;     if (wr == 1) PG8_BAR;
;     PG8_WAIT_V(2); PG8_BAR;
;     PG8_STAGE(PG8_SB(1, 0), cB + kstep, voffB); PG8_STAGE(PG8_SA(1, 0), cA + kstep, voffA); PG8_STAGE(PG8_SB(1, 1), cB + hstepB + kstep, voffB);
;     PG8_WAIT_V(6); PG8_BAR;
;     for (;;) {
;         const bool has_next = S.next(ui + 1, nxt);
;         const char* nA = has_next ? (const char*)g.A + (size_t)nxt.pm * tstepA : cA; const char* nB = has_next ? (const char*)g.Bt + (size_t)nxt.pb * tstepB : cB;
;         for (int t = 0; t < nt; t += 2) {
;             const bool last = (t == nt - 2);
.LBB0_1035:
	s_ashr_i32 s1, s9, 31
	s_lshr_b32 s1, s1, 26
	s_add_i32 s1, s9, s1
	s_ashr_i32 s59, s1, 6
	s_lshl_b32 s22, s10, 6
	s_lshl_b32 s1, s10, 13
	s_lshl_b32 s10, s11, 5
	s_mov_b64 s[16:17], 0x80
	s_and_b32 s24, s10, 0x60
	s_add_i32 m0, s5, 0x18000
	v_lshl_add_u64 v[6:7], v[6:7], 0, s[16:17]
	s_lshl_b32 s18, s24, 7
	s_waitcnt vmcnt(2)
	s_barrier
	global_load_lds_dwordx4 v[6:7], off
	v_lshl_add_u64 v[2:3], v[2:3], 0, s[16:17]
	s_add_i32 m0, s5, 0x1a000
	s_add_i32 s60, s5, 0x8000
	s_add_i32 s61, s5, 0xa000
	global_load_lds_dwordx4 v[2:3], off
	v_lshl_add_u64 v[0:1], v[0:1], 0, s[16:17]
	s_mov_b32 m0, s60
	s_add_u32 s10, s46, 0x80080
	global_load_lds_dwordx4 v[0:1], off
	v_lshl_add_u64 v[0:1], v[4:5], 0, s[16:17]
	s_mov_b32 m0, s61
	s_addc_u32 s11, s47, 0
	global_load_lds_dwordx4 v[0:1], off
	s_add_i32 m0, s5, 0x1c000
	s_nop 0
	global_load_lds_dwordx4 v162, s[10:11]
	v_lshl_add_u64 v[0:1], s[10:11], 0, v[166:167]
	s_add_i32 m0, s5, 0x1e000
	v_bfe_u32 v3, v8, 4, 2
	global_load_lds_dwordx4 v[0:1], off
	v_and_b32_e32 v0, 15, v8
	v_lshlrev_b32_e32 v1, 4, v3
	v_lshlrev_b32_e32 v168, 2, v0
	v_lshl_or_b32 v1, v0, 6, v1
	v_and_b32_e32 v2, 32, v168
	s_cmp_gt_i32 s9, 63
	v_bitop3_b32 v184, v1, s18, v2 bitop3:0xde
	s_cselect_b64 s[18:19], -1, 0
	s_add_i32 s62, s59, -2
	s_cmpk_lt_u32 s8, 0x100
	s_cselect_b64 s[20:21], -1, 0
	s_ashr_i32 s23, s22, 31
	v_bitop3_b32 v4, v1, s1, v2 bitop3:0xde
	v_or_b32_e32 v0, s22, v0
	v_mov_b32_e32 v1, s23
	v_lshlrev_b64 v[0:1], 12, v[0:1]
	v_lshl_add_u64 v[172:173], s[74:75], 0, v[0:1]
	v_lshlrev_b32_e32 v0, 15, v9
	v_and_b32_e32 v0, 0xffff0000, v0
	v_lshl_add_u32 v0, v10, 12, v0
	v_and_b32_e32 v1, 1, v9
	v_lshl_or_b32 v0, v1, 6, v0
	v_lshl_add_u32 v174, v11, 1, v0
	v_lshlrev_b32_e32 v0, 15, v12
	s_ashr_i32 s63, s94, 31
	s_lshl_b64 s[10:11], s[22:23], 2
	v_and_b32_e32 v0, 0xffff0000, v0
	s_waitcnt vmcnt(6)
	s_add_u32 s10, s50, s10
	v_lshl_add_u32 v0, v13, 12, v0
	v_and_b32_e32 v1, 1, v12
	v_lshl_or_b32 v2, v3, 3, s24
	s_addc_u32 s11, s51, s11
	v_lshl_or_b32 v0, v1, 6, v0
	s_add_i32 s65, 0, 0x10000
	s_add_i32 s66, 0, 0x14000
	v_cmp_eq_u32_e64 s[8:9], 0, v3
	s_mov_b32 s64, s94
	v_lshl_add_u64 v[170:171], s[10:11], 0, v[168:169]
	v_mov_b32_e32 v175, v169
	v_lshl_add_u32 v176, v14, 1, v0
	v_mov_b32_e32 v177, v169
	v_mov_b64_e32 v[178:179], 0x400
	v_mov_b64_e32 v[180:181], 0x3ff
	v_add_u32_e32 v185, s65, v184
	v_add_u32_e32 v186, s66, v184
	v_add_u32_e32 v187, 0, v4
	v_lshlrev_b32_e32 v168, 1, v2
	v_mbcnt_hi_u32_b32 v188, -1, v205
	s_mov_b32 s67, 0x80000
	s_mov_b64 s[22:23], 0x80100
	s_mov_b64 s[24:25], 0x90000
	s_mov_b32 s68, 0x90000
	s_mov_b64 s[26:27], 0x90100
	s_mov_b64 s[28:29], 0xa0000
	s_mov_b32 s69, 0xa0000
	s_mov_b64 s[30:31], 0xa0100
	s_mov_b64 s[34:35], 0xb0000
	s_mov_b32 s70, 0xb0000
	s_mov_b64 s[36:37], 0xb0100
	s_barrier
	s_branch .LBB0_1038

; #define PG8_STAGE(bufoff, gbase, voff) do { _Pragma("unroll") for (int _i = 0; _i < 2; ++_i) \
;         __builtin_amdgcn_global_load_lds((const unsigned*)((const char*)(gbase) + (voff)[_i]), (LAS unsigned*)(lds + (bufoff) + ldsw + _i * 8192), 16, 0, 0); } while (0)
; #define PG8_LDA(dst, b, h) do { _Pragma("unroll") for (int m = 0; m < 4; ++m) _Pragma("unroll") for (int k = 0; k < 2; ++k) dst[m][k] = *(const LAS bf16x8*)(lds + PG8_SA(b, h) + aoff + m * 2048 + k * 1024); } while (0)
; #define PG8_LDB(dst, b, h) do { _Pragma("unroll") for (int n = 0; n < 2; ++n) _Pragma("unroll") for (int k = 0; k < 2; ++k) dst[n][k] = *(const LAS bf16x8*)(lds + PG8_SB(b, h) + boff + n * 2048 + k * 1024); } while (0)
; #define PG8_MMA(ai, bj, At, Bt) do { __builtin_amdgcn_s_setprio(1); _Pragma("unroll") for (int m = 0; m < 4; ++m) _Pragma("unroll") for (int n = 0; n < 2; ++n) _Pragma("unroll") for (int k = 0; k < 2; ++k) \
;         acc[ai][bj][m][n] = __builtin_amdgcn_mfma_f32_16x16x32_bf16(Bt[n][k], At[m][k], acc[ai][bj][m][n], 0, 0, 0); __builtin_amdgcn_s_setprio(0); } while (0)
; #define PG8_WAIT_V(n) asm volatile("s_waitcnt vmcnt(" #n ")" ::: "memory")
; #define PG8_WAIT_L(n) asm volatile("s_waitcnt lgkmcnt(" #n ")" ::: "memory")
; #define PG8_BAR __builtin_amdgcn_s_barrier()
; #define PG8_SCHED __builtin_amdgcn_sched_barrier(0)
; template <class Epi>
; __device__ __forceinline__ void gemm_phase(LAS unsigned char* lds, const Gemm g, const StaticOrder& S, const Epi& E) {
;     ...
;             PG8_LDB(B0, 0, 0); PG8_LDB(B1, 0, 1); PG8_SCHED; PG8_LDA(At, 0, 0); PG8_STAGE(PG8_SA(1, 1), a1 + hstepA, voffA);
;             PG8_WAIT_V(8); PG8_WAIT_L(0); PG8_BAR; PG8_MMA(0, 0, At, B0); PG8_MMA(0, 1, At, B1); PG8_BAR; PG8_SCHED;
;             PG8_LDA(At, 0, 1); PG8_STAGE(PG8_SB(0, 0), b2, voffB); PG8_STAGE(PG8_SB(0, 1), b2 + hstepB, voffB); PG8_STAGE(PG8_SA(0, 0), a2, voffA);
.LBB0_1046:
	ds_read_b128 v[128:131], v185
	ds_read_b128 v[132:135], v185 offset:1024
	ds_read_b128 v[136:139], v185 offset:2048
	ds_read_b128 v[140:143], v185 offset:3072
	ds_read_b128 v[144:147], v186
	ds_read_b128 v[148:151], v186 offset:1024
	ds_read_b128 v[152:155], v186 offset:2048
	ds_read_b128 v[156:159], v186 offset:3072
	s_add_i32 s73, s46, 2
	s_add_u32 s47, s12, 0xfff80080
	s_addc_u32 s48, s13, -1
	s_cmp_eq_u32 s62, s46
	s_cselect_b32 s46, s41, s71
	s_cselect_b32 s49, s1, s48
	s_cselect_b32 s48, s33, s47
	s_cselect_b32 s47, s39, s72
	s_add_i32 m0, s5, 0xc000
	ds_read_b128 v[190:193], v187
	ds_read_b128 v[194:197], v187 offset:1024
	ds_read_b128 v[198:201], v187 offset:2048
	ds_read_b128 v[208:211], v187 offset:3072
	ds_read_b128 v[212:215], v187 offset:4096
	ds_read_b128 v[216:219], v187 offset:5120
	ds_read_b128 v[220:223], v187 offset:6144
	ds_read_b128 v[224:227], v187 offset:7168
	global_load_lds_dwordx4 v174, s[12:13]
	s_add_i32 m0, s5, 0xe000
	s_nop 0
	global_load_lds_dwordx4 v176, s[12:13]
	s_waitcnt vmcnt(8)
	s_waitcnt lgkmcnt(0)
	s_barrier
	s_setprio 1
	s_waitcnt lgkmcnt(0)
	v_mfma_f32_16x16x32_bf16 v[120:123], v[128:131], v[190:193], v[120:123]
	v_mfma_f32_16x16x32_bf16 v[120:123], v[132:135], v[194:197], v[120:123]
	v_mfma_f32_16x16x32_bf16 v[124:127], v[140:143], v[194:197], v[124:127]
	v_mfma_f32_16x16x32_bf16 v[124:127], v[136:139], v[190:193], v[124:127]
	v_mfma_f32_16x16x32_bf16 v[116:119], v[144:147], v[190:193], v[116:119]
	v_mfma_f32_16x16x32_bf16 v[116:119], v[148:151], v[194:197], v[116:119]
	v_mfma_f32_16x16x32_bf16 v[112:115], v[156:159], v[194:197], v[112:115]
	v_mfma_f32_16x16x32_bf16 v[112:115], v[152:155], v[190:193], v[112:115]
	v_mfma_f32_16x16x32_bf16 v[96:99], v[152:155], v[198:201], v[96:99]
	v_mfma_f32_16x16x32_bf16 v[96:99], v[156:159], v[208:211], v[96:99]
	v_mfma_f32_16x16x32_bf16 v[100:103], v[148:151], v[208:211], v[100:103]
	v_mfma_f32_16x16x32_bf16 v[100:103], v[144:147], v[198:201], v[100:103]
	v_mfma_f32_16x16x32_bf16 v[104:107], v[136:139], v[198:201], v[104:107]
	v_mfma_f32_16x16x32_bf16 v[104:107], v[140:143], v[208:211], v[104:107]
	v_mfma_f32_16x16x32_bf16 v[108:111], v[132:135], v[208:211], v[108:111]
	v_mfma_f32_16x16x32_bf16 v[108:111], v[128:131], v[198:201], v[108:111]
	s_setprio 0
	s_setprio 1
	v_mfma_f32_16x16x32_bf16 v[92:95], v[128:131], v[212:215], v[92:95]
	v_mfma_f32_16x16x32_bf16 v[92:95], v[132:135], v[216:219], v[92:95]
	v_mfma_f32_16x16x32_bf16 v[88:91], v[140:143], v[216:219], v[88:91]
	v_mfma_f32_16x16x32_bf16 v[88:91], v[136:139], v[212:215], v[88:91]
	v_mfma_f32_16x16x32_bf16 v[84:87], v[144:147], v[212:215], v[84:87]
	v_mfma_f32_16x16x32_bf16 v[84:87], v[148:151], v[216:219], v[84:87]
	v_mfma_f32_16x16x32_bf16 v[80:83], v[156:159], v[216:219], v[80:83]
	v_mfma_f32_16x16x32_bf16 v[80:83], v[152:155], v[212:215], v[80:83]
	v_mfma_f32_16x16x32_bf16 v[64:67], v[152:155], v[220:223], v[64:67]
	v_mfma_f32_16x16x32_bf16 v[64:67], v[156:159], v[224:227], v[64:67]
	v_mfma_f32_16x16x32_bf16 v[68:71], v[148:151], v[224:227], v[68:71]
	v_mfma_f32_16x16x32_bf16 v[68:71], v[144:147], v[220:223], v[68:71]
	v_mfma_f32_16x16x32_bf16 v[72:75], v[136:139], v[220:223], v[72:75]
	v_mfma_f32_16x16x32_bf16 v[72:75], v[140:143], v[224:227], v[72:75]
	v_mfma_f32_16x16x32_bf16 v[76:79], v[132:135], v[224:227], v[76:79]
	v_mfma_f32_16x16x32_bf16 v[76:79], v[128:131], v[220:223], v[76:79]
	s_setprio 0
	s_barrier
	s_add_i32 s76, s65, s54
	v_lshl_add_u64 v[182:183], s[46:47], 0, v[162:163]
	s_mov_b32 m0, s76
	ds_read_b128 v[190:193], v187 offset:16384
	ds_read_b128 v[194:197], v187 offset:17408
	ds_read_b128 v[198:201], v187 offset:18432
	ds_read_b128 v[208:211], v187 offset:19456
	ds_read_b128 v[212:215], v187 offset:20480
	ds_read_b128 v[216:219], v187 offset:21504
	ds_read_b128 v[220:223], v187 offset:22528
	ds_read_b128 v[224:227], v187 offset:23552
	global_load_lds_dwordx4 v[182:183], off
	s_add_i32 m0, s76, 0x2000
	s_add_u32 s76, s46, 0x80000
	v_lshl_add_u64 v[202:203], s[46:47], 0, v[166:167]
	s_addc_u32 s77, s47, 0
	s_add_i32 s78, s66, s54
	global_load_lds_dwordx4 v[202:203], off
	s_mov_b32 m0, s78
	v_lshl_add_u64 v[232:233], s[48:49], 0, v[164:165]
	global_load_lds_dwordx4 v162, s[76:77]
	s_add_i32 m0, s78, 0x2000
	s_nop 0
	global_load_lds_dwordx4 v166, s[76:77]
	v_lshl_add_u64 v[230:231], s[48:49], 0, v[160:161]
	s_mov_b32 m0, s5
	s_nop 0
	global_load_lds_dwordx4 v[230:231], off
	s_mov_b32 m0, s55
	s_nop 0
	global_load_lds_dwordx4 v[232:233], off
	s_waitcnt vmcnt(8)
	s_waitcnt lgkmcnt(0)
	s_barrier
; #define PG8_STAGE(bufoff, gbase, voff) do { _Pragma("unroll") for (int _i = 0; _i < 2; ++_i) \
;         __builtin_amdgcn_global_load_lds((const unsigned*)((const char*)(gbase) + (voff)[_i]), (LAS unsigned*)(lds + (bufoff) + ldsw + _i * 8192), 16, 0, 0); } while (0)
; #define PG8_LDA(dst, b, h) do { _Pragma("unroll") for (int m = 0; m < 4; ++m) _Pragma("unroll") for (int k = 0; k < 2; ++k) dst[m][k] = *(const LAS bf16x8*)(lds + PG8_SA(b, h) + aoff + m * 2048 + k * 1024); } while (0)
; #define PG8_LDB(dst, b, h) do { _Pragma("unroll") for (int n = 0; n < 2; ++n) _Pragma("unroll") for (int k = 0; k < 2; ++k) dst[n][k] = *(const LAS bf16x8*)(lds + PG8_SB(b, h) + boff + n * 2048 + k * 1024); } while (0)
; #define PG8_MMA(ai, bj, At, Bt) do { __builtin_amdgcn_s_setprio(1); _Pragma("unroll") for (int m = 0; m < 4; ++m) _Pragma("unroll") for (int n = 0; n < 2; ++n) _Pragma("unroll") for (int k = 0; k < 2; ++k) \
;         acc[ai][bj][m][n] = __builtin_amdgcn_mfma_f32_16x16x32_bf16(Bt[n][k], At[m][k], acc[ai][bj][m][n], 0, 0, 0); __builtin_amdgcn_s_setprio(0); } while (0)
; #define PG8_WAIT_V(n) asm volatile("s_waitcnt vmcnt(" #n ")" ::: "memory")
; #define PG8_WAIT_L(n) asm volatile("s_waitcnt lgkmcnt(" #n ")" ::: "memory")
; #define PG8_BAR __builtin_amdgcn_s_barrier()
; #define PG8_SCHED __builtin_amdgcn_sched_barrier(0)
; template <class Epi>
; __device__ __forceinline__ void gemm_phase(LAS unsigned char* lds, const Gemm g, const StaticOrder& S, const Epi& E) {
;     ...
;             PG8_LDA(At, 0, 1); PG8_STAGE(PG8_SB(0, 0), b2, voffB); PG8_STAGE(PG8_SB(0, 1), b2 + hstepB, voffB); PG8_STAGE(PG8_SA(0, 0), a2, voffA);
;             PG8_WAIT_V(8); PG8_WAIT_L(0); PG8_BAR; PG8_MMA(1, 0, At, B0); PG8_MMA(1, 1, At, B1); PG8_BAR; PG8_SCHED;
;             PG8_LDB(B0, 1, 0); PG8_LDB(B1, 1, 1); PG8_SCHED; PG8_LDA(At, 1, 0); PG8_STAGE(PG8_SA(0, 1), a2 + hstepA, voffA);
;             PG8_WAIT_V(8); PG8_WAIT_L(0); PG8_BAR; PG8_MMA(0, 0, At, B0); PG8_MMA(0, 1, At, B1); PG8_BAR; PG8_SCHED;
	s_setprio 1
	s_waitcnt lgkmcnt(0)
	v_mfma_f32_16x16x32_bf16 v[60:63], v[128:131], v[190:193], v[60:63]
	v_mfma_f32_16x16x32_bf16 v[60:63], v[132:135], v[194:197], v[60:63]
	v_mfma_f32_16x16x32_bf16 v[56:59], v[140:143], v[194:197], v[56:59]
	v_mfma_f32_16x16x32_bf16 v[56:59], v[136:139], v[190:193], v[56:59]
	v_mfma_f32_16x16x32_bf16 v[52:55], v[144:147], v[190:193], v[52:55]
	v_mfma_f32_16x16x32_bf16 v[52:55], v[148:151], v[194:197], v[52:55]
	v_mfma_f32_16x16x32_bf16 v[48:51], v[156:159], v[194:197], v[48:51]
	v_mfma_f32_16x16x32_bf16 v[48:51], v[152:155], v[190:193], v[48:51]
	v_mfma_f32_16x16x32_bf16 v[32:35], v[152:155], v[198:201], v[32:35]
	v_mfma_f32_16x16x32_bf16 v[32:35], v[156:159], v[208:211], v[32:35]
	v_mfma_f32_16x16x32_bf16 v[36:39], v[148:151], v[208:211], v[36:39]
	v_mfma_f32_16x16x32_bf16 v[36:39], v[144:147], v[198:201], v[36:39]
	v_mfma_f32_16x16x32_bf16 v[40:43], v[136:139], v[198:201], v[40:43]
	v_mfma_f32_16x16x32_bf16 v[40:43], v[140:143], v[208:211], v[40:43]
	v_mfma_f32_16x16x32_bf16 v[44:47], v[132:135], v[208:211], v[44:47]
	v_mfma_f32_16x16x32_bf16 v[44:47], v[128:131], v[198:201], v[44:47]
	s_setprio 0
	s_setprio 1
	v_mfma_f32_16x16x32_bf16 v[28:31], v[128:131], v[212:215], v[28:31]
	v_mfma_f32_16x16x32_bf16 v[28:31], v[132:135], v[216:219], v[28:31]
	v_mfma_f32_16x16x32_bf16 v[24:27], v[140:143], v[216:219], v[24:27]
	v_mfma_f32_16x16x32_bf16 v[24:27], v[136:139], v[212:215], v[24:27]
	v_mfma_f32_16x16x32_bf16 v[20:23], v[144:147], v[212:215], v[20:23]
	v_mfma_f32_16x16x32_bf16 v[20:23], v[148:151], v[216:219], v[20:23]
	v_mfma_f32_16x16x32_bf16 v[16:19], v[156:159], v[216:219], v[16:19]
	v_mfma_f32_16x16x32_bf16 v[16:19], v[152:155], v[212:215], v[16:19]
	v_mfma_f32_16x16x32_bf16 v[0:3], v[152:155], v[220:223], v[0:3]
	v_mfma_f32_16x16x32_bf16 v[0:3], v[156:159], v[224:227], v[0:3]
	v_mfma_f32_16x16x32_bf16 v[4:7], v[148:151], v[224:227], v[4:7]
	v_mfma_f32_16x16x32_bf16 v[4:7], v[144:147], v[220:223], v[4:7]
	v_mfma_f32_16x16x32_bf16 v[8:11], v[136:139], v[220:223], v[8:11]
	v_mfma_f32_16x16x32_bf16 v[8:11], v[140:143], v[224:227], v[8:11]
	v_mfma_f32_16x16x32_bf16 v[12:15], v[132:135], v[224:227], v[12:15]
	v_mfma_f32_16x16x32_bf16 v[12:15], v[128:131], v[220:223], v[12:15]
	s_setprio 0
	s_barrier
	s_add_i32 s76, 0, 0x18000
	s_add_i32 s77, 0, 0x1c000
	v_add_u32_e32 v140, s76, v184
	v_add_u32_e32 v156, s77, v184
	ds_read_b128 v[128:131], v140
	ds_read_b128 v[132:135], v140 offset:1024
	ds_read_b128 v[136:139], v140 offset:2048
	ds_read_b128 v[140:143], v140 offset:3072
	ds_read_b128 v[144:147], v156
	ds_read_b128 v[148:151], v156 offset:1024
	ds_read_b128 v[152:155], v156 offset:2048
	ds_read_b128 v[156:159], v156 offset:3072
	s_add_u32 s48, s48, 0x80000
	s_addc_u32 s49, s49, 0
	s_mov_b32 m0, s56
	ds_read_b128 v[190:193], v187 offset:32768
	ds_read_b128 v[194:197], v187 offset:33792
	ds_read_b128 v[198:201], v187 offset:34816
	ds_read_b128 v[208:211], v187 offset:35840
	ds_read_b128 v[212:215], v187 offset:36864
	ds_read_b128 v[216:219], v187 offset:37888
	ds_read_b128 v[220:223], v187 offset:38912
	ds_read_b128 v[224:227], v187 offset:39936
	global_load_lds_dwordx4 v160, s[48:49]
	s_mov_b32 m0, s57
	s_nop 0
	global_load_lds_dwordx4 v164, s[48:49]
	s_waitcnt vmcnt(8)
	s_waitcnt lgkmcnt(0)
	s_barrier
	s_setprio 1
	s_waitcnt lgkmcnt(0)
	v_mfma_f32_16x16x32_bf16 v[120:123], v[128:131], v[190:193], v[120:123]
	v_mfma_f32_16x16x32_bf16 v[120:123], v[132:135], v[194:197], v[120:123]
	v_mfma_f32_16x16x32_bf16 v[124:127], v[140:143], v[194:197], v[124:127]
	v_mfma_f32_16x16x32_bf16 v[124:127], v[136:139], v[190:193], v[124:127]
	v_mfma_f32_16x16x32_bf16 v[116:119], v[144:147], v[190:193], v[116:119]
	v_mfma_f32_16x16x32_bf16 v[116:119], v[148:151], v[194:197], v[116:119]
	v_mfma_f32_16x16x32_bf16 v[112:115], v[156:159], v[194:197], v[112:115]
	v_mfma_f32_16x16x32_bf16 v[112:115], v[152:155], v[190:193], v[112:115]
	v_mfma_f32_16x16x32_bf16 v[96:99], v[152:155], v[198:201], v[96:99]
	v_mfma_f32_16x16x32_bf16 v[96:99], v[156:159], v[208:211], v[96:99]
	v_mfma_f32_16x16x32_bf16 v[100:103], v[148:151], v[208:211], v[100:103]
	v_mfma_f32_16x16x32_bf16 v[100:103], v[144:147], v[198:201], v[100:103]
	v_mfma_f32_16x16x32_bf16 v[104:107], v[136:139], v[198:201], v[104:107]
	v_mfma_f32_16x16x32_bf16 v[104:107], v[140:143], v[208:211], v[104:107]
	v_mfma_f32_16x16x32_bf16 v[108:111], v[132:135], v[208:211], v[108:111]
	v_mfma_f32_16x16x32_bf16 v[108:111], v[128:131], v[198:201], v[108:111]
	s_setprio 0
	s_setprio 1
	v_mfma_f32_16x16x32_bf16 v[92:95], v[128:131], v[212:215], v[92:95]
	v_mfma_f32_16x16x32_bf16 v[92:95], v[132:135], v[216:219], v[92:95]
	v_mfma_f32_16x16x32_bf16 v[88:91], v[140:143], v[216:219], v[88:91]
	v_mfma_f32_16x16x32_bf16 v[88:91], v[136:139], v[212:215], v[88:91]
	v_mfma_f32_16x16x32_bf16 v[84:87], v[144:147], v[212:215], v[84:87]
	v_mfma_f32_16x16x32_bf16 v[84:87], v[148:151], v[216:219], v[84:87]
	v_mfma_f32_16x16x32_bf16 v[80:83], v[156:159], v[216:219], v[80:83]
	v_mfma_f32_16x16x32_bf16 v[80:83], v[152:155], v[212:215], v[80:83]
	v_mfma_f32_16x16x32_bf16 v[64:67], v[152:155], v[220:223], v[64:67]
	v_mfma_f32_16x16x32_bf16 v[64:67], v[156:159], v[224:227], v[64:67]
	v_mfma_f32_16x16x32_bf16 v[68:71], v[148:151], v[224:227], v[68:71]
	v_mfma_f32_16x16x32_bf16 v[68:71], v[144:147], v[220:223], v[68:71]
	v_mfma_f32_16x16x32_bf16 v[72:75], v[136:139], v[220:223], v[72:75]
	v_mfma_f32_16x16x32_bf16 v[72:75], v[140:143], v[224:227], v[72:75]
	v_mfma_f32_16x16x32_bf16 v[76:79], v[132:135], v[224:227], v[76:79]
	v_mfma_f32_16x16x32_bf16 v[76:79], v[128:131], v[220:223], v[76:79]
	s_setprio 0
	s_barrier
; #define PG8_STAGE(bufoff, gbase, voff) do { _Pragma("unroll") for (int _i = 0; _i < 2; ++_i) \
;         __builtin_amdgcn_global_load_lds((const unsigned*)((const char*)(gbase) + (voff)[_i]), (LAS unsigned*)(lds + (bufoff) + ldsw + _i * 8192), 16, 0, 0); } while (0)
; #define PG8_LDA(dst, b, h) do { _Pragma("unroll") for (int m = 0; m < 4; ++m) _Pragma("unroll") for (int k = 0; k < 2; ++k) dst[m][k] = *(const LAS bf16x8*)(lds + PG8_SA(b, h) + aoff + m * 2048 + k * 1024); } while (0)
; #define PG8_MMA(ai, bj, At, Bt) do { __builtin_amdgcn_s_setprio(1); _Pragma("unroll") for (int m = 0; m < 4; ++m) _Pragma("unroll") for (int n = 0; n < 2; ++n) _Pragma("unroll") for (int k = 0; k < 2; ++k) \
;         acc[ai][bj][m][n] = __builtin_amdgcn_mfma_f32_16x16x32_bf16(Bt[n][k], At[m][k], acc[ai][bj][m][n], 0, 0, 0); __builtin_amdgcn_s_setprio(0); } while (0)
; #define PG8_WAIT_V(n) asm volatile("s_waitcnt vmcnt(" #n ")" ::: "memory")
; #define PG8_WAIT_L(n) asm volatile("s_waitcnt lgkmcnt(" #n ")" ::: "memory")
; #define PG8_BAR __builtin_amdgcn_s_barrier()
; #define PG8_SCHED __builtin_amdgcn_sched_barrier(0)
; template <class Epi>
; __device__ __forceinline__ void gemm_phase(LAS unsigned char* lds, const Gemm g, const StaticOrder& S, const Epi& E) {
;     ...
;         for (int t = 0; t < nt; t += 2) {
;             const bool last = (t == nt - 2);
;             const char* a1 = cA + (size_t)(t + 1) * kstep;
;             const char* a2 = last ? nA : cA + (size_t)(t + 2) * kstep; const char* b2 = last ? nB : cB + (size_t)(t + 2) * kstep;
;             const char* a3 = a2 + kstep; const char* b3 = b2 + kstep;
;     ...
;             PG8_LDA(At, 1, 1); PG8_STAGE(PG8_SB(1, 0), b3, voffB); PG8_STAGE(PG8_SB(1, 1), b3 + hstepB, voffB); PG8_STAGE(PG8_SA(1, 0), a3, voffA);
;             PG8_WAIT_V(8); PG8_WAIT_L(0); PG8_BAR; PG8_MMA(1, 0, At, B0); PG8_MMA(1, 1, At, B1); PG8_BAR; PG8_SCHED;
;         }
	s_add_i32 s48, s76, s54
	v_lshl_add_u64 v[182:183], v[182:183], 0, s[16:17]
	s_mov_b32 m0, s48
	ds_read_b128 v[190:193], v187 offset:49152
	ds_read_b128 v[194:197], v187 offset:50176
	ds_read_b128 v[198:201], v187 offset:51200
	ds_read_b128 v[208:211], v187 offset:52224
	ds_read_b128 v[212:215], v187 offset:53248
	ds_read_b128 v[216:219], v187 offset:54272
	ds_read_b128 v[220:223], v187 offset:55296
	ds_read_b128 v[224:227], v187 offset:56320
	global_load_lds_dwordx4 v[182:183], off
	s_add_i32 m0, s48, 0x2000
	s_add_u32 s46, s46, 0x80080
	v_lshl_add_u64 v[182:183], v[202:203], 0, s[16:17]
	s_addc_u32 s47, s47, 0
	s_add_i32 s48, s77, s54
	global_load_lds_dwordx4 v[182:183], off
	s_mov_b32 m0, s48
	s_nop 0
	global_load_lds_dwordx4 v162, s[46:47]
	s_add_i32 m0, s48, 0x2000
	s_nop 0
	global_load_lds_dwordx4 v166, s[46:47]
	v_lshl_add_u64 v[182:183], v[230:231], 0, s[16:17]
	s_mov_b32 m0, s60
	s_nop 0
	global_load_lds_dwordx4 v[182:183], off
	v_lshl_add_u64 v[182:183], v[232:233], 0, s[16:17]
	s_mov_b32 m0, s61
	s_nop 0
	global_load_lds_dwordx4 v[182:183], off
	s_waitcnt vmcnt(8)
	s_waitcnt lgkmcnt(0)
	s_barrier
	s_setprio 1
	s_waitcnt lgkmcnt(0)
	v_mfma_f32_16x16x32_bf16 v[60:63], v[128:131], v[190:193], v[60:63]
	v_mfma_f32_16x16x32_bf16 v[60:63], v[132:135], v[194:197], v[60:63]
	v_mfma_f32_16x16x32_bf16 v[56:59], v[140:143], v[194:197], v[56:59]
	v_mfma_f32_16x16x32_bf16 v[56:59], v[136:139], v[190:193], v[56:59]
	v_mfma_f32_16x16x32_bf16 v[52:55], v[144:147], v[190:193], v[52:55]
	v_mfma_f32_16x16x32_bf16 v[52:55], v[148:151], v[194:197], v[52:55]
	v_mfma_f32_16x16x32_bf16 v[48:51], v[156:159], v[194:197], v[48:51]
	v_mfma_f32_16x16x32_bf16 v[48:51], v[152:155], v[190:193], v[48:51]
	v_mfma_f32_16x16x32_bf16 v[32:35], v[152:155], v[198:201], v[32:35]
	v_mfma_f32_16x16x32_bf16 v[32:35], v[156:159], v[208:211], v[32:35]
	v_mfma_f32_16x16x32_bf16 v[36:39], v[148:151], v[208:211], v[36:39]
	v_mfma_f32_16x16x32_bf16 v[36:39], v[144:147], v[198:201], v[36:39]
	v_mfma_f32_16x16x32_bf16 v[40:43], v[136:139], v[198:201], v[40:43]
	v_mfma_f32_16x16x32_bf16 v[40:43], v[140:143], v[208:211], v[40:43]
	v_mfma_f32_16x16x32_bf16 v[44:47], v[132:135], v[208:211], v[44:47]
	v_mfma_f32_16x16x32_bf16 v[44:47], v[128:131], v[198:201], v[44:47]
	s_setprio 0
	s_setprio 1
	v_mfma_f32_16x16x32_bf16 v[28:31], v[128:131], v[212:215], v[28:31]
	v_mfma_f32_16x16x32_bf16 v[28:31], v[132:135], v[216:219], v[28:31]
	v_mfma_f32_16x16x32_bf16 v[24:27], v[140:143], v[216:219], v[24:27]
	v_mfma_f32_16x16x32_bf16 v[24:27], v[136:139], v[212:215], v[24:27]
	v_mfma_f32_16x16x32_bf16 v[20:23], v[144:147], v[212:215], v[20:23]
	v_mfma_f32_16x16x32_bf16 v[20:23], v[148:151], v[216:219], v[20:23]
	v_mfma_f32_16x16x32_bf16 v[16:19], v[156:159], v[216:219], v[16:19]
	v_mfma_f32_16x16x32_bf16 v[16:19], v[152:155], v[212:215], v[16:19]
	v_mfma_f32_16x16x32_bf16 v[0:3], v[152:155], v[220:223], v[0:3]
	v_mfma_f32_16x16x32_bf16 v[0:3], v[156:159], v[224:227], v[0:3]
	v_mfma_f32_16x16x32_bf16 v[4:7], v[148:151], v[224:227], v[4:7]
	v_mfma_f32_16x16x32_bf16 v[4:7], v[144:147], v[220:223], v[4:7]
	v_mfma_f32_16x16x32_bf16 v[8:11], v[136:139], v[220:223], v[8:11]
	v_mfma_f32_16x16x32_bf16 v[8:11], v[140:143], v[224:227], v[8:11]
	v_mfma_f32_16x16x32_bf16 v[12:15], v[132:135], v[224:227], v[12:15]
	v_mfma_f32_16x16x32_bf16 v[12:15], v[128:131], v[220:223], v[12:15]
	s_setprio 0
	s_barrier
	s_add_u32 s12, s12, 0x100
	s_addc_u32 s13, s13, 0
	s_add_u32 s71, s71, 0x100
	s_addc_u32 s72, s72, 0
	s_cmp_ge_i32 s73, s59
	s_mov_b32 s46, s73
	s_cbranch_scc0 .LBB0_1046

; #define PG8_STAGE(bufoff, gbase, voff) do { _Pragma("unroll") for (int _i = 0; _i < 2; ++_i) \
;         __builtin_amdgcn_global_load_lds((const unsigned*)((const char*)(gbase) + (voff)[_i]), (LAS unsigned*)(lds + (bufoff) + ldsw + _i * 8192), 16, 0, 0); } while (0)
; #define PG8_WAIT_V(n) asm volatile("s_waitcnt vmcnt(" #n ")" ::: "memory")
; #define PG8_BAR __builtin_amdgcn_s_barrier()
; template <class Epi>
; __device__ __forceinline__ void gemm_phase(LAS unsigned char* lds, const Gemm g, const StaticOrder& S, const Epi& E) {
;     ...
;     for (int i = 0; i < 2; ++i) { int R, C; stage_rc(tid * 16 + i * 8192, R, C); const int Rb = Epi::PERM ? ((R & ~31) + perm32(R & 31)) : R;
;         voffA[i] = (unsigned)(R * g.lda + C) * 2u; voffB[i] = (unsigned)(Rb * g.ldb + C) * 2u; }
;     const size_t kstep = (size_t)(BK * 2);
;     const size_t hstepA = (size_t)HALF * g.lda * 2, hstepB = (size_t)HALF * g.ldb * 2;
;     const size_t tstepA = 2 * hstepA, tstepB = 2 * hstepB;
;     const unsigned ldsw = (unsigned)wid * 1024u;
;     const int aoff = lds_byte(wr * 64 + fr, fq * 8), boff = lds_byte(wc * 32 + fr, fq * 8);
;     ...
;     Unit cur, nxt; int ui = 0;
;     if (!S.next(0, cur)) return;
;     f32x4 acc[2][2][4][2];
; #pragma unroll
;     for (int a = 0; a < 2; ++a)
; #pragma unroll
;         for (int b = 0; b < 2; ++b)
; #pragma unroll
;             for (int m = 0; m < 4; ++m)
; #pragma unroll
;                 for (int n = 0; n < 2; ++n) acc[a][b][m][n] = (f32x4){0.f, 0.f, 0.f, 0.f};
;     bf16x8 At[4][2], B0[2][2], B1[2][2];
;     const char* cA = (const char*)g.A + (size_t)cur.pm * tstepA; const char* cB = (const char*)g.Bt + (size_t)cur.pb * tstepB;
;     PG8_STAGE(PG8_SB(0, 0), cB, voffB); PG8_STAGE(PG8_SB(0, 1), cB + hstepB, voffB); PG8_STAGE(PG8_SA(0, 0), cA, voffA); PG8_STAGE(PG8_SA(0, 1), cA + hstepA, voffA);
;     if (wr == 1) PG8_BAR;
;     PG8_WAIT_V(2); PG8_BAR;
;     PG8_STAGE(PG8_SB(1, 0), cB + kstep, voffB); PG8_STAGE(PG8_SA(1, 0), cA + kstep, voffA); PG8_STAGE(PG8_SB(1, 1), cB + hstepB + kstep, voffB);
;     PG8_WAIT_V(6); PG8_BAR;
;     for (;;) {
;         const bool has_next = S.next(ui + 1, nxt);
;         const char* nA = has_next ? (const char*)g.A + (size_t)nxt.pm * tstepA : cA; const char* nB = has_next ? (const char*)g.Bt + (size_t)nxt.pb * tstepB : cB;
.LBB0_1124:
	s_ashr_i32 s15, s14, 31
	s_lshr_b32 s15, s15, 26
	s_add_i32 s15, s14, s15
	s_lshl_b32 s4, s4, 5
	s_ashr_i32 s55, s15, 6
	s_lshl_b32 s16, s5, 6
	s_lshl_b32 s15, s5, 13
	s_and_b32 s20, s4, 0x60
	s_mov_b64 s[4:5], 0x80
	s_add_i32 m0, s33, 0x18000
	v_lshl_add_u64 v[6:7], v[6:7], 0, s[4:5]
	s_lshl_b32 s17, s20, 7
	s_waitcnt vmcnt(2)
	s_barrier
	global_load_lds_dwordx4 v[6:7], off
	v_lshl_add_u64 v[4:5], v[4:5], 0, s[4:5]
	s_add_i32 m0, s33, 0x1a000
	s_add_i32 s56, s33, 0x8000
	s_add_i32 s57, s33, 0xa000
	global_load_lds_dwordx4 v[4:5], off
	v_lshl_add_u64 v[0:1], v[0:1], 0, s[4:5]
	s_mov_b32 m0, s56
	s_add_u32 s18, s12, 0x80080
	global_load_lds_dwordx4 v[0:1], off
	v_lshl_add_u64 v[0:1], v[2:3], 0, s[4:5]
	s_mov_b32 m0, s57
	s_addc_u32 s19, s13, 0
	global_load_lds_dwordx4 v[0:1], off
	s_add_i32 m0, s33, 0x1c000
	s_nop 0
	global_load_lds_dwordx4 v132, s[18:19]
	v_lshl_add_u64 v[0:1], s[18:19], 0, v[128:129]
	s_add_i32 m0, s33, 0x1e000
	v_and_b32_e32 v2, 15, v10
	global_load_lds_dwordx4 v[0:1], off
	v_lshrrev_b32_e32 v0, 1, v10
	v_and_b32_e32 v3, 24, v0
	v_lshlrev_b32_e32 v0, 1, v3
	s_cmp_gt_i32 s14, 63
	v_lshl_or_b32 v1, v2, 6, v0
	v_lshlrev_b32_e32 v0, 2, v2
	s_cselect_b64 s[26:27], -1, 0
	s_add_i32 s58, s55, -2
	v_and_b32_e32 v4, 32, v0
	s_cmpk_lt_u32 s9, 0x100
	v_bitop3_b32 v180, v1, s17, v4 bitop3:0xde
	s_cselect_b64 s[28:29], -1, 0
	s_ashr_i32 s17, s16, 31
	s_sext_i32_i16 s72, s8
	s_ashr_i32 s59, s94, 31
	s_lshl_b64 s[8:9], s[16:17], 2
	s_add_u32 s8, s50, s8
	v_bitop3_b32 v5, v1, s15, v4 bitop3:0xde
	s_addc_u32 s9, s51, s9
	v_mov_b32_e32 v1, v133
	v_lshl_add_u64 v[136:137], s[8:9], 0, v[0:1]
	v_lshlrev_b32_e32 v0, 15, v13
	v_and_b32_e32 v0, 0xffff0000, v0
	v_lshl_add_u32 v0, v12, 12, v0
	v_and_b32_e32 v1, 1, v13
	v_lshl_or_b32 v0, v1, 6, v0
	v_lshl_add_u32 v140, v14, 1, v0
	v_lshlrev_b32_e32 v0, 15, v8
	v_and_b32_e32 v0, 0xffff0000, v0
	s_waitcnt vmcnt(6)
	v_lshl_add_u32 v0, v9, 12, v0
	v_and_b32_e32 v1, 1, v8
	v_lshl_or_b32 v0, v1, 6, v0
	v_mov_b32_e32 v148, v133
	v_mov_b32_e32 v149, v133
	s_add_i32 s62, 0, 0x10000
	s_add_i32 s63, 0, 0x14000
	s_mov_b32 s60, s94
	v_or_b32_e32 v138, s16, v2
	v_mov_b32_e32 v139, s17
	v_or_b32_e32 v181, s20, v3
	v_mov_b32_e32 v141, v133
	v_lshl_add_u32 v142, v11, 1, v0
	v_mov_b32_e32 v143, v133
	s_mov_b32 s61, 0
	s_mov_b32 s48, -1
	v_mov_b64_e32 v[144:145], 0x1580
	v_mov_b64_e32 v[146:147], 0x157f
	v_add_u32_e32 v182, s62, v180
	v_add_u32_e32 v183, s63, v180
	v_add_u32_e32 v184, 0, v5
	s_mov_b32 s30, 0x3a000000
	s_mov_b32 s34, 0x358637bd
	s_mov_b32 s64, 0x800000
	s_mov_b32 s36, 0x45800000
	s_mov_b32 s38, 0xbfb8aa3b
	s_movk_i32 s65, 0x2b00
	s_mov_b32 s66, 0x2b000
	s_mov_b32 s67, 0x56000
	s_mov_b32 s68, 0x81000
	s_mov_b32 s69, 0x158000
	s_mov_b32 s70, 0x183000
	s_mov_b32 s71, 0x1ae000
	v_mov_b64_e32 v[150:151], v[148:149]
	v_mov_b64_e32 v[152:153], v[148:149]
	v_mov_b64_e32 v[154:155], v[148:149]
	v_mov_b64_e32 v[156:157], v[148:149]
	v_mov_b64_e32 v[158:159], v[148:149]
	v_mov_b64_e32 v[160:161], v[148:149]
	v_mov_b64_e32 v[162:163], v[148:149]
	s_barrier
	s_branch .LBB0_1127

; #define PG8_STAGE(bufoff, gbase, voff) do { _Pragma("unroll") for (int _i = 0; _i < 2; ++_i) \
;         __builtin_amdgcn_global_load_lds((const unsigned*)((const char*)(gbase) + (voff)[_i]), (LAS unsigned*)(lds + (bufoff) + ldsw + _i * 8192), 16, 0, 0); } while (0)
; #define PG8_LDA(dst, b, h) do { _Pragma("unroll") for (int m = 0; m < 4; ++m) _Pragma("unroll") for (int k = 0; k < 2; ++k) dst[m][k] = *(const LAS bf16x8*)(lds + PG8_SA(b, h) + aoff + m * 2048 + k * 1024); } while (0)
; #define PG8_LDB(dst, b, h) do { _Pragma("unroll") for (int n = 0; n < 2; ++n) _Pragma("unroll") for (int k = 0; k < 2; ++k) dst[n][k] = *(const LAS bf16x8*)(lds + PG8_SB(b, h) + boff + n * 2048 + k * 1024); } while (0)
; #define PG8_MMA(ai, bj, At, Bt) do { __builtin_amdgcn_s_setprio(1); _Pragma("unroll") for (int m = 0; m < 4; ++m) _Pragma("unroll") for (int n = 0; n < 2; ++n) _Pragma("unroll") for (int k = 0; k < 2; ++k) \
;         acc[ai][bj][m][n] = __builtin_amdgcn_mfma_f32_16x16x32_bf16(Bt[n][k], At[m][k], acc[ai][bj][m][n], 0, 0, 0); __builtin_amdgcn_s_setprio(0); } while (0)
; #define PG8_WAIT_V(n) asm volatile("s_waitcnt vmcnt(" #n ")" ::: "memory")
; #define PG8_WAIT_L(n) asm volatile("s_waitcnt lgkmcnt(" #n ")" ::: "memory")
; #define PG8_BAR __builtin_amdgcn_s_barrier()
; #define PG8_SCHED __builtin_amdgcn_sched_barrier(0)
; template <class Epi>
; __device__ __forceinline__ void gemm_phase(LAS unsigned char* lds, const Gemm g, const StaticOrder& S, const Epi& E) {
;     ...
;             const bool last = (t == nt - 2);
;             const char* a1 = cA + (size_t)(t + 1) * kstep;
;             const char* a2 = last ? nA : cA + (size_t)(t + 2) * kstep; const char* b2 = last ? nB : cB + (size_t)(t + 2) * kstep;
;             const char* a3 = a2 + kstep; const char* b3 = b2 + kstep;
;             PG8_LDB(B0, 0, 0); PG8_LDB(B1, 0, 1); PG8_SCHED; PG8_LDA(At, 0, 0); PG8_STAGE(PG8_SA(1, 1), a1 + hstepA, voffA);
;             PG8_WAIT_V(8); PG8_WAIT_L(0); PG8_BAR; PG8_MMA(0, 0, At, B0); PG8_MMA(0, 1, At, B1); PG8_BAR; PG8_SCHED;
;             PG8_LDA(At, 0, 1); PG8_STAGE(PG8_SB(0, 0), b2, voffB); PG8_STAGE(PG8_SB(0, 1), b2 + hstepB, voffB); PG8_STAGE(PG8_SA(0, 0), a2, voffA);
.LBB0_1131:
	ds_read_b128 v[164:167], v182
	ds_read_b128 v[168:171], v182 offset:1024
	ds_read_b128 v[172:175], v182 offset:2048
	ds_read_b128 v[176:179], v182 offset:3072
	ds_read_b128 v[186:189], v183
	ds_read_b128 v[190:193], v183 offset:1024
	ds_read_b128 v[194:197], v183 offset:2048
	ds_read_b128 v[198:201], v183 offset:3072
	s_add_i32 s22, s12, 2
	s_add_u32 s13, s10, 0xfff80080
	s_addc_u32 s14, s11, -1
	s_cmp_eq_u32 s58, s12
	s_cselect_b32 s12, s19, s20
	s_cselect_b32 s15, s16, s14
	s_cselect_b32 s14, s17, s13
	s_cselect_b32 s13, s18, s21
	s_add_i32 m0, s33, 0xc000
	ds_read_b128 v[208:211], v184
	ds_read_b128 v[212:215], v184 offset:1024
	ds_read_b128 v[216:219], v184 offset:2048
	ds_read_b128 v[220:223], v184 offset:3072
	ds_read_b128 v[224:227], v184 offset:4096
	ds_read_b128 v[230:233], v184 offset:5120
	ds_read_b128 v[234:237], v184 offset:6144
	ds_read_b128 v[238:241], v184 offset:7168
	global_load_lds_dwordx4 v140, s[10:11]
	s_add_i32 m0, s33, 0xe000
	s_nop 0
	global_load_lds_dwordx4 v142, s[10:11]
	s_waitcnt vmcnt(8)
	s_waitcnt lgkmcnt(0)
	s_barrier
	s_setprio 1
	s_waitcnt lgkmcnt(0)
	v_mfma_f32_16x16x32_bf16 v[120:123], v[164:167], v[208:211], v[120:123]
	v_mfma_f32_16x16x32_bf16 v[120:123], v[168:171], v[212:215], v[120:123]
	v_mfma_f32_16x16x32_bf16 v[116:119], v[176:179], v[212:215], v[116:119]
	v_mfma_f32_16x16x32_bf16 v[116:119], v[172:175], v[208:211], v[116:119]
	v_mfma_f32_16x16x32_bf16 v[124:127], v[186:189], v[208:211], v[124:127]
	v_mfma_f32_16x16x32_bf16 v[124:127], v[190:193], v[212:215], v[124:127]
	v_mfma_f32_16x16x32_bf16 v[112:115], v[198:201], v[212:215], v[112:115]
	v_mfma_f32_16x16x32_bf16 v[112:115], v[194:197], v[208:211], v[112:115]
	v_mfma_f32_16x16x32_bf16 v[96:99], v[194:197], v[216:219], v[96:99]
	v_mfma_f32_16x16x32_bf16 v[96:99], v[198:201], v[220:223], v[96:99]
	v_mfma_f32_16x16x32_bf16 v[104:107], v[190:193], v[220:223], v[104:107]
	v_mfma_f32_16x16x32_bf16 v[104:107], v[186:189], v[216:219], v[104:107]
	v_mfma_f32_16x16x32_bf16 v[100:103], v[172:175], v[216:219], v[100:103]
	v_mfma_f32_16x16x32_bf16 v[100:103], v[176:179], v[220:223], v[100:103]
	v_mfma_f32_16x16x32_bf16 v[108:111], v[168:171], v[220:223], v[108:111]
	v_mfma_f32_16x16x32_bf16 v[108:111], v[164:167], v[216:219], v[108:111]
	s_setprio 0
	s_setprio 1
	v_mfma_f32_16x16x32_bf16 v[92:95], v[164:167], v[224:227], v[92:95]
	v_mfma_f32_16x16x32_bf16 v[92:95], v[168:171], v[230:233], v[92:95]
	v_mfma_f32_16x16x32_bf16 v[84:87], v[176:179], v[230:233], v[84:87]
	v_mfma_f32_16x16x32_bf16 v[84:87], v[172:175], v[224:227], v[84:87]
	v_mfma_f32_16x16x32_bf16 v[88:91], v[186:189], v[224:227], v[88:91]
	v_mfma_f32_16x16x32_bf16 v[88:91], v[190:193], v[230:233], v[88:91]
	v_mfma_f32_16x16x32_bf16 v[80:83], v[198:201], v[230:233], v[80:83]
	v_mfma_f32_16x16x32_bf16 v[80:83], v[194:197], v[224:227], v[80:83]
	v_mfma_f32_16x16x32_bf16 v[64:67], v[194:197], v[234:237], v[64:67]
	v_mfma_f32_16x16x32_bf16 v[64:67], v[198:201], v[238:241], v[64:67]
	v_mfma_f32_16x16x32_bf16 v[72:75], v[190:193], v[238:241], v[72:75]
	v_mfma_f32_16x16x32_bf16 v[72:75], v[186:189], v[234:237], v[72:75]
	v_mfma_f32_16x16x32_bf16 v[68:71], v[172:175], v[234:237], v[68:71]
	v_mfma_f32_16x16x32_bf16 v[68:71], v[176:179], v[238:241], v[68:71]
	v_mfma_f32_16x16x32_bf16 v[76:79], v[168:171], v[238:241], v[76:79]
	v_mfma_f32_16x16x32_bf16 v[76:79], v[164:167], v[234:237], v[76:79]
	s_setprio 0
	s_barrier
	s_add_i32 s23, s62, s37
	v_lshl_add_u64 v[202:203], s[12:13], 0, v[132:133]
	s_mov_b32 m0, s23
	ds_read_b128 v[208:211], v184 offset:16384
	ds_read_b128 v[212:215], v184 offset:17408
	ds_read_b128 v[216:219], v184 offset:18432
	ds_read_b128 v[220:223], v184 offset:19456
	ds_read_b128 v[224:227], v184 offset:20480
	ds_read_b128 v[230:233], v184 offset:21504
	ds_read_b128 v[234:237], v184 offset:22528
	ds_read_b128 v[238:241], v184 offset:23552
	global_load_lds_dwordx4 v[202:203], off
	s_add_i32 m0, s23, 0x2000
	s_add_u32 s50, s12, 0x80000
	v_lshl_add_u64 v[242:243], s[12:13], 0, v[128:129]
	s_addc_u32 s51, s13, 0
	s_add_i32 s23, s63, s37
	global_load_lds_dwordx4 v[242:243], off
	s_mov_b32 m0, s23
	v_lshl_add_u64 v[246:247], s[14:15], 0, v[130:131]
	global_load_lds_dwordx4 v132, s[50:51]
	s_add_i32 m0, s23, 0x2000
	s_nop 0
	global_load_lds_dwordx4 v128, s[50:51]
	v_lshl_add_u64 v[244:245], s[14:15], 0, v[134:135]
	s_mov_b32 m0, s33
	s_nop 0
	global_load_lds_dwordx4 v[244:245], off
	s_mov_b32 m0, s52
	s_nop 0
	global_load_lds_dwordx4 v[246:247], off
	s_waitcnt vmcnt(8)
	s_waitcnt lgkmcnt(0)
	s_barrier
; #define PG8_STAGE(bufoff, gbase, voff) do { _Pragma("unroll") for (int _i = 0; _i < 2; ++_i) \
;         __builtin_amdgcn_global_load_lds((const unsigned*)((const char*)(gbase) + (voff)[_i]), (LAS unsigned*)(lds + (bufoff) + ldsw + _i * 8192), 16, 0, 0); } while (0)
; #define PG8_LDA(dst, b, h) do { _Pragma("unroll") for (int m = 0; m < 4; ++m) _Pragma("unroll") for (int k = 0; k < 2; ++k) dst[m][k] = *(const LAS bf16x8*)(lds + PG8_SA(b, h) + aoff + m * 2048 + k * 1024); } while (0)
; #define PG8_LDB(dst, b, h) do { _Pragma("unroll") for (int n = 0; n < 2; ++n) _Pragma("unroll") for (int k = 0; k < 2; ++k) dst[n][k] = *(const LAS bf16x8*)(lds + PG8_SB(b, h) + boff + n * 2048 + k * 1024); } while (0)
; #define PG8_MMA(ai, bj, At, Bt) do { __builtin_amdgcn_s_setprio(1); _Pragma("unroll") for (int m = 0; m < 4; ++m) _Pragma("unroll") for (int n = 0; n < 2; ++n) _Pragma("unroll") for (int k = 0; k < 2; ++k) \
;         acc[ai][bj][m][n] = __builtin_amdgcn_mfma_f32_16x16x32_bf16(Bt[n][k], At[m][k], acc[ai][bj][m][n], 0, 0, 0); __builtin_amdgcn_s_setprio(0); } while (0)
; #define PG8_WAIT_V(n) asm volatile("s_waitcnt vmcnt(" #n ")" ::: "memory")
; #define PG8_WAIT_L(n) asm volatile("s_waitcnt lgkmcnt(" #n ")" ::: "memory")
; #define PG8_BAR __builtin_amdgcn_s_barrier()
; #define PG8_SCHED __builtin_amdgcn_sched_barrier(0)
; template <class Epi>
; __device__ __forceinline__ void gemm_phase(LAS unsigned char* lds, const Gemm g, const StaticOrder& S, const Epi& E) {
;     ...
;             PG8_WAIT_V(8); PG8_WAIT_L(0); PG8_BAR; PG8_MMA(1, 0, At, B0); PG8_MMA(1, 1, At, B1); PG8_BAR; PG8_SCHED;
;             PG8_LDB(B0, 1, 0); PG8_LDB(B1, 1, 1); PG8_SCHED; PG8_LDA(At, 1, 0); PG8_STAGE(PG8_SA(0, 1), a2 + hstepA, voffA);
;             PG8_WAIT_V(8); PG8_WAIT_L(0); PG8_BAR; PG8_MMA(0, 0, At, B0); PG8_MMA(0, 1, At, B1); PG8_BAR; PG8_SCHED;
	s_setprio 1
	s_waitcnt lgkmcnt(0)
	v_mfma_f32_16x16x32_bf16 v[60:63], v[164:167], v[208:211], v[60:63]
	v_mfma_f32_16x16x32_bf16 v[60:63], v[168:171], v[212:215], v[60:63]
	v_mfma_f32_16x16x32_bf16 v[52:55], v[176:179], v[212:215], v[52:55]
	v_mfma_f32_16x16x32_bf16 v[52:55], v[172:175], v[208:211], v[52:55]
	v_mfma_f32_16x16x32_bf16 v[56:59], v[186:189], v[208:211], v[56:59]
	v_mfma_f32_16x16x32_bf16 v[56:59], v[190:193], v[212:215], v[56:59]
	v_mfma_f32_16x16x32_bf16 v[48:51], v[198:201], v[212:215], v[48:51]
	v_mfma_f32_16x16x32_bf16 v[48:51], v[194:197], v[208:211], v[48:51]
	v_mfma_f32_16x16x32_bf16 v[32:35], v[194:197], v[216:219], v[32:35]
	v_mfma_f32_16x16x32_bf16 v[32:35], v[198:201], v[220:223], v[32:35]
	v_mfma_f32_16x16x32_bf16 v[40:43], v[190:193], v[220:223], v[40:43]
	v_mfma_f32_16x16x32_bf16 v[40:43], v[186:189], v[216:219], v[40:43]
	v_mfma_f32_16x16x32_bf16 v[36:39], v[172:175], v[216:219], v[36:39]
	v_mfma_f32_16x16x32_bf16 v[36:39], v[176:179], v[220:223], v[36:39]
	v_mfma_f32_16x16x32_bf16 v[44:47], v[168:171], v[220:223], v[44:47]
	v_mfma_f32_16x16x32_bf16 v[44:47], v[164:167], v[216:219], v[44:47]
	s_setprio 0
	s_setprio 1
	v_mfma_f32_16x16x32_bf16 v[28:31], v[164:167], v[224:227], v[28:31]
	v_mfma_f32_16x16x32_bf16 v[28:31], v[168:171], v[230:233], v[28:31]
	v_mfma_f32_16x16x32_bf16 v[20:23], v[176:179], v[230:233], v[20:23]
	v_mfma_f32_16x16x32_bf16 v[20:23], v[172:175], v[224:227], v[20:23]
	v_mfma_f32_16x16x32_bf16 v[24:27], v[186:189], v[224:227], v[24:27]
	v_mfma_f32_16x16x32_bf16 v[24:27], v[190:193], v[230:233], v[24:27]
	v_mfma_f32_16x16x32_bf16 v[16:19], v[198:201], v[230:233], v[16:19]
	v_mfma_f32_16x16x32_bf16 v[16:19], v[194:197], v[224:227], v[16:19]
	v_mfma_f32_16x16x32_bf16 v[0:3], v[194:197], v[234:237], v[0:3]
	v_mfma_f32_16x16x32_bf16 v[0:3], v[198:201], v[238:241], v[0:3]
	v_mfma_f32_16x16x32_bf16 v[8:11], v[190:193], v[238:241], v[8:11]
	v_mfma_f32_16x16x32_bf16 v[8:11], v[186:189], v[234:237], v[8:11]
	v_mfma_f32_16x16x32_bf16 v[4:7], v[172:175], v[234:237], v[4:7]
	v_mfma_f32_16x16x32_bf16 v[4:7], v[176:179], v[238:241], v[4:7]
	v_mfma_f32_16x16x32_bf16 v[12:15], v[168:171], v[238:241], v[12:15]
	v_mfma_f32_16x16x32_bf16 v[12:15], v[164:167], v[234:237], v[12:15]
	s_setprio 0
	s_barrier
	s_add_i32 s23, 0, 0x18000
	s_add_i32 s25, 0, 0x1c000
	v_add_u32_e32 v176, s23, v180
	v_add_u32_e32 v185, s25, v180
	ds_read_b128 v[164:167], v176
	ds_read_b128 v[168:171], v176 offset:1024
	ds_read_b128 v[172:175], v176 offset:2048
	ds_read_b128 v[176:179], v176 offset:3072
	ds_read_b128 v[186:189], v185
	ds_read_b128 v[190:193], v185 offset:1024
	ds_read_b128 v[194:197], v185 offset:2048
	ds_read_b128 v[198:201], v185 offset:3072
	s_add_u32 s14, s14, 0x80000
	s_addc_u32 s15, s15, 0
	s_mov_b32 m0, s53
	ds_read_b128 v[208:211], v184 offset:32768
	ds_read_b128 v[212:215], v184 offset:33792
	ds_read_b128 v[216:219], v184 offset:34816
	ds_read_b128 v[220:223], v184 offset:35840
	ds_read_b128 v[224:227], v184 offset:36864
	ds_read_b128 v[230:233], v184 offset:37888
	ds_read_b128 v[234:237], v184 offset:38912
	ds_read_b128 v[238:241], v184 offset:39936
	global_load_lds_dwordx4 v134, s[14:15]
	s_mov_b32 m0, s54
	s_nop 0
	global_load_lds_dwordx4 v130, s[14:15]
	s_waitcnt vmcnt(8)
	s_waitcnt lgkmcnt(0)
	s_barrier
	s_setprio 1
	s_waitcnt lgkmcnt(0)
	v_mfma_f32_16x16x32_bf16 v[120:123], v[164:167], v[208:211], v[120:123]
	v_mfma_f32_16x16x32_bf16 v[120:123], v[168:171], v[212:215], v[120:123]
	v_mfma_f32_16x16x32_bf16 v[116:119], v[176:179], v[212:215], v[116:119]
	v_mfma_f32_16x16x32_bf16 v[116:119], v[172:175], v[208:211], v[116:119]
	v_mfma_f32_16x16x32_bf16 v[124:127], v[186:189], v[208:211], v[124:127]
	v_mfma_f32_16x16x32_bf16 v[124:127], v[190:193], v[212:215], v[124:127]
	v_mfma_f32_16x16x32_bf16 v[112:115], v[198:201], v[212:215], v[112:115]
	v_mfma_f32_16x16x32_bf16 v[112:115], v[194:197], v[208:211], v[112:115]
	v_mfma_f32_16x16x32_bf16 v[96:99], v[194:197], v[216:219], v[96:99]
	v_mfma_f32_16x16x32_bf16 v[96:99], v[198:201], v[220:223], v[96:99]
	v_mfma_f32_16x16x32_bf16 v[104:107], v[190:193], v[220:223], v[104:107]
	v_mfma_f32_16x16x32_bf16 v[104:107], v[186:189], v[216:219], v[104:107]
	v_mfma_f32_16x16x32_bf16 v[100:103], v[172:175], v[216:219], v[100:103]
	v_mfma_f32_16x16x32_bf16 v[100:103], v[176:179], v[220:223], v[100:103]
	v_mfma_f32_16x16x32_bf16 v[108:111], v[168:171], v[220:223], v[108:111]
	v_mfma_f32_16x16x32_bf16 v[108:111], v[164:167], v[216:219], v[108:111]
	s_setprio 0
	s_setprio 1
	v_mfma_f32_16x16x32_bf16 v[92:95], v[164:167], v[224:227], v[92:95]
	v_mfma_f32_16x16x32_bf16 v[92:95], v[168:171], v[230:233], v[92:95]
	v_mfma_f32_16x16x32_bf16 v[84:87], v[176:179], v[230:233], v[84:87]
	v_mfma_f32_16x16x32_bf16 v[84:87], v[172:175], v[224:227], v[84:87]
	v_mfma_f32_16x16x32_bf16 v[88:91], v[186:189], v[224:227], v[88:91]
	v_mfma_f32_16x16x32_bf16 v[88:91], v[190:193], v[230:233], v[88:91]
	v_mfma_f32_16x16x32_bf16 v[80:83], v[198:201], v[230:233], v[80:83]
	v_mfma_f32_16x16x32_bf16 v[80:83], v[194:197], v[224:227], v[80:83]
	v_mfma_f32_16x16x32_bf16 v[64:67], v[194:197], v[234:237], v[64:67]
	v_mfma_f32_16x16x32_bf16 v[64:67], v[198:201], v[238:241], v[64:67]
	v_mfma_f32_16x16x32_bf16 v[72:75], v[190:193], v[238:241], v[72:75]
	v_mfma_f32_16x16x32_bf16 v[72:75], v[186:189], v[234:237], v[72:75]
	v_mfma_f32_16x16x32_bf16 v[68:71], v[172:175], v[234:237], v[68:71]
	v_mfma_f32_16x16x32_bf16 v[68:71], v[176:179], v[238:241], v[68:71]
	v_mfma_f32_16x16x32_bf16 v[76:79], v[168:171], v[238:241], v[76:79]
	v_mfma_f32_16x16x32_bf16 v[76:79], v[164:167], v[234:237], v[76:79]
	s_setprio 0
	s_barrier
; #define PG8_STAGE(bufoff, gbase, voff) do { _Pragma("unroll") for (int _i = 0; _i < 2; ++_i) \
;         __builtin_amdgcn_global_load_lds((const unsigned*)((const char*)(gbase) + (voff)[_i]), (LAS unsigned*)(lds + (bufoff) + ldsw + _i * 8192), 16, 0, 0); } while (0)
; #define PG8_LDA(dst, b, h) do { _Pragma("unroll") for (int m = 0; m < 4; ++m) _Pragma("unroll") for (int k = 0; k < 2; ++k) dst[m][k] = *(const LAS bf16x8*)(lds + PG8_SA(b, h) + aoff + m * 2048 + k * 1024); } while (0)
; #define PG8_MMA(ai, bj, At, Bt) do { __builtin_amdgcn_s_setprio(1); _Pragma("unroll") for (int m = 0; m < 4; ++m) _Pragma("unroll") for (int n = 0; n < 2; ++n) _Pragma("unroll") for (int k = 0; k < 2; ++k) \
;         acc[ai][bj][m][n] = __builtin_amdgcn_mfma_f32_16x16x32_bf16(Bt[n][k], At[m][k], acc[ai][bj][m][n], 0, 0, 0); __builtin_amdgcn_s_setprio(0); } while (0)
; #define PG8_WAIT_V(n) asm volatile("s_waitcnt vmcnt(" #n ")" ::: "memory")
; #define PG8_WAIT_L(n) asm volatile("s_waitcnt lgkmcnt(" #n ")" ::: "memory")
; #define PG8_BAR __builtin_amdgcn_s_barrier()
; #define PG8_SCHED __builtin_amdgcn_sched_barrier(0)
; template <class Epi>
; __device__ __forceinline__ void gemm_phase(LAS unsigned char* lds, const Gemm g, const StaticOrder& S, const Epi& E) {
;     ...
;         for (int t = 0; t < nt; t += 2) {
;             const bool last = (t == nt - 2);
;             const char* a1 = cA + (size_t)(t + 1) * kstep;
;             const char* a2 = last ? nA : cA + (size_t)(t + 2) * kstep; const char* b2 = last ? nB : cB + (size_t)(t + 2) * kstep;
;             const char* a3 = a2 + kstep; const char* b3 = b2 + kstep;
;     ...
;             PG8_LDA(At, 1, 1); PG8_STAGE(PG8_SB(1, 0), b3, voffB); PG8_STAGE(PG8_SB(1, 1), b3 + hstepB, voffB); PG8_STAGE(PG8_SA(1, 0), a3, voffA);
;             PG8_WAIT_V(8); PG8_WAIT_L(0); PG8_BAR; PG8_MMA(1, 0, At, B0); PG8_MMA(1, 1, At, B1); PG8_BAR; PG8_SCHED;
;         }
	s_add_i32 s14, s23, s37
	v_lshl_add_u64 v[202:203], v[202:203], 0, s[4:5]
	s_mov_b32 m0, s14
	ds_read_b128 v[208:211], v184 offset:49152
	ds_read_b128 v[212:215], v184 offset:50176
	ds_read_b128 v[216:219], v184 offset:51200
	ds_read_b128 v[220:223], v184 offset:52224
	ds_read_b128 v[224:227], v184 offset:53248
	ds_read_b128 v[230:233], v184 offset:54272
	ds_read_b128 v[234:237], v184 offset:55296
	ds_read_b128 v[238:241], v184 offset:56320
	global_load_lds_dwordx4 v[202:203], off
	s_add_i32 m0, s14, 0x2000
	s_add_u32 s12, s12, 0x80080
	v_lshl_add_u64 v[202:203], v[242:243], 0, s[4:5]
	s_addc_u32 s13, s13, 0
	s_add_i32 s14, s25, s37
	global_load_lds_dwordx4 v[202:203], off
	s_mov_b32 m0, s14
	s_nop 0
	global_load_lds_dwordx4 v132, s[12:13]
	s_add_i32 m0, s14, 0x2000
	s_nop 0
	global_load_lds_dwordx4 v128, s[12:13]
	v_lshl_add_u64 v[202:203], v[244:245], 0, s[4:5]
	s_mov_b32 m0, s56
	s_nop 0
	global_load_lds_dwordx4 v[202:203], off
	v_lshl_add_u64 v[202:203], v[246:247], 0, s[4:5]
	s_mov_b32 m0, s57
	s_nop 0
	global_load_lds_dwordx4 v[202:203], off
	s_waitcnt vmcnt(8)
	s_waitcnt lgkmcnt(0)
	s_barrier
	s_setprio 1
	s_waitcnt lgkmcnt(0)
	v_mfma_f32_16x16x32_bf16 v[60:63], v[164:167], v[208:211], v[60:63]
	v_mfma_f32_16x16x32_bf16 v[60:63], v[168:171], v[212:215], v[60:63]
	v_mfma_f32_16x16x32_bf16 v[52:55], v[176:179], v[212:215], v[52:55]
	v_mfma_f32_16x16x32_bf16 v[52:55], v[172:175], v[208:211], v[52:55]
	v_mfma_f32_16x16x32_bf16 v[56:59], v[186:189], v[208:211], v[56:59]
	v_mfma_f32_16x16x32_bf16 v[56:59], v[190:193], v[212:215], v[56:59]
	v_mfma_f32_16x16x32_bf16 v[48:51], v[198:201], v[212:215], v[48:51]
	v_mfma_f32_16x16x32_bf16 v[48:51], v[194:197], v[208:211], v[48:51]
	v_mfma_f32_16x16x32_bf16 v[32:35], v[194:197], v[216:219], v[32:35]
	v_mfma_f32_16x16x32_bf16 v[32:35], v[198:201], v[220:223], v[32:35]
	v_mfma_f32_16x16x32_bf16 v[40:43], v[190:193], v[220:223], v[40:43]
	v_mfma_f32_16x16x32_bf16 v[40:43], v[186:189], v[216:219], v[40:43]
	v_mfma_f32_16x16x32_bf16 v[36:39], v[172:175], v[216:219], v[36:39]
	v_mfma_f32_16x16x32_bf16 v[36:39], v[176:179], v[220:223], v[36:39]
	v_mfma_f32_16x16x32_bf16 v[44:47], v[168:171], v[220:223], v[44:47]
	v_mfma_f32_16x16x32_bf16 v[44:47], v[164:167], v[216:219], v[44:47]
	s_setprio 0
	s_setprio 1
	v_mfma_f32_16x16x32_bf16 v[28:31], v[164:167], v[224:227], v[28:31]
	v_mfma_f32_16x16x32_bf16 v[28:31], v[168:171], v[230:233], v[28:31]
	v_mfma_f32_16x16x32_bf16 v[20:23], v[176:179], v[230:233], v[20:23]
	v_mfma_f32_16x16x32_bf16 v[20:23], v[172:175], v[224:227], v[20:23]
	v_mfma_f32_16x16x32_bf16 v[24:27], v[186:189], v[224:227], v[24:27]
	v_mfma_f32_16x16x32_bf16 v[24:27], v[190:193], v[230:233], v[24:27]
	v_mfma_f32_16x16x32_bf16 v[16:19], v[198:201], v[230:233], v[16:19]
	v_mfma_f32_16x16x32_bf16 v[16:19], v[194:197], v[224:227], v[16:19]
	v_mfma_f32_16x16x32_bf16 v[0:3], v[194:197], v[234:237], v[0:3]
	v_mfma_f32_16x16x32_bf16 v[0:3], v[198:201], v[238:241], v[0:3]
	v_mfma_f32_16x16x32_bf16 v[8:11], v[190:193], v[238:241], v[8:11]
	v_mfma_f32_16x16x32_bf16 v[8:11], v[186:189], v[234:237], v[8:11]
	v_mfma_f32_16x16x32_bf16 v[4:7], v[172:175], v[234:237], v[4:7]
	v_mfma_f32_16x16x32_bf16 v[4:7], v[176:179], v[238:241], v[4:7]
	v_mfma_f32_16x16x32_bf16 v[12:15], v[168:171], v[238:241], v[12:15]
	v_mfma_f32_16x16x32_bf16 v[12:15], v[164:167], v[234:237], v[12:15]
	s_setprio 0
	s_barrier
	s_add_u32 s10, s10, 0x100
	s_addc_u32 s11, s11, 0
	s_add_u32 s20, s20, 0x100
	s_addc_u32 s21, s21, 0
	s_cmp_ge_i32 s22, s55
	s_mov_b32 s12, s22
	s_cbranch_scc0 .LBB0_1131

; #define PG8_STAGE(bufoff, gbase, voff) do { _Pragma("unroll") for (int _i = 0; _i < 2; ++_i) \
;         __builtin_amdgcn_global_load_lds((const unsigned*)((const char*)(gbase) + (voff)[_i]), (LAS unsigned*)(lds + (bufoff) + ldsw + _i * 8192), 16, 0, 0); } while (0)
; #define PG8_WAIT_V(n) asm volatile("s_waitcnt vmcnt(" #n ")" ::: "memory")
; #define PG8_BAR __builtin_amdgcn_s_barrier()
; template <class Epi>
; __device__ __forceinline__ void gemm_phase(LAS unsigned char* lds, const Gemm g, const StaticOrder& S, const Epi& E) {
;     ...
;     for (int i = 0; i < 2; ++i) { int R, C; stage_rc(tid * 16 + i * 8192, R, C); const int Rb = Epi::PERM ? ((R & ~31) + perm32(R & 31)) : R;
;         voffA[i] = (unsigned)(R * g.lda + C) * 2u; voffB[i] = (unsigned)(Rb * g.ldb + C) * 2u; }
;     const size_t kstep = (size_t)(BK * 2);
;     const size_t hstepA = (size_t)HALF * g.lda * 2, hstepB = (size_t)HALF * g.ldb * 2;
;     const size_t tstepA = 2 * hstepA, tstepB = 2 * hstepB;
;     const unsigned ldsw = (unsigned)wid * 1024u;
;     const int aoff = lds_byte(wr * 64 + fr, fq * 8), boff = lds_byte(wc * 32 + fr, fq * 8);
;     ...
;     Unit cur, nxt; int ui = 0;
;     if (!S.next(0, cur)) return;
;     f32x4 acc[2][2][4][2];
; #pragma unroll
;     for (int a = 0; a < 2; ++a)
; #pragma unroll
;         for (int b = 0; b < 2; ++b)
; #pragma unroll
;             for (int m = 0; m < 4; ++m)
; #pragma unroll
;                 for (int n = 0; n < 2; ++n) acc[a][b][m][n] = (f32x4){0.f, 0.f, 0.f, 0.f};
;     bf16x8 At[4][2], B0[2][2], B1[2][2];
;     const char* cA = (const char*)g.A + (size_t)cur.pm * tstepA; const char* cB = (const char*)g.Bt + (size_t)cur.pb * tstepB;
;     PG8_STAGE(PG8_SB(0, 0), cB, voffB); PG8_STAGE(PG8_SB(0, 1), cB + hstepB, voffB); PG8_STAGE(PG8_SA(0, 0), cA, voffA); PG8_STAGE(PG8_SA(0, 1), cA + hstepA, voffA);
;     if (wr == 1) PG8_BAR;
;     PG8_WAIT_V(2); PG8_BAR;
;     PG8_STAGE(PG8_SB(1, 0), cB + kstep, voffB); PG8_STAGE(PG8_SA(1, 0), cA + kstep, voffA); PG8_STAGE(PG8_SB(1, 1), cB + hstepB + kstep, voffB);
;     PG8_WAIT_V(6); PG8_BAR;
;     for (;;) {
;         const bool has_next = S.next(ui + 1, nxt);
;         const char* nA = has_next ? (const char*)g.A + (size_t)nxt.pm * tstepA : cA; const char* nB = has_next ? (const char*)g.Bt + (size_t)nxt.pb * tstepB : cB;
.LBB0_1150:
	s_ashr_i32 s14, s9, 31
	s_lshr_b32 s14, s14, 26
	s_lshl_b32 s18, s12, 6
	s_lshl_b32 s16, s12, 13
	s_lshl_b32 s12, s13, 5
	s_add_i32 s14, s9, s14
	s_and_b32 s19, s12, 0x60
	s_ashr_i32 s61, s14, 6
	s_lshl_b32 s17, s19, 7
	s_and_b64 s[12:13], s[82:83], exec
	s_mov_b64 s[12:13], 0x80
	s_cselect_b32 s62, 0x80, s94
	s_add_i32 m0, s56, 0x18000
	v_lshl_add_u64 v[6:7], v[6:7], 0, s[12:13]
	s_waitcnt vmcnt(2)
	s_barrier
	global_load_lds_dwordx4 v[6:7], off
	v_lshl_add_u64 v[2:3], v[2:3], 0, s[12:13]
	s_add_i32 m0, s56, 0x1a000
	s_add_i32 s63, s56, 0x8000
	s_add_i32 s64, s56, 0xa000
	global_load_lds_dwordx4 v[2:3], off
	v_lshl_add_u64 v[0:1], v[0:1], 0, s[12:13]
	s_mov_b32 m0, s63
	s_add_u32 s14, s46, 0x10080
	global_load_lds_dwordx4 v[0:1], off
	v_lshl_add_u64 v[0:1], v[4:5], 0, s[12:13]
	s_mov_b32 m0, s64
	s_addc_u32 s15, s47, 0
	global_load_lds_dwordx4 v[0:1], off
	s_add_i32 m0, s56, 0x1c000
	s_nop 0
	global_load_lds_dwordx4 v130, s[14:15]
	v_lshl_add_u64 v[0:1], s[14:15], 0, v[134:135]
	s_add_i32 m0, s56, 0x1e000
	s_cmp_gt_i32 s9, 63
	global_load_lds_dwordx4 v[0:1], off
	v_lshrrev_b32_e32 v0, 1, v8
	v_and_b32_e32 v0, 24, v0
	v_and_b32_e32 v1, 15, v8
	v_lshlrev_b32_e32 v2, 1, v0
	v_lshlrev_b32_e32 v3, 2, v8
	s_cselect_b64 s[14:15], -1, 0
	s_add_i32 s65, s61, -2
	v_lshl_or_b32 v2, v1, 6, v2
	v_and_b32_e32 v3, 32, v3
	s_cmpk_lt_u32 s8, 0x100
	s_sext_i32_i8 s77, s0
	v_bitop3_b32 v4, v2, s16, v3 bitop3:0xde
	v_bitop3_b32 v148, v2, s17, v3 bitop3:0xde
	s_cselect_b64 s[16:17], -1, 0
	s_ashr_i32 s0, s18, 31
	v_or_b32_e32 v2, s18, v1
	v_mov_b32_e32 v3, s0
	v_lshlrev_b32_e32 v1, 12, v9
	v_lshlrev_b64 v[2:3], 12, v[2:3]
	v_and_b32_e32 v1, 0xffffe000, v1
	v_lshl_add_u64 v[138:139], s[22:23], 0, v[2:3]
	v_lshl_add_u32 v1, v10, 9, v1
	v_and_b32_e32 v2, 1, v9
	v_lshl_or_b32 v1, v2, 6, v1
	v_lshl_add_u32 v140, v11, 1, v1
	v_lshlrev_b32_e32 v1, 12, v12
	v_and_b32_e32 v1, 0xffffe000, v1
	s_waitcnt vmcnt(6)
	v_lshl_add_u32 v1, v13, 9, v1
	v_and_b32_e32 v2, 1, v12
	v_lshl_or_b32 v1, v2, 6, v1
	s_add_i32 s67, 0, 0x10000
	s_add_i32 s68, 0, 0x14000
	s_ashr_i32 s66, s62, 31
	v_mov_b32_e32 v141, v137
	v_lshl_add_u32 v142, v14, 1, v1
	v_mov_b32_e32 v143, v137
	v_mov_b64_e32 v[144:145], 0x400
	v_mov_b64_e32 v[146:147], 0x3ff
	v_add_u32_e32 v149, s67, v148
	v_add_u32_e32 v150, s68, v148
	v_add_u32_e32 v151, 0, v4
	s_lshl_b32 s0, s19, 1
	v_lshlrev_b32_e32 v136, 1, v0
	s_mov_b64 s[18:19], 0x20000
	s_mov_b32 s69, 0x20000
	s_mov_b64 s[20:21], 0x30000
	s_mov_b32 s70, 0x30000
	s_mov_b64 s[24:25], 0x80000
	s_mov_b32 s71, 0x80000
	s_mov_b64 s[26:27], 0x90000
	s_mov_b32 s72, 0x90000
	s_mov_b64 s[28:29], 0xa0000
	s_mov_b32 s73, 0xa0000
	s_mov_b64 s[30:31], 0xb0000
	s_mov_b32 s76, s1
	s_barrier
	s_branch .LBB0_1153

; #define PG8_STAGE(bufoff, gbase, voff) do { _Pragma("unroll") for (int _i = 0; _i < 2; ++_i) \
;         __builtin_amdgcn_global_load_lds((const unsigned*)((const char*)(gbase) + (voff)[_i]), (LAS unsigned*)(lds + (bufoff) + ldsw + _i * 8192), 16, 0, 0); } while (0)
; #define PG8_LDA(dst, b, h) do { _Pragma("unroll") for (int m = 0; m < 4; ++m) _Pragma("unroll") for (int k = 0; k < 2; ++k) dst[m][k] = *(const LAS bf16x8*)(lds + PG8_SA(b, h) + aoff + m * 2048 + k * 1024); } while (0)
; #define PG8_LDB(dst, b, h) do { _Pragma("unroll") for (int n = 0; n < 2; ++n) _Pragma("unroll") for (int k = 0; k < 2; ++k) dst[n][k] = *(const LAS bf16x8*)(lds + PG8_SB(b, h) + boff + n * 2048 + k * 1024); } while (0)
; #define PG8_MMA(ai, bj, At, Bt) do { __builtin_amdgcn_s_setprio(1); _Pragma("unroll") for (int m = 0; m < 4; ++m) _Pragma("unroll") for (int n = 0; n < 2; ++n) _Pragma("unroll") for (int k = 0; k < 2; ++k) \
;         acc[ai][bj][m][n] = __builtin_amdgcn_mfma_f32_16x16x32_bf16(Bt[n][k], At[m][k], acc[ai][bj][m][n], 0, 0, 0); __builtin_amdgcn_s_setprio(0); } while (0)
; #define PG8_WAIT_V(n) asm volatile("s_waitcnt vmcnt(" #n ")" ::: "memory")
; #define PG8_WAIT_L(n) asm volatile("s_waitcnt lgkmcnt(" #n ")" ::: "memory")
; #define PG8_BAR __builtin_amdgcn_s_barrier()
; #define PG8_SCHED __builtin_amdgcn_sched_barrier(0)
; template <class Epi>
; __device__ __forceinline__ void gemm_phase(LAS unsigned char* lds, const Gemm g, const StaticOrder& S, const Epi& E) {
;     ...
;             const bool last = (t == nt - 2);
;             const char* a1 = cA + (size_t)(t + 1) * kstep;
;             const char* a2 = last ? nA : cA + (size_t)(t + 2) * kstep; const char* b2 = last ? nB : cB + (size_t)(t + 2) * kstep;
;             const char* a3 = a2 + kstep; const char* b3 = b2 + kstep;
;             PG8_LDB(B0, 0, 0); PG8_LDB(B1, 0, 1); PG8_SCHED; PG8_LDA(At, 0, 0); PG8_STAGE(PG8_SA(1, 1), a1 + hstepA, voffA);
;             PG8_WAIT_V(8); PG8_WAIT_L(0); PG8_BAR; PG8_MMA(0, 0, At, B0); PG8_MMA(0, 1, At, B1); PG8_BAR; PG8_SCHED;
;             PG8_LDA(At, 0, 1); PG8_STAGE(PG8_SB(0, 0), b2, voffB); PG8_STAGE(PG8_SB(0, 1), b2 + hstepB, voffB); PG8_STAGE(PG8_SA(0, 0), a2, voffA);
.LBB0_1161:
	ds_read_b128 v[152:155], v149
	ds_read_b128 v[156:159], v149 offset:1024
	ds_read_b128 v[160:163], v149 offset:2048
	ds_read_b128 v[164:167], v149 offset:3072
	ds_read_b128 v[168:171], v150
	ds_read_b128 v[172:175], v150 offset:1024
	ds_read_b128 v[176:179], v150 offset:2048
	ds_read_b128 v[180:183], v150 offset:3072
	s_add_i32 s83, s46, 2
	s_add_u32 s47, s44, 0xffff0080
	s_addc_u32 s48, s45, -1
	s_cmp_eq_u32 s65, s46
	s_cselect_b32 s46, s78, s79
	s_cselect_b32 s49, s35, s48
	s_cselect_b32 s48, s37, s47
	s_cselect_b32 s47, s39, s82
	s_add_i32 m0, s56, 0xc000
	ds_read_b128 v[184:187], v151
	ds_read_b128 v[188:191], v151 offset:1024
	ds_read_b128 v[192:195], v151 offset:2048
	ds_read_b128 v[196:199], v151 offset:3072
	ds_read_b128 v[200:203], v151 offset:4096
	ds_read_b128 v[208:211], v151 offset:5120
	ds_read_b128 v[212:215], v151 offset:6144
	ds_read_b128 v[216:219], v151 offset:7168
	global_load_lds_dwordx4 v140, s[44:45]
	s_add_i32 m0, s56, 0xe000
	s_nop 0
	global_load_lds_dwordx4 v142, s[44:45]
	s_waitcnt vmcnt(8)
	s_waitcnt lgkmcnt(0)
	s_barrier
	s_setprio 1
	s_waitcnt lgkmcnt(0)
	v_mfma_f32_16x16x32_bf16 v[120:123], v[152:155], v[184:187], v[120:123]
	v_mfma_f32_16x16x32_bf16 v[120:123], v[156:159], v[188:191], v[120:123]
	v_mfma_f32_16x16x32_bf16 v[124:127], v[164:167], v[188:191], v[124:127]
	v_mfma_f32_16x16x32_bf16 v[124:127], v[160:163], v[184:187], v[124:127]
	v_mfma_f32_16x16x32_bf16 v[116:119], v[168:171], v[184:187], v[116:119]
	v_mfma_f32_16x16x32_bf16 v[116:119], v[172:175], v[188:191], v[116:119]
	v_mfma_f32_16x16x32_bf16 v[112:115], v[180:183], v[188:191], v[112:115]
	v_mfma_f32_16x16x32_bf16 v[112:115], v[176:179], v[184:187], v[112:115]
	v_mfma_f32_16x16x32_bf16 v[96:99], v[176:179], v[192:195], v[96:99]
	v_mfma_f32_16x16x32_bf16 v[96:99], v[180:183], v[196:199], v[96:99]
	v_mfma_f32_16x16x32_bf16 v[100:103], v[172:175], v[196:199], v[100:103]
	v_mfma_f32_16x16x32_bf16 v[100:103], v[168:171], v[192:195], v[100:103]
	v_mfma_f32_16x16x32_bf16 v[104:107], v[160:163], v[192:195], v[104:107]
	v_mfma_f32_16x16x32_bf16 v[104:107], v[164:167], v[196:199], v[104:107]
	v_mfma_f32_16x16x32_bf16 v[108:111], v[156:159], v[196:199], v[108:111]
	v_mfma_f32_16x16x32_bf16 v[108:111], v[152:155], v[192:195], v[108:111]
	s_setprio 0
	s_setprio 1
	v_mfma_f32_16x16x32_bf16 v[92:95], v[152:155], v[200:203], v[92:95]
	v_mfma_f32_16x16x32_bf16 v[92:95], v[156:159], v[208:211], v[92:95]
	v_mfma_f32_16x16x32_bf16 v[88:91], v[164:167], v[208:211], v[88:91]
	v_mfma_f32_16x16x32_bf16 v[88:91], v[160:163], v[200:203], v[88:91]
	v_mfma_f32_16x16x32_bf16 v[84:87], v[168:171], v[200:203], v[84:87]
	v_mfma_f32_16x16x32_bf16 v[84:87], v[172:175], v[208:211], v[84:87]
	v_mfma_f32_16x16x32_bf16 v[80:83], v[180:183], v[208:211], v[80:83]
	v_mfma_f32_16x16x32_bf16 v[80:83], v[176:179], v[200:203], v[80:83]
	v_mfma_f32_16x16x32_bf16 v[64:67], v[176:179], v[212:215], v[64:67]
	v_mfma_f32_16x16x32_bf16 v[64:67], v[180:183], v[216:219], v[64:67]
	v_mfma_f32_16x16x32_bf16 v[68:71], v[172:175], v[216:219], v[68:71]
	v_mfma_f32_16x16x32_bf16 v[68:71], v[168:171], v[212:215], v[68:71]
	v_mfma_f32_16x16x32_bf16 v[72:75], v[160:163], v[212:215], v[72:75]
	v_mfma_f32_16x16x32_bf16 v[72:75], v[164:167], v[216:219], v[72:75]
	v_mfma_f32_16x16x32_bf16 v[76:79], v[156:159], v[216:219], v[76:79]
	v_mfma_f32_16x16x32_bf16 v[76:79], v[152:155], v[212:215], v[76:79]
	s_setprio 0
	s_barrier
	s_add_i32 s84, s67, s51
	v_lshl_add_u64 v[220:221], s[46:47], 0, v[130:131]
	s_mov_b32 m0, s84
	ds_read_b128 v[184:187], v151 offset:16384
	ds_read_b128 v[188:191], v151 offset:17408
	ds_read_b128 v[192:195], v151 offset:18432
	ds_read_b128 v[196:199], v151 offset:19456
	ds_read_b128 v[200:203], v151 offset:20480
	ds_read_b128 v[208:211], v151 offset:21504
	ds_read_b128 v[212:215], v151 offset:22528
	ds_read_b128 v[216:219], v151 offset:23552
	global_load_lds_dwordx4 v[220:221], off
	s_add_i32 m0, s84, 0x2000
	s_add_u32 s84, s46, 0x10000
	v_lshl_add_u64 v[222:223], s[46:47], 0, v[134:135]
	s_addc_u32 s85, s47, 0
	s_add_i32 s86, s68, s51
	global_load_lds_dwordx4 v[222:223], off
	s_mov_b32 m0, s86
	v_lshl_add_u64 v[226:227], s[48:49], 0, v[132:133]
	global_load_lds_dwordx4 v130, s[84:85]
	s_add_i32 m0, s86, 0x2000
	s_nop 0
	global_load_lds_dwordx4 v134, s[84:85]
	v_lshl_add_u64 v[224:225], s[48:49], 0, v[128:129]
	s_mov_b32 m0, s56
	s_nop 0
	global_load_lds_dwordx4 v[224:225], off
	s_mov_b32 m0, s57
	s_nop 0
	global_load_lds_dwordx4 v[226:227], off
	s_waitcnt vmcnt(8)
	s_waitcnt lgkmcnt(0)
	s_barrier
; #define PG8_STAGE(bufoff, gbase, voff) do { _Pragma("unroll") for (int _i = 0; _i < 2; ++_i) \
;         __builtin_amdgcn_global_load_lds((const unsigned*)((const char*)(gbase) + (voff)[_i]), (LAS unsigned*)(lds + (bufoff) + ldsw + _i * 8192), 16, 0, 0); } while (0)
; #define PG8_LDA(dst, b, h) do { _Pragma("unroll") for (int m = 0; m < 4; ++m) _Pragma("unroll") for (int k = 0; k < 2; ++k) dst[m][k] = *(const LAS bf16x8*)(lds + PG8_SA(b, h) + aoff + m * 2048 + k * 1024); } while (0)
; #define PG8_LDB(dst, b, h) do { _Pragma("unroll") for (int n = 0; n < 2; ++n) _Pragma("unroll") for (int k = 0; k < 2; ++k) dst[n][k] = *(const LAS bf16x8*)(lds + PG8_SB(b, h) + boff + n * 2048 + k * 1024); } while (0)
; #define PG8_MMA(ai, bj, At, Bt) do { __builtin_amdgcn_s_setprio(1); _Pragma("unroll") for (int m = 0; m < 4; ++m) _Pragma("unroll") for (int n = 0; n < 2; ++n) _Pragma("unroll") for (int k = 0; k < 2; ++k) \
;         acc[ai][bj][m][n] = __builtin_amdgcn_mfma_f32_16x16x32_bf16(Bt[n][k], At[m][k], acc[ai][bj][m][n], 0, 0, 0); __builtin_amdgcn_s_setprio(0); } while (0)
; #define PG8_WAIT_V(n) asm volatile("s_waitcnt vmcnt(" #n ")" ::: "memory")
; #define PG8_WAIT_L(n) asm volatile("s_waitcnt lgkmcnt(" #n ")" ::: "memory")
; #define PG8_BAR __builtin_amdgcn_s_barrier()
; #define PG8_SCHED __builtin_amdgcn_sched_barrier(0)
; template <class Epi>
; __device__ __forceinline__ void gemm_phase(LAS unsigned char* lds, const Gemm g, const StaticOrder& S, const Epi& E) {
;     ...
;             PG8_WAIT_V(8); PG8_WAIT_L(0); PG8_BAR; PG8_MMA(1, 0, At, B0); PG8_MMA(1, 1, At, B1); PG8_BAR; PG8_SCHED;
;             PG8_LDB(B0, 1, 0); PG8_LDB(B1, 1, 1); PG8_SCHED; PG8_LDA(At, 1, 0); PG8_STAGE(PG8_SA(0, 1), a2 + hstepA, voffA);
;             PG8_WAIT_V(8); PG8_WAIT_L(0); PG8_BAR; PG8_MMA(0, 0, At, B0); PG8_MMA(0, 1, At, B1); PG8_BAR; PG8_SCHED;
	s_setprio 1
	s_waitcnt lgkmcnt(0)
	v_mfma_f32_16x16x32_bf16 v[60:63], v[152:155], v[184:187], v[60:63]
	v_mfma_f32_16x16x32_bf16 v[60:63], v[156:159], v[188:191], v[60:63]
	v_mfma_f32_16x16x32_bf16 v[56:59], v[164:167], v[188:191], v[56:59]
	v_mfma_f32_16x16x32_bf16 v[56:59], v[160:163], v[184:187], v[56:59]
	v_mfma_f32_16x16x32_bf16 v[52:55], v[168:171], v[184:187], v[52:55]
	v_mfma_f32_16x16x32_bf16 v[52:55], v[172:175], v[188:191], v[52:55]
	v_mfma_f32_16x16x32_bf16 v[48:51], v[180:183], v[188:191], v[48:51]
	v_mfma_f32_16x16x32_bf16 v[48:51], v[176:179], v[184:187], v[48:51]
	v_mfma_f32_16x16x32_bf16 v[32:35], v[176:179], v[192:195], v[32:35]
	v_mfma_f32_16x16x32_bf16 v[32:35], v[180:183], v[196:199], v[32:35]
	v_mfma_f32_16x16x32_bf16 v[36:39], v[172:175], v[196:199], v[36:39]
	v_mfma_f32_16x16x32_bf16 v[36:39], v[168:171], v[192:195], v[36:39]
	v_mfma_f32_16x16x32_bf16 v[40:43], v[160:163], v[192:195], v[40:43]
	v_mfma_f32_16x16x32_bf16 v[40:43], v[164:167], v[196:199], v[40:43]
	v_mfma_f32_16x16x32_bf16 v[44:47], v[156:159], v[196:199], v[44:47]
	v_mfma_f32_16x16x32_bf16 v[44:47], v[152:155], v[192:195], v[44:47]
	s_setprio 0
	s_setprio 1
	v_mfma_f32_16x16x32_bf16 v[28:31], v[152:155], v[200:203], v[28:31]
	v_mfma_f32_16x16x32_bf16 v[28:31], v[156:159], v[208:211], v[28:31]
	v_mfma_f32_16x16x32_bf16 v[24:27], v[164:167], v[208:211], v[24:27]
	v_mfma_f32_16x16x32_bf16 v[24:27], v[160:163], v[200:203], v[24:27]
	v_mfma_f32_16x16x32_bf16 v[20:23], v[168:171], v[200:203], v[20:23]
	v_mfma_f32_16x16x32_bf16 v[20:23], v[172:175], v[208:211], v[20:23]
	v_mfma_f32_16x16x32_bf16 v[16:19], v[180:183], v[208:211], v[16:19]
	v_mfma_f32_16x16x32_bf16 v[16:19], v[176:179], v[200:203], v[16:19]
	v_mfma_f32_16x16x32_bf16 v[0:3], v[176:179], v[212:215], v[0:3]
	v_mfma_f32_16x16x32_bf16 v[0:3], v[180:183], v[216:219], v[0:3]
	v_mfma_f32_16x16x32_bf16 v[4:7], v[172:175], v[216:219], v[4:7]
	v_mfma_f32_16x16x32_bf16 v[4:7], v[168:171], v[212:215], v[4:7]
	v_mfma_f32_16x16x32_bf16 v[8:11], v[160:163], v[212:215], v[8:11]
	v_mfma_f32_16x16x32_bf16 v[8:11], v[164:167], v[216:219], v[8:11]
	v_mfma_f32_16x16x32_bf16 v[12:15], v[156:159], v[216:219], v[12:15]
	v_mfma_f32_16x16x32_bf16 v[12:15], v[152:155], v[212:215], v[12:15]
	s_setprio 0
	s_barrier
	s_add_i32 s84, 0, 0x18000
	s_add_i32 s85, 0, 0x1c000
	v_add_u32_e32 v164, s84, v148
	v_add_u32_e32 v180, s85, v148
	ds_read_b128 v[152:155], v164
	ds_read_b128 v[156:159], v164 offset:1024
	ds_read_b128 v[160:163], v164 offset:2048
	ds_read_b128 v[164:167], v164 offset:3072
	ds_read_b128 v[168:171], v180
	ds_read_b128 v[172:175], v180 offset:1024
	ds_read_b128 v[176:179], v180 offset:2048
	ds_read_b128 v[180:183], v180 offset:3072
	s_add_u32 s48, s48, 0x10000
	s_addc_u32 s49, s49, 0
	s_mov_b32 m0, s58
	ds_read_b128 v[184:187], v151 offset:32768
	ds_read_b128 v[188:191], v151 offset:33792
	ds_read_b128 v[192:195], v151 offset:34816
	ds_read_b128 v[196:199], v151 offset:35840
	ds_read_b128 v[200:203], v151 offset:36864
	ds_read_b128 v[208:211], v151 offset:37888
	ds_read_b128 v[212:215], v151 offset:38912
	ds_read_b128 v[216:219], v151 offset:39936
	global_load_lds_dwordx4 v128, s[48:49]
	s_mov_b32 m0, s59
	s_nop 0
	global_load_lds_dwordx4 v132, s[48:49]
	s_waitcnt vmcnt(8)
	s_waitcnt lgkmcnt(0)
	s_barrier
	s_setprio 1
	s_waitcnt lgkmcnt(0)
	v_mfma_f32_16x16x32_bf16 v[120:123], v[152:155], v[184:187], v[120:123]
	v_mfma_f32_16x16x32_bf16 v[120:123], v[156:159], v[188:191], v[120:123]
	v_mfma_f32_16x16x32_bf16 v[124:127], v[164:167], v[188:191], v[124:127]
	v_mfma_f32_16x16x32_bf16 v[124:127], v[160:163], v[184:187], v[124:127]
	v_mfma_f32_16x16x32_bf16 v[116:119], v[168:171], v[184:187], v[116:119]
	v_mfma_f32_16x16x32_bf16 v[116:119], v[172:175], v[188:191], v[116:119]
	v_mfma_f32_16x16x32_bf16 v[112:115], v[180:183], v[188:191], v[112:115]
	v_mfma_f32_16x16x32_bf16 v[112:115], v[176:179], v[184:187], v[112:115]
	v_mfma_f32_16x16x32_bf16 v[96:99], v[176:179], v[192:195], v[96:99]
	v_mfma_f32_16x16x32_bf16 v[96:99], v[180:183], v[196:199], v[96:99]
	v_mfma_f32_16x16x32_bf16 v[100:103], v[172:175], v[196:199], v[100:103]
	v_mfma_f32_16x16x32_bf16 v[100:103], v[168:171], v[192:195], v[100:103]
	v_mfma_f32_16x16x32_bf16 v[104:107], v[160:163], v[192:195], v[104:107]
	v_mfma_f32_16x16x32_bf16 v[104:107], v[164:167], v[196:199], v[104:107]
	v_mfma_f32_16x16x32_bf16 v[108:111], v[156:159], v[196:199], v[108:111]
	v_mfma_f32_16x16x32_bf16 v[108:111], v[152:155], v[192:195], v[108:111]
	s_setprio 0
	s_setprio 1
	v_mfma_f32_16x16x32_bf16 v[92:95], v[152:155], v[200:203], v[92:95]
	v_mfma_f32_16x16x32_bf16 v[92:95], v[156:159], v[208:211], v[92:95]
	v_mfma_f32_16x16x32_bf16 v[88:91], v[164:167], v[208:211], v[88:91]
	v_mfma_f32_16x16x32_bf16 v[88:91], v[160:163], v[200:203], v[88:91]
	v_mfma_f32_16x16x32_bf16 v[84:87], v[168:171], v[200:203], v[84:87]
	v_mfma_f32_16x16x32_bf16 v[84:87], v[172:175], v[208:211], v[84:87]
	v_mfma_f32_16x16x32_bf16 v[80:83], v[180:183], v[208:211], v[80:83]
	v_mfma_f32_16x16x32_bf16 v[80:83], v[176:179], v[200:203], v[80:83]
	v_mfma_f32_16x16x32_bf16 v[64:67], v[176:179], v[212:215], v[64:67]
	v_mfma_f32_16x16x32_bf16 v[64:67], v[180:183], v[216:219], v[64:67]
	v_mfma_f32_16x16x32_bf16 v[68:71], v[172:175], v[216:219], v[68:71]
	v_mfma_f32_16x16x32_bf16 v[68:71], v[168:171], v[212:215], v[68:71]
	v_mfma_f32_16x16x32_bf16 v[72:75], v[160:163], v[212:215], v[72:75]
	v_mfma_f32_16x16x32_bf16 v[72:75], v[164:167], v[216:219], v[72:75]
	v_mfma_f32_16x16x32_bf16 v[76:79], v[156:159], v[216:219], v[76:79]
	v_mfma_f32_16x16x32_bf16 v[76:79], v[152:155], v[212:215], v[76:79]
	s_setprio 0
	s_barrier
; #define PG8_STAGE(bufoff, gbase, voff) do { _Pragma("unroll") for (int _i = 0; _i < 2; ++_i) \
;         __builtin_amdgcn_global_load_lds((const unsigned*)((const char*)(gbase) + (voff)[_i]), (LAS unsigned*)(lds + (bufoff) + ldsw + _i * 8192), 16, 0, 0); } while (0)
; #define PG8_LDA(dst, b, h) do { _Pragma("unroll") for (int m = 0; m < 4; ++m) _Pragma("unroll") for (int k = 0; k < 2; ++k) dst[m][k] = *(const LAS bf16x8*)(lds + PG8_SA(b, h) + aoff + m * 2048 + k * 1024); } while (0)
; #define PG8_MMA(ai, bj, At, Bt) do { __builtin_amdgcn_s_setprio(1); _Pragma("unroll") for (int m = 0; m < 4; ++m) _Pragma("unroll") for (int n = 0; n < 2; ++n) _Pragma("unroll") for (int k = 0; k < 2; ++k) \
;         acc[ai][bj][m][n] = __builtin_amdgcn_mfma_f32_16x16x32_bf16(Bt[n][k], At[m][k], acc[ai][bj][m][n], 0, 0, 0); __builtin_amdgcn_s_setprio(0); } while (0)
; #define PG8_WAIT_V(n) asm volatile("s_waitcnt vmcnt(" #n ")" ::: "memory")
; #define PG8_WAIT_L(n) asm volatile("s_waitcnt lgkmcnt(" #n ")" ::: "memory")
; #define PG8_BAR __builtin_amdgcn_s_barrier()
; #define PG8_SCHED __builtin_amdgcn_sched_barrier(0)
; template <class Epi>
; __device__ __forceinline__ void gemm_phase(LAS unsigned char* lds, const Gemm g, const StaticOrder& S, const Epi& E) {
;     ...
;         for (int t = 0; t < nt; t += 2) {
;             const bool last = (t == nt - 2);
;             const char* a1 = cA + (size_t)(t + 1) * kstep;
;             const char* a2 = last ? nA : cA + (size_t)(t + 2) * kstep; const char* b2 = last ? nB : cB + (size_t)(t + 2) * kstep;
;             const char* a3 = a2 + kstep; const char* b3 = b2 + kstep;
;     ...
;             PG8_LDA(At, 1, 1); PG8_STAGE(PG8_SB(1, 0), b3, voffB); PG8_STAGE(PG8_SB(1, 1), b3 + hstepB, voffB); PG8_STAGE(PG8_SA(1, 0), a3, voffA);
;             PG8_WAIT_V(8); PG8_WAIT_L(0); PG8_BAR; PG8_MMA(1, 0, At, B0); PG8_MMA(1, 1, At, B1); PG8_BAR; PG8_SCHED;
;         }
	s_add_i32 s48, s84, s51
	v_lshl_add_u64 v[220:221], v[220:221], 0, s[12:13]
	s_mov_b32 m0, s48
	ds_read_b128 v[184:187], v151 offset:49152
	ds_read_b128 v[188:191], v151 offset:50176
	ds_read_b128 v[192:195], v151 offset:51200
	ds_read_b128 v[196:199], v151 offset:52224
	ds_read_b128 v[200:203], v151 offset:53248
	ds_read_b128 v[208:211], v151 offset:54272
	ds_read_b128 v[212:215], v151 offset:55296
	ds_read_b128 v[216:219], v151 offset:56320
	global_load_lds_dwordx4 v[220:221], off
	s_add_i32 m0, s48, 0x2000
	s_add_u32 s46, s46, 0x10080
	v_lshl_add_u64 v[220:221], v[222:223], 0, s[12:13]
	s_addc_u32 s47, s47, 0
	s_add_i32 s48, s85, s51
	global_load_lds_dwordx4 v[220:221], off
	s_mov_b32 m0, s48
	s_nop 0
	global_load_lds_dwordx4 v130, s[46:47]
	s_add_i32 m0, s48, 0x2000
	s_nop 0
	global_load_lds_dwordx4 v134, s[46:47]
	v_lshl_add_u64 v[220:221], v[224:225], 0, s[12:13]
	s_mov_b32 m0, s63
	s_nop 0
	global_load_lds_dwordx4 v[220:221], off
	v_lshl_add_u64 v[220:221], v[226:227], 0, s[12:13]
	s_mov_b32 m0, s64
	s_nop 0
	global_load_lds_dwordx4 v[220:221], off
	s_waitcnt vmcnt(8)
	s_waitcnt lgkmcnt(0)
	s_barrier
	s_setprio 1
	s_waitcnt lgkmcnt(0)
	v_mfma_f32_16x16x32_bf16 v[60:63], v[152:155], v[184:187], v[60:63]
	v_mfma_f32_16x16x32_bf16 v[60:63], v[156:159], v[188:191], v[60:63]
	v_mfma_f32_16x16x32_bf16 v[56:59], v[164:167], v[188:191], v[56:59]
	v_mfma_f32_16x16x32_bf16 v[56:59], v[160:163], v[184:187], v[56:59]
	v_mfma_f32_16x16x32_bf16 v[52:55], v[168:171], v[184:187], v[52:55]
	v_mfma_f32_16x16x32_bf16 v[52:55], v[172:175], v[188:191], v[52:55]
	v_mfma_f32_16x16x32_bf16 v[48:51], v[180:183], v[188:191], v[48:51]
	v_mfma_f32_16x16x32_bf16 v[48:51], v[176:179], v[184:187], v[48:51]
	v_mfma_f32_16x16x32_bf16 v[32:35], v[176:179], v[192:195], v[32:35]
	v_mfma_f32_16x16x32_bf16 v[32:35], v[180:183], v[196:199], v[32:35]
	v_mfma_f32_16x16x32_bf16 v[36:39], v[172:175], v[196:199], v[36:39]
	v_mfma_f32_16x16x32_bf16 v[36:39], v[168:171], v[192:195], v[36:39]
	v_mfma_f32_16x16x32_bf16 v[40:43], v[160:163], v[192:195], v[40:43]
	v_mfma_f32_16x16x32_bf16 v[40:43], v[164:167], v[196:199], v[40:43]
	v_mfma_f32_16x16x32_bf16 v[44:47], v[156:159], v[196:199], v[44:47]
	v_mfma_f32_16x16x32_bf16 v[44:47], v[152:155], v[192:195], v[44:47]
	s_setprio 0
	s_setprio 1
	v_mfma_f32_16x16x32_bf16 v[28:31], v[152:155], v[200:203], v[28:31]
	v_mfma_f32_16x16x32_bf16 v[28:31], v[156:159], v[208:211], v[28:31]
	v_mfma_f32_16x16x32_bf16 v[24:27], v[164:167], v[208:211], v[24:27]
	v_mfma_f32_16x16x32_bf16 v[24:27], v[160:163], v[200:203], v[24:27]
	v_mfma_f32_16x16x32_bf16 v[20:23], v[168:171], v[200:203], v[20:23]
	v_mfma_f32_16x16x32_bf16 v[20:23], v[172:175], v[208:211], v[20:23]
	v_mfma_f32_16x16x32_bf16 v[16:19], v[180:183], v[208:211], v[16:19]
	v_mfma_f32_16x16x32_bf16 v[16:19], v[176:179], v[200:203], v[16:19]
	v_mfma_f32_16x16x32_bf16 v[0:3], v[176:179], v[212:215], v[0:3]
	v_mfma_f32_16x16x32_bf16 v[0:3], v[180:183], v[216:219], v[0:3]
	v_mfma_f32_16x16x32_bf16 v[4:7], v[172:175], v[216:219], v[4:7]
	v_mfma_f32_16x16x32_bf16 v[4:7], v[168:171], v[212:215], v[4:7]
	v_mfma_f32_16x16x32_bf16 v[8:11], v[160:163], v[212:215], v[8:11]
	v_mfma_f32_16x16x32_bf16 v[8:11], v[164:167], v[216:219], v[8:11]
	v_mfma_f32_16x16x32_bf16 v[12:15], v[156:159], v[216:219], v[12:15]
	v_mfma_f32_16x16x32_bf16 v[12:15], v[152:155], v[212:215], v[12:15]
	s_setprio 0
	s_barrier
	s_add_u32 s44, s44, 0x100
	s_addc_u32 s45, s45, 0
	s_add_u32 s79, s79, 0x100
	s_addc_u32 s82, s82, 0
	s_cmp_ge_i32 s83, s61
	s_mov_b32 s46, s83
	s_cbranch_scc0 .LBB0_1161

; #define PG8_STAGE(bufoff, gbase, voff) do { _Pragma("unroll") for (int _i = 0; _i < 2; ++_i) \
;         __builtin_amdgcn_global_load_lds((const unsigned*)((const char*)(gbase) + (voff)[_i]), (LAS unsigned*)(lds + (bufoff) + ldsw + _i * 8192), 16, 0, 0); } while (0)
; #define PG8_WAIT_V(n) asm volatile("s_waitcnt vmcnt(" #n ")" ::: "memory")
; #define PG8_BAR __builtin_amdgcn_s_barrier()
; template <class Epi>
; __device__ __forceinline__ void gemm_phase(LAS unsigned char* lds, const Gemm g, const StaticOrder& S, const Epi& E) {
;     ...
;     for (int i = 0; i < 2; ++i) { int R, C; stage_rc(tid * 16 + i * 8192, R, C); const int Rb = Epi::PERM ? ((R & ~31) + perm32(R & 31)) : R;
;         voffA[i] = (unsigned)(R * g.lda + C) * 2u; voffB[i] = (unsigned)(Rb * g.ldb + C) * 2u; }
;     const size_t kstep = (size_t)(BK * 2);
;     const size_t hstepA = (size_t)HALF * g.lda * 2, hstepB = (size_t)HALF * g.ldb * 2;
;     const size_t tstepA = 2 * hstepA, tstepB = 2 * hstepB;
;     const unsigned ldsw = (unsigned)wid * 1024u;
;     const int aoff = lds_byte(wr * 64 + fr, fq * 8), boff = lds_byte(wc * 32 + fr, fq * 8);
;     ...
;     Unit cur, nxt; int ui = 0;
;     if (!S.next(0, cur)) return;
;     f32x4 acc[2][2][4][2];
; #pragma unroll
;     for (int a = 0; a < 2; ++a)
; #pragma unroll
;         for (int b = 0; b < 2; ++b)
; #pragma unroll
;             for (int m = 0; m < 4; ++m)
; #pragma unroll
;                 for (int n = 0; n < 2; ++n) acc[a][b][m][n] = (f32x4){0.f, 0.f, 0.f, 0.f};
;     bf16x8 At[4][2], B0[2][2], B1[2][2];
;     const char* cA = (const char*)g.A + (size_t)cur.pm * tstepA; const char* cB = (const char*)g.Bt + (size_t)cur.pb * tstepB;
;     PG8_STAGE(PG8_SB(0, 0), cB, voffB); PG8_STAGE(PG8_SB(0, 1), cB + hstepB, voffB); PG8_STAGE(PG8_SA(0, 0), cA, voffA); PG8_STAGE(PG8_SA(0, 1), cA + hstepA, voffA);
;     if (wr == 1) PG8_BAR;
;     PG8_WAIT_V(2); PG8_BAR;
;     PG8_STAGE(PG8_SB(1, 0), cB + kstep, voffB); PG8_STAGE(PG8_SA(1, 0), cA + kstep, voffA); PG8_STAGE(PG8_SB(1, 1), cB + hstepB + kstep, voffB);
;     PG8_WAIT_V(6); PG8_BAR;
;     for (;;) {
;         const bool has_next = S.next(ui + 1, nxt);
;         const char* nA = has_next ? (const char*)g.A + (size_t)nxt.pm * tstepA : cA; const char* nB = has_next ? (const char*)g.Bt + (size_t)nxt.pb * tstepB : cB;
.LBB0_1229:
	s_ashr_i32 s12, s9, 31
	s_lshr_b32 s12, s12, 26
	s_add_i32 s12, s9, s12
	s_ashr_i32 s64, s12, 6
	s_lshl_b32 s12, s10, 6
	s_lshl_b32 s13, s10, 13
	s_lshl_b32 s10, s11, 5
	s_mov_b64 s[16:17], 0x80
	s_and_b32 s26, s10, 0x60
	s_add_i32 m0, s59, 0x18000
	v_lshl_add_u64 v[6:7], v[6:7], 0, s[16:17]
	s_lshl_b32 s18, s26, 7
	s_waitcnt vmcnt(2)
	s_barrier
	global_load_lds_dwordx4 v[6:7], off
	v_lshl_add_u64 v[4:5], v[4:5], 0, s[16:17]
	s_add_i32 m0, s59, 0x1a000
	s_add_i32 s65, s59, 0x8000
	s_add_i32 s66, s59, 0xa000
	global_load_lds_dwordx4 v[4:5], off
	v_lshl_add_u64 v[0:1], v[0:1], 0, s[16:17]
	s_mov_b32 m0, s65
	s_add_u32 s10, s52, 0x158080
	global_load_lds_dwordx4 v[0:1], off
	v_lshl_add_u64 v[0:1], v[2:3], 0, s[16:17]
	s_mov_b32 m0, s66
	s_addc_u32 s11, s53, 0
	global_load_lds_dwordx4 v[0:1], off
	s_add_i32 m0, s59, 0x1c000
	s_nop 0
	global_load_lds_dwordx4 v130, s[10:11]
	v_lshl_add_u64 v[0:1], s[10:11], 0, v[134:135]
	s_add_i32 m0, s59, 0x1e000
	v_and_b32_e32 v17, 15, v8
	global_load_lds_dwordx4 v[0:1], off
	v_bfe_u32 v3, v8, 4, 2
	v_lshlrev_b32_e32 v0, 4, v3
	v_lshlrev_b32_e32 v136, 2, v17
	v_lshl_or_b32 v0, v17, 6, v0
	v_and_b32_e32 v1, 32, v136
	s_cmp_gt_i32 s9, 63
	v_bitop3_b32 v186, v0, s18, v1 bitop3:0xde
	s_cselect_b64 s[18:19], -1, 0
	s_add_i32 s67, s64, -2
	s_cmpk_lt_u32 s8, 0x100
	v_bitop3_b32 v4, v0, s13, v1 bitop3:0xde
	s_cselect_b64 s[20:21], -1, 0
	s_ashr_i32 s13, s12, 31
	v_or_b32_e32 v0, s12, v17
	v_mov_b32_e32 v1, s13
	s_ashr_i32 s68, s94, 31
	s_lshl_b64 s[12:13], s[12:13], 2
	s_add_u32 s12, s24, s12
	v_lshlrev_b64 v[0:1], 12, v[0:1]
	v_lshl_or_b32 v2, v3, 3, s26
	s_addc_u32 s13, s25, s13
	v_lshl_add_u64 v[140:141], s[74:75], 0, v[0:1]
	v_lshrrev_b32_e32 v1, 1, v9
	v_mul_lo_u32 v0, v11, s1
	s_mov_b32 s26, 0x15800
	v_lshl_add_u64 v[138:139], s[12:13], 0, v[136:137]
	v_mad_u64_u32 v[0:1], s[12:13], v1, s26, v[0:1]
	v_or_b32_e32 v0, v0, v10
	v_add_lshl_u32 v136, v0, v12, 1
	v_lshrrev_b32_e32 v1, 1, v13
	v_mul_lo_u32 v0, v14, s1
	v_mad_u64_u32 v[0:1], s[12:13], v1, s26, v[0:1]
	s_mov_b64 s[10:11], 0x158080
	s_waitcnt vmcnt(6)
	v_or_b32_e32 v0, v0, v15
	v_lshl_add_u64 v[142:143], v[136:137], 0, s[10:11]
	v_add_lshl_u32 v136, v0, v16, 1
	s_add_i32 s70, 0, 0x10000
	s_add_i32 s71, 0, 0x14000
	v_cmp_eq_u32_e64 s[8:9], 0, v3
	s_mov_b32 s69, s94
	v_lshl_add_u64 v[144:145], v[136:137], 0, s[10:11]
	v_mov_b64_e32 v[146:147], 0x400
	v_mov_b64_e32 v[148:149], 0x3ff
	v_add_u32_e32 v187, s70, v186
	v_add_u32_e32 v188, s71, v186
	v_add_u32_e32 v189, 0, v4
	v_lshlrev_b32_e32 v136, 1, v2
	s_mov_b64 s[26:27], 0x30000
	s_mov_b32 s72, 0x30000
	s_mov_b64 s[28:29], 0x30100
	v_mbcnt_hi_u32_b32 v190, -1, v205
	s_mov_b64 s[30:31], 0x80000
	s_mov_b32 s73, 0x80000
	s_mov_b64 s[34:35], 0x80100
	s_mov_b64 s[36:37], 0x90000
	s_mov_b32 s76, 0x90000
	s_mov_b64 s[38:39], 0x90100
	s_mov_b64 s[40:41], 0xa0000
	s_mov_b32 s78, 0xa0000
	s_mov_b64 s[42:43], 0xa0100
	s_mov_b64 s[44:45], 0xb0000
	s_mov_b32 s79, 0xb0000
	s_mov_b64 s[46:47], 0xb0100
	s_barrier
	s_branch .LBB0_1232

; #define PG8_STAGE(bufoff, gbase, voff) do { _Pragma("unroll") for (int _i = 0; _i < 2; ++_i) \
;         __builtin_amdgcn_global_load_lds((const unsigned*)((const char*)(gbase) + (voff)[_i]), (LAS unsigned*)(lds + (bufoff) + ldsw + _i * 8192), 16, 0, 0); } while (0)
; #define PG8_LDA(dst, b, h) do { _Pragma("unroll") for (int m = 0; m < 4; ++m) _Pragma("unroll") for (int k = 0; k < 2; ++k) dst[m][k] = *(const LAS bf16x8*)(lds + PG8_SA(b, h) + aoff + m * 2048 + k * 1024); } while (0)
; #define PG8_LDB(dst, b, h) do { _Pragma("unroll") for (int n = 0; n < 2; ++n) _Pragma("unroll") for (int k = 0; k < 2; ++k) dst[n][k] = *(const LAS bf16x8*)(lds + PG8_SB(b, h) + boff + n * 2048 + k * 1024); } while (0)
; #define PG8_MMA(ai, bj, At, Bt) do { __builtin_amdgcn_s_setprio(1); _Pragma("unroll") for (int m = 0; m < 4; ++m) _Pragma("unroll") for (int n = 0; n < 2; ++n) _Pragma("unroll") for (int k = 0; k < 2; ++k) \
;         acc[ai][bj][m][n] = __builtin_amdgcn_mfma_f32_16x16x32_bf16(Bt[n][k], At[m][k], acc[ai][bj][m][n], 0, 0, 0); __builtin_amdgcn_s_setprio(0); } while (0)
; #define PG8_WAIT_V(n) asm volatile("s_waitcnt vmcnt(" #n ")" ::: "memory")
; #define PG8_WAIT_L(n) asm volatile("s_waitcnt lgkmcnt(" #n ")" ::: "memory")
; #define PG8_BAR __builtin_amdgcn_s_barrier()
; #define PG8_SCHED __builtin_amdgcn_sched_barrier(0)
; template <class Epi>
; __device__ __forceinline__ void gemm_phase(LAS unsigned char* lds, const Gemm g, const StaticOrder& S, const Epi& E) {
;     ...
;             const bool last = (t == nt - 2);
;             const char* a1 = cA + (size_t)(t + 1) * kstep;
;             const char* a2 = last ? nA : cA + (size_t)(t + 2) * kstep; const char* b2 = last ? nB : cB + (size_t)(t + 2) * kstep;
;             const char* a3 = a2 + kstep; const char* b3 = b2 + kstep;
;             PG8_LDB(B0, 0, 0); PG8_LDB(B1, 0, 1); PG8_SCHED; PG8_LDA(At, 0, 0); PG8_STAGE(PG8_SA(1, 1), a1 + hstepA, voffA);
;             PG8_WAIT_V(8); PG8_WAIT_L(0); PG8_BAR; PG8_MMA(0, 0, At, B0); PG8_MMA(0, 1, At, B1); PG8_BAR; PG8_SCHED;
;             PG8_LDA(At, 0, 1); PG8_STAGE(PG8_SB(0, 0), b2, voffB); PG8_STAGE(PG8_SB(0, 1), b2 + hstepB, voffB); PG8_STAGE(PG8_SA(0, 0), a2, voffA);
.LBB0_1244:
	ds_read_b128 v[150:153], v187
	ds_read_b128 v[154:157], v187 offset:1024
	ds_read_b128 v[158:161], v187 offset:2048
	ds_read_b128 v[162:165], v187 offset:3072
	ds_read_b128 v[166:169], v188
	ds_read_b128 v[170:173], v188 offset:1024
	ds_read_b128 v[174:177], v188 offset:2048
	ds_read_b128 v[178:181], v188 offset:3072
	s_add_i32 s84, s52, 2
	s_add_u32 s12, s4, 0x100
	s_addc_u32 s13, s5, 0
	s_cmp_eq_u32 s67, s52
	s_cselect_b32 s52, s50, s1
	s_cselect_b32 s55, s49, s13
	s_cselect_b32 s54, s48, s12
	s_cselect_b32 s53, s51, s77
	v_lshl_add_u64 v[224:225], s[4:5], 0, v[142:143]
	s_add_i32 m0, s59, 0xc000
	ds_read_b128 v[182:185], v189
	ds_read_b128 v[192:195], v189 offset:1024
	ds_read_b128 v[196:199], v189 offset:2048
	ds_read_b128 v[200:203], v189 offset:3072
	ds_read_b128 v[208:211], v189 offset:4096
	ds_read_b128 v[212:215], v189 offset:5120
	ds_read_b128 v[216:219], v189 offset:6144
	ds_read_b128 v[220:223], v189 offset:7168
	global_load_lds_dwordx4 v[224:225], off
	v_lshl_add_u64 v[224:225], s[4:5], 0, v[144:145]
	s_add_i32 m0, s59, 0xe000
	s_nop 0
	global_load_lds_dwordx4 v[224:225], off
	s_waitcnt vmcnt(8)
	s_waitcnt lgkmcnt(0)
	s_barrier
	s_setprio 1
	s_waitcnt lgkmcnt(0)
	v_mfma_f32_16x16x32_bf16 v[124:127], v[150:153], v[182:185], v[124:127]
	v_mfma_f32_16x16x32_bf16 v[124:127], v[154:157], v[192:195], v[124:127]
	v_mfma_f32_16x16x32_bf16 v[120:123], v[162:165], v[192:195], v[120:123]
	v_mfma_f32_16x16x32_bf16 v[120:123], v[158:161], v[182:185], v[120:123]
	v_mfma_f32_16x16x32_bf16 v[108:111], v[166:169], v[182:185], v[108:111]
	v_mfma_f32_16x16x32_bf16 v[108:111], v[170:173], v[192:195], v[108:111]
	v_mfma_f32_16x16x32_bf16 v[100:103], v[178:181], v[192:195], v[100:103]
	v_mfma_f32_16x16x32_bf16 v[100:103], v[174:177], v[182:185], v[100:103]
	v_mfma_f32_16x16x32_bf16 v[84:87], v[174:177], v[196:199], v[84:87]
	v_mfma_f32_16x16x32_bf16 v[84:87], v[178:181], v[200:203], v[84:87]
	v_mfma_f32_16x16x32_bf16 v[92:95], v[170:173], v[200:203], v[92:95]
	v_mfma_f32_16x16x32_bf16 v[92:95], v[166:169], v[196:199], v[92:95]
	v_mfma_f32_16x16x32_bf16 v[112:115], v[158:161], v[196:199], v[112:115]
	v_mfma_f32_16x16x32_bf16 v[112:115], v[162:165], v[200:203], v[112:115]
	v_mfma_f32_16x16x32_bf16 v[116:119], v[154:157], v[200:203], v[116:119]
	v_mfma_f32_16x16x32_bf16 v[116:119], v[150:153], v[196:199], v[116:119]
	s_setprio 0
	s_setprio 1
	v_mfma_f32_16x16x32_bf16 v[104:107], v[150:153], v[208:211], v[104:107]
	v_mfma_f32_16x16x32_bf16 v[104:107], v[154:157], v[212:215], v[104:107]
	v_mfma_f32_16x16x32_bf16 v[96:99], v[162:165], v[212:215], v[96:99]
	v_mfma_f32_16x16x32_bf16 v[96:99], v[158:161], v[208:211], v[96:99]
	v_mfma_f32_16x16x32_bf16 v[76:79], v[166:169], v[208:211], v[76:79]
	v_mfma_f32_16x16x32_bf16 v[76:79], v[170:173], v[212:215], v[76:79]
	v_mfma_f32_16x16x32_bf16 v[72:75], v[178:181], v[212:215], v[72:75]
	v_mfma_f32_16x16x32_bf16 v[72:75], v[174:177], v[208:211], v[72:75]
	v_mfma_f32_16x16x32_bf16 v[64:67], v[174:177], v[216:219], v[64:67]
	v_mfma_f32_16x16x32_bf16 v[64:67], v[178:181], v[220:223], v[64:67]
	v_mfma_f32_16x16x32_bf16 v[68:71], v[170:173], v[220:223], v[68:71]
	v_mfma_f32_16x16x32_bf16 v[68:71], v[166:169], v[216:219], v[68:71]
	v_mfma_f32_16x16x32_bf16 v[80:83], v[158:161], v[216:219], v[80:83]
	v_mfma_f32_16x16x32_bf16 v[80:83], v[162:165], v[220:223], v[80:83]
	v_mfma_f32_16x16x32_bf16 v[88:91], v[154:157], v[220:223], v[88:91]
	v_mfma_f32_16x16x32_bf16 v[88:91], v[150:153], v[216:219], v[88:91]
	s_setprio 0
	s_barrier
	s_add_i32 s4, s70, s58
	v_lshl_add_u64 v[224:225], s[52:53], 0, v[130:131]
	s_mov_b32 m0, s4
	ds_read_b128 v[182:185], v189 offset:16384
	ds_read_b128 v[192:195], v189 offset:17408
	ds_read_b128 v[196:199], v189 offset:18432
	ds_read_b128 v[200:203], v189 offset:19456
	ds_read_b128 v[208:211], v189 offset:20480
	ds_read_b128 v[212:215], v189 offset:21504
	ds_read_b128 v[216:219], v189 offset:22528
	ds_read_b128 v[220:223], v189 offset:23552
	global_load_lds_dwordx4 v[224:225], off
	s_add_i32 m0, s4, 0x2000
	s_add_u32 s4, s52, 0x158000
	v_lshl_add_u64 v[226:227], s[52:53], 0, v[134:135]
	s_addc_u32 s5, s53, 0
	s_add_i32 s85, s71, s58
	global_load_lds_dwordx4 v[226:227], off
	s_mov_b32 m0, s85
	v_lshl_add_u64 v[232:233], s[54:55], 0, v[132:133]
	global_load_lds_dwordx4 v130, s[4:5]
	s_add_i32 m0, s85, 0x2000
	s_nop 0
	global_load_lds_dwordx4 v134, s[4:5]
	v_lshl_add_u64 v[230:231], s[54:55], 0, v[128:129]
	s_mov_b32 m0, s59
	s_nop 0
	global_load_lds_dwordx4 v[230:231], off
	s_mov_b32 m0, s60
	s_nop 0
	global_load_lds_dwordx4 v[232:233], off
	s_waitcnt vmcnt(8)
	s_waitcnt lgkmcnt(0)
	s_barrier
; #define PG8_STAGE(bufoff, gbase, voff) do { _Pragma("unroll") for (int _i = 0; _i < 2; ++_i) \
;         __builtin_amdgcn_global_load_lds((const unsigned*)((const char*)(gbase) + (voff)[_i]), (LAS unsigned*)(lds + (bufoff) + ldsw + _i * 8192), 16, 0, 0); } while (0)
; #define PG8_LDA(dst, b, h) do { _Pragma("unroll") for (int m = 0; m < 4; ++m) _Pragma("unroll") for (int k = 0; k < 2; ++k) dst[m][k] = *(const LAS bf16x8*)(lds + PG8_SA(b, h) + aoff + m * 2048 + k * 1024); } while (0)
; #define PG8_LDB(dst, b, h) do { _Pragma("unroll") for (int n = 0; n < 2; ++n) _Pragma("unroll") for (int k = 0; k < 2; ++k) dst[n][k] = *(const LAS bf16x8*)(lds + PG8_SB(b, h) + boff + n * 2048 + k * 1024); } while (0)
; #define PG8_MMA(ai, bj, At, Bt) do { __builtin_amdgcn_s_setprio(1); _Pragma("unroll") for (int m = 0; m < 4; ++m) _Pragma("unroll") for (int n = 0; n < 2; ++n) _Pragma("unroll") for (int k = 0; k < 2; ++k) \
;         acc[ai][bj][m][n] = __builtin_amdgcn_mfma_f32_16x16x32_bf16(Bt[n][k], At[m][k], acc[ai][bj][m][n], 0, 0, 0); __builtin_amdgcn_s_setprio(0); } while (0)
; #define PG8_WAIT_V(n) asm volatile("s_waitcnt vmcnt(" #n ")" ::: "memory")
; #define PG8_WAIT_L(n) asm volatile("s_waitcnt lgkmcnt(" #n ")" ::: "memory")
; #define PG8_BAR __builtin_amdgcn_s_barrier()
; #define PG8_SCHED __builtin_amdgcn_sched_barrier(0)
; template <class Epi>
; __device__ __forceinline__ void gemm_phase(LAS unsigned char* lds, const Gemm g, const StaticOrder& S, const Epi& E) {
;     ...
;             PG8_WAIT_V(8); PG8_WAIT_L(0); PG8_BAR; PG8_MMA(1, 0, At, B0); PG8_MMA(1, 1, At, B1); PG8_BAR; PG8_SCHED;
;             PG8_LDB(B0, 1, 0); PG8_LDB(B1, 1, 1); PG8_SCHED; PG8_LDA(At, 1, 0); PG8_STAGE(PG8_SA(0, 1), a2 + hstepA, voffA);
;             PG8_WAIT_V(8); PG8_WAIT_L(0); PG8_BAR; PG8_MMA(0, 0, At, B0); PG8_MMA(0, 1, At, B1); PG8_BAR; PG8_SCHED;
	s_setprio 1
	s_waitcnt lgkmcnt(0)
	v_mfma_f32_16x16x32_bf16 v[60:63], v[150:153], v[182:185], v[60:63]
	v_mfma_f32_16x16x32_bf16 v[60:63], v[154:157], v[192:195], v[60:63]
	v_mfma_f32_16x16x32_bf16 v[56:59], v[162:165], v[192:195], v[56:59]
	v_mfma_f32_16x16x32_bf16 v[56:59], v[158:161], v[182:185], v[56:59]
	v_mfma_f32_16x16x32_bf16 v[44:47], v[166:169], v[182:185], v[44:47]
	v_mfma_f32_16x16x32_bf16 v[44:47], v[170:173], v[192:195], v[44:47]
	v_mfma_f32_16x16x32_bf16 v[36:39], v[178:181], v[192:195], v[36:39]
	v_mfma_f32_16x16x32_bf16 v[36:39], v[174:177], v[182:185], v[36:39]
	v_mfma_f32_16x16x32_bf16 v[20:23], v[174:177], v[196:199], v[20:23]
	v_mfma_f32_16x16x32_bf16 v[20:23], v[178:181], v[200:203], v[20:23]
	v_mfma_f32_16x16x32_bf16 v[28:31], v[170:173], v[200:203], v[28:31]
	v_mfma_f32_16x16x32_bf16 v[28:31], v[166:169], v[196:199], v[28:31]
	v_mfma_f32_16x16x32_bf16 v[48:51], v[158:161], v[196:199], v[48:51]
	v_mfma_f32_16x16x32_bf16 v[48:51], v[162:165], v[200:203], v[48:51]
	v_mfma_f32_16x16x32_bf16 v[52:55], v[154:157], v[200:203], v[52:55]
	v_mfma_f32_16x16x32_bf16 v[52:55], v[150:153], v[196:199], v[52:55]
	s_setprio 0
	s_setprio 1
	v_mfma_f32_16x16x32_bf16 v[40:43], v[150:153], v[208:211], v[40:43]
	v_mfma_f32_16x16x32_bf16 v[40:43], v[154:157], v[212:215], v[40:43]
	v_mfma_f32_16x16x32_bf16 v[32:35], v[162:165], v[212:215], v[32:35]
	v_mfma_f32_16x16x32_bf16 v[32:35], v[158:161], v[208:211], v[32:35]
	v_mfma_f32_16x16x32_bf16 v[12:15], v[166:169], v[208:211], v[12:15]
	v_mfma_f32_16x16x32_bf16 v[12:15], v[170:173], v[212:215], v[12:15]
	v_mfma_f32_16x16x32_bf16 v[8:11], v[178:181], v[212:215], v[8:11]
	v_mfma_f32_16x16x32_bf16 v[8:11], v[174:177], v[208:211], v[8:11]
	v_mfma_f32_16x16x32_bf16 v[0:3], v[174:177], v[216:219], v[0:3]
	v_mfma_f32_16x16x32_bf16 v[0:3], v[178:181], v[220:223], v[0:3]
	v_mfma_f32_16x16x32_bf16 v[4:7], v[170:173], v[220:223], v[4:7]
	v_mfma_f32_16x16x32_bf16 v[4:7], v[166:169], v[216:219], v[4:7]
	v_mfma_f32_16x16x32_bf16 v[16:19], v[158:161], v[216:219], v[16:19]
	v_mfma_f32_16x16x32_bf16 v[16:19], v[162:165], v[220:223], v[16:19]
	v_mfma_f32_16x16x32_bf16 v[24:27], v[154:157], v[220:223], v[24:27]
	v_mfma_f32_16x16x32_bf16 v[24:27], v[150:153], v[216:219], v[24:27]
	s_setprio 0
	s_barrier
	s_add_i32 s85, 0, 0x18000
	s_add_i32 s86, 0, 0x1c000
	v_add_u32_e32 v162, s85, v186
	v_add_u32_e32 v178, s86, v186
	ds_read_b128 v[150:153], v162
	ds_read_b128 v[154:157], v162 offset:1024
	ds_read_b128 v[158:161], v162 offset:2048
	ds_read_b128 v[162:165], v162 offset:3072
	ds_read_b128 v[166:169], v178
	ds_read_b128 v[170:173], v178 offset:1024
	ds_read_b128 v[174:177], v178 offset:2048
	ds_read_b128 v[178:181], v178 offset:3072
	s_add_u32 s4, s54, 0x158000
	s_addc_u32 s5, s55, 0
	s_mov_b32 m0, s61
	ds_read_b128 v[182:185], v189 offset:32768
	ds_read_b128 v[192:195], v189 offset:33792
	ds_read_b128 v[196:199], v189 offset:34816
	ds_read_b128 v[200:203], v189 offset:35840
	ds_read_b128 v[208:211], v189 offset:36864
	ds_read_b128 v[212:215], v189 offset:37888
	ds_read_b128 v[216:219], v189 offset:38912
	ds_read_b128 v[220:223], v189 offset:39936
	global_load_lds_dwordx4 v128, s[4:5]
	s_mov_b32 m0, s62
	s_nop 0
	global_load_lds_dwordx4 v132, s[4:5]
	s_waitcnt vmcnt(8)
	s_waitcnt lgkmcnt(0)
	s_barrier
	s_setprio 1
	s_waitcnt lgkmcnt(0)
	v_mfma_f32_16x16x32_bf16 v[124:127], v[150:153], v[182:185], v[124:127]
	v_mfma_f32_16x16x32_bf16 v[124:127], v[154:157], v[192:195], v[124:127]
	v_mfma_f32_16x16x32_bf16 v[120:123], v[162:165], v[192:195], v[120:123]
	v_mfma_f32_16x16x32_bf16 v[120:123], v[158:161], v[182:185], v[120:123]
	v_mfma_f32_16x16x32_bf16 v[108:111], v[166:169], v[182:185], v[108:111]
	v_mfma_f32_16x16x32_bf16 v[108:111], v[170:173], v[192:195], v[108:111]
	v_mfma_f32_16x16x32_bf16 v[100:103], v[178:181], v[192:195], v[100:103]
	v_mfma_f32_16x16x32_bf16 v[100:103], v[174:177], v[182:185], v[100:103]
	v_mfma_f32_16x16x32_bf16 v[84:87], v[174:177], v[196:199], v[84:87]
	v_mfma_f32_16x16x32_bf16 v[84:87], v[178:181], v[200:203], v[84:87]
	v_mfma_f32_16x16x32_bf16 v[92:95], v[170:173], v[200:203], v[92:95]
	v_mfma_f32_16x16x32_bf16 v[92:95], v[166:169], v[196:199], v[92:95]
	v_mfma_f32_16x16x32_bf16 v[112:115], v[158:161], v[196:199], v[112:115]
	v_mfma_f32_16x16x32_bf16 v[112:115], v[162:165], v[200:203], v[112:115]
	v_mfma_f32_16x16x32_bf16 v[116:119], v[154:157], v[200:203], v[116:119]
	v_mfma_f32_16x16x32_bf16 v[116:119], v[150:153], v[196:199], v[116:119]
	s_setprio 0
	s_setprio 1
	v_mfma_f32_16x16x32_bf16 v[104:107], v[150:153], v[208:211], v[104:107]
	v_mfma_f32_16x16x32_bf16 v[104:107], v[154:157], v[212:215], v[104:107]
	v_mfma_f32_16x16x32_bf16 v[96:99], v[162:165], v[212:215], v[96:99]
	v_mfma_f32_16x16x32_bf16 v[96:99], v[158:161], v[208:211], v[96:99]
	v_mfma_f32_16x16x32_bf16 v[76:79], v[166:169], v[208:211], v[76:79]
	v_mfma_f32_16x16x32_bf16 v[76:79], v[170:173], v[212:215], v[76:79]
	v_mfma_f32_16x16x32_bf16 v[72:75], v[178:181], v[212:215], v[72:75]
	v_mfma_f32_16x16x32_bf16 v[72:75], v[174:177], v[208:211], v[72:75]
	v_mfma_f32_16x16x32_bf16 v[64:67], v[174:177], v[216:219], v[64:67]
	v_mfma_f32_16x16x32_bf16 v[64:67], v[178:181], v[220:223], v[64:67]
	v_mfma_f32_16x16x32_bf16 v[68:71], v[170:173], v[220:223], v[68:71]
	v_mfma_f32_16x16x32_bf16 v[68:71], v[166:169], v[216:219], v[68:71]
	v_mfma_f32_16x16x32_bf16 v[80:83], v[158:161], v[216:219], v[80:83]
	v_mfma_f32_16x16x32_bf16 v[80:83], v[162:165], v[220:223], v[80:83]
	v_mfma_f32_16x16x32_bf16 v[88:91], v[154:157], v[220:223], v[88:91]
	v_mfma_f32_16x16x32_bf16 v[88:91], v[150:153], v[216:219], v[88:91]
	s_setprio 0
	s_barrier
; #define PG8_STAGE(bufoff, gbase, voff) do { _Pragma("unroll") for (int _i = 0; _i < 2; ++_i) \
;         __builtin_amdgcn_global_load_lds((const unsigned*)((const char*)(gbase) + (voff)[_i]), (LAS unsigned*)(lds + (bufoff) + ldsw + _i * 8192), 16, 0, 0); } while (0)
; #define PG8_LDA(dst, b, h) do { _Pragma("unroll") for (int m = 0; m < 4; ++m) _Pragma("unroll") for (int k = 0; k < 2; ++k) dst[m][k] = *(const LAS bf16x8*)(lds + PG8_SA(b, h) + aoff + m * 2048 + k * 1024); } while (0)
; #define PG8_MMA(ai, bj, At, Bt) do { __builtin_amdgcn_s_setprio(1); _Pragma("unroll") for (int m = 0; m < 4; ++m) _Pragma("unroll") for (int n = 0; n < 2; ++n) _Pragma("unroll") for (int k = 0; k < 2; ++k) \
;         acc[ai][bj][m][n] = __builtin_amdgcn_mfma_f32_16x16x32_bf16(Bt[n][k], At[m][k], acc[ai][bj][m][n], 0, 0, 0); __builtin_amdgcn_s_setprio(0); } while (0)
; #define PG8_WAIT_V(n) asm volatile("s_waitcnt vmcnt(" #n ")" ::: "memory")
; #define PG8_WAIT_L(n) asm volatile("s_waitcnt lgkmcnt(" #n ")" ::: "memory")
; #define PG8_BAR __builtin_amdgcn_s_barrier()
; #define PG8_SCHED __builtin_amdgcn_sched_barrier(0)
; template <class Epi>
; __device__ __forceinline__ void gemm_phase(LAS unsigned char* lds, const Gemm g, const StaticOrder& S, const Epi& E) {
;     ...
;         for (int t = 0; t < nt; t += 2) {
;             const bool last = (t == nt - 2);
;             const char* a1 = cA + (size_t)(t + 1) * kstep;
;             const char* a2 = last ? nA : cA + (size_t)(t + 2) * kstep; const char* b2 = last ? nB : cB + (size_t)(t + 2) * kstep;
;             const char* a3 = a2 + kstep; const char* b3 = b2 + kstep;
;     ...
;             PG8_LDA(At, 1, 1); PG8_STAGE(PG8_SB(1, 0), b3, voffB); PG8_STAGE(PG8_SB(1, 1), b3 + hstepB, voffB); PG8_STAGE(PG8_SA(1, 0), a3, voffA);
;             PG8_WAIT_V(8); PG8_WAIT_L(0); PG8_BAR; PG8_MMA(1, 0, At, B0); PG8_MMA(1, 1, At, B1); PG8_BAR; PG8_SCHED;
;         }
	s_add_i32 s4, s85, s58
	v_lshl_add_u64 v[224:225], v[224:225], 0, s[16:17]
	s_mov_b32 m0, s4
	ds_read_b128 v[182:185], v189 offset:49152
	ds_read_b128 v[192:195], v189 offset:50176
	ds_read_b128 v[196:199], v189 offset:51200
	ds_read_b128 v[200:203], v189 offset:52224
	ds_read_b128 v[208:211], v189 offset:53248
	ds_read_b128 v[212:215], v189 offset:54272
	ds_read_b128 v[216:219], v189 offset:55296
	ds_read_b128 v[220:223], v189 offset:56320
	global_load_lds_dwordx4 v[224:225], off
	s_add_i32 m0, s4, 0x2000
	s_add_u32 s4, s52, 0x158080
	v_lshl_add_u64 v[224:225], v[226:227], 0, s[16:17]
	s_addc_u32 s5, s53, 0
	s_add_i32 s52, s86, s58
	global_load_lds_dwordx4 v[224:225], off
	s_mov_b32 m0, s52
	s_nop 0
	global_load_lds_dwordx4 v130, s[4:5]
	s_add_i32 m0, s52, 0x2000
	s_nop 0
	global_load_lds_dwordx4 v134, s[4:5]
	v_lshl_add_u64 v[224:225], v[230:231], 0, s[16:17]
	s_mov_b32 m0, s65
	s_nop 0
	global_load_lds_dwordx4 v[224:225], off
	v_lshl_add_u64 v[224:225], v[232:233], 0, s[16:17]
	s_mov_b32 m0, s66
	s_nop 0
	global_load_lds_dwordx4 v[224:225], off
	s_waitcnt vmcnt(8)
	s_waitcnt lgkmcnt(0)
	s_barrier
	s_setprio 1
	s_waitcnt lgkmcnt(0)
	v_mfma_f32_16x16x32_bf16 v[60:63], v[150:153], v[182:185], v[60:63]
	v_mfma_f32_16x16x32_bf16 v[60:63], v[154:157], v[192:195], v[60:63]
	v_mfma_f32_16x16x32_bf16 v[56:59], v[162:165], v[192:195], v[56:59]
	v_mfma_f32_16x16x32_bf16 v[56:59], v[158:161], v[182:185], v[56:59]
	v_mfma_f32_16x16x32_bf16 v[44:47], v[166:169], v[182:185], v[44:47]
	v_mfma_f32_16x16x32_bf16 v[44:47], v[170:173], v[192:195], v[44:47]
	v_mfma_f32_16x16x32_bf16 v[36:39], v[178:181], v[192:195], v[36:39]
	v_mfma_f32_16x16x32_bf16 v[36:39], v[174:177], v[182:185], v[36:39]
	v_mfma_f32_16x16x32_bf16 v[20:23], v[174:177], v[196:199], v[20:23]
	v_mfma_f32_16x16x32_bf16 v[20:23], v[178:181], v[200:203], v[20:23]
	v_mfma_f32_16x16x32_bf16 v[28:31], v[170:173], v[200:203], v[28:31]
	v_mfma_f32_16x16x32_bf16 v[28:31], v[166:169], v[196:199], v[28:31]
	v_mfma_f32_16x16x32_bf16 v[48:51], v[158:161], v[196:199], v[48:51]
	v_mfma_f32_16x16x32_bf16 v[48:51], v[162:165], v[200:203], v[48:51]
	v_mfma_f32_16x16x32_bf16 v[52:55], v[154:157], v[200:203], v[52:55]
	v_mfma_f32_16x16x32_bf16 v[52:55], v[150:153], v[196:199], v[52:55]
	s_setprio 0
	s_setprio 1
	v_mfma_f32_16x16x32_bf16 v[40:43], v[150:153], v[208:211], v[40:43]
	v_mfma_f32_16x16x32_bf16 v[40:43], v[154:157], v[212:215], v[40:43]
	v_mfma_f32_16x16x32_bf16 v[32:35], v[162:165], v[212:215], v[32:35]
	v_mfma_f32_16x16x32_bf16 v[32:35], v[158:161], v[208:211], v[32:35]
	v_mfma_f32_16x16x32_bf16 v[12:15], v[166:169], v[208:211], v[12:15]
	v_mfma_f32_16x16x32_bf16 v[12:15], v[170:173], v[212:215], v[12:15]
	v_mfma_f32_16x16x32_bf16 v[8:11], v[178:181], v[212:215], v[8:11]
	v_mfma_f32_16x16x32_bf16 v[8:11], v[174:177], v[208:211], v[8:11]
	v_mfma_f32_16x16x32_bf16 v[0:3], v[174:177], v[216:219], v[0:3]
	v_mfma_f32_16x16x32_bf16 v[0:3], v[178:181], v[220:223], v[0:3]
	v_mfma_f32_16x16x32_bf16 v[4:7], v[170:173], v[220:223], v[4:7]
	v_mfma_f32_16x16x32_bf16 v[4:7], v[166:169], v[216:219], v[4:7]
	v_mfma_f32_16x16x32_bf16 v[16:19], v[158:161], v[216:219], v[16:19]
	v_mfma_f32_16x16x32_bf16 v[16:19], v[162:165], v[220:223], v[16:19]
	v_mfma_f32_16x16x32_bf16 v[24:27], v[154:157], v[220:223], v[24:27]
	v_mfma_f32_16x16x32_bf16 v[24:27], v[150:153], v[216:219], v[24:27]
	s_setprio 0
	s_barrier
	s_add_u32 s1, s1, 0x100
	s_addc_u32 s77, s77, 0
	s_cmp_ge_i32 s84, s64
	s_mov_b64 s[4:5], s[12:13]
	s_mov_b32 s52, s84
	s_cbranch_scc0 .LBB0_1244
;     __device__ __forceinline__ void operator()(Acc& acc, const Unit& u, int wr, int wc, int fr, int fq) const {
;         const size_t off0 = ((size_t)u.pm * BM + wr * 64 + fr) * DM + u.pn * BM + wc * 32 + 8 * fq;
;         u32x4 pa[2][2], pb[2][2];
	v_pk_mul_f32 v[170:171], v[126:127], 0.5 op_sel_hi:[1,0]
	v_pk_mul_f32 v[172:173], v[124:125], 0.5 op_sel_hi:[1,0]
	v_pk_mul_f32 v[174:175], v[122:123], 0.5 op_sel_hi:[1,0]
	v_pk_mul_f32 v[176:177], v[120:121], 0.5 op_sel_hi:[1,0]
	v_pk_mul_f32 v[178:179], v[110:111], 0.5 op_sel_hi:[1,0]
	v_pk_mul_f32 v[180:181], v[108:109], 0.5 op_sel_hi:[1,0]
	v_pk_mul_f32 v[182:183], v[102:103], 0.5 op_sel_hi:[1,0]
	v_pk_mul_f32 v[184:185], v[100:101], 0.5 op_sel_hi:[1,0]
	v_pk_mul_f32 v[160:161], v[118:119], 0.5 op_sel_hi:[1,0]
	v_pk_mul_f32 v[158:159], v[116:117], 0.5 op_sel_hi:[1,0]
	v_pk_mul_f32 v[156:157], v[114:115], 0.5 op_sel_hi:[1,0]
	v_pk_mul_f32 v[154:155], v[112:113], 0.5 op_sel_hi:[1,0]
	v_pk_mul_f32 v[168:169], v[94:95], 0.5 op_sel_hi:[1,0]
	v_pk_mul_f32 v[166:167], v[92:93], 0.5 op_sel_hi:[1,0]
	v_pk_mul_f32 v[164:165], v[86:87], 0.5 op_sel_hi:[1,0]
	v_pk_mul_f32 v[162:163], v[84:85], 0.5 op_sel_hi:[1,0]
	v_pk_mul_f32 v[116:117], v[106:107], 0.5 op_sel_hi:[1,0]
	v_pk_mul_f32 v[118:119], v[104:105], 0.5 op_sel_hi:[1,0]
	v_pk_mul_f32 v[120:121], v[98:99], 0.5 op_sel_hi:[1,0]
	v_pk_mul_f32 v[122:123], v[96:97], 0.5 op_sel_hi:[1,0]
	v_pk_mul_f32 v[124:125], v[78:79], 0.5 op_sel_hi:[1,0]
	v_pk_mul_f32 v[126:127], v[76:77], 0.5 op_sel_hi:[1,0]
	v_pk_mul_f32 v[150:151], v[74:75], 0.5 op_sel_hi:[1,0]
	v_pk_mul_f32 v[152:153], v[72:73], 0.5 op_sel_hi:[1,0]
	v_pk_mul_f32 v[104:105], v[90:91], 0.5 op_sel_hi:[1,0]
	v_pk_mul_f32 v[102:103], v[88:89], 0.5 op_sel_hi:[1,0]
	v_pk_mul_f32 v[100:101], v[82:83], 0.5 op_sel_hi:[1,0]
	v_pk_mul_f32 v[98:99], v[80:81], 0.5 op_sel_hi:[1,0]
	v_pk_mul_f32 v[112:113], v[70:71], 0.5 op_sel_hi:[1,0]
	v_pk_mul_f32 v[110:111], v[68:69], 0.5 op_sel_hi:[1,0]
	v_pk_mul_f32 v[108:109], v[66:67], 0.5 op_sel_hi:[1,0]
	v_pk_mul_f32 v[106:107], v[64:65], 0.5 op_sel_hi:[1,0]
	v_pk_mul_f32 v[80:81], v[62:63], 0.5 op_sel_hi:[1,0]
	v_pk_mul_f32 v[82:83], v[60:61], 0.5 op_sel_hi:[1,0]
	v_pk_mul_f32 v[84:85], v[58:59], 0.5 op_sel_hi:[1,0]
	v_pk_mul_f32 v[86:87], v[56:57], 0.5 op_sel_hi:[1,0]
	v_pk_mul_f32 v[88:89], v[46:47], 0.5 op_sel_hi:[1,0]
	v_pk_mul_f32 v[90:91], v[44:45], 0.5 op_sel_hi:[1,0]
	v_pk_mul_f32 v[92:93], v[38:39], 0.5 op_sel_hi:[1,0]
	v_pk_mul_f32 v[94:95], v[36:37], 0.5 op_sel_hi:[1,0]
	v_pk_mul_f32 v[70:71], v[54:55], 0.5 op_sel_hi:[1,0]
	v_pk_mul_f32 v[68:69], v[52:53], 0.5 op_sel_hi:[1,0]
	v_pk_mul_f32 v[66:67], v[50:51], 0.5 op_sel_hi:[1,0]
	v_pk_mul_f32 v[64:65], v[48:49], 0.5 op_sel_hi:[1,0]
	v_pk_mul_f32 v[78:79], v[30:31], 0.5 op_sel_hi:[1,0]
	v_pk_mul_f32 v[76:77], v[28:29], 0.5 op_sel_hi:[1,0]
	v_pk_mul_f32 v[74:75], v[22:23], 0.5 op_sel_hi:[1,0]
	v_pk_mul_f32 v[72:73], v[20:21], 0.5 op_sel_hi:[1,0]
	v_pk_mul_f32 v[54:55], v[42:43], 0.5 op_sel_hi:[1,0]
	v_pk_mul_f32 v[52:53], v[40:41], 0.5 op_sel_hi:[1,0]
	v_pk_mul_f32 v[50:51], v[34:35], 0.5 op_sel_hi:[1,0]
	v_pk_mul_f32 v[48:49], v[32:33], 0.5 op_sel_hi:[1,0]
	v_pk_mul_f32 v[62:63], v[14:15], 0.5 op_sel_hi:[1,0]
	v_pk_mul_f32 v[60:61], v[12:13], 0.5 op_sel_hi:[1,0]
	v_pk_mul_f32 v[58:59], v[10:11], 0.5 op_sel_hi:[1,0]
	v_pk_mul_f32 v[56:57], v[8:9], 0.5 op_sel_hi:[1,0]
	v_pk_mul_f32 v[38:39], v[26:27], 0.5 op_sel_hi:[1,0]
	v_pk_mul_f32 v[36:37], v[24:25], 0.5 op_sel_hi:[1,0]
	v_pk_mul_f32 v[34:35], v[18:19], 0.5 op_sel_hi:[1,0]
	v_pk_mul_f32 v[32:33], v[16:17], 0.5 op_sel_hi:[1,0]
	v_pk_mul_f32 v[46:47], v[6:7], 0.5 op_sel_hi:[1,0]
	v_pk_mul_f32 v[44:45], v[4:5], 0.5 op_sel_hi:[1,0]
	v_pk_mul_f32 v[42:43], v[2:3], 0.5 op_sel_hi:[1,0]
	v_pk_mul_f32 v[40:41], v[0:1], 0.5 op_sel_hi:[1,0]

; #define PG8_STAGE(bufoff, gbase, voff) do { _Pragma("unroll") for (int _i = 0; _i < 2; ++_i) \
;         __builtin_amdgcn_global_load_lds((const unsigned*)((const char*)(gbase) + (voff)[_i]), (LAS unsigned*)(lds + (bufoff) + ldsw + _i * 8192), 16, 0, 0); } while (0)
; #define PG8_WAIT_V(n) asm volatile("s_waitcnt vmcnt(" #n ")" ::: "memory")
; #define PG8_BAR __builtin_amdgcn_s_barrier()
; template <class Epi>
; __device__ __forceinline__ void gemm_phase(LAS unsigned char* lds, const Gemm g, const StaticOrder& S, const Epi& E) {
;     ...
;     for (int i = 0; i < 2; ++i) { int R, C; stage_rc(tid * 16 + i * 8192, R, C); const int Rb = Epi::PERM ? ((R & ~31) + perm32(R & 31)) : R;
;         voffA[i] = (unsigned)(R * g.lda + C) * 2u; voffB[i] = (unsigned)(Rb * g.ldb + C) * 2u; }
;     const size_t kstep = (size_t)(BK * 2);
;     const size_t hstepA = (size_t)HALF * g.lda * 2, hstepB = (size_t)HALF * g.ldb * 2;
;     const size_t tstepA = 2 * hstepA, tstepB = 2 * hstepB;
;     const unsigned ldsw = (unsigned)wid * 1024u;
;     const int aoff = lds_byte(wr * 64 + fr, fq * 8), boff = lds_byte(wc * 32 + fr, fq * 8);
;     ...
;     Unit cur, nxt; int ui = 0;
;     if (!S.next(0, cur)) return;
;     f32x4 acc[2][2][4][2];
; #pragma unroll
;     for (int a = 0; a < 2; ++a)
; #pragma unroll
;         for (int b = 0; b < 2; ++b)
; #pragma unroll
;             for (int m = 0; m < 4; ++m)
; #pragma unroll
;                 for (int n = 0; n < 2; ++n) acc[a][b][m][n] = (f32x4){0.f, 0.f, 0.f, 0.f};
;     bf16x8 At[4][2], B0[2][2], B1[2][2];
;     const char* cA = (const char*)g.A + (size_t)cur.pm * tstepA; const char* cB = (const char*)g.Bt + (size_t)cur.pb * tstepB;
;     PG8_STAGE(PG8_SB(0, 0), cB, voffB); PG8_STAGE(PG8_SB(0, 1), cB + hstepB, voffB); PG8_STAGE(PG8_SA(0, 0), cA, voffA); PG8_STAGE(PG8_SA(0, 1), cA + hstepA, voffA);
;     if (wr == 1) PG8_BAR;
;     PG8_WAIT_V(2); PG8_BAR;
;     PG8_STAGE(PG8_SB(1, 0), cB + kstep, voffB); PG8_STAGE(PG8_SA(1, 0), cA + kstep, voffA); PG8_STAGE(PG8_SB(1, 1), cB + hstepB + kstep, voffB);
;     PG8_WAIT_V(6); PG8_BAR;
;     for (;;) {
;         const bool has_next = S.next(ui + 1, nxt);
;         const char* nA = has_next ? (const char*)g.A + (size_t)nxt.pm * tstepA : cA; const char* nB = has_next ? (const char*)g.Bt + (size_t)nxt.pb * tstepB : cB;
.LBB0_1327:
	s_ashr_i32 s1, s12, 31
	s_lshr_b32 s1, s1, 26
	s_lshl_b32 s14, s14, 5
	s_mov_b64 s[28:29], 0x80
	s_add_i32 s1, s12, s1
	s_and_b32 s16, s14, 0x60
	s_add_i32 m0, s47, 0x18000
	v_lshl_add_u64 v[6:7], v[6:7], 0, s[28:29]
	s_ashr_i32 s53, s1, 6
	s_lshl_b32 s1, s13, 6
	s_lshl_b32 s13, s13, 13
	s_lshl_b32 s17, s16, 7
	s_waitcnt vmcnt(2)
	s_barrier
	global_load_lds_dwordx4 v[6:7], off
	v_lshl_add_u64 v[4:5], v[4:5], 0, s[28:29]
	s_add_i32 m0, s47, 0x1a000
	s_add_i32 s54, s47, 0x8000
	s_add_i32 s55, s47, 0xa000
	global_load_lds_dwordx4 v[4:5], off
	v_lshl_add_u64 v[0:1], v[0:1], 0, s[28:29]
	s_mov_b32 m0, s54
	s_add_u32 s14, s10, 0x80080
	global_load_lds_dwordx4 v[0:1], off
	v_lshl_add_u64 v[0:1], v[2:3], 0, s[28:29]
	s_mov_b32 m0, s55
	s_addc_u32 s15, s11, 0
	global_load_lds_dwordx4 v[0:1], off
	s_add_i32 m0, s47, 0x1c000
	s_nop 0
	global_load_lds_dwordx4 v154, s[14:15]
	v_lshl_add_u64 v[0:1], s[14:15], 0, v[158:159]
	s_add_i32 m0, s47, 0x1e000
	s_cmp_gt_i32 s12, 63
	global_load_lds_dwordx4 v[0:1], off
	v_lshrrev_b32_e32 v1, 1, v204
	v_and_b32_e32 v1, 24, v1
	v_and_b32_e32 v0, 15, v204
	v_lshlrev_b32_e32 v2, 1, v1
	v_lshl_or_b32 v2, v0, 6, v2
	v_or_b32_e32 v160, s1, v0
	v_lshlrev_b32_e32 v0, 15, v8
	v_and_b32_e32 v0, 0xffff0000, v0
	v_or_b32_e32 v162, s16, v1
	v_lshl_add_u32 v0, v9, 12, v0
	v_and_b32_e32 v1, 1, v8
	v_lshl_or_b32 v0, v1, 6, v0
	v_lshl_add_u32 v164, v10, 1, v0
	v_lshlrev_b32_e32 v0, 15, v11
	v_lshlrev_b32_e32 v3, 2, v204
	s_cselect_b64 s[30:31], -1, 0
	s_add_i32 s56, s53, -2
	v_and_b32_e32 v0, 0xffff0000, v0
	v_and_b32_e32 v3, 32, v3
	s_waitcnt vmcnt(6)
	s_cmpk_lt_u32 s5, 0x100
	v_lshl_add_u32 v0, v12, 12, v0
	v_and_b32_e32 v1, 1, v11
	s_sext_i32_i8 s14, s4
	v_bitop3_b32 v4, v2, s13, v3 bitop3:0xde
	v_bitop3_b32 v163, v2, s17, v3 bitop3:0xde
	s_cselect_b64 s[34:35], -1, 0
	s_ashr_i32 s4, s1, 31
	v_lshl_or_b32 v0, v1, 6, v0
	s_add_i32 s59, 0, 0x10000
	s_add_i32 s60, 0, 0x14000
	v_mov_b32_e32 v161, s4
	s_ashr_i32 s57, s94, 31
	s_mov_b32 s58, s94
	v_mov_b32_e32 v165, v155
	v_lshl_add_u32 v166, v13, 1, v0
	v_mov_b32_e32 v167, v155
	v_mov_b64_e32 v[168:169], 0x400
	v_mov_b64_e32 v[170:171], 0x3ff
	v_add_u32_e32 v173, s59, v163
	v_add_u32_e32 v175, s60, v163
	v_add_u32_e32 v181, 0, v4
	v_mov_b32_e32 v183, 0x358637bd
	s_mov_b32 s61, 0x800000
	s_mov_b32 s62, 0x20000
	s_mov_b32 s63, 0x30000
	s_mov_b32 s64, 0x80000
	s_mov_b32 s65, 0x90000
	s_mov_b32 s66, 0xa0000
	s_mov_b32 s67, 0xb0000
	s_barrier
	s_branch .LBB0_1330

; #define PG8_STAGE(bufoff, gbase, voff) do { _Pragma("unroll") for (int _i = 0; _i < 2; ++_i) \
;         __builtin_amdgcn_global_load_lds((const unsigned*)((const char*)(gbase) + (voff)[_i]), (LAS unsigned*)(lds + (bufoff) + ldsw + _i * 8192), 16, 0, 0); } while (0)
; #define PG8_LDA(dst, b, h) do { _Pragma("unroll") for (int m = 0; m < 4; ++m) _Pragma("unroll") for (int k = 0; k < 2; ++k) dst[m][k] = *(const LAS bf16x8*)(lds + PG8_SA(b, h) + aoff + m * 2048 + k * 1024); } while (0)
; #define PG8_LDB(dst, b, h) do { _Pragma("unroll") for (int n = 0; n < 2; ++n) _Pragma("unroll") for (int k = 0; k < 2; ++k) dst[n][k] = *(const LAS bf16x8*)(lds + PG8_SB(b, h) + boff + n * 2048 + k * 1024); } while (0)
; #define PG8_MMA(ai, bj, At, Bt) do { __builtin_amdgcn_s_setprio(1); _Pragma("unroll") for (int m = 0; m < 4; ++m) _Pragma("unroll") for (int n = 0; n < 2; ++n) _Pragma("unroll") for (int k = 0; k < 2; ++k) \
;         acc[ai][bj][m][n] = __builtin_amdgcn_mfma_f32_16x16x32_bf16(Bt[n][k], At[m][k], acc[ai][bj][m][n], 0, 0, 0); __builtin_amdgcn_s_setprio(0); } while (0)
; #define PG8_WAIT_V(n) asm volatile("s_waitcnt vmcnt(" #n ")" ::: "memory")
; #define PG8_WAIT_L(n) asm volatile("s_waitcnt lgkmcnt(" #n ")" ::: "memory")
; #define PG8_BAR __builtin_amdgcn_s_barrier()
; #define PG8_SCHED __builtin_amdgcn_sched_barrier(0)
; template <class Epi>
; __device__ __forceinline__ void gemm_phase(LAS unsigned char* lds, const Gemm g, const StaticOrder& S, const Epi& E) {
;     ...
;             const bool last = (t == nt - 2);
;             const char* a1 = cA + (size_t)(t + 1) * kstep;
;             const char* a2 = last ? nA : cA + (size_t)(t + 2) * kstep; const char* b2 = last ? nB : cB + (size_t)(t + 2) * kstep;
;             const char* a3 = a2 + kstep; const char* b3 = b2 + kstep;
;             PG8_LDB(B0, 0, 0); PG8_LDB(B1, 0, 1); PG8_SCHED; PG8_LDA(At, 0, 0); PG8_STAGE(PG8_SA(1, 1), a1 + hstepA, voffA);
;             PG8_WAIT_V(8); PG8_WAIT_L(0); PG8_BAR; PG8_MMA(0, 0, At, B0); PG8_MMA(0, 1, At, B1); PG8_BAR; PG8_SCHED;
;             PG8_LDA(At, 0, 1); PG8_STAGE(PG8_SB(0, 0), b2, voffB); PG8_STAGE(PG8_SB(0, 1), b2 + hstepB, voffB); PG8_STAGE(PG8_SA(0, 0), a2, voffA);
.LBB0_1338:
	ds_read_b128 v[128:131], v173
	ds_read_b128 v[132:135], v173 offset:1024
	ds_read_b128 v[136:139], v173 offset:2048
	ds_read_b128 v[140:143], v173 offset:3072
	ds_read_b128 v[144:147], v175
	ds_read_b128 v[148:151], v175 offset:1024
	ds_read_b128 v[176:179], v175 offset:2048
	ds_read_b128 v[184:187], v175 offset:3072
	s_add_i32 s20, s10, 2
	s_add_u32 s11, s8, 0xfff80080
	s_addc_u32 s12, s9, -1
	s_cmp_eq_u32 s56, s10
	s_cselect_b32 s10, s17, s18
	s_cselect_b32 s13, s1, s12
	s_cselect_b32 s12, s15, s11
	s_cselect_b32 s11, s16, s19
	s_add_i32 m0, s47, 0xc000
	ds_read_b128 v[188:191], v181
	ds_read_b128 v[192:195], v181 offset:1024
	ds_read_b128 v[196:199], v181 offset:2048
	ds_read_b128 v[200:203], v181 offset:3072
	ds_read_b128 v[208:211], v181 offset:4096
	ds_read_b128 v[212:215], v181 offset:5120
	ds_read_b128 v[216:219], v181 offset:6144
	ds_read_b128 v[220:223], v181 offset:7168
	global_load_lds_dwordx4 v164, s[8:9]
	s_add_i32 m0, s47, 0xe000
	s_nop 0
	global_load_lds_dwordx4 v166, s[8:9]
	s_waitcnt vmcnt(8)
	s_waitcnt lgkmcnt(0)
	s_barrier
	s_setprio 1
	s_waitcnt lgkmcnt(0)
	v_mfma_f32_16x16x32_bf16 v[124:127], v[128:131], v[188:191], v[124:127]
	v_mfma_f32_16x16x32_bf16 v[124:127], v[132:135], v[192:195], v[124:127]
	v_mfma_f32_16x16x32_bf16 v[120:123], v[140:143], v[192:195], v[120:123]
	v_mfma_f32_16x16x32_bf16 v[120:123], v[136:139], v[188:191], v[120:123]
	v_mfma_f32_16x16x32_bf16 v[116:119], v[144:147], v[188:191], v[116:119]
	v_mfma_f32_16x16x32_bf16 v[116:119], v[148:151], v[192:195], v[116:119]
	v_mfma_f32_16x16x32_bf16 v[112:115], v[184:187], v[192:195], v[112:115]
	v_mfma_f32_16x16x32_bf16 v[112:115], v[176:179], v[188:191], v[112:115]
	v_mfma_f32_16x16x32_bf16 v[96:99], v[176:179], v[196:199], v[96:99]
	v_mfma_f32_16x16x32_bf16 v[96:99], v[184:187], v[200:203], v[96:99]
	v_mfma_f32_16x16x32_bf16 v[100:103], v[148:151], v[200:203], v[100:103]
	v_mfma_f32_16x16x32_bf16 v[100:103], v[144:147], v[196:199], v[100:103]
	v_mfma_f32_16x16x32_bf16 v[104:107], v[136:139], v[196:199], v[104:107]
	v_mfma_f32_16x16x32_bf16 v[104:107], v[140:143], v[200:203], v[104:107]
	v_mfma_f32_16x16x32_bf16 v[108:111], v[132:135], v[200:203], v[108:111]
	v_mfma_f32_16x16x32_bf16 v[108:111], v[128:131], v[196:199], v[108:111]
	s_setprio 0
	s_setprio 1
	v_mfma_f32_16x16x32_bf16 v[92:95], v[128:131], v[208:211], v[92:95]
	v_mfma_f32_16x16x32_bf16 v[92:95], v[132:135], v[212:215], v[92:95]
	v_mfma_f32_16x16x32_bf16 v[88:91], v[140:143], v[212:215], v[88:91]
	v_mfma_f32_16x16x32_bf16 v[88:91], v[136:139], v[208:211], v[88:91]
	v_mfma_f32_16x16x32_bf16 v[84:87], v[144:147], v[208:211], v[84:87]
	v_mfma_f32_16x16x32_bf16 v[84:87], v[148:151], v[212:215], v[84:87]
	v_mfma_f32_16x16x32_bf16 v[80:83], v[184:187], v[212:215], v[80:83]
	v_mfma_f32_16x16x32_bf16 v[80:83], v[176:179], v[208:211], v[80:83]
	v_mfma_f32_16x16x32_bf16 v[64:67], v[176:179], v[216:219], v[64:67]
	v_mfma_f32_16x16x32_bf16 v[64:67], v[184:187], v[220:223], v[64:67]
	v_mfma_f32_16x16x32_bf16 v[68:71], v[148:151], v[220:223], v[68:71]
	v_mfma_f32_16x16x32_bf16 v[68:71], v[144:147], v[216:219], v[68:71]
	v_mfma_f32_16x16x32_bf16 v[72:75], v[136:139], v[216:219], v[72:75]
	v_mfma_f32_16x16x32_bf16 v[72:75], v[140:143], v[220:223], v[72:75]
	v_mfma_f32_16x16x32_bf16 v[76:79], v[132:135], v[220:223], v[76:79]
	v_mfma_f32_16x16x32_bf16 v[76:79], v[128:131], v[216:219], v[76:79]
	s_setprio 0
	s_barrier
	s_add_i32 s21, s59, s46
	v_lshl_add_u64 v[224:225], s[10:11], 0, v[154:155]
	s_mov_b32 m0, s21
	ds_read_b128 v[188:191], v181 offset:16384
	ds_read_b128 v[192:195], v181 offset:17408
	ds_read_b128 v[196:199], v181 offset:18432
	ds_read_b128 v[200:203], v181 offset:19456
	ds_read_b128 v[208:211], v181 offset:20480
	ds_read_b128 v[212:215], v181 offset:21504
	ds_read_b128 v[216:219], v181 offset:22528
	ds_read_b128 v[220:223], v181 offset:23552
	global_load_lds_dwordx4 v[224:225], off
	s_add_i32 m0, s21, 0x2000
	s_add_u32 s68, s10, 0x80000
	v_lshl_add_u64 v[226:227], s[10:11], 0, v[158:159]
	s_addc_u32 s69, s11, 0
	s_add_i32 s21, s60, s46
	global_load_lds_dwordx4 v[226:227], off
	s_mov_b32 m0, s21
	v_lshl_add_u64 v[232:233], s[12:13], 0, v[156:157]
	global_load_lds_dwordx4 v154, s[68:69]
	s_add_i32 m0, s21, 0x2000
	s_nop 0
	global_load_lds_dwordx4 v158, s[68:69]
	v_lshl_add_u64 v[230:231], s[12:13], 0, v[152:153]
	s_mov_b32 m0, s47
	s_nop 0
	global_load_lds_dwordx4 v[230:231], off
	s_mov_b32 m0, s48
	s_nop 0
	global_load_lds_dwordx4 v[232:233], off
	s_waitcnt vmcnt(8)
	s_waitcnt lgkmcnt(0)
	s_barrier
; #define PG8_STAGE(bufoff, gbase, voff) do { _Pragma("unroll") for (int _i = 0; _i < 2; ++_i) \
;         __builtin_amdgcn_global_load_lds((const unsigned*)((const char*)(gbase) + (voff)[_i]), (LAS unsigned*)(lds + (bufoff) + ldsw + _i * 8192), 16, 0, 0); } while (0)
; #define PG8_LDA(dst, b, h) do { _Pragma("unroll") for (int m = 0; m < 4; ++m) _Pragma("unroll") for (int k = 0; k < 2; ++k) dst[m][k] = *(const LAS bf16x8*)(lds + PG8_SA(b, h) + aoff + m * 2048 + k * 1024); } while (0)
; #define PG8_LDB(dst, b, h) do { _Pragma("unroll") for (int n = 0; n < 2; ++n) _Pragma("unroll") for (int k = 0; k < 2; ++k) dst[n][k] = *(const LAS bf16x8*)(lds + PG8_SB(b, h) + boff + n * 2048 + k * 1024); } while (0)
; #define PG8_MMA(ai, bj, At, Bt) do { __builtin_amdgcn_s_setprio(1); _Pragma("unroll") for (int m = 0; m < 4; ++m) _Pragma("unroll") for (int n = 0; n < 2; ++n) _Pragma("unroll") for (int k = 0; k < 2; ++k) \
;         acc[ai][bj][m][n] = __builtin_amdgcn_mfma_f32_16x16x32_bf16(Bt[n][k], At[m][k], acc[ai][bj][m][n], 0, 0, 0); __builtin_amdgcn_s_setprio(0); } while (0)
; #define PG8_WAIT_V(n) asm volatile("s_waitcnt vmcnt(" #n ")" ::: "memory")
; #define PG8_WAIT_L(n) asm volatile("s_waitcnt lgkmcnt(" #n ")" ::: "memory")
; #define PG8_BAR __builtin_amdgcn_s_barrier()
; #define PG8_SCHED __builtin_amdgcn_sched_barrier(0)
; template <class Epi>
; __device__ __forceinline__ void gemm_phase(LAS unsigned char* lds, const Gemm g, const StaticOrder& S, const Epi& E) {
;     ...
;             PG8_WAIT_V(8); PG8_WAIT_L(0); PG8_BAR; PG8_MMA(1, 0, At, B0); PG8_MMA(1, 1, At, B1); PG8_BAR; PG8_SCHED;
;             PG8_LDB(B0, 1, 0); PG8_LDB(B1, 1, 1); PG8_SCHED; PG8_LDA(At, 1, 0); PG8_STAGE(PG8_SA(0, 1), a2 + hstepA, voffA);
;             PG8_WAIT_V(8); PG8_WAIT_L(0); PG8_BAR; PG8_MMA(0, 0, At, B0); PG8_MMA(0, 1, At, B1); PG8_BAR; PG8_SCHED;
	s_setprio 1
	s_waitcnt lgkmcnt(0)
	v_mfma_f32_16x16x32_bf16 v[60:63], v[128:131], v[188:191], v[60:63]
	v_mfma_f32_16x16x32_bf16 v[60:63], v[132:135], v[192:195], v[60:63]
	v_mfma_f32_16x16x32_bf16 v[56:59], v[140:143], v[192:195], v[56:59]
	v_mfma_f32_16x16x32_bf16 v[56:59], v[136:139], v[188:191], v[56:59]
	v_mfma_f32_16x16x32_bf16 v[52:55], v[144:147], v[188:191], v[52:55]
	v_mfma_f32_16x16x32_bf16 v[52:55], v[148:151], v[192:195], v[52:55]
	v_mfma_f32_16x16x32_bf16 v[48:51], v[184:187], v[192:195], v[48:51]
	v_mfma_f32_16x16x32_bf16 v[48:51], v[176:179], v[188:191], v[48:51]
	v_mfma_f32_16x16x32_bf16 v[32:35], v[176:179], v[196:199], v[32:35]
	v_mfma_f32_16x16x32_bf16 v[32:35], v[184:187], v[200:203], v[32:35]
	v_mfma_f32_16x16x32_bf16 v[36:39], v[148:151], v[200:203], v[36:39]
	v_mfma_f32_16x16x32_bf16 v[36:39], v[144:147], v[196:199], v[36:39]
	v_mfma_f32_16x16x32_bf16 v[40:43], v[136:139], v[196:199], v[40:43]
	v_mfma_f32_16x16x32_bf16 v[40:43], v[140:143], v[200:203], v[40:43]
	v_mfma_f32_16x16x32_bf16 v[44:47], v[132:135], v[200:203], v[44:47]
	v_mfma_f32_16x16x32_bf16 v[44:47], v[128:131], v[196:199], v[44:47]
	s_setprio 0
	s_setprio 1
	v_mfma_f32_16x16x32_bf16 v[28:31], v[128:131], v[208:211], v[28:31]
	v_mfma_f32_16x16x32_bf16 v[28:31], v[132:135], v[212:215], v[28:31]
	v_mfma_f32_16x16x32_bf16 v[24:27], v[140:143], v[212:215], v[24:27]
	v_mfma_f32_16x16x32_bf16 v[24:27], v[136:139], v[208:211], v[24:27]
	v_mfma_f32_16x16x32_bf16 v[20:23], v[144:147], v[208:211], v[20:23]
	v_mfma_f32_16x16x32_bf16 v[20:23], v[148:151], v[212:215], v[20:23]
	v_mfma_f32_16x16x32_bf16 v[16:19], v[184:187], v[212:215], v[16:19]
	v_mfma_f32_16x16x32_bf16 v[16:19], v[176:179], v[208:211], v[16:19]
	v_mfma_f32_16x16x32_bf16 v[0:3], v[176:179], v[216:219], v[0:3]
	v_mfma_f32_16x16x32_bf16 v[0:3], v[184:187], v[220:223], v[0:3]
	v_mfma_f32_16x16x32_bf16 v[4:7], v[148:151], v[220:223], v[4:7]
	v_mfma_f32_16x16x32_bf16 v[4:7], v[144:147], v[216:219], v[4:7]
	v_mfma_f32_16x16x32_bf16 v[8:11], v[136:139], v[216:219], v[8:11]
	v_mfma_f32_16x16x32_bf16 v[8:11], v[140:143], v[220:223], v[8:11]
	v_mfma_f32_16x16x32_bf16 v[12:15], v[132:135], v[220:223], v[12:15]
	v_mfma_f32_16x16x32_bf16 v[12:15], v[128:131], v[216:219], v[12:15]
	s_setprio 0
	s_barrier
	s_add_i32 s21, 0, 0x18000
	s_add_i32 s33, 0, 0x1c000
	v_add_u32_e32 v140, s21, v163
	v_add_u32_e32 v172, s33, v163
	ds_read_b128 v[128:131], v140
	ds_read_b128 v[132:135], v140 offset:1024
	ds_read_b128 v[136:139], v140 offset:2048
	ds_read_b128 v[140:143], v140 offset:3072
	ds_read_b128 v[144:147], v172
	ds_read_b128 v[148:151], v172 offset:1024
	ds_read_b128 v[176:179], v172 offset:2048
	ds_read_b128 v[184:187], v172 offset:3072
	s_add_u32 s12, s12, 0x80000
	s_addc_u32 s13, s13, 0
	s_mov_b32 m0, s49
	ds_read_b128 v[188:191], v181 offset:32768
	ds_read_b128 v[192:195], v181 offset:33792
	ds_read_b128 v[196:199], v181 offset:34816
	ds_read_b128 v[200:203], v181 offset:35840
	ds_read_b128 v[208:211], v181 offset:36864
	ds_read_b128 v[212:215], v181 offset:37888
	ds_read_b128 v[216:219], v181 offset:38912
	ds_read_b128 v[220:223], v181 offset:39936
	global_load_lds_dwordx4 v152, s[12:13]
	s_mov_b32 m0, s50
	s_nop 0
	global_load_lds_dwordx4 v156, s[12:13]
	s_waitcnt vmcnt(8)
	s_waitcnt lgkmcnt(0)
	s_barrier
	s_setprio 1
	s_waitcnt lgkmcnt(0)
	v_mfma_f32_16x16x32_bf16 v[124:127], v[128:131], v[188:191], v[124:127]
	v_mfma_f32_16x16x32_bf16 v[124:127], v[132:135], v[192:195], v[124:127]
	v_mfma_f32_16x16x32_bf16 v[120:123], v[140:143], v[192:195], v[120:123]
	v_mfma_f32_16x16x32_bf16 v[120:123], v[136:139], v[188:191], v[120:123]
	v_mfma_f32_16x16x32_bf16 v[116:119], v[144:147], v[188:191], v[116:119]
	v_mfma_f32_16x16x32_bf16 v[116:119], v[148:151], v[192:195], v[116:119]
	v_mfma_f32_16x16x32_bf16 v[112:115], v[184:187], v[192:195], v[112:115]
	v_mfma_f32_16x16x32_bf16 v[112:115], v[176:179], v[188:191], v[112:115]
	v_mfma_f32_16x16x32_bf16 v[96:99], v[176:179], v[196:199], v[96:99]
	v_mfma_f32_16x16x32_bf16 v[96:99], v[184:187], v[200:203], v[96:99]
	v_mfma_f32_16x16x32_bf16 v[100:103], v[148:151], v[200:203], v[100:103]
	v_mfma_f32_16x16x32_bf16 v[100:103], v[144:147], v[196:199], v[100:103]
	v_mfma_f32_16x16x32_bf16 v[104:107], v[136:139], v[196:199], v[104:107]
	v_mfma_f32_16x16x32_bf16 v[104:107], v[140:143], v[200:203], v[104:107]
	v_mfma_f32_16x16x32_bf16 v[108:111], v[132:135], v[200:203], v[108:111]
	v_mfma_f32_16x16x32_bf16 v[108:111], v[128:131], v[196:199], v[108:111]
	s_setprio 0
	s_setprio 1
	v_mfma_f32_16x16x32_bf16 v[92:95], v[128:131], v[208:211], v[92:95]
	v_mfma_f32_16x16x32_bf16 v[92:95], v[132:135], v[212:215], v[92:95]
	v_mfma_f32_16x16x32_bf16 v[88:91], v[140:143], v[212:215], v[88:91]
	v_mfma_f32_16x16x32_bf16 v[88:91], v[136:139], v[208:211], v[88:91]
	v_mfma_f32_16x16x32_bf16 v[84:87], v[144:147], v[208:211], v[84:87]
	v_mfma_f32_16x16x32_bf16 v[84:87], v[148:151], v[212:215], v[84:87]
	v_mfma_f32_16x16x32_bf16 v[80:83], v[184:187], v[212:215], v[80:83]
	v_mfma_f32_16x16x32_bf16 v[80:83], v[176:179], v[208:211], v[80:83]
	v_mfma_f32_16x16x32_bf16 v[64:67], v[176:179], v[216:219], v[64:67]
	v_mfma_f32_16x16x32_bf16 v[64:67], v[184:187], v[220:223], v[64:67]
	v_mfma_f32_16x16x32_bf16 v[68:71], v[148:151], v[220:223], v[68:71]
	v_mfma_f32_16x16x32_bf16 v[68:71], v[144:147], v[216:219], v[68:71]
	v_mfma_f32_16x16x32_bf16 v[72:75], v[136:139], v[216:219], v[72:75]
	v_mfma_f32_16x16x32_bf16 v[72:75], v[140:143], v[220:223], v[72:75]
	v_mfma_f32_16x16x32_bf16 v[76:79], v[132:135], v[220:223], v[76:79]
	v_mfma_f32_16x16x32_bf16 v[76:79], v[128:131], v[216:219], v[76:79]
	s_setprio 0
	s_barrier
; #define PG8_STAGE(bufoff, gbase, voff) do { _Pragma("unroll") for (int _i = 0; _i < 2; ++_i) \
;         __builtin_amdgcn_global_load_lds((const unsigned*)((const char*)(gbase) + (voff)[_i]), (LAS unsigned*)(lds + (bufoff) + ldsw + _i * 8192), 16, 0, 0); } while (0)
; #define PG8_LDA(dst, b, h) do { _Pragma("unroll") for (int m = 0; m < 4; ++m) _Pragma("unroll") for (int k = 0; k < 2; ++k) dst[m][k] = *(const LAS bf16x8*)(lds + PG8_SA(b, h) + aoff + m * 2048 + k * 1024); } while (0)
; #define PG8_MMA(ai, bj, At, Bt) do { __builtin_amdgcn_s_setprio(1); _Pragma("unroll") for (int m = 0; m < 4; ++m) _Pragma("unroll") for (int n = 0; n < 2; ++n) _Pragma("unroll") for (int k = 0; k < 2; ++k) \
;         acc[ai][bj][m][n] = __builtin_amdgcn_mfma_f32_16x16x32_bf16(Bt[n][k], At[m][k], acc[ai][bj][m][n], 0, 0, 0); __builtin_amdgcn_s_setprio(0); } while (0)
; #define PG8_WAIT_V(n) asm volatile("s_waitcnt vmcnt(" #n ")" ::: "memory")
; #define PG8_WAIT_L(n) asm volatile("s_waitcnt lgkmcnt(" #n ")" ::: "memory")
; #define PG8_BAR __builtin_amdgcn_s_barrier()
; #define PG8_SCHED __builtin_amdgcn_sched_barrier(0)
; template <class Epi>
; __device__ __forceinline__ void gemm_phase(LAS unsigned char* lds, const Gemm g, const StaticOrder& S, const Epi& E) {
;     ...
;         for (int t = 0; t < nt; t += 2) {
;             const bool last = (t == nt - 2);
;             const char* a1 = cA + (size_t)(t + 1) * kstep;
;             const char* a2 = last ? nA : cA + (size_t)(t + 2) * kstep; const char* b2 = last ? nB : cB + (size_t)(t + 2) * kstep;
;             const char* a3 = a2 + kstep; const char* b3 = b2 + kstep;
;     ...
;             PG8_LDA(At, 1, 1); PG8_STAGE(PG8_SB(1, 0), b3, voffB); PG8_STAGE(PG8_SB(1, 1), b3 + hstepB, voffB); PG8_STAGE(PG8_SA(1, 0), a3, voffA);
;             PG8_WAIT_V(8); PG8_WAIT_L(0); PG8_BAR; PG8_MMA(1, 0, At, B0); PG8_MMA(1, 1, At, B1); PG8_BAR; PG8_SCHED;
;         }
	s_add_i32 s12, s21, s46
	v_lshl_add_u64 v[224:225], v[224:225], 0, s[28:29]
	s_mov_b32 m0, s12
	ds_read_b128 v[188:191], v181 offset:49152
	ds_read_b128 v[192:195], v181 offset:50176
	ds_read_b128 v[196:199], v181 offset:51200
	ds_read_b128 v[200:203], v181 offset:52224
	ds_read_b128 v[208:211], v181 offset:53248
	ds_read_b128 v[212:215], v181 offset:54272
	ds_read_b128 v[216:219], v181 offset:55296
	ds_read_b128 v[220:223], v181 offset:56320
	global_load_lds_dwordx4 v[224:225], off
	s_add_i32 m0, s12, 0x2000
	s_add_u32 s10, s10, 0x80080
	v_lshl_add_u64 v[224:225], v[226:227], 0, s[28:29]
	s_addc_u32 s11, s11, 0
	s_add_i32 s12, s33, s46
	global_load_lds_dwordx4 v[224:225], off
	s_mov_b32 m0, s12
	s_nop 0
	global_load_lds_dwordx4 v154, s[10:11]
	s_add_i32 m0, s12, 0x2000
	s_nop 0
	global_load_lds_dwordx4 v158, s[10:11]
	v_lshl_add_u64 v[224:225], v[230:231], 0, s[28:29]
	s_mov_b32 m0, s54
	s_nop 0
	global_load_lds_dwordx4 v[224:225], off
	v_lshl_add_u64 v[224:225], v[232:233], 0, s[28:29]
	s_mov_b32 m0, s55
	s_nop 0
	global_load_lds_dwordx4 v[224:225], off
	s_waitcnt vmcnt(8)
	s_waitcnt lgkmcnt(0)
	s_barrier
	s_setprio 1
	s_waitcnt lgkmcnt(0)
	v_mfma_f32_16x16x32_bf16 v[60:63], v[128:131], v[188:191], v[60:63]
	v_mfma_f32_16x16x32_bf16 v[60:63], v[132:135], v[192:195], v[60:63]
	v_mfma_f32_16x16x32_bf16 v[56:59], v[140:143], v[192:195], v[56:59]
	v_mfma_f32_16x16x32_bf16 v[56:59], v[136:139], v[188:191], v[56:59]
	v_mfma_f32_16x16x32_bf16 v[52:55], v[144:147], v[188:191], v[52:55]
	v_mfma_f32_16x16x32_bf16 v[52:55], v[148:151], v[192:195], v[52:55]
	v_mfma_f32_16x16x32_bf16 v[48:51], v[184:187], v[192:195], v[48:51]
	v_mfma_f32_16x16x32_bf16 v[48:51], v[176:179], v[188:191], v[48:51]
	v_mfma_f32_16x16x32_bf16 v[32:35], v[176:179], v[196:199], v[32:35]
	v_mfma_f32_16x16x32_bf16 v[32:35], v[184:187], v[200:203], v[32:35]
	v_mfma_f32_16x16x32_bf16 v[36:39], v[148:151], v[200:203], v[36:39]
	v_mfma_f32_16x16x32_bf16 v[36:39], v[144:147], v[196:199], v[36:39]
	v_mfma_f32_16x16x32_bf16 v[40:43], v[136:139], v[196:199], v[40:43]
	v_mfma_f32_16x16x32_bf16 v[40:43], v[140:143], v[200:203], v[40:43]
	v_mfma_f32_16x16x32_bf16 v[44:47], v[132:135], v[200:203], v[44:47]
	v_mfma_f32_16x16x32_bf16 v[44:47], v[128:131], v[196:199], v[44:47]
	s_setprio 0
	s_setprio 1
	v_mfma_f32_16x16x32_bf16 v[28:31], v[128:131], v[208:211], v[28:31]
	v_mfma_f32_16x16x32_bf16 v[28:31], v[132:135], v[212:215], v[28:31]
	v_mfma_f32_16x16x32_bf16 v[24:27], v[140:143], v[212:215], v[24:27]
	v_mfma_f32_16x16x32_bf16 v[24:27], v[136:139], v[208:211], v[24:27]
	v_mfma_f32_16x16x32_bf16 v[20:23], v[144:147], v[208:211], v[20:23]
	v_mfma_f32_16x16x32_bf16 v[20:23], v[148:151], v[212:215], v[20:23]
	v_mfma_f32_16x16x32_bf16 v[16:19], v[184:187], v[212:215], v[16:19]
	v_mfma_f32_16x16x32_bf16 v[16:19], v[176:179], v[208:211], v[16:19]
	v_mfma_f32_16x16x32_bf16 v[0:3], v[176:179], v[216:219], v[0:3]
	v_mfma_f32_16x16x32_bf16 v[0:3], v[184:187], v[220:223], v[0:3]
	v_mfma_f32_16x16x32_bf16 v[4:7], v[148:151], v[220:223], v[4:7]
	v_mfma_f32_16x16x32_bf16 v[4:7], v[144:147], v[216:219], v[4:7]
	v_mfma_f32_16x16x32_bf16 v[8:11], v[136:139], v[216:219], v[8:11]
	v_mfma_f32_16x16x32_bf16 v[8:11], v[140:143], v[220:223], v[8:11]
	v_mfma_f32_16x16x32_bf16 v[12:15], v[132:135], v[220:223], v[12:15]
	v_mfma_f32_16x16x32_bf16 v[12:15], v[128:131], v[216:219], v[12:15]
	s_setprio 0
	s_barrier
	s_add_u32 s8, s8, 0x100
	s_addc_u32 s9, s9, 0
	s_add_u32 s18, s18, 0x100
	s_addc_u32 s19, s19, 0
	s_cmp_ge_i32 s20, s53
	s_mov_b32 s10, s20
	s_cbranch_scc0 .LBB0_1338
